# E36: trailing half executes its re-stagger barrier after the next-unit scheduling (flag in m0 at the old site, barrier in front of the peeled first L-segment), 14 phases; on E28
# baseline (speedup 1.0000x reference)
.LBB0_303:
	s_lshl_b32 s18, s91, 20
	s_and_b64 s[8:9], s[34:35], exec
	s_cselect_b32 s8, s18, s94
	s_lshl_b32 s19, s90, 20
	s_and_b64 s[42:43], s[34:35], exec
	s_cselect_b32 s9, s19, s95
	s_add_i32 s94, s94, 0x80080
	s_addk_i32 s95, 0x100
	s_mov_b32 vcc_lo, -2
	s_cmp_eq_u32 m0, -1
	s_cbranch_scc0 .Lgk_rs_0
	s_barrier
.Lgk_rs_0:
	ds_read_b128 v[142:145], v136
	ds_read_b128 v[170:173], v136 offset:1024
	ds_read_b128 v[174:177], v136 offset:2048
	ds_read_b128 v[178:181], v136 offset:3072
	ds_read_b128 v[182:185], v137
	ds_read_b128 v[186:189], v137 offset:1024
	ds_read_b128 v[190:193], v137 offset:2048
	ds_read_b128 v[194:197], v137 offset:3072
	s_add_i32 s42, s94, 0xfff80080
	s_cmp_eq_u32 vcc_lo, 28
	s_cselect_b32 s97, s8, s42
	s_cselect_b32 s52, s9, s95
	s_or_b32 vcc_hi, s97, 0x80
	s_mov_b32 m0, s72
	ds_read_b128 v[198:201], v138
	ds_read_b128 v[202:205], v138 offset:1024
	ds_read_b128 v[228:231], v138 offset:2048
	ds_read_b128 v[232:235], v138 offset:3072
	ds_read_b128 v[236:239], v138 offset:4096
	ds_read_b128 v[240:243], v138 offset:5120
	ds_read_b128 v[244:247], v138 offset:6144
	ds_read_b128 v[248:251], v138 offset:7168
	buffer_load_dwordx4 v132, s[60:63], s94 offen lds
	s_mov_b32 m0, s47
	s_nop 0
	buffer_load_dwordx4 v134, s[60:63], s94 offen lds
	s_waitcnt vmcnt(8)
	s_waitcnt lgkmcnt(0)
	s_setprio 1
	s_barrier
	v_mfma_f32_16x16x32_bf16 v[114:117], v[142:145], v[198:201], 0
	v_mfma_f32_16x16x32_bf16 v[114:117], v[170:173], v[202:205], v[114:117]
	v_mfma_f32_16x16x32_bf16 v[110:113], v[174:177], v[198:201], 0
	v_mfma_f32_16x16x32_bf16 v[110:113], v[178:181], v[202:205], v[110:113]
	v_mfma_f32_16x16x32_bf16 v[122:125], v[190:193], v[198:201], 0
	v_mfma_f32_16x16x32_bf16 v[122:125], v[194:197], v[202:205], v[122:125]
	v_mfma_f32_16x16x32_bf16 v[126:129], v[182:185], v[198:201], 0
	v_mfma_f32_16x16x32_bf16 v[126:129], v[186:189], v[202:205], v[126:129]
	v_mfma_f32_16x16x32_bf16 v[118:121], v[182:185], v[228:231], 0
	v_mfma_f32_16x16x32_bf16 v[118:121], v[186:189], v[232:235], v[118:121]
	v_mfma_f32_16x16x32_bf16 v[98:101], v[190:193], v[228:231], 0
	v_mfma_f32_16x16x32_bf16 v[98:101], v[194:197], v[232:235], v[98:101]
	v_mfma_f32_16x16x32_bf16 v[102:105], v[174:177], v[228:231], 0
	v_mfma_f32_16x16x32_bf16 v[102:105], v[178:181], v[232:235], v[102:105]
	v_mfma_f32_16x16x32_bf16 v[106:109], v[142:145], v[228:231], 0
	v_mfma_f32_16x16x32_bf16 v[106:109], v[170:173], v[232:235], v[106:109]
	v_mfma_f32_16x16x32_bf16 v[94:97], v[142:145], v[236:239], 0
	v_mfma_f32_16x16x32_bf16 v[94:97], v[170:173], v[240:243], v[94:97]
	v_mfma_f32_16x16x32_bf16 v[86:89], v[174:177], v[236:239], 0
	v_mfma_f32_16x16x32_bf16 v[86:89], v[178:181], v[240:243], v[86:89]
	v_mfma_f32_16x16x32_bf16 v[82:85], v[190:193], v[236:239], 0
	v_mfma_f32_16x16x32_bf16 v[82:85], v[194:197], v[240:243], v[82:85]
	v_mfma_f32_16x16x32_bf16 v[90:93], v[182:185], v[236:239], 0
	v_mfma_f32_16x16x32_bf16 v[90:93], v[186:189], v[240:243], v[90:93]
	v_mfma_f32_16x16x32_bf16 v[74:77], v[182:185], v[244:247], 0
	v_mfma_f32_16x16x32_bf16 v[74:77], v[186:189], v[248:251], v[74:77]
	v_mfma_f32_16x16x32_bf16 v[66:69], v[190:193], v[244:247], 0
	v_mfma_f32_16x16x32_bf16 v[66:69], v[194:197], v[248:251], v[66:69]
	v_mfma_f32_16x16x32_bf16 v[70:73], v[174:177], v[244:247], 0
	v_mfma_f32_16x16x32_bf16 v[70:73], v[178:181], v[248:251], v[70:73]
	v_mfma_f32_16x16x32_bf16 v[78:81], v[142:145], v[244:247], 0
	v_mfma_f32_16x16x32_bf16 v[78:81], v[170:173], v[248:251], v[78:81]
	s_barrier
	s_setprio 0
	s_mov_b32 s42, s62
	s_mov_b32 s43, s63
	s_mov_b32 m0, s13
	ds_read_b128 v[198:201], v138 offset:16384
	buffer_load_dwordx4 v133, s[40:43], s52 offen lds
	s_add_i32 s96, s52, 0x80000
	s_mov_b32 m0, s14
	ds_read_b128 v[202:205], v138 offset:17408
	buffer_load_dwordx4 v135, s[40:43], s52 offen lds
	s_mov_b32 m0, s15
	ds_read_b128 v[228:231], v138 offset:18432
	buffer_load_dwordx4 v133, s[40:43], s96 offen lds
	s_mov_b32 m0, s16
	ds_read_b128 v[232:235], v138 offset:19456
	buffer_load_dwordx4 v135, s[40:43], s96 offen lds
	s_mov_b32 m0, s2
	ds_read_b128 v[236:239], v138 offset:20480
	buffer_load_dwordx4 v132, s[60:63], s97 offen lds
	s_mov_b32 m0, s21
	ds_read_b128 v[240:243], v138 offset:21504
	buffer_load_dwordx4 v134, s[60:63], s97 offen lds
	ds_read_b128 v[244:247], v138 offset:22528
	ds_read_b128 v[248:251], v138 offset:23552
	s_waitcnt vmcnt(8)
	s_waitcnt lgkmcnt(0)
	s_setprio 1
	s_barrier
	v_mfma_f32_16x16x32_bf16 v[62:65], v[142:145], v[198:201], 0
	v_mfma_f32_16x16x32_bf16 v[62:65], v[170:173], v[202:205], v[62:65]
	v_mfma_f32_16x16x32_bf16 v[54:57], v[174:177], v[198:201], 0
	v_mfma_f32_16x16x32_bf16 v[54:57], v[178:181], v[202:205], v[54:57]
	v_mfma_f32_16x16x32_bf16 v[50:53], v[190:193], v[198:201], 0
	v_mfma_f32_16x16x32_bf16 v[50:53], v[194:197], v[202:205], v[50:53]
	v_mfma_f32_16x16x32_bf16 v[58:61], v[182:185], v[198:201], 0
	v_mfma_f32_16x16x32_bf16 v[58:61], v[186:189], v[202:205], v[58:61]
	v_mfma_f32_16x16x32_bf16 v[42:45], v[182:185], v[228:231], 0
	v_mfma_f32_16x16x32_bf16 v[42:45], v[186:189], v[232:235], v[42:45]
	v_mfma_f32_16x16x32_bf16 v[34:37], v[190:193], v[228:231], 0
	v_mfma_f32_16x16x32_bf16 v[34:37], v[194:197], v[232:235], v[34:37]
	v_mfma_f32_16x16x32_bf16 v[38:41], v[174:177], v[228:231], 0
	v_mfma_f32_16x16x32_bf16 v[38:41], v[178:181], v[232:235], v[38:41]
	v_mfma_f32_16x16x32_bf16 v[46:49], v[142:145], v[228:231], 0
	v_mfma_f32_16x16x32_bf16 v[46:49], v[170:173], v[232:235], v[46:49]
	v_mfma_f32_16x16x32_bf16 v[30:33], v[142:145], v[236:239], 0
	v_mfma_f32_16x16x32_bf16 v[30:33], v[170:173], v[240:243], v[30:33]
	v_mfma_f32_16x16x32_bf16 v[22:25], v[174:177], v[236:239], 0
	v_mfma_f32_16x16x32_bf16 v[22:25], v[178:181], v[240:243], v[22:25]
	v_mfma_f32_16x16x32_bf16 v[18:21], v[190:193], v[236:239], 0
	v_mfma_f32_16x16x32_bf16 v[18:21], v[194:197], v[240:243], v[18:21]
	v_mfma_f32_16x16x32_bf16 v[26:29], v[182:185], v[236:239], 0
	v_mfma_f32_16x16x32_bf16 v[26:29], v[186:189], v[240:243], v[26:29]
	v_mfma_f32_16x16x32_bf16 v[10:13], v[182:185], v[244:247], 0
	v_mfma_f32_16x16x32_bf16 v[10:13], v[186:189], v[248:251], v[10:13]
	v_mfma_f32_16x16x32_bf16 v[2:5], v[190:193], v[244:247], 0
	v_mfma_f32_16x16x32_bf16 v[2:5], v[194:197], v[248:251], v[2:5]
	v_mfma_f32_16x16x32_bf16 v[6:9], v[174:177], v[244:247], 0
	v_mfma_f32_16x16x32_bf16 v[6:9], v[178:181], v[248:251], v[6:9]
	v_mfma_f32_16x16x32_bf16 v[14:17], v[142:145], v[244:247], 0
	v_mfma_f32_16x16x32_bf16 v[14:17], v[170:173], v[248:251], v[14:17]
	s_barrier
	s_setprio 0
	ds_read_b128 v[142:145], v139
	ds_read_b128 v[170:173], v139 offset:1024
	ds_read_b128 v[174:177], v139 offset:2048
	ds_read_b128 v[178:181], v139 offset:3072
	ds_read_b128 v[182:185], v140
	ds_read_b128 v[186:189], v140 offset:1024
	ds_read_b128 v[190:193], v140 offset:2048
	ds_read_b128 v[194:197], v140 offset:3072
	s_add_i32 s97, s97, 0x80000
	s_mov_b32 m0, s23
	ds_read_b128 v[198:201], v138 offset:32768
	ds_read_b128 v[202:205], v138 offset:33792
	ds_read_b128 v[228:231], v138 offset:34816
	ds_read_b128 v[232:235], v138 offset:35840
	ds_read_b128 v[236:239], v138 offset:36864
	ds_read_b128 v[240:243], v138 offset:37888
	ds_read_b128 v[244:247], v138 offset:38912
	ds_read_b128 v[248:251], v138 offset:39936
	buffer_load_dwordx4 v132, s[60:63], s97 offen lds
	s_mov_b32 m0, s24
	s_nop 0
	buffer_load_dwordx4 v134, s[60:63], s97 offen lds
	s_waitcnt vmcnt(8)
	s_waitcnt lgkmcnt(0)
	s_setprio 1
	s_barrier
	v_mfma_f32_16x16x32_bf16 v[114:117], v[142:145], v[198:201], v[114:117]
	v_mfma_f32_16x16x32_bf16 v[114:117], v[170:173], v[202:205], v[114:117]
	v_mfma_f32_16x16x32_bf16 v[110:113], v[174:177], v[198:201], v[110:113]
	v_mfma_f32_16x16x32_bf16 v[110:113], v[178:181], v[202:205], v[110:113]
	v_mfma_f32_16x16x32_bf16 v[122:125], v[190:193], v[198:201], v[122:125]
	v_mfma_f32_16x16x32_bf16 v[122:125], v[194:197], v[202:205], v[122:125]
	v_mfma_f32_16x16x32_bf16 v[126:129], v[182:185], v[198:201], v[126:129]
	v_mfma_f32_16x16x32_bf16 v[126:129], v[186:189], v[202:205], v[126:129]
	v_mfma_f32_16x16x32_bf16 v[118:121], v[182:185], v[228:231], v[118:121]
	v_mfma_f32_16x16x32_bf16 v[118:121], v[186:189], v[232:235], v[118:121]
	v_mfma_f32_16x16x32_bf16 v[98:101], v[190:193], v[228:231], v[98:101]
	v_mfma_f32_16x16x32_bf16 v[98:101], v[194:197], v[232:235], v[98:101]
	v_mfma_f32_16x16x32_bf16 v[102:105], v[174:177], v[228:231], v[102:105]
	v_mfma_f32_16x16x32_bf16 v[102:105], v[178:181], v[232:235], v[102:105]
	v_mfma_f32_16x16x32_bf16 v[106:109], v[142:145], v[228:231], v[106:109]
	v_mfma_f32_16x16x32_bf16 v[106:109], v[170:173], v[232:235], v[106:109]
	v_mfma_f32_16x16x32_bf16 v[94:97], v[142:145], v[236:239], v[94:97]
	v_mfma_f32_16x16x32_bf16 v[94:97], v[170:173], v[240:243], v[94:97]
	v_mfma_f32_16x16x32_bf16 v[86:89], v[174:177], v[236:239], v[86:89]
	v_mfma_f32_16x16x32_bf16 v[86:89], v[178:181], v[240:243], v[86:89]
	v_mfma_f32_16x16x32_bf16 v[82:85], v[190:193], v[236:239], v[82:85]
	v_mfma_f32_16x16x32_bf16 v[82:85], v[194:197], v[240:243], v[82:85]
	v_mfma_f32_16x16x32_bf16 v[90:93], v[182:185], v[236:239], v[90:93]
	v_mfma_f32_16x16x32_bf16 v[90:93], v[186:189], v[240:243], v[90:93]
	v_mfma_f32_16x16x32_bf16 v[74:77], v[182:185], v[244:247], v[74:77]
	v_mfma_f32_16x16x32_bf16 v[74:77], v[186:189], v[248:251], v[74:77]
	v_mfma_f32_16x16x32_bf16 v[66:69], v[190:193], v[244:247], v[66:69]
	v_mfma_f32_16x16x32_bf16 v[66:69], v[194:197], v[248:251], v[66:69]
	v_mfma_f32_16x16x32_bf16 v[70:73], v[174:177], v[244:247], v[70:73]
	v_mfma_f32_16x16x32_bf16 v[70:73], v[178:181], v[248:251], v[70:73]
	v_mfma_f32_16x16x32_bf16 v[78:81], v[142:145], v[244:247], v[78:81]
	v_mfma_f32_16x16x32_bf16 v[78:81], v[170:173], v[248:251], v[78:81]
	s_barrier
	s_setprio 0
	s_or_b32 s53, s52, 0x80
	s_mov_b32 m0, s31
	ds_read_b128 v[198:201], v138 offset:49152
	buffer_load_dwordx4 v133, s[40:43], s53 offen lds
	s_add_i32 s52, s52, 0x80080
	s_mov_b32 m0, s33
	ds_read_b128 v[202:205], v138 offset:50176
	buffer_load_dwordx4 v135, s[40:43], s53 offen lds
	s_mov_b32 m0, s68
	ds_read_b128 v[228:231], v138 offset:51200
	buffer_load_dwordx4 v133, s[40:43], s52 offen lds
	s_mov_b32 m0, s69
	ds_read_b128 v[232:235], v138 offset:52224
	buffer_load_dwordx4 v135, s[40:43], s52 offen lds
	s_mov_b32 m0, s36
	ds_read_b128 v[236:239], v138 offset:53248
	buffer_load_dwordx4 v132, s[60:63], vcc_hi offen lds
	s_mov_b32 m0, s37
	ds_read_b128 v[240:243], v138 offset:54272
	buffer_load_dwordx4 v134, s[60:63], vcc_hi offen lds
	ds_read_b128 v[244:247], v138 offset:55296
	ds_read_b128 v[248:251], v138 offset:56320
	s_waitcnt vmcnt(8)
	s_waitcnt lgkmcnt(0)
	s_setprio 1
	s_barrier
	v_mfma_f32_16x16x32_bf16 v[62:65], v[142:145], v[198:201], v[62:65]
	v_mfma_f32_16x16x32_bf16 v[62:65], v[170:173], v[202:205], v[62:65]
	v_mfma_f32_16x16x32_bf16 v[54:57], v[174:177], v[198:201], v[54:57]
	v_mfma_f32_16x16x32_bf16 v[54:57], v[178:181], v[202:205], v[54:57]
	v_mfma_f32_16x16x32_bf16 v[50:53], v[190:193], v[198:201], v[50:53]
	v_mfma_f32_16x16x32_bf16 v[50:53], v[194:197], v[202:205], v[50:53]
	v_mfma_f32_16x16x32_bf16 v[58:61], v[182:185], v[198:201], v[58:61]
	v_mfma_f32_16x16x32_bf16 v[58:61], v[186:189], v[202:205], v[58:61]
	v_mfma_f32_16x16x32_bf16 v[42:45], v[182:185], v[228:231], v[42:45]
	v_mfma_f32_16x16x32_bf16 v[42:45], v[186:189], v[232:235], v[42:45]
	v_mfma_f32_16x16x32_bf16 v[34:37], v[190:193], v[228:231], v[34:37]
	v_mfma_f32_16x16x32_bf16 v[34:37], v[194:197], v[232:235], v[34:37]
	v_mfma_f32_16x16x32_bf16 v[38:41], v[174:177], v[228:231], v[38:41]
	v_mfma_f32_16x16x32_bf16 v[38:41], v[178:181], v[232:235], v[38:41]
	v_mfma_f32_16x16x32_bf16 v[46:49], v[142:145], v[228:231], v[46:49]
	v_mfma_f32_16x16x32_bf16 v[46:49], v[170:173], v[232:235], v[46:49]
	v_mfma_f32_16x16x32_bf16 v[30:33], v[142:145], v[236:239], v[30:33]
	v_mfma_f32_16x16x32_bf16 v[30:33], v[170:173], v[240:243], v[30:33]
	v_mfma_f32_16x16x32_bf16 v[22:25], v[174:177], v[236:239], v[22:25]
	v_mfma_f32_16x16x32_bf16 v[22:25], v[178:181], v[240:243], v[22:25]
	v_mfma_f32_16x16x32_bf16 v[18:21], v[190:193], v[236:239], v[18:21]
	v_mfma_f32_16x16x32_bf16 v[18:21], v[194:197], v[240:243], v[18:21]
	v_mfma_f32_16x16x32_bf16 v[26:29], v[182:185], v[236:239], v[26:29]
	v_mfma_f32_16x16x32_bf16 v[26:29], v[186:189], v[240:243], v[26:29]
	v_mfma_f32_16x16x32_bf16 v[10:13], v[182:185], v[244:247], v[10:13]
	v_mfma_f32_16x16x32_bf16 v[10:13], v[186:189], v[248:251], v[10:13]
	v_mfma_f32_16x16x32_bf16 v[2:5], v[190:193], v[244:247], v[2:5]
	v_mfma_f32_16x16x32_bf16 v[2:5], v[194:197], v[248:251], v[2:5]
	v_mfma_f32_16x16x32_bf16 v[6:9], v[174:177], v[244:247], v[6:9]
	v_mfma_f32_16x16x32_bf16 v[6:9], v[178:181], v[248:251], v[6:9]
	v_mfma_f32_16x16x32_bf16 v[14:17], v[142:145], v[244:247], v[14:17]
	v_mfma_f32_16x16x32_bf16 v[14:17], v[170:173], v[248:251], v[14:17]
	s_barrier
	s_setprio 0
	s_add_i32 vcc_lo, vcc_lo, 2
	s_addk_i32 s94, 0x100
	s_addk_i32 s95, 0x100
	s_cmp_gt_u32 vcc_lo, 29

.LBB0_307:
	s_lshl_b32 s8, s93, 8
	s_add_i32 s8, s8, s46
	s_ashr_i32 s9, s8, 31
	v_lshl_add_u64 v[142:143], s[8:9], 3, v[130:131]
	global_load_dwordx2 v[144:145], v[142:143], off
	global_load_dwordx2 v[154:155], v[142:143], off offset:128
	v_pk_mul_f32 v[156:157], v[114:115], v[126:127]
	v_pk_mul_f32 v[170:171], v[112:113], v[124:125]
	v_pk_mul_f32 v[172:173], v[110:111], v[122:123]
	v_pk_mul_f32 v[174:175], v[108:109], v[120:121]
	v_pk_mul_f32 v[176:177], v[106:107], v[118:119]
	global_load_dwordx2 v[178:179], v[142:143], off offset:256
	global_load_dwordx2 v[126:127], v[142:143], off offset:384
	global_load_dwordx2 v[124:125], v[142:143], off offset:1024
	global_load_dwordx2 v[122:123], v[142:143], off offset:1152
	global_load_dwordx2 v[120:121], v[142:143], off offset:1280
	global_load_dwordx2 v[118:119], v[142:143], off offset:1408
	s_flbit_i32_b32 s8, 0
	s_min_u32 s42, s8, 32
	s_mul_i32 s8, s93, 0x58
	s_sub_i32 s93, 32, s42
	v_pk_mul_f32 v[128:129], v[116:117], v[128:129]
	s_lshl_b32 s9, s92, 1
	s_or_b32 s9, s9, s73
	s_add_i32 s8, s9, s8
	s_ashr_i32 s9, s8, 31
	s_lshl_b64 s[8:9], s[8:9], 15
	s_add_u32 s43, s25, s8
	s_addc_u32 s92, s30, s9
	s_add_u32 s8, s43, s64
	s_addc_u32 s9, s92, s65
	s_add_u32 s8, s8, s88
	s_addc_u32 s9, s9, 0
	v_pk_mul_f32 v[98:99], v[102:103], v[98:99]
	v_pk_mul_f32 v[100:101], v[104:105], v[100:101]
	v_pk_mul_f32 v[90:91], v[94:95], v[90:91]
	v_pk_mul_f32 v[92:93], v[96:97], v[92:93]
	v_pk_mul_f32 v[82:83], v[86:87], v[82:83]
	v_pk_mul_f32 v[84:85], v[88:89], v[84:85]
	v_pk_mul_f32 v[74:75], v[78:79], v[74:75]
	v_pk_mul_f32 v[76:77], v[80:81], v[76:77]
	v_pk_mul_f32 v[66:67], v[70:71], v[66:67]
	v_pk_mul_f32 v[68:69], v[72:73], v[68:69]
	v_pk_mul_f32 v[58:59], v[62:63], v[58:59]
	v_pk_mul_f32 v[60:61], v[64:65], v[60:61]
	v_pk_mul_f32 v[50:51], v[54:55], v[50:51]
	v_pk_mul_f32 v[52:53], v[56:57], v[52:53]
	v_pk_mul_f32 v[42:43], v[46:47], v[42:43]
	v_pk_mul_f32 v[44:45], v[48:49], v[44:45]
	v_pk_mul_f32 v[34:35], v[38:39], v[34:35]
	v_pk_mul_f32 v[36:37], v[40:41], v[36:37]
	v_pk_mul_f32 v[26:27], v[30:31], v[26:27]
	v_pk_mul_f32 v[28:29], v[32:33], v[28:29]
	v_pk_mul_f32 v[18:19], v[22:23], v[18:19]
	v_pk_mul_f32 v[20:21], v[24:25], v[20:21]
	v_pk_mul_f32 v[12:13], v[16:17], v[12:13]
	v_pk_mul_f32 v[10:11], v[14:15], v[10:11]
	v_pk_mul_f32 v[4:5], v[8:9], v[4:5]
	v_pk_mul_f32 v[2:3], v[6:7], v[2:3]
	v_readlane_b32 s97, v252, 18
	v_readlane_b32 s96, v252, 46
	s_waitcnt vmcnt(0)
	v_mov_b32_e32 v146, v145
	v_lshlrev_b64 v[142:143], s42, v[146:147]
	v_min_u32_e32 v142, 1, v142
	s_waitcnt vmcnt(6)
	v_mov_b32_e32 v146, v155
	v_or_b32_e32 v143, v143, v142
	v_cvt_f32_u32_e32 v180, v144
	v_lshlrev_b64 v[144:145], s42, v[146:147]
	v_cvt_f32_u32_e32 v143, v143
	v_min_u32_e32 v146, 1, v144
	v_or_b32_e32 v145, v145, v146
	v_cvt_f32_u32_e32 v154, v154
	v_cvt_f32_u32_e32 v145, v145
	v_fmamk_f32 v142, v180, 0x30000000, v209
	v_ldexp_f32 v143, v143, s93
	v_fmac_f32_e32 v142, 2.0, v143
	v_rsq_f32_e32 v143, v142
	v_fmamk_f32 v144, v154, 0x30000000, v209
	v_ldexp_f32 v145, v145, s93
	v_fmac_f32_e32 v144, 2.0, v145
	v_rsq_f32_e32 v145, v144
	v_mul_f32_e32 v146, 0xbfb8aa3b, v143
	v_pk_mul_f32 v[114:115], v[114:115], v[146:147] op_sel_hi:[1,0]
	v_pk_mul_f32 v[116:117], v[116:117], v[146:147] op_sel_hi:[1,0]
	v_exp_f32_e32 v114, v114
	v_exp_f32_e32 v115, v115
	v_pk_mul_f32 v[110:111], v[110:111], v[146:147] op_sel_hi:[1,0]
	v_pk_mul_f32 v[112:113], v[112:113], v[146:147] op_sel_hi:[1,0]
	v_mul_f32_e32 v146, 0xbfb8aa3b, v145
	v_exp_f32_e32 v116, v116
	v_exp_f32_e32 v117, v117
	v_exp_f32_e32 v110, v110
	v_exp_f32_e32 v111, v111
	v_exp_f32_e32 v112, v112
	v_exp_f32_e32 v113, v113
	v_pk_mul_f32 v[154:155], v[102:103], v[146:147] op_sel_hi:[1,0]
	v_pk_mul_f32 v[106:107], v[106:107], v[146:147] op_sel_hi:[1,0]
	v_exp_f32_e32 v154, v154
	v_exp_f32_e32 v155, v155
	v_pk_mul_f32 v[108:109], v[108:109], v[146:147] op_sel_hi:[1,0]
	v_exp_f32_e32 v106, v106
	v_exp_f32_e32 v107, v107
	v_pk_fma_f32 v[114:115], v[142:143], v[114:115], v[142:143] op_sel_hi:[0,1,0]
	v_pk_mul_f32 v[180:181], v[104:105], v[146:147] op_sel_hi:[1,0]
	v_exp_f32_e32 v108, v108
	v_exp_f32_e32 v109, v109
	v_pk_fma_f32 v[116:117], v[142:143], v[116:117], v[142:143] op_sel_hi:[0,1,0]
	v_rcp_f32_e32 v114, v114
	v_rcp_f32_e32 v115, v115
	v_exp_f32_e32 v180, v180
	v_exp_f32_e32 v181, v181
	v_pk_fma_f32 v[110:111], v[142:143], v[110:111], v[142:143] op_sel_hi:[0,1,0]
	v_pk_fma_f32 v[112:113], v[142:143], v[112:113], v[142:143] op_sel_hi:[0,1,0]
	v_rcp_f32_e32 v116, v116
	v_rcp_f32_e32 v117, v117
	v_rcp_f32_e32 v110, v110
	v_rcp_f32_e32 v111, v111
	v_rcp_f32_e32 v112, v112
	v_rcp_f32_e32 v113, v113
	v_pk_fma_f32 v[142:143], v[144:145], v[154:155], v[144:145] op_sel_hi:[0,1,0]
	v_pk_fma_f32 v[106:107], v[144:145], v[106:107], v[144:145] op_sel_hi:[0,1,0]
	v_rcp_f32_e32 v142, v142
	v_rcp_f32_e32 v143, v143
	v_pk_fma_f32 v[108:109], v[144:145], v[108:109], v[144:145] op_sel_hi:[0,1,0]
	v_rcp_f32_e32 v154, v106
	v_rcp_f32_e32 v155, v107
	v_pk_mul_f32 v[106:107], v[156:157], v[114:115]
	v_pk_fma_f32 v[144:145], v[144:145], v[180:181], v[144:145] op_sel_hi:[0,1,0]
	v_rcp_f32_e32 v180, v108
	v_rcp_f32_e32 v181, v109
	v_pk_mul_f32 v[108:109], v[128:129], v[116:117]
	v_cvt_pk_bf16_f32 v106, v106, v107
	v_pk_mul_f32 v[110:111], v[172:173], v[110:111]
	v_cvt_pk_bf16_f32 v107, v108, v109
	v_pk_mul_f32 v[112:113], v[170:171], v[112:113]
	v_cvt_pk_bf16_f32 v108, v110, v111
	s_waitcnt vmcnt(5)
	v_mov_b32_e32 v146, v179
	v_cvt_pk_bf16_f32 v109, v112, v113
	global_store_dwordx4 v141, v[106:109], s[8:9]
	v_pk_mul_f32 v[102:103], v[98:99], v[142:143]
	v_lshlrev_b64 v[98:99], s42, v[146:147]
	v_rcp_f32_e32 v106, v144
	v_rcp_f32_e32 v107, v145
	v_min_u32_e32 v98, 1, v98
	v_or_b32_e32 v98, v99, v98
	s_add_u32 s8, s43, s66
	v_pk_mul_f32 v[104:105], v[100:101], v[106:107]
	v_cvt_f32_u32_e32 v100, v178
	v_cvt_f32_u32_e32 v101, v98
	s_addc_u32 s9, s92, s67
	s_add_u32 s8, s8, s88
	v_fmamk_f32 v106, v100, 0x30000000, v209
	v_ldexp_f32 v100, v101, s93
	v_fmac_f32_e32 v106, 2.0, v100
	v_rsq_f32_e32 v107, v106
	v_pk_mul_f32 v[110:111], v[176:177], v[154:155]
	s_addc_u32 s9, s9, 0
	v_cvt_pk_bf16_f32 v98, v110, v111
	v_pk_mul_f32 v[112:113], v[174:175], v[180:181]
	s_waitcnt vmcnt(5)
	v_mov_b32_e32 v146, v127
	v_cvt_pk_bf16_f32 v99, v112, v113
	v_cvt_pk_bf16_f32 v100, v102, v103
	v_cvt_pk_bf16_f32 v101, v104, v105
	global_store_dwordx4 v141, v[98:101], s[8:9]
	s_add_u32 s8, s43, s70
	s_addc_u32 s9, s92, s71
	v_mul_f32_e32 v98, 0xbfb8aa3b, v107
	v_pk_mul_f32 v[100:101], v[94:95], v[98:99] op_sel_hi:[1,0]
	v_pk_mul_f32 v[94:95], v[86:87], v[98:99] op_sel_hi:[1,0]
	v_pk_mul_f32 v[102:103], v[96:97], v[98:99] op_sel_hi:[1,0]
	v_exp_f32_e32 v94, v94
	v_exp_f32_e32 v95, v95
	v_pk_mul_f32 v[96:97], v[88:89], v[98:99] op_sel_hi:[1,0]
	v_exp_f32_e32 v100, v100
	v_exp_f32_e32 v96, v96
	v_exp_f32_e32 v97, v97
	v_pk_fma_f32 v[94:95], v[106:107], v[94:95], v[106:107] op_sel_hi:[0,1,0]
	v_rcp_f32_e32 v94, v94
	v_rcp_f32_e32 v95, v95
	v_exp_f32_e32 v101, v101
	v_pk_fma_f32 v[96:97], v[106:107], v[96:97], v[106:107] op_sel_hi:[0,1,0]
	v_rcp_f32_e32 v96, v96
	v_rcp_f32_e32 v97, v97
	v_pk_mul_f32 v[86:87], v[82:83], v[94:95]
	v_lshlrev_b64 v[82:83], s42, v[146:147]
	v_pk_fma_f32 v[100:101], v[106:107], v[100:101], v[106:107] op_sel_hi:[0,1,0]
	v_min_u32_e32 v82, 1, v82
	v_rcp_f32_e32 v100, v100
	v_rcp_f32_e32 v101, v101
	v_or_b32_e32 v82, v83, v82
	v_pk_mul_f32 v[88:89], v[84:85], v[96:97]
	v_cvt_f32_u32_e32 v84, v126
	v_cvt_f32_u32_e32 v85, v82
	v_exp_f32_e32 v102, v102
	v_exp_f32_e32 v103, v103
	v_pk_mul_f32 v[90:91], v[90:91], v[100:101]
	s_add_u32 s8, s8, s88
	v_cvt_pk_bf16_f32 v82, v90, v91
	v_fmamk_f32 v90, v84, 0x30000000, v209
	v_ldexp_f32 v84, v85, s93
	v_pk_fma_f32 v[102:103], v[106:107], v[102:103], v[106:107] op_sel_hi:[0,1,0]
	v_fmac_f32_e32 v90, 2.0, v84
	v_rcp_f32_e32 v102, v102
	v_rcp_f32_e32 v103, v103
	v_rsq_f32_e32 v91, v90
	s_addc_u32 s9, s9, 0
	s_waitcnt vmcnt(5)
	v_mov_b32_e32 v146, v125
	v_pk_mul_f32 v[92:93], v[92:93], v[102:103]
	s_nop 0
	v_cvt_pk_bf16_f32 v83, v92, v93
	v_cvt_pk_bf16_f32 v84, v86, v87
	v_cvt_pk_bf16_f32 v85, v88, v89
	global_store_dwordx4 v141, v[82:85], s[8:9]
	s_add_u32 s8, s43, s26
	s_addc_u32 s9, s92, s27
	v_mul_f32_e32 v82, 0xbfb8aa3b, v91
	v_pk_mul_f32 v[84:85], v[78:79], v[82:83] op_sel_hi:[1,0]
	v_pk_mul_f32 v[78:79], v[70:71], v[82:83] op_sel_hi:[1,0]
	v_pk_mul_f32 v[86:87], v[80:81], v[82:83] op_sel_hi:[1,0]
	v_exp_f32_e32 v78, v78
	v_exp_f32_e32 v79, v79
	v_pk_mul_f32 v[80:81], v[72:73], v[82:83] op_sel_hi:[1,0]
	v_exp_f32_e32 v84, v84
	v_exp_f32_e32 v80, v80
	v_exp_f32_e32 v81, v81
	v_pk_fma_f32 v[78:79], v[90:91], v[78:79], v[90:91] op_sel_hi:[0,1,0]
	v_rcp_f32_e32 v78, v78
	v_rcp_f32_e32 v79, v79
	v_exp_f32_e32 v85, v85
	v_pk_fma_f32 v[80:81], v[90:91], v[80:81], v[90:91] op_sel_hi:[0,1,0]
	v_rcp_f32_e32 v80, v80
	v_rcp_f32_e32 v81, v81
	v_pk_mul_f32 v[70:71], v[66:67], v[78:79]
	v_lshlrev_b64 v[66:67], s42, v[146:147]
	v_pk_fma_f32 v[84:85], v[90:91], v[84:85], v[90:91] op_sel_hi:[0,1,0]
	v_min_u32_e32 v66, 1, v66
	v_rcp_f32_e32 v84, v84
	v_rcp_f32_e32 v85, v85
	v_or_b32_e32 v66, v67, v66
	v_pk_mul_f32 v[72:73], v[68:69], v[80:81]
	v_cvt_f32_u32_e32 v68, v124
	v_cvt_f32_u32_e32 v69, v66
	v_exp_f32_e32 v86, v86
	v_exp_f32_e32 v87, v87
	v_pk_mul_f32 v[74:75], v[74:75], v[84:85]
	s_add_u32 s8, s8, s88
	v_cvt_pk_bf16_f32 v66, v74, v75
	v_fmamk_f32 v74, v68, 0x30000000, v209
	v_ldexp_f32 v68, v69, s93
	v_pk_fma_f32 v[86:87], v[90:91], v[86:87], v[90:91] op_sel_hi:[0,1,0]
	v_fmac_f32_e32 v74, 2.0, v68
	v_rcp_f32_e32 v86, v86
	v_rcp_f32_e32 v87, v87
	v_rsq_f32_e32 v75, v74
	s_addc_u32 s9, s9, 0
	s_waitcnt vmcnt(5)
	v_mov_b32_e32 v146, v123
	v_pk_mul_f32 v[76:77], v[76:77], v[86:87]
	s_nop 0
	v_cvt_pk_bf16_f32 v67, v76, v77
	v_cvt_pk_bf16_f32 v68, v70, v71
	v_cvt_pk_bf16_f32 v69, v72, v73
	global_store_dwordx4 v141, v[66:69], s[8:9]
	s_add_u32 s8, s43, s22
	s_addc_u32 s9, s92, s82
	v_mul_f32_e32 v66, 0xbfb8aa3b, v75
	v_pk_mul_f32 v[68:69], v[62:63], v[66:67] op_sel_hi:[1,0]
	v_pk_mul_f32 v[62:63], v[54:55], v[66:67] op_sel_hi:[1,0]
	v_pk_mul_f32 v[70:71], v[64:65], v[66:67] op_sel_hi:[1,0]
	v_exp_f32_e32 v62, v62
	v_exp_f32_e32 v63, v63
	v_pk_mul_f32 v[64:65], v[56:57], v[66:67] op_sel_hi:[1,0]
	v_exp_f32_e32 v68, v68
	v_exp_f32_e32 v64, v64
	v_exp_f32_e32 v65, v65
	v_pk_fma_f32 v[62:63], v[74:75], v[62:63], v[74:75] op_sel_hi:[0,1,0]
	v_rcp_f32_e32 v62, v62
	v_rcp_f32_e32 v63, v63
	v_exp_f32_e32 v69, v69
	v_pk_fma_f32 v[64:65], v[74:75], v[64:65], v[74:75] op_sel_hi:[0,1,0]
	v_rcp_f32_e32 v64, v64
	v_rcp_f32_e32 v65, v65
	v_pk_mul_f32 v[54:55], v[50:51], v[62:63]
	v_lshlrev_b64 v[50:51], s42, v[146:147]
	v_pk_fma_f32 v[68:69], v[74:75], v[68:69], v[74:75] op_sel_hi:[0,1,0]
	v_min_u32_e32 v50, 1, v50
	v_rcp_f32_e32 v68, v68
	v_rcp_f32_e32 v69, v69
	v_or_b32_e32 v50, v51, v50
	v_pk_mul_f32 v[56:57], v[52:53], v[64:65]
	v_cvt_f32_u32_e32 v52, v122
	v_cvt_f32_u32_e32 v53, v50
	v_exp_f32_e32 v70, v70
	v_exp_f32_e32 v71, v71
	v_pk_mul_f32 v[58:59], v[58:59], v[68:69]
	s_add_u32 s8, s8, s88
	v_cvt_pk_bf16_f32 v50, v58, v59
	v_fmamk_f32 v58, v52, 0x30000000, v209
	v_ldexp_f32 v52, v53, s93
	v_pk_fma_f32 v[70:71], v[74:75], v[70:71], v[74:75] op_sel_hi:[0,1,0]
	v_fmac_f32_e32 v58, 2.0, v52
	v_rcp_f32_e32 v70, v70
	v_rcp_f32_e32 v71, v71
	v_rsq_f32_e32 v59, v58
	s_addc_u32 s9, s9, 0
	s_waitcnt vmcnt(5)
	v_mov_b32_e32 v146, v121
	v_pk_mul_f32 v[60:61], v[60:61], v[70:71]
	s_nop 0
	v_cvt_pk_bf16_f32 v51, v60, v61
	v_cvt_pk_bf16_f32 v52, v54, v55
	v_cvt_pk_bf16_f32 v53, v56, v57
	global_store_dwordx4 v141, v[50:53], s[8:9]
	s_add_u32 s8, s43, s12
	s_addc_u32 s9, s92, s83
	v_mul_f32_e32 v50, 0xbfb8aa3b, v59
	v_pk_mul_f32 v[52:53], v[46:47], v[50:51] op_sel_hi:[1,0]
	v_pk_mul_f32 v[46:47], v[38:39], v[50:51] op_sel_hi:[1,0]
	v_pk_mul_f32 v[54:55], v[48:49], v[50:51] op_sel_hi:[1,0]
	v_exp_f32_e32 v46, v46
	v_exp_f32_e32 v47, v47
	v_pk_mul_f32 v[48:49], v[40:41], v[50:51] op_sel_hi:[1,0]
	v_exp_f32_e32 v52, v52
	v_exp_f32_e32 v48, v48
	v_exp_f32_e32 v49, v49
	v_pk_fma_f32 v[46:47], v[58:59], v[46:47], v[58:59] op_sel_hi:[0,1,0]
	v_rcp_f32_e32 v46, v46
	v_rcp_f32_e32 v47, v47
	v_exp_f32_e32 v53, v53
	v_pk_fma_f32 v[48:49], v[58:59], v[48:49], v[58:59] op_sel_hi:[0,1,0]
	v_rcp_f32_e32 v48, v48
	v_rcp_f32_e32 v49, v49
	v_pk_mul_f32 v[38:39], v[34:35], v[46:47]
	v_lshlrev_b64 v[34:35], s42, v[146:147]
	v_pk_fma_f32 v[52:53], v[58:59], v[52:53], v[58:59] op_sel_hi:[0,1,0]
	v_min_u32_e32 v34, 1, v34
	v_rcp_f32_e32 v52, v52
	v_rcp_f32_e32 v53, v53
	v_or_b32_e32 v34, v35, v34
	v_pk_mul_f32 v[40:41], v[36:37], v[48:49]
	v_cvt_f32_u32_e32 v36, v120
	v_cvt_f32_u32_e32 v37, v34
	v_exp_f32_e32 v54, v54
	v_exp_f32_e32 v55, v55
	v_pk_mul_f32 v[42:43], v[42:43], v[52:53]
	s_add_u32 s8, s8, s88
	v_cvt_pk_bf16_f32 v34, v42, v43
	v_fmamk_f32 v42, v36, 0x30000000, v209
	v_ldexp_f32 v36, v37, s93
	v_pk_fma_f32 v[54:55], v[58:59], v[54:55], v[58:59] op_sel_hi:[0,1,0]
	v_fmac_f32_e32 v42, 2.0, v36
	v_rcp_f32_e32 v54, v54
	v_rcp_f32_e32 v55, v55
	v_rsq_f32_e32 v43, v42
	s_addc_u32 s9, s9, 0
	s_waitcnt vmcnt(5)
	v_mov_b32_e32 v146, v119
	v_pk_mul_f32 v[44:45], v[44:45], v[54:55]
	s_nop 0
	v_cvt_pk_bf16_f32 v35, v44, v45
	v_cvt_pk_bf16_f32 v36, v38, v39
	v_cvt_pk_bf16_f32 v37, v40, v41
	global_store_dwordx4 v141, v[34:37], s[8:9]
	s_add_u32 s8, s43, s84
	s_addc_u32 s9, s92, s85
	v_mul_f32_e32 v34, 0xbfb8aa3b, v43
	v_pk_mul_f32 v[36:37], v[30:31], v[34:35] op_sel_hi:[1,0]
	v_pk_mul_f32 v[30:31], v[22:23], v[34:35] op_sel_hi:[1,0]
	v_pk_mul_f32 v[38:39], v[32:33], v[34:35] op_sel_hi:[1,0]
	v_exp_f32_e32 v30, v30
	v_exp_f32_e32 v31, v31
	v_pk_mul_f32 v[32:33], v[24:25], v[34:35] op_sel_hi:[1,0]
	v_exp_f32_e32 v36, v36
	v_exp_f32_e32 v32, v32
	v_exp_f32_e32 v33, v33
	v_pk_fma_f32 v[30:31], v[42:43], v[30:31], v[42:43] op_sel_hi:[0,1,0]
	v_rcp_f32_e32 v30, v30
	v_rcp_f32_e32 v31, v31
	v_exp_f32_e32 v37, v37
	v_pk_fma_f32 v[32:33], v[42:43], v[32:33], v[42:43] op_sel_hi:[0,1,0]
	v_rcp_f32_e32 v32, v32
	v_rcp_f32_e32 v33, v33
	v_pk_mul_f32 v[22:23], v[18:19], v[30:31]
	v_lshlrev_b64 v[18:19], s42, v[146:147]
	v_pk_fma_f32 v[36:37], v[42:43], v[36:37], v[42:43] op_sel_hi:[0,1,0]
	v_min_u32_e32 v18, 1, v18
	v_rcp_f32_e32 v36, v36
	v_rcp_f32_e32 v37, v37
	v_or_b32_e32 v18, v19, v18
	v_pk_mul_f32 v[24:25], v[20:21], v[32:33]
	v_cvt_f32_u32_e32 v20, v118
	v_cvt_f32_u32_e32 v21, v18
	v_exp_f32_e32 v38, v38
	v_exp_f32_e32 v39, v39
	v_pk_mul_f32 v[26:27], v[26:27], v[36:37]
	s_add_u32 s8, s8, s88
	v_cvt_pk_bf16_f32 v18, v26, v27
	v_fmamk_f32 v26, v20, 0x30000000, v209
	v_ldexp_f32 v20, v21, s93
	v_pk_fma_f32 v[38:39], v[42:43], v[38:39], v[42:43] op_sel_hi:[0,1,0]
	v_fmac_f32_e32 v26, 2.0, v20
	v_rcp_f32_e32 v38, v38
	v_rcp_f32_e32 v39, v39
	v_rsq_f32_e32 v27, v26
	s_addc_u32 s9, s9, 0
	v_pk_mul_f32 v[28:29], v[28:29], v[38:39]
	s_nop 0
	v_cvt_pk_bf16_f32 v19, v28, v29
	v_cvt_pk_bf16_f32 v20, v22, v23
	v_cvt_pk_bf16_f32 v21, v24, v25
	global_store_dwordx4 v141, v[18:21], s[8:9]
	s_add_u32 s8, s43, s86
	s_addc_u32 s9, s92, s87
	v_mul_f32_e32 v18, 0xbfb8aa3b, v27
	v_pk_mul_f32 v[20:21], v[14:15], v[18:19] op_sel_hi:[1,0]
	v_pk_mul_f32 v[22:23], v[16:17], v[18:19] op_sel_hi:[1,0]
	v_pk_mul_f32 v[14:15], v[6:7], v[18:19] op_sel_hi:[1,0]
	v_pk_mul_f32 v[16:17], v[8:9], v[18:19] op_sel_hi:[1,0]
	v_exp_f32_e32 v20, v20
	v_exp_f32_e32 v21, v21
	v_exp_f32_e32 v22, v22
	v_exp_f32_e32 v23, v23
	v_exp_f32_e32 v14, v14
	v_exp_f32_e32 v15, v15
	v_exp_f32_e32 v16, v16
	v_exp_f32_e32 v17, v17
	v_pk_fma_f32 v[20:21], v[26:27], v[20:21], v[26:27] op_sel_hi:[0,1,0]
	v_pk_fma_f32 v[22:23], v[26:27], v[22:23], v[26:27] op_sel_hi:[0,1,0]
	v_pk_fma_f32 v[14:15], v[26:27], v[14:15], v[26:27] op_sel_hi:[0,1,0]
	v_pk_fma_f32 v[16:17], v[26:27], v[16:17], v[26:27] op_sel_hi:[0,1,0]
	v_rcp_f32_e32 v20, v20
	v_rcp_f32_e32 v21, v21
	v_rcp_f32_e32 v22, v22
	v_rcp_f32_e32 v23, v23
	v_rcp_f32_e32 v14, v14
	v_rcp_f32_e32 v15, v15
	v_rcp_f32_e32 v16, v16
	v_rcp_f32_e32 v17, v17
	s_add_u32 s8, s8, s88
	s_addc_u32 s9, s9, 0
	v_pk_mul_f32 v[10:11], v[10:11], v[20:21]
	v_pk_mul_f32 v[12:13], v[12:13], v[22:23]
	v_pk_mul_f32 v[6:7], v[2:3], v[14:15]
	v_pk_mul_f32 v[8:9], v[4:5], v[16:17]
	v_cvt_pk_bf16_f32 v2, v10, v11
	v_cvt_pk_bf16_f32 v3, v12, v13
	v_cvt_pk_bf16_f32 v4, v6, v7
	s_andn2_b64 vcc, exec, s[34:35]
	v_cvt_pk_bf16_f32 v5, v8, v9
	global_store_dwordx4 v141, v[2:5], s[8:9]
	s_mov_b64 s[8:9], -1
	s_cbranch_vccnz .LBB0_293
	s_andn2_b64 vcc, exec, s[44:45]
	s_cbranch_vccnz .LBB0_292
	s_mov_b32 m0, -1
	s_branch .LBB0_292

.LBB0_579:
	s_mul_i32 s73, s72, 0x2c0000
	s_and_b64 s[8:9], s[42:43], exec
	s_mul_i32 s84, s71, 0x2c0000
	s_cselect_b32 s8, s73, s21
	s_cselect_b32 s9, s84, s13
	s_addk_i32 s13, 0x100
	s_add_i32 s21, s21, 0xc000
	s_mov_b32 s22, -2
	s_waitcnt lgkmcnt(0)
	s_cmp_eq_u32 m0, -1
	s_cbranch_scc0 .Lgk_rs_1
	s_barrier
.Lgk_rs_1:
	v_add_u32_e32 v154, 0x10000, v140
	ds_read_b128 v[132:135], v154
	ds_read_b128 v[142:145], v154 offset:1024
	ds_read_b128 v[170:173], v154 offset:2048
	ds_read_b128 v[174:177], v154 offset:3072
	v_add_u32_e32 v154, 0x14000, v140
	ds_read_b128 v[178:181], v154
	ds_read_b128 v[182:185], v154 offset:1024
	ds_read_b128 v[186:189], v154 offset:2048
	ds_read_b128 v[190:193], v154 offset:3072
	s_add_i32 s23, s21, 0x4000
	s_cmpk_eq_i32 s22, 0x54
	s_cselect_b32 s27, s8, s23
	s_cselect_b32 s26, s9, s13
	s_or_b32 s23, s27, 0x8000
	s_mov_b32 m0, s68
	ds_read_b128 v[194:197], v141
	ds_read_b128 v[198:201], v141 offset:1024
	ds_read_b128 v[202:205], v141 offset:2048
	ds_read_b128 v[228:231], v141 offset:3072
	ds_read_b128 v[232:235], v141 offset:4096
	ds_read_b128 v[236:239], v141 offset:5120
	ds_read_b128 v[240:243], v141 offset:6144
	ds_read_b128 v[244:247], v141 offset:7168
	buffer_load_dwordx4 v136, s[60:63], s21 offen lds
	s_mov_b32 m0, s70
	s_nop 0
	buffer_load_dwordx4 v138, s[60:63], s21 offen lds
	s_waitcnt vmcnt(8)
	s_waitcnt lgkmcnt(0)
	s_setprio 1
	s_barrier
	v_mfma_f32_16x16x32_bf16 v[126:129], v[132:135], v[194:197], 0
	v_mfma_f32_16x16x32_bf16 v[126:129], v[142:145], v[198:201], v[126:129]
	v_mfma_f32_16x16x32_bf16 v[106:109], v[170:173], v[194:197], 0
	v_mfma_f32_16x16x32_bf16 v[106:109], v[174:177], v[198:201], v[106:109]
	v_mfma_f32_16x16x32_bf16 v[110:113], v[186:189], v[194:197], 0
	v_mfma_f32_16x16x32_bf16 v[110:113], v[190:193], v[198:201], v[110:113]
	v_mfma_f32_16x16x32_bf16 v[122:125], v[178:181], v[194:197], 0
	v_mfma_f32_16x16x32_bf16 v[122:125], v[182:185], v[198:201], v[122:125]
	v_mfma_f32_16x16x32_bf16 v[102:105], v[178:181], v[202:205], 0
	v_mfma_f32_16x16x32_bf16 v[102:105], v[182:185], v[228:231], v[102:105]
	v_mfma_f32_16x16x32_bf16 v[98:101], v[186:189], v[202:205], 0
	v_mfma_f32_16x16x32_bf16 v[98:101], v[190:193], v[228:231], v[98:101]
	v_mfma_f32_16x16x32_bf16 v[114:117], v[170:173], v[202:205], 0
	v_mfma_f32_16x16x32_bf16 v[114:117], v[174:177], v[228:231], v[114:117]
	v_mfma_f32_16x16x32_bf16 v[118:121], v[132:135], v[202:205], 0
	v_mfma_f32_16x16x32_bf16 v[118:121], v[142:145], v[228:231], v[118:121]
	v_mfma_f32_16x16x32_bf16 v[94:97], v[132:135], v[232:235], 0
	v_mfma_f32_16x16x32_bf16 v[94:97], v[142:145], v[236:239], v[94:97]
	v_mfma_f32_16x16x32_bf16 v[90:93], v[170:173], v[232:235], 0
	v_mfma_f32_16x16x32_bf16 v[90:93], v[174:177], v[236:239], v[90:93]
	v_mfma_f32_16x16x32_bf16 v[82:85], v[186:189], v[232:235], 0
	v_mfma_f32_16x16x32_bf16 v[82:85], v[190:193], v[236:239], v[82:85]
	v_mfma_f32_16x16x32_bf16 v[86:89], v[178:181], v[232:235], 0
	v_mfma_f32_16x16x32_bf16 v[86:89], v[182:185], v[236:239], v[86:89]
	v_mfma_f32_16x16x32_bf16 v[70:73], v[178:181], v[240:243], 0
	v_mfma_f32_16x16x32_bf16 v[70:73], v[182:185], v[244:247], v[70:73]
	v_mfma_f32_16x16x32_bf16 v[66:69], v[186:189], v[240:243], 0
	v_mfma_f32_16x16x32_bf16 v[66:69], v[190:193], v[244:247], v[66:69]
	v_mfma_f32_16x16x32_bf16 v[74:77], v[170:173], v[240:243], 0
	v_mfma_f32_16x16x32_bf16 v[74:77], v[174:177], v[244:247], v[74:77]
	v_mfma_f32_16x16x32_bf16 v[78:81], v[132:135], v[240:243], 0
	v_mfma_f32_16x16x32_bf16 v[78:81], v[142:145], v[244:247], v[78:81]
	s_barrier
	s_setprio 0
	s_mov_b32 s46, s62
	s_mov_b32 s47, s63
	s_mov_b32 m0, s15
	ds_read_b128 v[194:197], v141 offset:16384
	buffer_load_dwordx4 v137, s[44:47], s26 offen lds
	s_add_i32 s52, s26, 0x160000
	s_mov_b32 m0, s16
	ds_read_b128 v[198:201], v141 offset:17408
	buffer_load_dwordx4 v139, s[44:47], s26 offen lds
	s_mov_b32 m0, s18
	ds_read_b128 v[202:205], v141 offset:18432
	buffer_load_dwordx4 v137, s[44:47], s52 offen lds
	s_mov_b32 m0, s19
	ds_read_b128 v[228:231], v141 offset:19456
	buffer_load_dwordx4 v139, s[44:47], s52 offen lds
	s_mov_b32 m0, s14
	ds_read_b128 v[232:235], v141 offset:20480
	buffer_load_dwordx4 v136, s[60:63], s27 offen lds
	s_mov_b32 m0, s24
	ds_read_b128 v[236:239], v141 offset:21504
	buffer_load_dwordx4 v138, s[60:63], s27 offen lds
	ds_read_b128 v[240:243], v141 offset:22528
	ds_read_b128 v[244:247], v141 offset:23552
	s_waitcnt vmcnt(8)
	s_waitcnt lgkmcnt(0)
	s_setprio 1
	s_barrier
	v_mfma_f32_16x16x32_bf16 v[62:65], v[132:135], v[194:197], 0
	v_mfma_f32_16x16x32_bf16 v[62:65], v[142:145], v[198:201], v[62:65]
	v_mfma_f32_16x16x32_bf16 v[58:61], v[170:173], v[194:197], 0
	v_mfma_f32_16x16x32_bf16 v[58:61], v[174:177], v[198:201], v[58:61]
	v_mfma_f32_16x16x32_bf16 v[50:53], v[186:189], v[194:197], 0
	v_mfma_f32_16x16x32_bf16 v[50:53], v[190:193], v[198:201], v[50:53]
	v_mfma_f32_16x16x32_bf16 v[54:57], v[178:181], v[194:197], 0
	v_mfma_f32_16x16x32_bf16 v[54:57], v[182:185], v[198:201], v[54:57]
	v_mfma_f32_16x16x32_bf16 v[38:41], v[178:181], v[202:205], 0
	v_mfma_f32_16x16x32_bf16 v[38:41], v[182:185], v[228:231], v[38:41]
	v_mfma_f32_16x16x32_bf16 v[34:37], v[186:189], v[202:205], 0
	v_mfma_f32_16x16x32_bf16 v[34:37], v[190:193], v[228:231], v[34:37]
	v_mfma_f32_16x16x32_bf16 v[42:45], v[170:173], v[202:205], 0
	v_mfma_f32_16x16x32_bf16 v[42:45], v[174:177], v[228:231], v[42:45]
	v_mfma_f32_16x16x32_bf16 v[46:49], v[132:135], v[202:205], 0
	v_mfma_f32_16x16x32_bf16 v[46:49], v[142:145], v[228:231], v[46:49]
	v_mfma_f32_16x16x32_bf16 v[30:33], v[132:135], v[232:235], 0
	v_mfma_f32_16x16x32_bf16 v[30:33], v[142:145], v[236:239], v[30:33]
	v_mfma_f32_16x16x32_bf16 v[26:29], v[170:173], v[232:235], 0
	v_mfma_f32_16x16x32_bf16 v[26:29], v[174:177], v[236:239], v[26:29]
	v_mfma_f32_16x16x32_bf16 v[18:21], v[186:189], v[232:235], 0
	v_mfma_f32_16x16x32_bf16 v[18:21], v[190:193], v[236:239], v[18:21]
	v_mfma_f32_16x16x32_bf16 v[22:25], v[178:181], v[232:235], 0
	v_mfma_f32_16x16x32_bf16 v[22:25], v[182:185], v[236:239], v[22:25]
	v_mfma_f32_16x16x32_bf16 v[6:9], v[178:181], v[240:243], 0
	v_mfma_f32_16x16x32_bf16 v[6:9], v[182:185], v[244:247], v[6:9]
	v_mfma_f32_16x16x32_bf16 v[2:5], v[186:189], v[240:243], 0
	v_mfma_f32_16x16x32_bf16 v[2:5], v[190:193], v[244:247], v[2:5]
	v_mfma_f32_16x16x32_bf16 v[10:13], v[170:173], v[240:243], 0
	v_mfma_f32_16x16x32_bf16 v[10:13], v[174:177], v[244:247], v[10:13]
	v_mfma_f32_16x16x32_bf16 v[14:17], v[132:135], v[240:243], 0
	v_mfma_f32_16x16x32_bf16 v[14:17], v[142:145], v[244:247], v[14:17]
	s_barrier
	s_setprio 0
	v_add_u32_e32 v154, 0x18000, v140
	ds_read_b128 v[132:135], v154
	ds_read_b128 v[142:145], v154 offset:1024
	ds_read_b128 v[170:173], v154 offset:2048
	ds_read_b128 v[174:177], v154 offset:3072
	v_add_u32_e32 v154, 0x1c000, v140
	ds_read_b128 v[178:181], v154
	ds_read_b128 v[182:185], v154 offset:1024
	ds_read_b128 v[186:189], v154 offset:2048
	ds_read_b128 v[190:193], v154 offset:3072
	s_bitset1_b32 s27, 14
	s_mov_b32 m0, s25
	ds_read_b128 v[194:197], v141 offset:32768
	ds_read_b128 v[198:201], v141 offset:33792
	ds_read_b128 v[202:205], v141 offset:34816
	ds_read_b128 v[228:231], v141 offset:35840
	ds_read_b128 v[232:235], v141 offset:36864
	ds_read_b128 v[236:239], v141 offset:37888
	ds_read_b128 v[240:243], v141 offset:38912
	ds_read_b128 v[244:247], v141 offset:39936
	buffer_load_dwordx4 v136, s[60:63], s27 offen lds
	s_mov_b32 m0, s30
	s_nop 0
	buffer_load_dwordx4 v138, s[60:63], s27 offen lds
	s_waitcnt vmcnt(8)
	s_waitcnt lgkmcnt(0)
	s_setprio 1
	s_barrier
	v_mfma_f32_16x16x32_bf16 v[126:129], v[132:135], v[194:197], v[126:129]
	v_mfma_f32_16x16x32_bf16 v[126:129], v[142:145], v[198:201], v[126:129]
	v_mfma_f32_16x16x32_bf16 v[106:109], v[170:173], v[194:197], v[106:109]
	v_mfma_f32_16x16x32_bf16 v[106:109], v[174:177], v[198:201], v[106:109]
	v_mfma_f32_16x16x32_bf16 v[110:113], v[186:189], v[194:197], v[110:113]
	v_mfma_f32_16x16x32_bf16 v[110:113], v[190:193], v[198:201], v[110:113]
	v_mfma_f32_16x16x32_bf16 v[122:125], v[178:181], v[194:197], v[122:125]
	v_mfma_f32_16x16x32_bf16 v[122:125], v[182:185], v[198:201], v[122:125]
	v_mfma_f32_16x16x32_bf16 v[102:105], v[178:181], v[202:205], v[102:105]
	v_mfma_f32_16x16x32_bf16 v[102:105], v[182:185], v[228:231], v[102:105]
	v_mfma_f32_16x16x32_bf16 v[98:101], v[186:189], v[202:205], v[98:101]
	v_mfma_f32_16x16x32_bf16 v[98:101], v[190:193], v[228:231], v[98:101]
	v_mfma_f32_16x16x32_bf16 v[114:117], v[170:173], v[202:205], v[114:117]
	v_mfma_f32_16x16x32_bf16 v[114:117], v[174:177], v[228:231], v[114:117]
	v_mfma_f32_16x16x32_bf16 v[118:121], v[132:135], v[202:205], v[118:121]
	v_mfma_f32_16x16x32_bf16 v[118:121], v[142:145], v[228:231], v[118:121]
	v_mfma_f32_16x16x32_bf16 v[94:97], v[132:135], v[232:235], v[94:97]
	v_mfma_f32_16x16x32_bf16 v[94:97], v[142:145], v[236:239], v[94:97]
	v_mfma_f32_16x16x32_bf16 v[90:93], v[170:173], v[232:235], v[90:93]
	v_mfma_f32_16x16x32_bf16 v[90:93], v[174:177], v[236:239], v[90:93]
	v_mfma_f32_16x16x32_bf16 v[82:85], v[186:189], v[232:235], v[82:85]
	v_mfma_f32_16x16x32_bf16 v[82:85], v[190:193], v[236:239], v[82:85]
	v_mfma_f32_16x16x32_bf16 v[86:89], v[178:181], v[232:235], v[86:89]
	v_mfma_f32_16x16x32_bf16 v[86:89], v[182:185], v[236:239], v[86:89]
	v_mfma_f32_16x16x32_bf16 v[70:73], v[178:181], v[240:243], v[70:73]
	v_mfma_f32_16x16x32_bf16 v[70:73], v[182:185], v[244:247], v[70:73]
	v_mfma_f32_16x16x32_bf16 v[66:69], v[186:189], v[240:243], v[66:69]
	v_mfma_f32_16x16x32_bf16 v[66:69], v[190:193], v[244:247], v[66:69]
	v_mfma_f32_16x16x32_bf16 v[74:77], v[170:173], v[240:243], v[74:77]
	v_mfma_f32_16x16x32_bf16 v[74:77], v[174:177], v[244:247], v[74:77]
	v_mfma_f32_16x16x32_bf16 v[78:81], v[132:135], v[240:243], v[78:81]
	v_mfma_f32_16x16x32_bf16 v[78:81], v[142:145], v[244:247], v[78:81]
	s_barrier
	s_setprio 0
	s_or_b32 s27, s26, 0x80
	s_mov_b32 m0, s36
	ds_read_b128 v[194:197], v141 offset:49152
	buffer_load_dwordx4 v137, s[44:47], s27 offen lds
	s_add_i32 s26, s26, 0x160080
	s_mov_b32 m0, s37
	ds_read_b128 v[198:201], v141 offset:50176
	buffer_load_dwordx4 v139, s[44:47], s27 offen lds
	s_mov_b32 m0, s66
	ds_read_b128 v[202:205], v141 offset:51200
	buffer_load_dwordx4 v137, s[44:47], s26 offen lds
	s_mov_b32 m0, s67
	ds_read_b128 v[228:231], v141 offset:52224
	buffer_load_dwordx4 v139, s[44:47], s26 offen lds
	s_mov_b32 m0, s48
	ds_read_b128 v[232:235], v141 offset:53248
	buffer_load_dwordx4 v136, s[60:63], s23 offen lds
	s_mov_b32 m0, s49
	ds_read_b128 v[236:239], v141 offset:54272
	buffer_load_dwordx4 v138, s[60:63], s23 offen lds
	ds_read_b128 v[240:243], v141 offset:55296
	ds_read_b128 v[244:247], v141 offset:56320
	s_waitcnt vmcnt(8)
	s_waitcnt lgkmcnt(0)
	s_setprio 1
	s_barrier
	v_mfma_f32_16x16x32_bf16 v[62:65], v[132:135], v[194:197], v[62:65]
	v_mfma_f32_16x16x32_bf16 v[62:65], v[142:145], v[198:201], v[62:65]
	v_mfma_f32_16x16x32_bf16 v[58:61], v[170:173], v[194:197], v[58:61]
	v_mfma_f32_16x16x32_bf16 v[58:61], v[174:177], v[198:201], v[58:61]
	v_mfma_f32_16x16x32_bf16 v[50:53], v[186:189], v[194:197], v[50:53]
	v_mfma_f32_16x16x32_bf16 v[50:53], v[190:193], v[198:201], v[50:53]
	v_mfma_f32_16x16x32_bf16 v[54:57], v[178:181], v[194:197], v[54:57]
	v_mfma_f32_16x16x32_bf16 v[54:57], v[182:185], v[198:201], v[54:57]
	v_mfma_f32_16x16x32_bf16 v[38:41], v[178:181], v[202:205], v[38:41]
	v_mfma_f32_16x16x32_bf16 v[38:41], v[182:185], v[228:231], v[38:41]
	v_mfma_f32_16x16x32_bf16 v[34:37], v[186:189], v[202:205], v[34:37]
	v_mfma_f32_16x16x32_bf16 v[34:37], v[190:193], v[228:231], v[34:37]
	v_mfma_f32_16x16x32_bf16 v[42:45], v[170:173], v[202:205], v[42:45]
	v_mfma_f32_16x16x32_bf16 v[42:45], v[174:177], v[228:231], v[42:45]
	v_mfma_f32_16x16x32_bf16 v[46:49], v[132:135], v[202:205], v[46:49]
	v_mfma_f32_16x16x32_bf16 v[46:49], v[142:145], v[228:231], v[46:49]
	v_mfma_f32_16x16x32_bf16 v[30:33], v[132:135], v[232:235], v[30:33]
	v_mfma_f32_16x16x32_bf16 v[30:33], v[142:145], v[236:239], v[30:33]
	v_mfma_f32_16x16x32_bf16 v[26:29], v[170:173], v[232:235], v[26:29]
	v_mfma_f32_16x16x32_bf16 v[26:29], v[174:177], v[236:239], v[26:29]
	v_mfma_f32_16x16x32_bf16 v[18:21], v[186:189], v[232:235], v[18:21]
	v_mfma_f32_16x16x32_bf16 v[18:21], v[190:193], v[236:239], v[18:21]
	v_mfma_f32_16x16x32_bf16 v[22:25], v[178:181], v[232:235], v[22:25]
	v_mfma_f32_16x16x32_bf16 v[22:25], v[182:185], v[236:239], v[22:25]
	v_mfma_f32_16x16x32_bf16 v[6:9], v[178:181], v[240:243], v[6:9]
	v_mfma_f32_16x16x32_bf16 v[6:9], v[182:185], v[244:247], v[6:9]
	v_mfma_f32_16x16x32_bf16 v[2:5], v[186:189], v[240:243], v[2:5]
	v_mfma_f32_16x16x32_bf16 v[2:5], v[190:193], v[244:247], v[2:5]
	v_mfma_f32_16x16x32_bf16 v[10:13], v[170:173], v[240:243], v[10:13]
	v_mfma_f32_16x16x32_bf16 v[10:13], v[174:177], v[244:247], v[10:13]
	v_mfma_f32_16x16x32_bf16 v[14:17], v[132:135], v[240:243], v[14:17]
	v_mfma_f32_16x16x32_bf16 v[14:17], v[142:145], v[244:247], v[14:17]
	s_barrier
	s_setprio 0
	s_addk_i32 s13, 0x100
	s_add_i32 s22, s22, 2
	s_add_i32 s21, s21, 0x10000
	s_cmpk_gt_u32 s22, 0x55

.LBB0_585:
	s_or_b64 exec, exec, s[8:9]
	s_andn2_b64 vcc, exec, s[42:43]
	s_mov_b64 s[8:9], -1
	s_cbranch_vccnz .LBB0_576
	s_andn2_b64 vcc, exec, s[38:39]
	s_cbranch_vccnz .LBB0_575
	s_mov_b32 m0, -1
	s_branch .LBB0_575

.LBB0_858:
	s_lshl_b32 s2, s21, 20
	s_and_b64 s[8:9], s[42:43], exec
	s_cselect_b32 s8, s2, s18
	s_lshl_b32 s82, s71, 20
	s_and_b64 s[26:27], s[42:43], exec
	s_cselect_b32 s9, s82, s19
	s_add_i32 s18, s18, 0x80080
	s_addk_i32 s19, 0x100
	s_mov_b32 s22, -2
	s_cmp_eq_u32 m0, -1
	s_cbranch_scc0 .Lgk_rs_2
	s_barrier
.Lgk_rs_2:
	v_add_u32_e32 v146, 0x10000, v195
	ds_read_b128 v[130:133], v146
	ds_read_b128 v[138:141], v146 offset:1024
	ds_read_b128 v[142:145], v146 offset:2048
	ds_read_b128 v[154:157], v146 offset:3072
	v_add_u32_e32 v146, 0x14000, v195
	ds_read_b128 v[170:173], v146
	ds_read_b128 v[174:177], v146 offset:1024
	ds_read_b128 v[178:181], v146 offset:2048
	ds_read_b128 v[182:185], v146 offset:3072
	s_add_i32 s26, s18, 0xfff80080
	s_cmp_eq_u32 s22, 28
	s_cselect_b32 s52, s8, s26
	s_cselect_b32 s27, s9, s19
	s_or_b32 s26, s52, 0x80
	s_mov_b32 m0, s85
	ds_read_b128 v[186:189], v196
	ds_read_b128 v[198:201], v196 offset:1024
	ds_read_b128 v[202:205], v196 offset:2048
	ds_read_b128 v[228:231], v196 offset:3072
	ds_read_b128 v[232:235], v196 offset:4096
	ds_read_b128 v[236:239], v196 offset:5120
	ds_read_b128 v[240:243], v196 offset:6144
	ds_read_b128 v[244:247], v196 offset:7168
	buffer_load_dwordx4 v135, s[44:47], s18 offen lds
	s_mov_b32 m0, s15
	s_nop 0
	buffer_load_dwordx4 v193, s[44:47], s18 offen lds
	s_waitcnt vmcnt(8)
	s_waitcnt lgkmcnt(0)
	s_setprio 1
	s_barrier
	v_mfma_f32_16x16x32_bf16 v[126:129], v[130:133], v[186:189], 0
	v_mfma_f32_16x16x32_bf16 v[126:129], v[138:141], v[198:201], v[126:129]
	v_mfma_f32_16x16x32_bf16 v[122:125], v[142:145], v[186:189], 0
	v_mfma_f32_16x16x32_bf16 v[122:125], v[154:157], v[198:201], v[122:125]
	v_mfma_f32_16x16x32_bf16 v[114:117], v[178:181], v[186:189], 0
	v_mfma_f32_16x16x32_bf16 v[114:117], v[182:185], v[198:201], v[114:117]
	v_mfma_f32_16x16x32_bf16 v[118:121], v[170:173], v[186:189], 0
	v_mfma_f32_16x16x32_bf16 v[118:121], v[174:177], v[198:201], v[118:121]
	v_mfma_f32_16x16x32_bf16 v[102:105], v[170:173], v[202:205], 0
	v_mfma_f32_16x16x32_bf16 v[102:105], v[174:177], v[228:231], v[102:105]
	v_mfma_f32_16x16x32_bf16 v[98:101], v[178:181], v[202:205], 0
	v_mfma_f32_16x16x32_bf16 v[98:101], v[182:185], v[228:231], v[98:101]
	v_mfma_f32_16x16x32_bf16 v[106:109], v[142:145], v[202:205], 0
	v_mfma_f32_16x16x32_bf16 v[106:109], v[154:157], v[228:231], v[106:109]
	v_mfma_f32_16x16x32_bf16 v[110:113], v[130:133], v[202:205], 0
	v_mfma_f32_16x16x32_bf16 v[110:113], v[138:141], v[228:231], v[110:113]
	v_mfma_f32_16x16x32_bf16 v[94:97], v[130:133], v[232:235], 0
	v_mfma_f32_16x16x32_bf16 v[94:97], v[138:141], v[236:239], v[94:97]
	v_mfma_f32_16x16x32_bf16 v[90:93], v[142:145], v[232:235], 0
	v_mfma_f32_16x16x32_bf16 v[90:93], v[154:157], v[236:239], v[90:93]
	v_mfma_f32_16x16x32_bf16 v[82:85], v[178:181], v[232:235], 0
	v_mfma_f32_16x16x32_bf16 v[82:85], v[182:185], v[236:239], v[82:85]
	v_mfma_f32_16x16x32_bf16 v[86:89], v[170:173], v[232:235], 0
	v_mfma_f32_16x16x32_bf16 v[86:89], v[174:177], v[236:239], v[86:89]
	v_mfma_f32_16x16x32_bf16 v[70:73], v[170:173], v[240:243], 0
	v_mfma_f32_16x16x32_bf16 v[70:73], v[174:177], v[244:247], v[70:73]
	v_mfma_f32_16x16x32_bf16 v[66:69], v[178:181], v[240:243], 0
	v_mfma_f32_16x16x32_bf16 v[66:69], v[182:185], v[244:247], v[66:69]
	v_mfma_f32_16x16x32_bf16 v[74:77], v[142:145], v[240:243], 0
	v_mfma_f32_16x16x32_bf16 v[74:77], v[154:157], v[244:247], v[74:77]
	v_mfma_f32_16x16x32_bf16 v[78:81], v[130:133], v[240:243], 0
	v_mfma_f32_16x16x32_bf16 v[78:81], v[138:141], v[244:247], v[78:81]
	s_barrier
	s_setprio 0
	s_mov_b32 s66, s46
	s_mov_b32 s67, s47
	s_mov_b32 m0, s23
	ds_read_b128 v[186:189], v196 offset:16384
	buffer_load_dwordx4 v192, s[64:67], s27 offen lds
	s_add_i32 s53, s27, 0x80000
	s_mov_b32 m0, s24
	ds_read_b128 v[198:201], v196 offset:17408
	buffer_load_dwordx4 v194, s[64:67], s27 offen lds
	s_mov_b32 m0, s25
	ds_read_b128 v[202:205], v196 offset:18432
	buffer_load_dwordx4 v192, s[64:67], s53 offen lds
	s_mov_b32 m0, s33
	ds_read_b128 v[228:231], v196 offset:19456
	buffer_load_dwordx4 v194, s[64:67], s53 offen lds
	s_mov_b32 m0, s13
	ds_read_b128 v[232:235], v196 offset:20480
	buffer_load_dwordx4 v135, s[44:47], s52 offen lds
	s_mov_b32 m0, s34
	ds_read_b128 v[236:239], v196 offset:21504
	buffer_load_dwordx4 v193, s[44:47], s52 offen lds
	ds_read_b128 v[240:243], v196 offset:22528
	ds_read_b128 v[244:247], v196 offset:23552
	s_waitcnt vmcnt(8)
	s_waitcnt lgkmcnt(0)
	s_setprio 1
	s_barrier
	v_mfma_f32_16x16x32_bf16 v[62:65], v[130:133], v[186:189], 0
	v_mfma_f32_16x16x32_bf16 v[62:65], v[138:141], v[198:201], v[62:65]
	v_mfma_f32_16x16x32_bf16 v[58:61], v[142:145], v[186:189], 0
	v_mfma_f32_16x16x32_bf16 v[58:61], v[154:157], v[198:201], v[58:61]
	v_mfma_f32_16x16x32_bf16 v[50:53], v[178:181], v[186:189], 0
	v_mfma_f32_16x16x32_bf16 v[50:53], v[182:185], v[198:201], v[50:53]
	v_mfma_f32_16x16x32_bf16 v[54:57], v[170:173], v[186:189], 0
	v_mfma_f32_16x16x32_bf16 v[54:57], v[174:177], v[198:201], v[54:57]
	v_mfma_f32_16x16x32_bf16 v[38:41], v[170:173], v[202:205], 0
	v_mfma_f32_16x16x32_bf16 v[38:41], v[174:177], v[228:231], v[38:41]
	v_mfma_f32_16x16x32_bf16 v[34:37], v[178:181], v[202:205], 0
	v_mfma_f32_16x16x32_bf16 v[34:37], v[182:185], v[228:231], v[34:37]
	v_mfma_f32_16x16x32_bf16 v[42:45], v[142:145], v[202:205], 0
	v_mfma_f32_16x16x32_bf16 v[42:45], v[154:157], v[228:231], v[42:45]
	v_mfma_f32_16x16x32_bf16 v[46:49], v[130:133], v[202:205], 0
	v_mfma_f32_16x16x32_bf16 v[46:49], v[138:141], v[228:231], v[46:49]
	v_mfma_f32_16x16x32_bf16 v[30:33], v[130:133], v[232:235], 0
	v_mfma_f32_16x16x32_bf16 v[30:33], v[138:141], v[236:239], v[30:33]
	v_mfma_f32_16x16x32_bf16 v[26:29], v[142:145], v[232:235], 0
	v_mfma_f32_16x16x32_bf16 v[26:29], v[154:157], v[236:239], v[26:29]
	v_mfma_f32_16x16x32_bf16 v[18:21], v[178:181], v[232:235], 0
	v_mfma_f32_16x16x32_bf16 v[18:21], v[182:185], v[236:239], v[18:21]
	v_mfma_f32_16x16x32_bf16 v[22:25], v[170:173], v[232:235], 0
	v_mfma_f32_16x16x32_bf16 v[22:25], v[174:177], v[236:239], v[22:25]
	v_mfma_f32_16x16x32_bf16 v[6:9], v[170:173], v[240:243], 0
	v_mfma_f32_16x16x32_bf16 v[6:9], v[174:177], v[244:247], v[6:9]
	v_mfma_f32_16x16x32_bf16 v[2:5], v[178:181], v[240:243], 0
	v_mfma_f32_16x16x32_bf16 v[2:5], v[182:185], v[244:247], v[2:5]
	v_mfma_f32_16x16x32_bf16 v[10:13], v[142:145], v[240:243], 0
	v_mfma_f32_16x16x32_bf16 v[10:13], v[154:157], v[244:247], v[10:13]
	v_mfma_f32_16x16x32_bf16 v[14:17], v[130:133], v[240:243], 0
	v_mfma_f32_16x16x32_bf16 v[14:17], v[138:141], v[244:247], v[14:17]
	s_barrier
	s_setprio 0
	v_add_u32_e32 v146, 0x18000, v195
	ds_read_b128 v[130:133], v146
	ds_read_b128 v[138:141], v146 offset:1024
	ds_read_b128 v[142:145], v146 offset:2048
	ds_read_b128 v[154:157], v146 offset:3072
	v_add_u32_e32 v146, 0x1c000, v195
	ds_read_b128 v[170:173], v146
	ds_read_b128 v[174:177], v146 offset:1024
	ds_read_b128 v[178:181], v146 offset:2048
	ds_read_b128 v[182:185], v146 offset:3072
	s_add_i32 s52, s52, 0x80000
	s_mov_b32 m0, s35
	ds_read_b128 v[186:189], v196 offset:32768
	ds_read_b128 v[198:201], v196 offset:33792
	ds_read_b128 v[202:205], v196 offset:34816
	ds_read_b128 v[228:231], v196 offset:35840
	ds_read_b128 v[232:235], v196 offset:36864
	ds_read_b128 v[236:239], v196 offset:37888
	ds_read_b128 v[240:243], v196 offset:38912
	ds_read_b128 v[244:247], v196 offset:39936
	buffer_load_dwordx4 v135, s[44:47], s52 offen lds
	s_mov_b32 m0, s36
	s_nop 0
	buffer_load_dwordx4 v193, s[44:47], s52 offen lds
	s_waitcnt vmcnt(8)
	s_waitcnt lgkmcnt(0)
	s_setprio 1
	s_barrier
	v_mfma_f32_16x16x32_bf16 v[126:129], v[130:133], v[186:189], v[126:129]
	v_mfma_f32_16x16x32_bf16 v[126:129], v[138:141], v[198:201], v[126:129]
	v_mfma_f32_16x16x32_bf16 v[122:125], v[142:145], v[186:189], v[122:125]
	v_mfma_f32_16x16x32_bf16 v[122:125], v[154:157], v[198:201], v[122:125]
	v_mfma_f32_16x16x32_bf16 v[114:117], v[178:181], v[186:189], v[114:117]
	v_mfma_f32_16x16x32_bf16 v[114:117], v[182:185], v[198:201], v[114:117]
	v_mfma_f32_16x16x32_bf16 v[118:121], v[170:173], v[186:189], v[118:121]
	v_mfma_f32_16x16x32_bf16 v[118:121], v[174:177], v[198:201], v[118:121]
	v_mfma_f32_16x16x32_bf16 v[102:105], v[170:173], v[202:205], v[102:105]
	v_mfma_f32_16x16x32_bf16 v[102:105], v[174:177], v[228:231], v[102:105]
	v_mfma_f32_16x16x32_bf16 v[98:101], v[178:181], v[202:205], v[98:101]
	v_mfma_f32_16x16x32_bf16 v[98:101], v[182:185], v[228:231], v[98:101]
	v_mfma_f32_16x16x32_bf16 v[106:109], v[142:145], v[202:205], v[106:109]
	v_mfma_f32_16x16x32_bf16 v[106:109], v[154:157], v[228:231], v[106:109]
	v_mfma_f32_16x16x32_bf16 v[110:113], v[130:133], v[202:205], v[110:113]
	v_mfma_f32_16x16x32_bf16 v[110:113], v[138:141], v[228:231], v[110:113]
	v_mfma_f32_16x16x32_bf16 v[94:97], v[130:133], v[232:235], v[94:97]
	v_mfma_f32_16x16x32_bf16 v[94:97], v[138:141], v[236:239], v[94:97]
	v_mfma_f32_16x16x32_bf16 v[90:93], v[142:145], v[232:235], v[90:93]
	v_mfma_f32_16x16x32_bf16 v[90:93], v[154:157], v[236:239], v[90:93]
	v_mfma_f32_16x16x32_bf16 v[82:85], v[178:181], v[232:235], v[82:85]
	v_mfma_f32_16x16x32_bf16 v[82:85], v[182:185], v[236:239], v[82:85]
	v_mfma_f32_16x16x32_bf16 v[86:89], v[170:173], v[232:235], v[86:89]
	v_mfma_f32_16x16x32_bf16 v[86:89], v[174:177], v[236:239], v[86:89]
	v_mfma_f32_16x16x32_bf16 v[70:73], v[170:173], v[240:243], v[70:73]
	v_mfma_f32_16x16x32_bf16 v[70:73], v[174:177], v[244:247], v[70:73]
	v_mfma_f32_16x16x32_bf16 v[66:69], v[178:181], v[240:243], v[66:69]
	v_mfma_f32_16x16x32_bf16 v[66:69], v[182:185], v[244:247], v[66:69]
	v_mfma_f32_16x16x32_bf16 v[74:77], v[142:145], v[240:243], v[74:77]
	v_mfma_f32_16x16x32_bf16 v[74:77], v[154:157], v[244:247], v[74:77]
	v_mfma_f32_16x16x32_bf16 v[78:81], v[130:133], v[240:243], v[78:81]
	v_mfma_f32_16x16x32_bf16 v[78:81], v[138:141], v[244:247], v[78:81]
	s_barrier
	s_setprio 0
	s_or_b32 s52, s27, 0x80
	s_mov_b32 m0, s41
	ds_read_b128 v[186:189], v196 offset:49152
	buffer_load_dwordx4 v192, s[64:67], s52 offen lds
	s_add_i32 s27, s27, 0x80080
	s_mov_b32 m0, s48
	ds_read_b128 v[198:201], v196 offset:50176
	buffer_load_dwordx4 v194, s[64:67], s52 offen lds
	s_mov_b32 m0, s69
	ds_read_b128 v[202:205], v196 offset:51200
	buffer_load_dwordx4 v192, s[64:67], s27 offen lds
	s_mov_b32 m0, s72
	ds_read_b128 v[228:231], v196 offset:52224
	buffer_load_dwordx4 v194, s[64:67], s27 offen lds
	s_mov_b32 m0, s49
	ds_read_b128 v[232:235], v196 offset:53248
	buffer_load_dwordx4 v135, s[44:47], s26 offen lds
	s_mov_b32 m0, s68
	ds_read_b128 v[236:239], v196 offset:54272
	buffer_load_dwordx4 v193, s[44:47], s26 offen lds
	ds_read_b128 v[240:243], v196 offset:55296
	ds_read_b128 v[244:247], v196 offset:56320
	s_waitcnt vmcnt(8)
	s_waitcnt lgkmcnt(0)
	s_setprio 1
	s_barrier
	v_mfma_f32_16x16x32_bf16 v[62:65], v[130:133], v[186:189], v[62:65]
	v_mfma_f32_16x16x32_bf16 v[62:65], v[138:141], v[198:201], v[62:65]
	v_mfma_f32_16x16x32_bf16 v[58:61], v[142:145], v[186:189], v[58:61]
	v_mfma_f32_16x16x32_bf16 v[58:61], v[154:157], v[198:201], v[58:61]
	v_mfma_f32_16x16x32_bf16 v[50:53], v[178:181], v[186:189], v[50:53]
	v_mfma_f32_16x16x32_bf16 v[50:53], v[182:185], v[198:201], v[50:53]
	v_mfma_f32_16x16x32_bf16 v[54:57], v[170:173], v[186:189], v[54:57]
	v_mfma_f32_16x16x32_bf16 v[54:57], v[174:177], v[198:201], v[54:57]
	v_mfma_f32_16x16x32_bf16 v[38:41], v[170:173], v[202:205], v[38:41]
	v_mfma_f32_16x16x32_bf16 v[38:41], v[174:177], v[228:231], v[38:41]
	v_mfma_f32_16x16x32_bf16 v[34:37], v[178:181], v[202:205], v[34:37]
	v_mfma_f32_16x16x32_bf16 v[34:37], v[182:185], v[228:231], v[34:37]
	v_mfma_f32_16x16x32_bf16 v[42:45], v[142:145], v[202:205], v[42:45]
	v_mfma_f32_16x16x32_bf16 v[42:45], v[154:157], v[228:231], v[42:45]
	v_mfma_f32_16x16x32_bf16 v[46:49], v[130:133], v[202:205], v[46:49]
	v_mfma_f32_16x16x32_bf16 v[46:49], v[138:141], v[228:231], v[46:49]
	v_mfma_f32_16x16x32_bf16 v[30:33], v[130:133], v[232:235], v[30:33]
	v_mfma_f32_16x16x32_bf16 v[30:33], v[138:141], v[236:239], v[30:33]
	v_mfma_f32_16x16x32_bf16 v[26:29], v[142:145], v[232:235], v[26:29]
	v_mfma_f32_16x16x32_bf16 v[26:29], v[154:157], v[236:239], v[26:29]
	v_mfma_f32_16x16x32_bf16 v[18:21], v[178:181], v[232:235], v[18:21]
	v_mfma_f32_16x16x32_bf16 v[18:21], v[182:185], v[236:239], v[18:21]
	v_mfma_f32_16x16x32_bf16 v[22:25], v[170:173], v[232:235], v[22:25]
	v_mfma_f32_16x16x32_bf16 v[22:25], v[174:177], v[236:239], v[22:25]
	v_mfma_f32_16x16x32_bf16 v[6:9], v[170:173], v[240:243], v[6:9]
	v_mfma_f32_16x16x32_bf16 v[6:9], v[174:177], v[244:247], v[6:9]
	v_mfma_f32_16x16x32_bf16 v[2:5], v[178:181], v[240:243], v[2:5]
	v_mfma_f32_16x16x32_bf16 v[2:5], v[182:185], v[244:247], v[2:5]
	v_mfma_f32_16x16x32_bf16 v[10:13], v[142:145], v[240:243], v[10:13]
	v_mfma_f32_16x16x32_bf16 v[10:13], v[154:157], v[244:247], v[10:13]
	v_mfma_f32_16x16x32_bf16 v[14:17], v[130:133], v[240:243], v[14:17]
	v_mfma_f32_16x16x32_bf16 v[14:17], v[138:141], v[244:247], v[14:17]
	s_barrier
	s_setprio 0
	s_add_i32 s22, s22, 2
	s_addk_i32 s18, 0x100
	s_addk_i32 s19, 0x100
	s_cmp_gt_u32 s22, 29

.LBB0_867:
	s_andn2_b64 vcc, exec, s[38:39]
	s_cbranch_vccnz .LBB0_854
	s_mov_b32 m0, -1
	s_branch .LBB0_854

.LBB0_880:
	s_lshl_b32 s14, s85, 20
	s_and_b64 s[8:9], s[42:43], exec
	s_cselect_b32 s8, s14, s12
	s_lshl_b32 s15, s66, 20
	s_and_b64 s[22:23], s[42:43], exec
	s_cselect_b32 s9, s15, s13
	s_add_i32 s12, s12, 0x80080
	s_addk_i32 s13, 0x100
	s_mov_b32 s16, -2
	s_cmp_eq_u32 m0, -1
	s_cbranch_scc0 .Lgk_rs_3
	s_barrier
.Lgk_rs_3:
	v_add_u32_e32 v139, 0x10000, v234
	ds_read_b128 v[130:133], v139
	ds_read_b128 v[140:143], v139 offset:1024
	ds_read_b128 v[170:173], v139 offset:2048
	ds_read_b128 v[174:177], v139 offset:3072
	v_add_u32_e32 v139, 0x14000, v234
	ds_read_b128 v[178:181], v139
	ds_read_b128 v[182:185], v139 offset:1024
	ds_read_b128 v[186:189], v139 offset:2048
	ds_read_b128 v[190:193], v139 offset:3072
	s_add_i32 s21, s12, 0xfff80080
	s_cmp_eq_u32 s16, 28
	s_cselect_b32 s23, s8, s21
	s_cselect_b32 s22, s9, s13
	s_or_b32 s21, s23, 0x80
	s_mov_b32 m0, s72
	ds_read_b128 v[194:197], v235
	ds_read_b128 v[198:201], v235 offset:1024
	ds_read_b128 v[202:205], v235 offset:2048
	ds_read_b128 v[236:239], v235 offset:3072
	ds_read_b128 v[240:243], v235 offset:4096
	ds_read_b128 v[244:247], v235 offset:5120
	ds_read_b128 v[248:251], v235 offset:6144
	ds_read_b128 v[154:157], v235 offset:7168
	buffer_load_dwordx4 v228, s[60:63], s12 offen lds
	s_mov_b32 m0, s73
	s_nop 0
	buffer_load_dwordx4 v230, s[60:63], s12 offen lds
	s_waitcnt vmcnt(8)
	s_waitcnt lgkmcnt(0)
	s_setprio 1
	s_barrier
	v_mfma_f32_16x16x32_bf16 v[126:129], v[130:133], v[194:197], 0
	v_mfma_f32_16x16x32_bf16 v[126:129], v[140:143], v[198:201], v[126:129]
	v_mfma_f32_16x16x32_bf16 v[122:125], v[170:173], v[194:197], 0
	v_mfma_f32_16x16x32_bf16 v[122:125], v[174:177], v[198:201], v[122:125]
	v_mfma_f32_16x16x32_bf16 v[110:113], v[186:189], v[194:197], 0
	v_mfma_f32_16x16x32_bf16 v[110:113], v[190:193], v[198:201], v[110:113]
	v_mfma_f32_16x16x32_bf16 v[118:121], v[178:181], v[194:197], 0
	v_mfma_f32_16x16x32_bf16 v[118:121], v[182:185], v[198:201], v[118:121]
	v_mfma_f32_16x16x32_bf16 v[102:105], v[178:181], v[202:205], 0
	v_mfma_f32_16x16x32_bf16 v[102:105], v[182:185], v[236:239], v[102:105]
	v_mfma_f32_16x16x32_bf16 v[94:97], v[186:189], v[202:205], 0
	v_mfma_f32_16x16x32_bf16 v[94:97], v[190:193], v[236:239], v[94:97]
	v_mfma_f32_16x16x32_bf16 v[106:109], v[170:173], v[202:205], 0
	v_mfma_f32_16x16x32_bf16 v[106:109], v[174:177], v[236:239], v[106:109]
	v_mfma_f32_16x16x32_bf16 v[114:117], v[130:133], v[202:205], 0
	v_mfma_f32_16x16x32_bf16 v[114:117], v[140:143], v[236:239], v[114:117]
	v_mfma_f32_16x16x32_bf16 v[98:101], v[130:133], v[240:243], 0
	v_mfma_f32_16x16x32_bf16 v[98:101], v[140:143], v[244:247], v[98:101]
	v_mfma_f32_16x16x32_bf16 v[90:93], v[170:173], v[240:243], 0
	v_mfma_f32_16x16x32_bf16 v[90:93], v[174:177], v[244:247], v[90:93]
	v_mfma_f32_16x16x32_bf16 v[78:81], v[186:189], v[240:243], 0
	v_mfma_f32_16x16x32_bf16 v[78:81], v[190:193], v[244:247], v[78:81]
	v_mfma_f32_16x16x32_bf16 v[86:89], v[178:181], v[240:243], 0
	v_mfma_f32_16x16x32_bf16 v[86:89], v[182:185], v[244:247], v[86:89]
	v_mfma_f32_16x16x32_bf16 v[70:73], v[178:181], v[248:251], 0
	v_mfma_f32_16x16x32_bf16 v[70:73], v[182:185], v[154:157], v[70:73]
	v_mfma_f32_16x16x32_bf16 v[66:69], v[186:189], v[248:251], 0
	v_mfma_f32_16x16x32_bf16 v[66:69], v[190:193], v[154:157], v[66:69]
	v_mfma_f32_16x16x32_bf16 v[74:77], v[170:173], v[248:251], 0
	v_mfma_f32_16x16x32_bf16 v[74:77], v[174:177], v[154:157], v[74:77]
	v_mfma_f32_16x16x32_bf16 v[82:85], v[130:133], v[248:251], 0
	v_mfma_f32_16x16x32_bf16 v[82:85], v[140:143], v[154:157], v[82:85]
	s_barrier
	s_setprio 0
	s_mov_b32 s46, s62
	s_mov_b32 s47, s63
	s_mov_b32 m0, s26
	ds_read_b128 v[154:157], v235 offset:16384
	buffer_load_dwordx4 v229, s[44:47], s22 offen lds
	s_add_i32 s38, s22, 0x80000
	s_mov_b32 m0, s27
	ds_read_b128 v[194:197], v235 offset:17408
	buffer_load_dwordx4 v231, s[44:47], s22 offen lds
	s_mov_b32 m0, s34
	ds_read_b128 v[198:201], v235 offset:18432
	buffer_load_dwordx4 v229, s[44:47], s38 offen lds
	s_mov_b32 m0, s35
	ds_read_b128 v[202:205], v235 offset:19456
	buffer_load_dwordx4 v231, s[44:47], s38 offen lds
	s_mov_b32 m0, s19
	ds_read_b128 v[236:239], v235 offset:20480
	buffer_load_dwordx4 v228, s[60:63], s23 offen lds
	s_mov_b32 m0, s36
	ds_read_b128 v[240:243], v235 offset:21504
	buffer_load_dwordx4 v230, s[60:63], s23 offen lds
	ds_read_b128 v[244:247], v235 offset:22528
	ds_read_b128 v[248:251], v235 offset:23552
	s_waitcnt vmcnt(8)
	s_waitcnt lgkmcnt(0)
	s_setprio 1
	s_barrier
	v_mfma_f32_16x16x32_bf16 v[62:65], v[130:133], v[154:157], 0
	v_mfma_f32_16x16x32_bf16 v[62:65], v[140:143], v[194:197], v[62:65]
	v_mfma_f32_16x16x32_bf16 v[58:61], v[170:173], v[154:157], 0
	v_mfma_f32_16x16x32_bf16 v[58:61], v[174:177], v[194:197], v[58:61]
	v_mfma_f32_16x16x32_bf16 v[46:49], v[186:189], v[154:157], 0
	v_mfma_f32_16x16x32_bf16 v[46:49], v[190:193], v[194:197], v[46:49]
	v_mfma_f32_16x16x32_bf16 v[54:57], v[178:181], v[154:157], 0
	v_mfma_f32_16x16x32_bf16 v[54:57], v[182:185], v[194:197], v[54:57]
	v_mfma_f32_16x16x32_bf16 v[38:41], v[178:181], v[198:201], 0
	v_mfma_f32_16x16x32_bf16 v[38:41], v[182:185], v[202:205], v[38:41]
	v_mfma_f32_16x16x32_bf16 v[30:33], v[186:189], v[198:201], 0
	v_mfma_f32_16x16x32_bf16 v[30:33], v[190:193], v[202:205], v[30:33]
	v_mfma_f32_16x16x32_bf16 v[42:45], v[170:173], v[198:201], 0
	v_mfma_f32_16x16x32_bf16 v[42:45], v[174:177], v[202:205], v[42:45]
	v_mfma_f32_16x16x32_bf16 v[50:53], v[130:133], v[198:201], 0
	v_mfma_f32_16x16x32_bf16 v[50:53], v[140:143], v[202:205], v[50:53]
	v_mfma_f32_16x16x32_bf16 v[34:37], v[130:133], v[236:239], 0
	v_mfma_f32_16x16x32_bf16 v[34:37], v[140:143], v[240:243], v[34:37]
	v_mfma_f32_16x16x32_bf16 v[26:29], v[170:173], v[236:239], 0
	v_mfma_f32_16x16x32_bf16 v[26:29], v[174:177], v[240:243], v[26:29]
	v_mfma_f32_16x16x32_bf16 v[14:17], v[186:189], v[236:239], 0
	v_mfma_f32_16x16x32_bf16 v[14:17], v[190:193], v[240:243], v[14:17]
	v_mfma_f32_16x16x32_bf16 v[22:25], v[178:181], v[236:239], 0
	v_mfma_f32_16x16x32_bf16 v[22:25], v[182:185], v[240:243], v[22:25]
	v_mfma_f32_16x16x32_bf16 v[6:9], v[178:181], v[244:247], 0
	v_mfma_f32_16x16x32_bf16 v[6:9], v[182:185], v[248:251], v[6:9]
	v_mfma_f32_16x16x32_bf16 v[2:5], v[186:189], v[244:247], 0
	v_mfma_f32_16x16x32_bf16 v[2:5], v[190:193], v[248:251], v[2:5]
	v_mfma_f32_16x16x32_bf16 v[10:13], v[170:173], v[244:247], 0
	v_mfma_f32_16x16x32_bf16 v[10:13], v[174:177], v[248:251], v[10:13]
	v_mfma_f32_16x16x32_bf16 v[18:21], v[130:133], v[244:247], 0
	v_mfma_f32_16x16x32_bf16 v[18:21], v[140:143], v[248:251], v[18:21]
	s_barrier
	s_setprio 0
	v_add_u32_e32 v139, 0x18000, v234
	ds_read_b128 v[130:133], v139
	ds_read_b128 v[140:143], v139 offset:1024
	ds_read_b128 v[154:157], v139 offset:2048
	ds_read_b128 v[170:173], v139 offset:3072
	v_add_u32_e32 v139, 0x1c000, v234
	ds_read_b128 v[174:177], v139
	ds_read_b128 v[178:181], v139 offset:1024
	ds_read_b128 v[182:185], v139 offset:2048
	ds_read_b128 v[186:189], v139 offset:3072
	s_add_i32 s23, s23, 0x80000
	s_mov_b32 m0, s37
	ds_read_b128 v[190:193], v235 offset:32768
	ds_read_b128 v[194:197], v235 offset:33792
	ds_read_b128 v[198:201], v235 offset:34816
	ds_read_b128 v[202:205], v235 offset:35840
	ds_read_b128 v[236:239], v235 offset:36864
	ds_read_b128 v[240:243], v235 offset:37888
	ds_read_b128 v[244:247], v235 offset:38912
	ds_read_b128 v[248:251], v235 offset:39936
	buffer_load_dwordx4 v228, s[60:63], s23 offen lds
	s_mov_b32 m0, s18
	s_nop 0
	buffer_load_dwordx4 v230, s[60:63], s23 offen lds
	s_waitcnt vmcnt(8)
	s_waitcnt lgkmcnt(0)
	s_setprio 1
	s_barrier
	v_mfma_f32_16x16x32_bf16 v[126:129], v[130:133], v[190:193], v[126:129]
	v_mfma_f32_16x16x32_bf16 v[126:129], v[140:143], v[194:197], v[126:129]
	v_mfma_f32_16x16x32_bf16 v[122:125], v[154:157], v[190:193], v[122:125]
	v_mfma_f32_16x16x32_bf16 v[122:125], v[170:173], v[194:197], v[122:125]
	v_mfma_f32_16x16x32_bf16 v[110:113], v[182:185], v[190:193], v[110:113]
	v_mfma_f32_16x16x32_bf16 v[110:113], v[186:189], v[194:197], v[110:113]
	v_mfma_f32_16x16x32_bf16 v[118:121], v[174:177], v[190:193], v[118:121]
	v_mfma_f32_16x16x32_bf16 v[118:121], v[178:181], v[194:197], v[118:121]
	v_mfma_f32_16x16x32_bf16 v[102:105], v[174:177], v[198:201], v[102:105]
	v_mfma_f32_16x16x32_bf16 v[102:105], v[178:181], v[202:205], v[102:105]
	v_mfma_f32_16x16x32_bf16 v[94:97], v[182:185], v[198:201], v[94:97]
	v_mfma_f32_16x16x32_bf16 v[94:97], v[186:189], v[202:205], v[94:97]
	v_mfma_f32_16x16x32_bf16 v[106:109], v[154:157], v[198:201], v[106:109]
	v_mfma_f32_16x16x32_bf16 v[106:109], v[170:173], v[202:205], v[106:109]
	v_mfma_f32_16x16x32_bf16 v[114:117], v[130:133], v[198:201], v[114:117]
	v_mfma_f32_16x16x32_bf16 v[114:117], v[140:143], v[202:205], v[114:117]
	v_mfma_f32_16x16x32_bf16 v[98:101], v[130:133], v[236:239], v[98:101]
	v_mfma_f32_16x16x32_bf16 v[98:101], v[140:143], v[240:243], v[98:101]
	v_mfma_f32_16x16x32_bf16 v[90:93], v[154:157], v[236:239], v[90:93]
	v_mfma_f32_16x16x32_bf16 v[90:93], v[170:173], v[240:243], v[90:93]
	v_mfma_f32_16x16x32_bf16 v[78:81], v[182:185], v[236:239], v[78:81]
	v_mfma_f32_16x16x32_bf16 v[78:81], v[186:189], v[240:243], v[78:81]
	v_mfma_f32_16x16x32_bf16 v[86:89], v[174:177], v[236:239], v[86:89]
	v_mfma_f32_16x16x32_bf16 v[86:89], v[178:181], v[240:243], v[86:89]
	v_mfma_f32_16x16x32_bf16 v[70:73], v[174:177], v[244:247], v[70:73]
	v_mfma_f32_16x16x32_bf16 v[70:73], v[178:181], v[248:251], v[70:73]
	v_mfma_f32_16x16x32_bf16 v[66:69], v[182:185], v[244:247], v[66:69]
	v_mfma_f32_16x16x32_bf16 v[66:69], v[186:189], v[248:251], v[66:69]
	v_mfma_f32_16x16x32_bf16 v[74:77], v[154:157], v[244:247], v[74:77]
	v_mfma_f32_16x16x32_bf16 v[74:77], v[170:173], v[248:251], v[74:77]
	v_mfma_f32_16x16x32_bf16 v[82:85], v[130:133], v[244:247], v[82:85]
	v_mfma_f32_16x16x32_bf16 v[82:85], v[140:143], v[248:251], v[82:85]
	s_barrier
	s_setprio 0
	s_or_b32 s23, s22, 0x80
	s_mov_b32 m0, s24
	ds_read_b128 v[190:193], v235 offset:49152
	buffer_load_dwordx4 v229, s[44:47], s23 offen lds
	s_add_i32 s22, s22, 0x80080
	s_mov_b32 m0, s25
	ds_read_b128 v[194:197], v235 offset:50176
	buffer_load_dwordx4 v231, s[44:47], s23 offen lds
	s_mov_b32 m0, s64
	ds_read_b128 v[198:201], v235 offset:51200
	buffer_load_dwordx4 v229, s[44:47], s22 offen lds
	s_mov_b32 m0, s65
	ds_read_b128 v[202:205], v235 offset:52224
	buffer_load_dwordx4 v231, s[44:47], s22 offen lds
	s_mov_b32 m0, s48
	ds_read_b128 v[236:239], v235 offset:53248
	buffer_load_dwordx4 v228, s[60:63], s21 offen lds
	s_mov_b32 m0, s49
	ds_read_b128 v[240:243], v235 offset:54272
	buffer_load_dwordx4 v230, s[60:63], s21 offen lds
	ds_read_b128 v[244:247], v235 offset:55296
	ds_read_b128 v[248:251], v235 offset:56320
	s_waitcnt vmcnt(8)
	s_waitcnt lgkmcnt(0)
	s_setprio 1
	s_barrier
	v_mfma_f32_16x16x32_bf16 v[62:65], v[130:133], v[190:193], v[62:65]
	v_mfma_f32_16x16x32_bf16 v[62:65], v[140:143], v[194:197], v[62:65]
	v_mfma_f32_16x16x32_bf16 v[58:61], v[154:157], v[190:193], v[58:61]
	v_mfma_f32_16x16x32_bf16 v[58:61], v[170:173], v[194:197], v[58:61]
	v_mfma_f32_16x16x32_bf16 v[46:49], v[182:185], v[190:193], v[46:49]
	v_mfma_f32_16x16x32_bf16 v[46:49], v[186:189], v[194:197], v[46:49]
	v_mfma_f32_16x16x32_bf16 v[54:57], v[174:177], v[190:193], v[54:57]
	v_mfma_f32_16x16x32_bf16 v[54:57], v[178:181], v[194:197], v[54:57]
	v_mfma_f32_16x16x32_bf16 v[38:41], v[174:177], v[198:201], v[38:41]
	v_mfma_f32_16x16x32_bf16 v[38:41], v[178:181], v[202:205], v[38:41]
	v_mfma_f32_16x16x32_bf16 v[30:33], v[182:185], v[198:201], v[30:33]
	v_mfma_f32_16x16x32_bf16 v[30:33], v[186:189], v[202:205], v[30:33]
	v_mfma_f32_16x16x32_bf16 v[42:45], v[154:157], v[198:201], v[42:45]
	v_mfma_f32_16x16x32_bf16 v[42:45], v[170:173], v[202:205], v[42:45]
	v_mfma_f32_16x16x32_bf16 v[50:53], v[130:133], v[198:201], v[50:53]
	v_mfma_f32_16x16x32_bf16 v[50:53], v[140:143], v[202:205], v[50:53]
	v_mfma_f32_16x16x32_bf16 v[34:37], v[130:133], v[236:239], v[34:37]
	v_mfma_f32_16x16x32_bf16 v[34:37], v[140:143], v[240:243], v[34:37]
	v_mfma_f32_16x16x32_bf16 v[26:29], v[154:157], v[236:239], v[26:29]
	v_mfma_f32_16x16x32_bf16 v[26:29], v[170:173], v[240:243], v[26:29]
	v_mfma_f32_16x16x32_bf16 v[14:17], v[182:185], v[236:239], v[14:17]
	v_mfma_f32_16x16x32_bf16 v[14:17], v[186:189], v[240:243], v[14:17]
	v_mfma_f32_16x16x32_bf16 v[22:25], v[174:177], v[236:239], v[22:25]
	v_mfma_f32_16x16x32_bf16 v[22:25], v[178:181], v[240:243], v[22:25]
	v_mfma_f32_16x16x32_bf16 v[6:9], v[174:177], v[244:247], v[6:9]
	v_mfma_f32_16x16x32_bf16 v[6:9], v[178:181], v[248:251], v[6:9]
	v_mfma_f32_16x16x32_bf16 v[2:5], v[182:185], v[244:247], v[2:5]
	v_mfma_f32_16x16x32_bf16 v[2:5], v[186:189], v[248:251], v[2:5]
	v_mfma_f32_16x16x32_bf16 v[10:13], v[154:157], v[244:247], v[10:13]
	v_mfma_f32_16x16x32_bf16 v[10:13], v[170:173], v[248:251], v[10:13]
	v_mfma_f32_16x16x32_bf16 v[18:21], v[130:133], v[244:247], v[18:21]
	v_mfma_f32_16x16x32_bf16 v[18:21], v[140:143], v[248:251], v[18:21]
	s_barrier
	s_setprio 0
	s_add_i32 s16, s16, 2
	s_addk_i32 s12, 0x100
	s_addk_i32 s13, 0x100
	s_cmp_gt_u32 s16, 29

.LBB0_892:
	v_readlane_b32 s52, v252, 36
	v_readlane_b32 s68, v252, 38
	s_andn2_b64 vcc, exec, s[42:43]
	s_mov_b64 s[8:9], -1
	v_readlane_b32 s53, v252, 37
	v_readlane_b32 s69, v252, 39
	global_store_dwordx4 v[194:195], v[130:133], off offset:256
	s_cbranch_vccnz .LBB0_877
	s_andn2_b64 vcc, exec, s[92:93]
	s_cbranch_vccnz .LBB0_876
	s_mov_b32 m0, -1
	s_branch .LBB0_876

.LBB0_904:
	s_lshl_b32 s73, s72, 20
	s_and_b64 s[8:9], s[42:43], exec
	s_cselect_b32 s8, s73, s13
	s_lshl_b32 s84, s71, 20
	s_and_b64 s[22:23], s[42:43], exec
	s_cselect_b32 s9, s84, s21
	s_add_i32 s13, s13, 0x80080
	s_addk_i32 s21, 0x100
	s_mov_b32 s22, -2
	s_cmp_eq_u32 m0, -1
	s_cbranch_scc0 .Lgk_rs_4
	s_barrier
.Lgk_rs_4:
	v_add_u32_e32 v133, 0x10000, v178
	ds_read_b128 v[134:137], v133
	ds_read_b128 v[138:141], v133 offset:1024
	ds_read_b128 v[142:145], v133 offset:2048
	ds_read_b128 v[154:157], v133 offset:3072
	v_add_u32_e32 v133, 0x14000, v178
	ds_read_b128 v[170:173], v133
	ds_read_b128 v[180:183], v133 offset:1024
	ds_read_b128 v[184:187], v133 offset:2048
	ds_read_b128 v[188:191], v133 offset:3072
	s_add_i32 s23, s13, 0xfff80080
	s_cmp_eq_u32 s22, 28
	s_cselect_b32 s27, s8, s23
	s_cselect_b32 s26, s9, s21
	s_or_b32 s23, s27, 0x80
	s_mov_b32 s46, s62
	s_mov_b32 s47, s63
	s_mov_b32 m0, s68
	ds_read_b128 v[192:195], v179
	ds_read_b128 v[196:199], v179 offset:1024
	ds_read_b128 v[200:203], v179 offset:2048
	ds_read_b128 v[204:207], v179 offset:3072
	ds_read_b128 v[228:231], v179 offset:4096
	ds_read_b128 v[232:235], v179 offset:5120
	ds_read_b128 v[236:239], v179 offset:6144
	ds_read_b128 v[240:243], v179 offset:7168
	buffer_load_dwordx4 v174, s[44:47], s13 offen lds
	s_mov_b32 m0, s69
	s_nop 0
	buffer_load_dwordx4 v176, s[44:47], s13 offen lds
	s_waitcnt vmcnt(8)
	s_waitcnt lgkmcnt(0)
	s_setprio 1
	s_barrier
	v_mfma_f32_16x16x32_bf16 v[126:129], v[134:137], v[192:195], 0
	v_mfma_f32_16x16x32_bf16 v[126:129], v[138:141], v[196:199], v[126:129]
	v_mfma_f32_16x16x32_bf16 v[122:125], v[142:145], v[192:195], 0
	v_mfma_f32_16x16x32_bf16 v[122:125], v[154:157], v[196:199], v[122:125]
	v_mfma_f32_16x16x32_bf16 v[114:117], v[184:187], v[192:195], 0
	v_mfma_f32_16x16x32_bf16 v[114:117], v[188:191], v[196:199], v[114:117]
	v_mfma_f32_16x16x32_bf16 v[118:121], v[170:173], v[192:195], 0
	v_mfma_f32_16x16x32_bf16 v[118:121], v[180:183], v[196:199], v[118:121]
	v_mfma_f32_16x16x32_bf16 v[102:105], v[170:173], v[200:203], 0
	v_mfma_f32_16x16x32_bf16 v[102:105], v[180:183], v[204:207], v[102:105]
	v_mfma_f32_16x16x32_bf16 v[98:101], v[184:187], v[200:203], 0
	v_mfma_f32_16x16x32_bf16 v[98:101], v[188:191], v[204:207], v[98:101]
	v_mfma_f32_16x16x32_bf16 v[106:109], v[142:145], v[200:203], 0
	v_mfma_f32_16x16x32_bf16 v[106:109], v[154:157], v[204:207], v[106:109]
	v_mfma_f32_16x16x32_bf16 v[110:113], v[134:137], v[200:203], 0
	v_mfma_f32_16x16x32_bf16 v[110:113], v[138:141], v[204:207], v[110:113]
	v_mfma_f32_16x16x32_bf16 v[94:97], v[134:137], v[228:231], 0
	v_mfma_f32_16x16x32_bf16 v[94:97], v[138:141], v[232:235], v[94:97]
	v_mfma_f32_16x16x32_bf16 v[90:93], v[142:145], v[228:231], 0
	v_mfma_f32_16x16x32_bf16 v[90:93], v[154:157], v[232:235], v[90:93]
	v_mfma_f32_16x16x32_bf16 v[82:85], v[184:187], v[228:231], 0
	v_mfma_f32_16x16x32_bf16 v[82:85], v[188:191], v[232:235], v[82:85]
	v_mfma_f32_16x16x32_bf16 v[86:89], v[170:173], v[228:231], 0
	v_mfma_f32_16x16x32_bf16 v[86:89], v[180:183], v[232:235], v[86:89]
	v_mfma_f32_16x16x32_bf16 v[70:73], v[170:173], v[236:239], 0
	v_mfma_f32_16x16x32_bf16 v[70:73], v[180:183], v[240:243], v[70:73]
	v_mfma_f32_16x16x32_bf16 v[66:69], v[184:187], v[236:239], 0
	v_mfma_f32_16x16x32_bf16 v[66:69], v[188:191], v[240:243], v[66:69]
	v_mfma_f32_16x16x32_bf16 v[74:77], v[142:145], v[236:239], 0
	v_mfma_f32_16x16x32_bf16 v[74:77], v[154:157], v[240:243], v[74:77]
	v_mfma_f32_16x16x32_bf16 v[78:81], v[134:137], v[236:239], 0
	v_mfma_f32_16x16x32_bf16 v[78:81], v[138:141], v[240:243], v[78:81]
	s_barrier
	s_setprio 0
	s_mov_b32 m0, s15
	ds_read_b128 v[192:195], v179 offset:16384
	buffer_load_dwordx4 v175, s[60:63], s26 offen lds
	s_add_i32 s34, s26, 0x80000
	s_mov_b32 m0, s16
	ds_read_b128 v[196:199], v179 offset:17408
	buffer_load_dwordx4 v177, s[60:63], s26 offen lds
	s_mov_b32 m0, s18
	ds_read_b128 v[200:203], v179 offset:18432
	buffer_load_dwordx4 v175, s[60:63], s34 offen lds
	s_mov_b32 m0, s19
	ds_read_b128 v[204:207], v179 offset:19456
	buffer_load_dwordx4 v177, s[60:63], s34 offen lds
	s_mov_b32 m0, s14
	ds_read_b128 v[228:231], v179 offset:20480
	buffer_load_dwordx4 v174, s[44:47], s27 offen lds
	s_mov_b32 m0, s24
	ds_read_b128 v[232:235], v179 offset:21504
	buffer_load_dwordx4 v176, s[44:47], s27 offen lds
	ds_read_b128 v[236:239], v179 offset:22528
	ds_read_b128 v[240:243], v179 offset:23552
	s_waitcnt vmcnt(8)
	s_waitcnt lgkmcnt(0)
	s_setprio 1
	s_barrier
	v_mfma_f32_16x16x32_bf16 v[62:65], v[134:137], v[192:195], 0
	v_mfma_f32_16x16x32_bf16 v[62:65], v[138:141], v[196:199], v[62:65]
	v_mfma_f32_16x16x32_bf16 v[58:61], v[142:145], v[192:195], 0
	v_mfma_f32_16x16x32_bf16 v[58:61], v[154:157], v[196:199], v[58:61]
	v_mfma_f32_16x16x32_bf16 v[50:53], v[184:187], v[192:195], 0
	v_mfma_f32_16x16x32_bf16 v[50:53], v[188:191], v[196:199], v[50:53]
	v_mfma_f32_16x16x32_bf16 v[54:57], v[170:173], v[192:195], 0
	v_mfma_f32_16x16x32_bf16 v[54:57], v[180:183], v[196:199], v[54:57]
	v_mfma_f32_16x16x32_bf16 v[38:41], v[170:173], v[200:203], 0
	v_mfma_f32_16x16x32_bf16 v[38:41], v[180:183], v[204:207], v[38:41]
	v_mfma_f32_16x16x32_bf16 v[34:37], v[184:187], v[200:203], 0
	v_mfma_f32_16x16x32_bf16 v[34:37], v[188:191], v[204:207], v[34:37]
	v_mfma_f32_16x16x32_bf16 v[42:45], v[142:145], v[200:203], 0
	v_mfma_f32_16x16x32_bf16 v[42:45], v[154:157], v[204:207], v[42:45]
	v_mfma_f32_16x16x32_bf16 v[46:49], v[134:137], v[200:203], 0
	v_mfma_f32_16x16x32_bf16 v[46:49], v[138:141], v[204:207], v[46:49]
	v_mfma_f32_16x16x32_bf16 v[30:33], v[134:137], v[228:231], 0
	v_mfma_f32_16x16x32_bf16 v[30:33], v[138:141], v[232:235], v[30:33]
	v_mfma_f32_16x16x32_bf16 v[26:29], v[142:145], v[228:231], 0
	v_mfma_f32_16x16x32_bf16 v[26:29], v[154:157], v[232:235], v[26:29]
	v_mfma_f32_16x16x32_bf16 v[18:21], v[184:187], v[228:231], 0
	v_mfma_f32_16x16x32_bf16 v[18:21], v[188:191], v[232:235], v[18:21]
	v_mfma_f32_16x16x32_bf16 v[22:25], v[170:173], v[228:231], 0
	v_mfma_f32_16x16x32_bf16 v[22:25], v[180:183], v[232:235], v[22:25]
	v_mfma_f32_16x16x32_bf16 v[6:9], v[170:173], v[236:239], 0
	v_mfma_f32_16x16x32_bf16 v[6:9], v[180:183], v[240:243], v[6:9]
	v_mfma_f32_16x16x32_bf16 v[2:5], v[184:187], v[236:239], 0
	v_mfma_f32_16x16x32_bf16 v[2:5], v[188:191], v[240:243], v[2:5]
	v_mfma_f32_16x16x32_bf16 v[10:13], v[142:145], v[236:239], 0
	v_mfma_f32_16x16x32_bf16 v[10:13], v[154:157], v[240:243], v[10:13]
	v_mfma_f32_16x16x32_bf16 v[14:17], v[134:137], v[236:239], 0
	v_mfma_f32_16x16x32_bf16 v[14:17], v[138:141], v[240:243], v[14:17]
	s_barrier
	s_setprio 0
	v_add_u32_e32 v133, 0x18000, v178
	ds_read_b128 v[134:137], v133
	ds_read_b128 v[138:141], v133 offset:1024
	ds_read_b128 v[142:145], v133 offset:2048
	ds_read_b128 v[154:157], v133 offset:3072
	v_add_u32_e32 v133, 0x1c000, v178
	ds_read_b128 v[170:173], v133
	ds_read_b128 v[180:183], v133 offset:1024
	ds_read_b128 v[184:187], v133 offset:2048
	ds_read_b128 v[188:191], v133 offset:3072
	s_add_i32 s27, s27, 0x80000
	s_mov_b32 m0, s25
	ds_read_b128 v[192:195], v179 offset:32768
	ds_read_b128 v[196:199], v179 offset:33792
	ds_read_b128 v[200:203], v179 offset:34816
	ds_read_b128 v[204:207], v179 offset:35840
	ds_read_b128 v[228:231], v179 offset:36864
	ds_read_b128 v[232:235], v179 offset:37888
	ds_read_b128 v[236:239], v179 offset:38912
	ds_read_b128 v[240:243], v179 offset:39936
	buffer_load_dwordx4 v174, s[44:47], s27 offen lds
	s_mov_b32 m0, s30
	s_nop 0
	buffer_load_dwordx4 v176, s[44:47], s27 offen lds
	s_waitcnt vmcnt(8)
	s_waitcnt lgkmcnt(0)
	s_setprio 1
	s_barrier
	v_mfma_f32_16x16x32_bf16 v[126:129], v[134:137], v[192:195], v[126:129]
	v_mfma_f32_16x16x32_bf16 v[126:129], v[138:141], v[196:199], v[126:129]
	v_mfma_f32_16x16x32_bf16 v[122:125], v[142:145], v[192:195], v[122:125]
	v_mfma_f32_16x16x32_bf16 v[122:125], v[154:157], v[196:199], v[122:125]
	v_mfma_f32_16x16x32_bf16 v[114:117], v[184:187], v[192:195], v[114:117]
	v_mfma_f32_16x16x32_bf16 v[114:117], v[188:191], v[196:199], v[114:117]
	v_mfma_f32_16x16x32_bf16 v[118:121], v[170:173], v[192:195], v[118:121]
	v_mfma_f32_16x16x32_bf16 v[118:121], v[180:183], v[196:199], v[118:121]
	v_mfma_f32_16x16x32_bf16 v[102:105], v[170:173], v[200:203], v[102:105]
	v_mfma_f32_16x16x32_bf16 v[102:105], v[180:183], v[204:207], v[102:105]
	v_mfma_f32_16x16x32_bf16 v[98:101], v[184:187], v[200:203], v[98:101]
	v_mfma_f32_16x16x32_bf16 v[98:101], v[188:191], v[204:207], v[98:101]
	v_mfma_f32_16x16x32_bf16 v[106:109], v[142:145], v[200:203], v[106:109]
	v_mfma_f32_16x16x32_bf16 v[106:109], v[154:157], v[204:207], v[106:109]
	v_mfma_f32_16x16x32_bf16 v[110:113], v[134:137], v[200:203], v[110:113]
	v_mfma_f32_16x16x32_bf16 v[110:113], v[138:141], v[204:207], v[110:113]
	v_mfma_f32_16x16x32_bf16 v[94:97], v[134:137], v[228:231], v[94:97]
	v_mfma_f32_16x16x32_bf16 v[94:97], v[138:141], v[232:235], v[94:97]
	v_mfma_f32_16x16x32_bf16 v[90:93], v[142:145], v[228:231], v[90:93]
	v_mfma_f32_16x16x32_bf16 v[90:93], v[154:157], v[232:235], v[90:93]
	v_mfma_f32_16x16x32_bf16 v[82:85], v[184:187], v[228:231], v[82:85]
	v_mfma_f32_16x16x32_bf16 v[82:85], v[188:191], v[232:235], v[82:85]
	v_mfma_f32_16x16x32_bf16 v[86:89], v[170:173], v[228:231], v[86:89]
	v_mfma_f32_16x16x32_bf16 v[86:89], v[180:183], v[232:235], v[86:89]
	v_mfma_f32_16x16x32_bf16 v[70:73], v[170:173], v[236:239], v[70:73]
	v_mfma_f32_16x16x32_bf16 v[70:73], v[180:183], v[240:243], v[70:73]
	v_mfma_f32_16x16x32_bf16 v[66:69], v[184:187], v[236:239], v[66:69]
	v_mfma_f32_16x16x32_bf16 v[66:69], v[188:191], v[240:243], v[66:69]
	v_mfma_f32_16x16x32_bf16 v[74:77], v[142:145], v[236:239], v[74:77]
	v_mfma_f32_16x16x32_bf16 v[74:77], v[154:157], v[240:243], v[74:77]
	v_mfma_f32_16x16x32_bf16 v[78:81], v[134:137], v[236:239], v[78:81]
	v_mfma_f32_16x16x32_bf16 v[78:81], v[138:141], v[240:243], v[78:81]
	s_barrier
	s_setprio 0
	s_or_b32 s27, s26, 0x80
	s_mov_b32 m0, s36
	ds_read_b128 v[192:195], v179 offset:49152
	buffer_load_dwordx4 v175, s[60:63], s27 offen lds
	s_add_i32 s26, s26, 0x80080
	s_mov_b32 m0, s37
	ds_read_b128 v[196:199], v179 offset:50176
	buffer_load_dwordx4 v177, s[60:63], s27 offen lds
	s_mov_b32 m0, s48
	ds_read_b128 v[200:203], v179 offset:51200
	buffer_load_dwordx4 v175, s[60:63], s26 offen lds
	s_mov_b32 m0, s49
	ds_read_b128 v[204:207], v179 offset:52224
	buffer_load_dwordx4 v177, s[60:63], s26 offen lds
	s_mov_b32 m0, s40
	ds_read_b128 v[228:231], v179 offset:53248
	buffer_load_dwordx4 v174, s[44:47], s23 offen lds
	s_mov_b32 m0, s41
	ds_read_b128 v[232:235], v179 offset:54272
	buffer_load_dwordx4 v176, s[44:47], s23 offen lds
	ds_read_b128 v[236:239], v179 offset:55296
	ds_read_b128 v[240:243], v179 offset:56320
	s_waitcnt vmcnt(8)
	s_waitcnt lgkmcnt(0)
	s_setprio 1
	s_barrier
	v_mfma_f32_16x16x32_bf16 v[62:65], v[134:137], v[192:195], v[62:65]
	v_mfma_f32_16x16x32_bf16 v[62:65], v[138:141], v[196:199], v[62:65]
	v_mfma_f32_16x16x32_bf16 v[58:61], v[142:145], v[192:195], v[58:61]
	v_mfma_f32_16x16x32_bf16 v[58:61], v[154:157], v[196:199], v[58:61]
	v_mfma_f32_16x16x32_bf16 v[50:53], v[184:187], v[192:195], v[50:53]
	v_mfma_f32_16x16x32_bf16 v[50:53], v[188:191], v[196:199], v[50:53]
	v_mfma_f32_16x16x32_bf16 v[54:57], v[170:173], v[192:195], v[54:57]
	v_mfma_f32_16x16x32_bf16 v[54:57], v[180:183], v[196:199], v[54:57]
	v_mfma_f32_16x16x32_bf16 v[38:41], v[170:173], v[200:203], v[38:41]
	v_mfma_f32_16x16x32_bf16 v[38:41], v[180:183], v[204:207], v[38:41]
	v_mfma_f32_16x16x32_bf16 v[34:37], v[184:187], v[200:203], v[34:37]
	v_mfma_f32_16x16x32_bf16 v[34:37], v[188:191], v[204:207], v[34:37]
	v_mfma_f32_16x16x32_bf16 v[42:45], v[142:145], v[200:203], v[42:45]
	v_mfma_f32_16x16x32_bf16 v[42:45], v[154:157], v[204:207], v[42:45]
	v_mfma_f32_16x16x32_bf16 v[46:49], v[134:137], v[200:203], v[46:49]
	v_mfma_f32_16x16x32_bf16 v[46:49], v[138:141], v[204:207], v[46:49]
	v_mfma_f32_16x16x32_bf16 v[30:33], v[134:137], v[228:231], v[30:33]
	v_mfma_f32_16x16x32_bf16 v[30:33], v[138:141], v[232:235], v[30:33]
	v_mfma_f32_16x16x32_bf16 v[26:29], v[142:145], v[228:231], v[26:29]
	v_mfma_f32_16x16x32_bf16 v[26:29], v[154:157], v[232:235], v[26:29]
	v_mfma_f32_16x16x32_bf16 v[18:21], v[184:187], v[228:231], v[18:21]
	v_mfma_f32_16x16x32_bf16 v[18:21], v[188:191], v[232:235], v[18:21]
	v_mfma_f32_16x16x32_bf16 v[22:25], v[170:173], v[228:231], v[22:25]
	v_mfma_f32_16x16x32_bf16 v[22:25], v[180:183], v[232:235], v[22:25]
	v_mfma_f32_16x16x32_bf16 v[6:9], v[170:173], v[236:239], v[6:9]
	v_mfma_f32_16x16x32_bf16 v[6:9], v[180:183], v[240:243], v[6:9]
	v_mfma_f32_16x16x32_bf16 v[2:5], v[184:187], v[236:239], v[2:5]
	v_mfma_f32_16x16x32_bf16 v[2:5], v[188:191], v[240:243], v[2:5]
	v_mfma_f32_16x16x32_bf16 v[10:13], v[142:145], v[236:239], v[10:13]
	v_mfma_f32_16x16x32_bf16 v[10:13], v[154:157], v[240:243], v[10:13]
	v_mfma_f32_16x16x32_bf16 v[14:17], v[134:137], v[236:239], v[14:17]
	v_mfma_f32_16x16x32_bf16 v[14:17], v[138:141], v[240:243], v[14:17]
	s_barrier
	s_setprio 0
	s_add_i32 s22, s22, 2
	s_addk_i32 s13, 0x100
	s_addk_i32 s21, 0x100
	s_cmp_gt_u32 s22, 29

.LBB0_908:
	s_lshl_b32 s8, s12, 8
	s_add_i32 s26, s8, s66
	s_ashr_i32 s27, s26, 31
	v_lshl_add_u64 v[134:135], s[26:27], 3, v[130:131]
	global_load_dwordx2 v[154:155], v[134:135], off
	global_load_dwordx2 v[172:173], v[134:135], off offset:128
	global_load_dwordx2 v[170:171], v[134:135], off offset:256
	global_load_dwordx2 v[144:145], v[134:135], off offset:384
	global_load_dwordx2 v[142:143], v[134:135], off offset:1024
	global_load_dwordx2 v[140:141], v[134:135], off offset:1152
	global_load_dwordx2 v[138:139], v[134:135], off offset:1280
	global_load_dwordx2 v[136:137], v[134:135], off offset:1408
	s_lshl_b32 s2, s2, 8
	s_or_b32 s8, s2, s67
	s_flbit_i32_b32 s2, 0
	s_min_u32 s85, s2, 32
	s_sub_i32 s23, 32, s85
	s_ashr_i32 s9, s8, 31
	s_lshl_b64 s[12:13], s[26:27], 11
	s_add_u32 s2, s31, s12
	s_addc_u32 s12, s33, s13
	s_lshl_b64 s[46:47], s[8:9], 1
	s_add_u32 s34, s2, s46
	s_addc_u32 s35, s12, s47
	s_or_b32 s8, s26, 16
	s_ashr_i32 s9, s8, 31
	s_lshl_b64 s[8:9], s[8:9], 11
	s_add_u32 s2, s31, s8
	s_addc_u32 s9, s33, s9
	s_add_u32 s8, s2, s46
	s_addc_u32 s9, s9, s47
	s_waitcnt vmcnt(0)
	v_mov_b32_e32 v146, v155
	v_lshlrev_b64 v[134:135], s85, v[146:147]
	v_min_u32_e32 v134, 1, v134
	v_or_b32_e32 v134, v135, v134
	v_cvt_f32_u32_e32 v133, v154
	v_cvt_f32_u32_e32 v134, v134
	v_fmamk_f32 v133, v133, 0x30000000, v209
	v_ldexp_f32 v134, v134, s23
	v_fmac_f32_e32 v133, 2.0, v134
	v_rsq_f32_e32 v146, v133
	v_mov_b32_e32 v133, v147
	v_lshl_add_u64 v[134:135], s[34:35], 0, v[132:133]
	v_pk_mul_f32 v[128:129], v[128:129], v[146:147] op_sel_hi:[1,0]
	s_nop 0
	v_mul_f32_e32 v133, 0x3d372713, v128
	v_mul_f32_e32 v133, v128, v133
	v_fma_f32 v133, v128, v133, v128
	v_mul_f32_e32 v133, 0x3fcc422a, v133
	v_mul_f32_e32 v133, 0xbfb8aa3b, v133
	v_exp_f32_e32 v133, v133
	v_pk_mul_f32 v[124:125], v[124:125], v[146:147] op_sel_hi:[1,0]
	v_pk_mul_f32 v[126:127], v[126:127], v[146:147] op_sel_hi:[1,0]
	v_pk_mul_f32 v[154:155], v[122:123], v[146:147] op_sel_hi:[1,0]
	v_add_f32_e32 v133, 1.0, v133
	v_rcp_f32_e32 v133, v133
	v_mul_f32_e32 v122, 0x3d372713, v126
	v_mul_f32_e32 v123, 0x3d372713, v154
	v_mul_f32_e32 v122, v126, v122
	v_mul_f32_e32 v128, v128, v133
	v_mul_f32_e32 v133, 0x3d372713, v124
	v_mul_f32_e32 v133, v124, v133
	v_mul_f32_e32 v123, v154, v123
	v_fma_f32 v133, v124, v133, v124
	v_fma_f32 v122, v126, v122, v126
	v_fma_f32 v123, v154, v123, v154
	v_mul_f32_e32 v133, 0x3fcc422a, v133
	v_mul_f32_e32 v122, 0x3fcc422a, v122
	v_mul_f32_e32 v123, 0x3fcc422a, v123
	v_mul_f32_e32 v133, 0xbfb8aa3b, v133
	v_mul_f32_e32 v122, 0xbfb8aa3b, v122
	v_mul_f32_e32 v123, 0xbfb8aa3b, v123
	v_exp_f32_e32 v133, v133
	v_exp_f32_e32 v122, v122
	v_exp_f32_e32 v123, v123
	v_pk_mul_f32 v[118:119], v[118:119], v[146:147] op_sel_hi:[1,0]
	v_add_f32_e32 v133, 1.0, v133
	v_add_f32_e32 v122, 1.0, v122
	v_add_f32_e32 v123, 1.0, v123
	v_rcp_f32_e32 v133, v133
	v_rcp_f32_e32 v122, v122
	v_rcp_f32_e32 v123, v123
	v_pk_mul_f32 v[114:115], v[114:115], v[146:147] op_sel_hi:[1,0]
	v_mul_f32_e32 v133, v124, v133
	v_mul_f32_e32 v124, 0x3d372713, v129
	v_mul_f32_e32 v122, v126, v122
	v_mul_f32_e32 v126, v154, v123
	v_mul_f32_e32 v123, 0x3d372713, v127
	v_mul_f32_e32 v124, v129, v124
	v_mul_f32_e32 v123, v127, v123
	v_fma_f32 v124, v129, v124, v129
	v_fma_f32 v123, v127, v123, v127
	v_mul_f32_e32 v124, 0x3fcc422a, v124
	v_mul_f32_e32 v123, 0x3fcc422a, v123
	v_mul_f32_e32 v124, 0xbfb8aa3b, v124
	v_mul_f32_e32 v123, 0xbfb8aa3b, v123
	v_exp_f32_e32 v124, v124
	v_exp_f32_e32 v123, v123
	v_pk_mul_f32 v[120:121], v[120:121], v[146:147] op_sel_hi:[1,0]
	v_pk_mul_f32 v[116:117], v[116:117], v[146:147] op_sel_hi:[1,0]
	v_add_f32_e32 v124, 1.0, v124
	v_add_f32_e32 v123, 1.0, v123
	v_rcp_f32_e32 v124, v124
	v_rcp_f32_e32 v123, v123
	s_waitcnt vmcnt(6)
	v_mov_b32_e32 v146, v173
	v_mul_f32_e32 v124, v129, v124
	v_mul_f32_e32 v129, 0x3d372713, v125
	v_mul_f32_e32 v123, v127, v123
	v_mul_f32_e32 v127, 0x3d372713, v155
	v_mul_f32_e32 v129, v125, v129
	v_mul_f32_e32 v127, v155, v127
	v_fma_f32 v129, v125, v129, v125
	v_fma_f32 v127, v155, v127, v155
	v_mul_f32_e32 v129, 0x3fcc422a, v129
	v_mul_f32_e32 v127, 0x3fcc422a, v127
	v_mul_f32_e32 v129, 0xbfb8aa3b, v129
	v_mul_f32_e32 v127, 0xbfb8aa3b, v127
	v_exp_f32_e32 v129, v129
	v_exp_f32_e32 v127, v127
	v_cvt_pk_bf16_f32 v122, v122, v123
	v_cvt_pk_bf16_f32 v123, v128, v124
	v_add_f32_e32 v129, 1.0, v129
	v_add_f32_e32 v127, 1.0, v127
	v_rcp_f32_e32 v129, v129
	v_rcp_f32_e32 v127, v127
	v_mul_f32_e32 v125, v125, v129
	v_mul_f32_e32 v127, v155, v127
	v_cvt_pk_bf16_f32 v124, v126, v127
	v_cvt_pk_bf16_f32 v125, v133, v125
	global_store_dwordx4 v132, v[122:125], s[34:35]
	s_nop 1
	v_mul_f32_e32 v122, 0x3d372713, v118
	v_mul_f32_e32 v122, v118, v122
	v_fma_f32 v122, v118, v122, v118
	v_mul_f32_e32 v122, 0x3fcc422a, v122
	v_mul_f32_e32 v122, 0xbfb8aa3b, v122
	v_exp_f32_e32 v122, v122
	s_nop 0
	v_add_f32_e32 v122, 1.0, v122
	v_rcp_f32_e32 v122, v122
	s_nop 0
	v_mul_f32_e32 v118, v118, v122
	v_mul_f32_e32 v122, 0x3d372713, v114
	v_mul_f32_e32 v122, v114, v122
	v_fma_f32 v122, v114, v122, v114
	v_mul_f32_e32 v122, 0x3fcc422a, v122
	v_mul_f32_e32 v122, 0xbfb8aa3b, v122
	v_exp_f32_e32 v122, v122
	s_nop 0
	v_add_f32_e32 v122, 1.0, v122
	v_rcp_f32_e32 v122, v122
	s_nop 0
	v_mul_f32_e32 v122, v114, v122
	v_mul_f32_e32 v114, 0x3d372713, v119
	v_mul_f32_e32 v114, v119, v114
	v_fma_f32 v114, v119, v114, v119
	v_mul_f32_e32 v114, 0x3fcc422a, v114
	v_mul_f32_e32 v114, 0xbfb8aa3b, v114
	v_exp_f32_e32 v114, v114
	s_nop 0
	v_add_f32_e32 v114, 1.0, v114
	v_rcp_f32_e32 v114, v114
	s_nop 0
	v_mul_f32_e32 v114, v119, v114
	v_mul_f32_e32 v119, 0x3d372713, v115
	v_mul_f32_e32 v119, v115, v119
	v_fma_f32 v119, v115, v119, v115
	v_mul_f32_e32 v119, 0x3fcc422a, v119
	v_mul_f32_e32 v119, 0xbfb8aa3b, v119
	v_exp_f32_e32 v119, v119
	v_cvt_pk_bf16_f32 v114, v118, v114
	s_nop 0
	v_add_f32_e32 v119, 1.0, v119
	v_rcp_f32_e32 v119, v119
	s_nop 0
	v_mul_f32_e32 v119, v115, v119
	v_mul_f32_e32 v115, 0x3d372713, v120
	v_mul_f32_e32 v115, v120, v115
	v_fma_f32 v115, v120, v115, v120
	v_mul_f32_e32 v115, 0x3fcc422a, v115
	v_mul_f32_e32 v115, 0xbfb8aa3b, v115
	v_exp_f32_e32 v115, v115
	s_nop 0
	v_add_f32_e32 v115, 1.0, v115
	v_rcp_f32_e32 v115, v115
	s_nop 0
	v_mul_f32_e32 v115, v120, v115
	v_mul_f32_e32 v120, 0x3d372713, v116
	v_mul_f32_e32 v120, v116, v120
	v_fma_f32 v120, v116, v120, v116
	v_mul_f32_e32 v120, 0x3fcc422a, v120
	v_mul_f32_e32 v120, 0xbfb8aa3b, v120
	v_exp_f32_e32 v120, v120
	s_nop 0
	v_add_f32_e32 v120, 1.0, v120
	v_rcp_f32_e32 v120, v120
	s_nop 0
	v_mul_f32_e32 v120, v116, v120
	v_mul_f32_e32 v116, 0x3d372713, v121
	v_mul_f32_e32 v116, v121, v116
	v_fma_f32 v116, v121, v116, v121
	v_mul_f32_e32 v116, 0x3fcc422a, v116
	v_mul_f32_e32 v116, 0xbfb8aa3b, v116
	v_exp_f32_e32 v116, v116
	s_nop 0
	v_add_f32_e32 v116, 1.0, v116
	v_rcp_f32_e32 v116, v116
	s_nop 0
	v_mul_f32_e32 v116, v121, v116
	v_mul_f32_e32 v121, 0x3d372713, v117
	v_mul_f32_e32 v121, v117, v121
	v_fma_f32 v121, v117, v121, v117
	v_mul_f32_e32 v121, 0x3fcc422a, v121
	v_mul_f32_e32 v121, 0xbfb8aa3b, v121
	v_exp_f32_e32 v121, v121
	v_cvt_pk_bf16_f32 v115, v115, v116
	v_cvt_pk_bf16_f32 v116, v122, v119
	s_nop 0
	v_add_f32_e32 v121, 1.0, v121
	v_rcp_f32_e32 v121, v121
	s_nop 0
	v_mul_f32_e32 v117, v117, v121
	v_cvt_pk_bf16_f32 v117, v120, v117
	global_store_dwordx4 v132, v[114:117], s[34:35] offset:256
	s_nop 1
	v_cvt_f32_u32_e32 v114, v172
	v_fmamk_f32 v116, v114, 0x30000000, v209
	v_lshlrev_b64 v[114:115], s85, v[146:147]
	v_min_u32_e32 v114, 1, v114
	v_or_b32_e32 v114, v115, v114
	v_cvt_f32_u32_e32 v114, v114
	s_waitcnt vmcnt(7)
	v_mov_b32_e32 v146, v171
	v_ldexp_f32 v114, v114, s23
	v_fmac_f32_e32 v116, 2.0, v114
	v_rsq_f32_e32 v114, v116
	s_nop 0
	v_pk_mul_f32 v[110:111], v[110:111], v[114:115] op_sel_hi:[1,0]
	v_pk_mul_f32 v[112:113], v[112:113], v[114:115] op_sel_hi:[1,0]
	v_pk_mul_f32 v[108:109], v[108:109], v[114:115] op_sel_hi:[1,0]
	v_pk_mul_f32 v[106:107], v[106:107], v[114:115] op_sel_hi:[1,0]
	v_mul_f32_e32 v115, 0x3d372713, v110
	v_mul_f32_e32 v115, v110, v115
	v_fma_f32 v115, v110, v115, v110
	v_mul_f32_e32 v115, 0x3fcc422a, v115
	v_mul_f32_e32 v115, 0xbfb8aa3b, v115
	v_exp_f32_e32 v115, v115
	s_nop 0
	v_add_f32_e32 v115, 1.0, v115
	v_rcp_f32_e32 v115, v115
	s_nop 0
	v_mul_f32_e32 v110, v110, v115
	v_mul_f32_e32 v115, 0x3d372713, v106
	v_mul_f32_e32 v115, v106, v115
	v_fma_f32 v115, v106, v115, v106
	v_mul_f32_e32 v115, 0x3fcc422a, v115
	v_mul_f32_e32 v115, 0xbfb8aa3b, v115
	v_exp_f32_e32 v115, v115
	s_nop 0
	v_add_f32_e32 v115, 1.0, v115
	v_rcp_f32_e32 v115, v115
	s_nop 0
	v_mul_f32_e32 v115, v106, v115
	v_mul_f32_e32 v106, 0x3d372713, v111
	v_mul_f32_e32 v106, v111, v106
	v_fma_f32 v106, v111, v106, v111
	v_mul_f32_e32 v106, 0x3fcc422a, v106
	v_mul_f32_e32 v106, 0xbfb8aa3b, v106
	v_exp_f32_e32 v106, v106
	v_pk_mul_f32 v[102:103], v[102:103], v[114:115] op_sel_hi:[1,0]
	v_pk_mul_f32 v[98:99], v[98:99], v[114:115] op_sel_hi:[1,0]
	v_pk_mul_f32 v[104:105], v[104:105], v[114:115] op_sel_hi:[1,0]
	v_add_f32_e32 v106, 1.0, v106
	v_rcp_f32_e32 v106, v106
	v_pk_mul_f32 v[100:101], v[100:101], v[114:115] op_sel_hi:[1,0]
	v_mul_f32_e32 v106, v111, v106
	v_mul_f32_e32 v111, 0x3d372713, v107
	v_mul_f32_e32 v111, v107, v111
	v_fma_f32 v111, v107, v111, v107
	v_mul_f32_e32 v111, 0x3fcc422a, v111
	v_mul_f32_e32 v111, 0xbfb8aa3b, v111
	v_exp_f32_e32 v111, v111
	v_cvt_pk_bf16_f32 v106, v110, v106
	s_nop 0
	v_add_f32_e32 v111, 1.0, v111
	v_rcp_f32_e32 v111, v111
	s_nop 0
	v_mul_f32_e32 v111, v107, v111
	v_mul_f32_e32 v107, 0x3d372713, v112
	v_mul_f32_e32 v107, v112, v107
	v_fma_f32 v107, v112, v107, v112
	v_mul_f32_e32 v107, 0x3fcc422a, v107
	v_mul_f32_e32 v107, 0xbfb8aa3b, v107
	v_exp_f32_e32 v107, v107
	s_nop 0
	v_add_f32_e32 v107, 1.0, v107
	v_rcp_f32_e32 v107, v107
	s_nop 0
	v_mul_f32_e32 v107, v112, v107
	v_mul_f32_e32 v112, 0x3d372713, v108
	v_mul_f32_e32 v112, v108, v112
	v_fma_f32 v112, v108, v112, v108
	v_mul_f32_e32 v112, 0x3fcc422a, v112
	v_mul_f32_e32 v112, 0xbfb8aa3b, v112
	v_exp_f32_e32 v112, v112
	s_nop 0
	v_add_f32_e32 v112, 1.0, v112
	v_rcp_f32_e32 v112, v112
	s_nop 0
	v_mul_f32_e32 v112, v108, v112
	v_mul_f32_e32 v108, 0x3d372713, v113
	v_mul_f32_e32 v108, v113, v108
	v_fma_f32 v108, v113, v108, v113
	v_mul_f32_e32 v108, 0x3fcc422a, v108
	v_mul_f32_e32 v108, 0xbfb8aa3b, v108
	v_exp_f32_e32 v108, v108
	s_nop 0
	v_add_f32_e32 v108, 1.0, v108
	v_rcp_f32_e32 v108, v108
	s_nop 0
	v_mul_f32_e32 v108, v113, v108
	v_mul_f32_e32 v113, 0x3d372713, v109
	v_mul_f32_e32 v113, v109, v113
	v_fma_f32 v113, v109, v113, v109
	v_mul_f32_e32 v113, 0x3fcc422a, v113
	v_mul_f32_e32 v113, 0xbfb8aa3b, v113
	v_exp_f32_e32 v113, v113
	v_cvt_pk_bf16_f32 v107, v107, v108
	v_cvt_pk_bf16_f32 v108, v115, v111
	s_nop 0
	v_add_f32_e32 v113, 1.0, v113
	v_rcp_f32_e32 v113, v113
	s_nop 0
	v_mul_f32_e32 v109, v109, v113
	v_cvt_pk_bf16_f32 v109, v112, v109
	global_store_dwordx4 v132, v[106:109], s[8:9]
	s_nop 1
	v_mul_f32_e32 v106, 0x3d372713, v102
	v_mul_f32_e32 v106, v102, v106
	v_fma_f32 v106, v102, v106, v102
	v_mul_f32_e32 v106, 0x3fcc422a, v106
	v_mul_f32_e32 v106, 0xbfb8aa3b, v106
	v_exp_f32_e32 v106, v106
	s_nop 0
	v_add_f32_e32 v106, 1.0, v106
	v_rcp_f32_e32 v106, v106
	s_nop 0
	v_mul_f32_e32 v102, v102, v106
	v_mul_f32_e32 v106, 0x3d372713, v98
	v_mul_f32_e32 v106, v98, v106
	v_fma_f32 v106, v98, v106, v98
	v_mul_f32_e32 v106, 0x3fcc422a, v106
	v_mul_f32_e32 v106, 0xbfb8aa3b, v106
	v_exp_f32_e32 v106, v106
	s_nop 0
	v_add_f32_e32 v106, 1.0, v106
	v_rcp_f32_e32 v106, v106
	s_nop 0
	v_mul_f32_e32 v106, v98, v106
	v_mul_f32_e32 v98, 0x3d372713, v103
	v_mul_f32_e32 v98, v103, v98
	v_fma_f32 v98, v103, v98, v103
	v_mul_f32_e32 v98, 0x3fcc422a, v98
	v_mul_f32_e32 v98, 0xbfb8aa3b, v98
	v_exp_f32_e32 v98, v98
	s_nop 0
	v_add_f32_e32 v98, 1.0, v98
	v_rcp_f32_e32 v98, v98
	s_nop 0
	v_mul_f32_e32 v98, v103, v98
	v_mul_f32_e32 v103, 0x3d372713, v99
	v_mul_f32_e32 v103, v99, v103
	v_fma_f32 v103, v99, v103, v99
	v_mul_f32_e32 v103, 0x3fcc422a, v103
	v_mul_f32_e32 v103, 0xbfb8aa3b, v103
	v_exp_f32_e32 v103, v103
	v_cvt_pk_bf16_f32 v98, v102, v98
	s_nop 0
	v_add_f32_e32 v103, 1.0, v103
	v_rcp_f32_e32 v103, v103
	s_nop 0
	v_mul_f32_e32 v103, v99, v103
	v_mul_f32_e32 v99, 0x3d372713, v104
	v_mul_f32_e32 v99, v104, v99
	v_fma_f32 v99, v104, v99, v104
	v_mul_f32_e32 v99, 0x3fcc422a, v99
	v_mul_f32_e32 v99, 0xbfb8aa3b, v99
	v_exp_f32_e32 v99, v99
	s_nop 0
	v_add_f32_e32 v99, 1.0, v99
	v_rcp_f32_e32 v99, v99
	s_nop 0
	v_mul_f32_e32 v99, v104, v99
	v_mul_f32_e32 v104, 0x3d372713, v100
	v_mul_f32_e32 v104, v100, v104
	v_fma_f32 v104, v100, v104, v100
	v_mul_f32_e32 v104, 0x3fcc422a, v104
	v_mul_f32_e32 v104, 0xbfb8aa3b, v104
	v_exp_f32_e32 v104, v104
	s_nop 0
	v_add_f32_e32 v104, 1.0, v104
	v_rcp_f32_e32 v104, v104
	s_nop 0
	v_mul_f32_e32 v104, v100, v104
	v_mul_f32_e32 v100, 0x3d372713, v105
	v_mul_f32_e32 v100, v105, v100
	v_fma_f32 v100, v105, v100, v105
	v_mul_f32_e32 v100, 0x3fcc422a, v100
	v_mul_f32_e32 v100, 0xbfb8aa3b, v100
	v_exp_f32_e32 v100, v100
	s_nop 0
	v_add_f32_e32 v100, 1.0, v100
	v_rcp_f32_e32 v100, v100
	s_nop 0
	v_mul_f32_e32 v100, v105, v100
	v_mul_f32_e32 v105, 0x3d372713, v101
	v_mul_f32_e32 v105, v101, v105
	v_fma_f32 v105, v101, v105, v101
	v_mul_f32_e32 v105, 0x3fcc422a, v105
	v_mul_f32_e32 v105, 0xbfb8aa3b, v105
	v_exp_f32_e32 v105, v105
	v_cvt_pk_bf16_f32 v99, v99, v100
	v_cvt_pk_bf16_f32 v100, v106, v103
	s_nop 0
	v_add_f32_e32 v105, 1.0, v105
	v_rcp_f32_e32 v105, v105
	s_nop 0
	v_mul_f32_e32 v101, v101, v105
	v_cvt_pk_bf16_f32 v101, v104, v101
	global_store_dwordx4 v132, v[98:101], s[8:9] offset:256
	s_or_b32 s8, s26, 32
	s_ashr_i32 s9, s8, 31
	v_cvt_f32_u32_e32 v98, v170
	s_lshl_b64 s[8:9], s[8:9], 11
	s_add_u32 s2, s31, s8
	s_addc_u32 s9, s33, s9
	v_fmamk_f32 v100, v98, 0x30000000, v209
	v_lshlrev_b64 v[98:99], s85, v[146:147]
	v_min_u32_e32 v98, 1, v98
	v_or_b32_e32 v98, v99, v98
	v_cvt_f32_u32_e32 v98, v98
	s_add_u32 s8, s2, s46
	s_addc_u32 s9, s9, s47
	s_waitcnt vmcnt(8)
	v_mov_b32_e32 v146, v145
	v_ldexp_f32 v98, v98, s23
	v_fmac_f32_e32 v100, 2.0, v98
	v_rsq_f32_e32 v98, v100
	s_nop 0
	v_pk_mul_f32 v[94:95], v[94:95], v[98:99] op_sel_hi:[1,0]
	v_pk_mul_f32 v[96:97], v[96:97], v[98:99] op_sel_hi:[1,0]
	v_pk_mul_f32 v[92:93], v[92:93], v[98:99] op_sel_hi:[1,0]
	v_pk_mul_f32 v[90:91], v[90:91], v[98:99] op_sel_hi:[1,0]
	v_mul_f32_e32 v99, 0x3d372713, v94
	v_mul_f32_e32 v99, v94, v99
	v_fma_f32 v99, v94, v99, v94
	v_mul_f32_e32 v99, 0x3fcc422a, v99
	v_mul_f32_e32 v99, 0xbfb8aa3b, v99
	v_exp_f32_e32 v99, v99
	s_nop 0
	v_add_f32_e32 v99, 1.0, v99
	v_rcp_f32_e32 v99, v99
	s_nop 0
	v_mul_f32_e32 v94, v94, v99
	v_mul_f32_e32 v99, 0x3d372713, v90
	v_mul_f32_e32 v99, v90, v99
	v_fma_f32 v99, v90, v99, v90
	v_mul_f32_e32 v99, 0x3fcc422a, v99
	v_mul_f32_e32 v99, 0xbfb8aa3b, v99
	v_exp_f32_e32 v99, v99
	s_nop 0
	v_add_f32_e32 v99, 1.0, v99
	v_rcp_f32_e32 v99, v99
	s_nop 0
	v_mul_f32_e32 v99, v90, v99
	v_mul_f32_e32 v90, 0x3d372713, v95
	v_mul_f32_e32 v90, v95, v90
	v_fma_f32 v90, v95, v90, v95
	v_mul_f32_e32 v90, 0x3fcc422a, v90
	v_mul_f32_e32 v90, 0xbfb8aa3b, v90
	v_exp_f32_e32 v90, v90
	v_pk_mul_f32 v[86:87], v[86:87], v[98:99] op_sel_hi:[1,0]
	v_pk_mul_f32 v[82:83], v[82:83], v[98:99] op_sel_hi:[1,0]
	v_pk_mul_f32 v[88:89], v[88:89], v[98:99] op_sel_hi:[1,0]
	v_add_f32_e32 v90, 1.0, v90
	v_rcp_f32_e32 v90, v90
	v_pk_mul_f32 v[84:85], v[84:85], v[98:99] op_sel_hi:[1,0]
	v_mul_f32_e32 v90, v95, v90
	v_mul_f32_e32 v95, 0x3d372713, v91
	v_mul_f32_e32 v95, v91, v95
	v_fma_f32 v95, v91, v95, v91
	v_mul_f32_e32 v95, 0x3fcc422a, v95
	v_mul_f32_e32 v95, 0xbfb8aa3b, v95
	v_exp_f32_e32 v95, v95
	v_cvt_pk_bf16_f32 v90, v94, v90
	s_nop 0
	v_add_f32_e32 v95, 1.0, v95
	v_rcp_f32_e32 v95, v95
	s_nop 0
	v_mul_f32_e32 v95, v91, v95
	v_mul_f32_e32 v91, 0x3d372713, v96
	v_mul_f32_e32 v91, v96, v91
	v_fma_f32 v91, v96, v91, v96
	v_mul_f32_e32 v91, 0x3fcc422a, v91
	v_mul_f32_e32 v91, 0xbfb8aa3b, v91
	v_exp_f32_e32 v91, v91
	s_nop 0
	v_add_f32_e32 v91, 1.0, v91
	v_rcp_f32_e32 v91, v91
	s_nop 0
	v_mul_f32_e32 v91, v96, v91
	v_mul_f32_e32 v96, 0x3d372713, v92
	v_mul_f32_e32 v96, v92, v96
	v_fma_f32 v96, v92, v96, v92
	v_mul_f32_e32 v96, 0x3fcc422a, v96
	v_mul_f32_e32 v96, 0xbfb8aa3b, v96
	v_exp_f32_e32 v96, v96
	s_nop 0
	v_add_f32_e32 v96, 1.0, v96
	v_rcp_f32_e32 v96, v96
	s_nop 0
	v_mul_f32_e32 v96, v92, v96
	v_mul_f32_e32 v92, 0x3d372713, v97
	v_mul_f32_e32 v92, v97, v92
	v_fma_f32 v92, v97, v92, v97
	v_mul_f32_e32 v92, 0x3fcc422a, v92
	v_mul_f32_e32 v92, 0xbfb8aa3b, v92
	v_exp_f32_e32 v92, v92
	s_nop 0
	v_add_f32_e32 v92, 1.0, v92
	v_rcp_f32_e32 v92, v92
	s_nop 0
	v_mul_f32_e32 v92, v97, v92
	v_mul_f32_e32 v97, 0x3d372713, v93
	v_mul_f32_e32 v97, v93, v97
	v_fma_f32 v97, v93, v97, v93
	v_mul_f32_e32 v97, 0x3fcc422a, v97
	v_mul_f32_e32 v97, 0xbfb8aa3b, v97
	v_exp_f32_e32 v97, v97
	v_cvt_pk_bf16_f32 v91, v91, v92
	v_cvt_pk_bf16_f32 v92, v99, v95
	s_nop 0
	v_add_f32_e32 v97, 1.0, v97
	v_rcp_f32_e32 v97, v97
	s_nop 0
	v_mul_f32_e32 v93, v93, v97
	v_cvt_pk_bf16_f32 v93, v96, v93
	global_store_dwordx4 v132, v[90:93], s[8:9]
	s_nop 1
	v_mul_f32_e32 v90, 0x3d372713, v86
	v_mul_f32_e32 v90, v86, v90
	v_fma_f32 v90, v86, v90, v86
	v_mul_f32_e32 v90, 0x3fcc422a, v90
	v_mul_f32_e32 v90, 0xbfb8aa3b, v90
	v_exp_f32_e32 v90, v90
	s_nop 0
	v_add_f32_e32 v90, 1.0, v90
	v_rcp_f32_e32 v90, v90
	s_nop 0
	v_mul_f32_e32 v86, v86, v90
	v_mul_f32_e32 v90, 0x3d372713, v82
	v_mul_f32_e32 v90, v82, v90
	v_fma_f32 v90, v82, v90, v82
	v_mul_f32_e32 v90, 0x3fcc422a, v90
	v_mul_f32_e32 v90, 0xbfb8aa3b, v90
	v_exp_f32_e32 v90, v90
	s_nop 0
	v_add_f32_e32 v90, 1.0, v90
	v_rcp_f32_e32 v90, v90
	s_nop 0
	v_mul_f32_e32 v90, v82, v90
	v_mul_f32_e32 v82, 0x3d372713, v87
	v_mul_f32_e32 v82, v87, v82
	v_fma_f32 v82, v87, v82, v87
	v_mul_f32_e32 v82, 0x3fcc422a, v82
	v_mul_f32_e32 v82, 0xbfb8aa3b, v82
	v_exp_f32_e32 v82, v82
	s_nop 0
	v_add_f32_e32 v82, 1.0, v82
	v_rcp_f32_e32 v82, v82
	s_nop 0
	v_mul_f32_e32 v82, v87, v82
	v_mul_f32_e32 v87, 0x3d372713, v83
	v_mul_f32_e32 v87, v83, v87
	v_fma_f32 v87, v83, v87, v83
	v_mul_f32_e32 v87, 0x3fcc422a, v87
	v_mul_f32_e32 v87, 0xbfb8aa3b, v87
	v_exp_f32_e32 v87, v87
	v_cvt_pk_bf16_f32 v82, v86, v82
	s_nop 0
	v_add_f32_e32 v87, 1.0, v87
	v_rcp_f32_e32 v87, v87
	s_nop 0
	v_mul_f32_e32 v87, v83, v87
	v_mul_f32_e32 v83, 0x3d372713, v88
	v_mul_f32_e32 v83, v88, v83
	v_fma_f32 v83, v88, v83, v88
	v_mul_f32_e32 v83, 0x3fcc422a, v83
	v_mul_f32_e32 v83, 0xbfb8aa3b, v83
	v_exp_f32_e32 v83, v83
	s_nop 0
	v_add_f32_e32 v83, 1.0, v83
	v_rcp_f32_e32 v83, v83
	s_nop 0
	v_mul_f32_e32 v83, v88, v83
	v_mul_f32_e32 v88, 0x3d372713, v84
	v_mul_f32_e32 v88, v84, v88
	v_fma_f32 v88, v84, v88, v84
	v_mul_f32_e32 v88, 0x3fcc422a, v88
	v_mul_f32_e32 v88, 0xbfb8aa3b, v88
	v_exp_f32_e32 v88, v88
	s_nop 0
	v_add_f32_e32 v88, 1.0, v88
	v_rcp_f32_e32 v88, v88
	s_nop 0
	v_mul_f32_e32 v88, v84, v88
	v_mul_f32_e32 v84, 0x3d372713, v89
	v_mul_f32_e32 v84, v89, v84
	v_fma_f32 v84, v89, v84, v89
	v_mul_f32_e32 v84, 0x3fcc422a, v84
	v_mul_f32_e32 v84, 0xbfb8aa3b, v84
	v_exp_f32_e32 v84, v84
	s_nop 0
	v_add_f32_e32 v84, 1.0, v84
	v_rcp_f32_e32 v84, v84
	s_nop 0
	v_mul_f32_e32 v84, v89, v84
	v_mul_f32_e32 v89, 0x3d372713, v85
	v_mul_f32_e32 v89, v85, v89
	v_fma_f32 v89, v85, v89, v85
	v_mul_f32_e32 v89, 0x3fcc422a, v89
	v_mul_f32_e32 v89, 0xbfb8aa3b, v89
	v_exp_f32_e32 v89, v89
	v_cvt_pk_bf16_f32 v83, v83, v84
	v_cvt_pk_bf16_f32 v84, v90, v87
	s_nop 0
	v_add_f32_e32 v89, 1.0, v89
	v_rcp_f32_e32 v89, v89
	s_nop 0
	v_mul_f32_e32 v85, v85, v89
	v_cvt_pk_bf16_f32 v85, v88, v85
	global_store_dwordx4 v132, v[82:85], s[8:9] offset:256
	s_or_b32 s8, s26, 48
	s_ashr_i32 s9, s8, 31
	v_cvt_f32_u32_e32 v82, v144
	s_lshl_b64 s[8:9], s[8:9], 11
	s_add_u32 s2, s31, s8
	s_addc_u32 s9, s33, s9
	v_fmamk_f32 v84, v82, 0x30000000, v209
	v_lshlrev_b64 v[82:83], s85, v[146:147]
	v_min_u32_e32 v82, 1, v82
	v_or_b32_e32 v82, v83, v82
	v_cvt_f32_u32_e32 v82, v82
	s_add_u32 s8, s2, s46
	s_addc_u32 s9, s9, s47
	s_waitcnt vmcnt(9)
	v_mov_b32_e32 v146, v143
	v_ldexp_f32 v82, v82, s23
	v_fmac_f32_e32 v84, 2.0, v82
	v_rsq_f32_e32 v82, v84
	s_mov_b32 s2, 0x40000
	v_pk_mul_f32 v[78:79], v[78:79], v[82:83] op_sel_hi:[1,0]
	v_pk_mul_f32 v[80:81], v[80:81], v[82:83] op_sel_hi:[1,0]
	v_pk_mul_f32 v[76:77], v[76:77], v[82:83] op_sel_hi:[1,0]
	v_pk_mul_f32 v[74:75], v[74:75], v[82:83] op_sel_hi:[1,0]
	v_mul_f32_e32 v83, 0x3d372713, v78
	v_mul_f32_e32 v83, v78, v83
	v_fma_f32 v83, v78, v83, v78
	v_mul_f32_e32 v83, 0x3fcc422a, v83
	v_mul_f32_e32 v83, 0xbfb8aa3b, v83
	v_exp_f32_e32 v83, v83
	s_nop 0
	v_add_f32_e32 v83, 1.0, v83
	v_rcp_f32_e32 v83, v83
	s_nop 0
	v_mul_f32_e32 v78, v78, v83
	v_mul_f32_e32 v83, 0x3d372713, v74
	v_mul_f32_e32 v83, v74, v83
	v_fma_f32 v83, v74, v83, v74
	v_mul_f32_e32 v83, 0x3fcc422a, v83
	v_mul_f32_e32 v83, 0xbfb8aa3b, v83
	v_exp_f32_e32 v83, v83
	s_nop 0
	v_add_f32_e32 v83, 1.0, v83
	v_rcp_f32_e32 v83, v83
	s_nop 0
	v_mul_f32_e32 v83, v74, v83
	v_mul_f32_e32 v74, 0x3d372713, v79
	v_mul_f32_e32 v74, v79, v74
	v_fma_f32 v74, v79, v74, v79
	v_mul_f32_e32 v74, 0x3fcc422a, v74
	v_mul_f32_e32 v74, 0xbfb8aa3b, v74
	v_exp_f32_e32 v74, v74
	v_pk_mul_f32 v[70:71], v[70:71], v[82:83] op_sel_hi:[1,0]
	v_pk_mul_f32 v[66:67], v[66:67], v[82:83] op_sel_hi:[1,0]
	v_pk_mul_f32 v[72:73], v[72:73], v[82:83] op_sel_hi:[1,0]
	v_add_f32_e32 v74, 1.0, v74
	v_rcp_f32_e32 v74, v74
	v_pk_mul_f32 v[68:69], v[68:69], v[82:83] op_sel_hi:[1,0]
	v_mul_f32_e32 v74, v79, v74
	v_mul_f32_e32 v79, 0x3d372713, v75
	v_mul_f32_e32 v79, v75, v79
	v_fma_f32 v79, v75, v79, v75
	v_mul_f32_e32 v79, 0x3fcc422a, v79
	v_mul_f32_e32 v79, 0xbfb8aa3b, v79
	v_exp_f32_e32 v79, v79
	v_cvt_pk_bf16_f32 v74, v78, v74
	s_nop 0
	v_add_f32_e32 v79, 1.0, v79
	v_rcp_f32_e32 v79, v79
	s_nop 0
	v_mul_f32_e32 v79, v75, v79
	v_mul_f32_e32 v75, 0x3d372713, v80
	v_mul_f32_e32 v75, v80, v75
	v_fma_f32 v75, v80, v75, v80
	v_mul_f32_e32 v75, 0x3fcc422a, v75
	v_mul_f32_e32 v75, 0xbfb8aa3b, v75
	v_exp_f32_e32 v75, v75
	s_nop 0
	v_add_f32_e32 v75, 1.0, v75
	v_rcp_f32_e32 v75, v75
	s_nop 0
	v_mul_f32_e32 v75, v80, v75
	v_mul_f32_e32 v80, 0x3d372713, v76
	v_mul_f32_e32 v80, v76, v80
	v_fma_f32 v80, v76, v80, v76
	v_mul_f32_e32 v80, 0x3fcc422a, v80
	v_mul_f32_e32 v80, 0xbfb8aa3b, v80
	v_exp_f32_e32 v80, v80
	s_nop 0
	v_add_f32_e32 v80, 1.0, v80
	v_rcp_f32_e32 v80, v80
	s_nop 0
	v_mul_f32_e32 v80, v76, v80
	v_mul_f32_e32 v76, 0x3d372713, v81
	v_mul_f32_e32 v76, v81, v76
	v_fma_f32 v76, v81, v76, v81
	v_mul_f32_e32 v76, 0x3fcc422a, v76
	v_mul_f32_e32 v76, 0xbfb8aa3b, v76
	v_exp_f32_e32 v76, v76
	s_nop 0
	v_add_f32_e32 v76, 1.0, v76
	v_rcp_f32_e32 v76, v76
	s_nop 0
	v_mul_f32_e32 v76, v81, v76
	v_mul_f32_e32 v81, 0x3d372713, v77
	v_mul_f32_e32 v81, v77, v81
	v_fma_f32 v81, v77, v81, v77
	v_mul_f32_e32 v81, 0x3fcc422a, v81
	v_mul_f32_e32 v81, 0xbfb8aa3b, v81
	v_exp_f32_e32 v81, v81
	v_cvt_pk_bf16_f32 v75, v75, v76
	v_cvt_pk_bf16_f32 v76, v83, v79
	s_nop 0
	v_add_f32_e32 v81, 1.0, v81
	v_rcp_f32_e32 v81, v81
	s_nop 0
	v_mul_f32_e32 v77, v77, v81
	v_cvt_pk_bf16_f32 v77, v80, v77
	global_store_dwordx4 v132, v[74:77], s[8:9]
	s_nop 1
	v_mul_f32_e32 v74, 0x3d372713, v70
	v_mul_f32_e32 v74, v70, v74
	v_fma_f32 v74, v70, v74, v70
	v_mul_f32_e32 v74, 0x3fcc422a, v74
	v_mul_f32_e32 v74, 0xbfb8aa3b, v74
	v_exp_f32_e32 v74, v74
	s_nop 0
	v_add_f32_e32 v74, 1.0, v74
	v_rcp_f32_e32 v74, v74
	s_nop 0
	v_mul_f32_e32 v70, v70, v74
	v_mul_f32_e32 v74, 0x3d372713, v66
	v_mul_f32_e32 v74, v66, v74
	v_fma_f32 v74, v66, v74, v66
	v_mul_f32_e32 v74, 0x3fcc422a, v74
	v_mul_f32_e32 v74, 0xbfb8aa3b, v74
	v_exp_f32_e32 v74, v74
	s_nop 0
	v_add_f32_e32 v74, 1.0, v74
	v_rcp_f32_e32 v74, v74
	s_nop 0
	v_mul_f32_e32 v74, v66, v74
	v_mul_f32_e32 v66, 0x3d372713, v71
	v_mul_f32_e32 v66, v71, v66
	v_fma_f32 v66, v71, v66, v71
	v_mul_f32_e32 v66, 0x3fcc422a, v66
	v_mul_f32_e32 v66, 0xbfb8aa3b, v66
	v_exp_f32_e32 v66, v66
	s_nop 0
	v_add_f32_e32 v66, 1.0, v66
	v_rcp_f32_e32 v66, v66
	s_nop 0
	v_mul_f32_e32 v66, v71, v66
	v_mul_f32_e32 v71, 0x3d372713, v67
	v_mul_f32_e32 v71, v67, v71
	v_fma_f32 v71, v67, v71, v67
	v_mul_f32_e32 v71, 0x3fcc422a, v71
	v_mul_f32_e32 v71, 0xbfb8aa3b, v71
	v_exp_f32_e32 v71, v71
	v_cvt_pk_bf16_f32 v66, v70, v66
	s_nop 0
	v_add_f32_e32 v71, 1.0, v71
	v_rcp_f32_e32 v71, v71
	s_nop 0
	v_mul_f32_e32 v71, v67, v71
	v_mul_f32_e32 v67, 0x3d372713, v72
	v_mul_f32_e32 v67, v72, v67
	v_fma_f32 v67, v72, v67, v72
	v_mul_f32_e32 v67, 0x3fcc422a, v67
	v_mul_f32_e32 v67, 0xbfb8aa3b, v67
	v_exp_f32_e32 v67, v67
	s_nop 0
	v_add_f32_e32 v67, 1.0, v67
	v_rcp_f32_e32 v67, v67
	s_nop 0
	v_mul_f32_e32 v67, v72, v67
	v_mul_f32_e32 v72, 0x3d372713, v68
	v_mul_f32_e32 v72, v68, v72
	v_fma_f32 v72, v68, v72, v68
	v_mul_f32_e32 v72, 0x3fcc422a, v72
	v_mul_f32_e32 v72, 0xbfb8aa3b, v72
	v_exp_f32_e32 v72, v72
	s_nop 0
	v_add_f32_e32 v72, 1.0, v72
	v_rcp_f32_e32 v72, v72
	s_nop 0
	v_mul_f32_e32 v72, v68, v72
	v_mul_f32_e32 v68, 0x3d372713, v73
	v_mul_f32_e32 v68, v73, v68
	v_fma_f32 v68, v73, v68, v73
	v_mul_f32_e32 v68, 0x3fcc422a, v68
	v_mul_f32_e32 v68, 0xbfb8aa3b, v68
	v_exp_f32_e32 v68, v68
	s_nop 0
	v_add_f32_e32 v68, 1.0, v68
	v_rcp_f32_e32 v68, v68
	s_nop 0
	v_mul_f32_e32 v68, v73, v68
	v_mul_f32_e32 v73, 0x3d372713, v69
	v_mul_f32_e32 v73, v69, v73
	v_fma_f32 v73, v69, v73, v69
	v_mul_f32_e32 v73, 0x3fcc422a, v73
	v_mul_f32_e32 v73, 0xbfb8aa3b, v73
	v_exp_f32_e32 v73, v73
	v_cvt_pk_bf16_f32 v67, v67, v68
	v_cvt_pk_bf16_f32 v68, v74, v71
	s_nop 0
	v_add_f32_e32 v73, 1.0, v73
	v_rcp_f32_e32 v73, v73
	s_nop 0
	v_mul_f32_e32 v69, v69, v73
	v_cvt_pk_bf16_f32 v69, v72, v69
	global_store_dwordx4 v132, v[66:69], s[8:9] offset:256
	s_mov_b64 s[8:9], 0x40000
	s_nop 0
	v_cvt_f32_u32_e32 v66, v142
	v_fmamk_f32 v68, v66, 0x30000000, v209
	v_lshlrev_b64 v[66:67], s85, v[146:147]
	v_min_u32_e32 v66, 1, v66
	v_or_b32_e32 v66, v67, v66
	v_cvt_f32_u32_e32 v66, v66
	s_waitcnt vmcnt(10)
	v_mov_b32_e32 v146, v141
	v_ldexp_f32 v66, v66, s23
	v_fmac_f32_e32 v68, 2.0, v66
	v_rsq_f32_e32 v68, v68
	v_lshl_add_u64 v[66:67], v[134:135], 0, s[8:9]
	s_mov_b64 s[8:9], 0x48000
	v_pk_mul_f32 v[62:63], v[62:63], v[68:69] op_sel_hi:[1,0]
	v_pk_mul_f32 v[64:65], v[64:65], v[68:69] op_sel_hi:[1,0]
	v_pk_mul_f32 v[60:61], v[60:61], v[68:69] op_sel_hi:[1,0]
	v_pk_mul_f32 v[58:59], v[58:59], v[68:69] op_sel_hi:[1,0]
	v_mul_f32_e32 v69, 0x3d372713, v62
	v_mul_f32_e32 v69, v62, v69
	v_fma_f32 v69, v62, v69, v62
	v_mul_f32_e32 v69, 0x3fcc422a, v69
	v_mul_f32_e32 v69, 0xbfb8aa3b, v69
	v_exp_f32_e32 v69, v69
	s_nop 0
	v_add_f32_e32 v69, 1.0, v69
	v_rcp_f32_e32 v69, v69
	s_nop 0
	v_mul_f32_e32 v62, v62, v69
	v_mul_f32_e32 v69, 0x3d372713, v58
	v_mul_f32_e32 v69, v58, v69
	v_fma_f32 v69, v58, v69, v58
	v_mul_f32_e32 v69, 0x3fcc422a, v69
	v_mul_f32_e32 v69, 0xbfb8aa3b, v69
	v_exp_f32_e32 v69, v69
	s_nop 0
	v_add_f32_e32 v69, 1.0, v69
	v_rcp_f32_e32 v69, v69
	s_nop 0
	v_mul_f32_e32 v69, v58, v69
	v_mul_f32_e32 v58, 0x3d372713, v63
	v_mul_f32_e32 v58, v63, v58
	v_fma_f32 v58, v63, v58, v63
	v_mul_f32_e32 v58, 0x3fcc422a, v58
	v_mul_f32_e32 v58, 0xbfb8aa3b, v58
	v_exp_f32_e32 v58, v58
	v_pk_mul_f32 v[54:55], v[54:55], v[68:69] op_sel_hi:[1,0]
	v_pk_mul_f32 v[50:51], v[50:51], v[68:69] op_sel_hi:[1,0]
	v_pk_mul_f32 v[56:57], v[56:57], v[68:69] op_sel_hi:[1,0]
	v_add_f32_e32 v58, 1.0, v58
	v_rcp_f32_e32 v58, v58
	v_pk_mul_f32 v[52:53], v[52:53], v[68:69] op_sel_hi:[1,0]
	v_mul_f32_e32 v58, v63, v58
	v_mul_f32_e32 v63, 0x3d372713, v59
	v_mul_f32_e32 v63, v59, v63
	v_fma_f32 v63, v59, v63, v59
	v_mul_f32_e32 v63, 0x3fcc422a, v63
	v_mul_f32_e32 v63, 0xbfb8aa3b, v63
	v_exp_f32_e32 v63, v63
	v_cvt_pk_bf16_f32 v58, v62, v58
	v_add_co_u32_e32 v62, vcc, s2, v134
	v_add_f32_e32 v63, 1.0, v63
	v_rcp_f32_e32 v63, v63
	s_mov_b32 s2, 0x48000
	v_mul_f32_e32 v63, v59, v63
	v_mul_f32_e32 v59, 0x3d372713, v64
	v_mul_f32_e32 v59, v64, v59
	v_fma_f32 v59, v64, v59, v64
	v_mul_f32_e32 v59, 0x3fcc422a, v59
	v_mul_f32_e32 v59, 0xbfb8aa3b, v59
	v_exp_f32_e32 v59, v59
	s_nop 0
	v_add_f32_e32 v59, 1.0, v59
	v_rcp_f32_e32 v59, v59
	s_nop 0
	v_mul_f32_e32 v59, v64, v59
	v_mul_f32_e32 v64, 0x3d372713, v60
	v_mul_f32_e32 v64, v60, v64
	v_fma_f32 v64, v60, v64, v60
	v_mul_f32_e32 v64, 0x3fcc422a, v64
	v_mul_f32_e32 v64, 0xbfb8aa3b, v64
	v_exp_f32_e32 v64, v64
	s_nop 0
	v_add_f32_e32 v64, 1.0, v64
	v_rcp_f32_e32 v64, v64
	s_nop 0
	v_mul_f32_e32 v64, v60, v64
	v_mul_f32_e32 v60, 0x3d372713, v65
	v_mul_f32_e32 v60, v65, v60
	v_fma_f32 v60, v65, v60, v65
	v_mul_f32_e32 v60, 0x3fcc422a, v60
	v_mul_f32_e32 v60, 0xbfb8aa3b, v60
	v_exp_f32_e32 v60, v60
	s_nop 0
	v_add_f32_e32 v60, 1.0, v60
	v_rcp_f32_e32 v60, v60
	s_nop 0
	v_mul_f32_e32 v60, v65, v60
	v_mul_f32_e32 v65, 0x3d372713, v61
	v_mul_f32_e32 v65, v61, v65
	v_fma_f32 v65, v61, v65, v61
	v_mul_f32_e32 v65, 0x3fcc422a, v65
	v_mul_f32_e32 v65, 0xbfb8aa3b, v65
	v_exp_f32_e32 v65, v65
	v_cvt_pk_bf16_f32 v59, v59, v60
	v_cvt_pk_bf16_f32 v60, v69, v63
	v_addc_co_u32_e32 v63, vcc, 0, v135, vcc
	v_add_f32_e32 v65, 1.0, v65
	v_rcp_f32_e32 v65, v65
	s_nop 0
	v_mul_f32_e32 v61, v61, v65
	v_cvt_pk_bf16_f32 v61, v64, v61
	global_store_dwordx4 v[62:63], v[58:61], off
	s_nop 1
	v_mul_f32_e32 v58, 0x3d372713, v54
	v_mul_f32_e32 v58, v54, v58
	v_fma_f32 v58, v54, v58, v54
	v_mul_f32_e32 v58, 0x3fcc422a, v58
	v_mul_f32_e32 v58, 0xbfb8aa3b, v58
	v_exp_f32_e32 v58, v58
	s_nop 0
	v_add_f32_e32 v58, 1.0, v58
	v_rcp_f32_e32 v58, v58
	s_nop 0
	v_mul_f32_e32 v54, v54, v58
	v_mul_f32_e32 v58, 0x3d372713, v50
	v_mul_f32_e32 v58, v50, v58
	v_fma_f32 v58, v50, v58, v50
	v_mul_f32_e32 v58, 0x3fcc422a, v58
	v_mul_f32_e32 v58, 0xbfb8aa3b, v58
	v_exp_f32_e32 v58, v58
	s_nop 0
	v_add_f32_e32 v58, 1.0, v58
	v_rcp_f32_e32 v58, v58
	s_nop 0
	v_mul_f32_e32 v58, v50, v58
	v_mul_f32_e32 v50, 0x3d372713, v55
	v_mul_f32_e32 v50, v55, v50
	v_fma_f32 v50, v55, v50, v55
	v_mul_f32_e32 v50, 0x3fcc422a, v50
	v_mul_f32_e32 v50, 0xbfb8aa3b, v50
	v_exp_f32_e32 v50, v50
	s_nop 0
	v_add_f32_e32 v50, 1.0, v50
	v_rcp_f32_e32 v50, v50
	s_nop 0
	v_mul_f32_e32 v50, v55, v50
	v_mul_f32_e32 v55, 0x3d372713, v51
	v_mul_f32_e32 v55, v51, v55
	v_fma_f32 v55, v51, v55, v51
	v_mul_f32_e32 v55, 0x3fcc422a, v55
	v_mul_f32_e32 v55, 0xbfb8aa3b, v55
	v_exp_f32_e32 v55, v55
	v_cvt_pk_bf16_f32 v50, v54, v50
	s_nop 0
	v_add_f32_e32 v55, 1.0, v55
	v_rcp_f32_e32 v55, v55
	s_nop 0
	v_mul_f32_e32 v55, v51, v55
	v_mul_f32_e32 v51, 0x3d372713, v56
	v_mul_f32_e32 v51, v56, v51
	v_fma_f32 v51, v56, v51, v56
	v_mul_f32_e32 v51, 0x3fcc422a, v51
	v_mul_f32_e32 v51, 0xbfb8aa3b, v51
	v_exp_f32_e32 v51, v51
	s_nop 0
	v_add_f32_e32 v51, 1.0, v51
	v_rcp_f32_e32 v51, v51
	s_nop 0
	v_mul_f32_e32 v51, v56, v51
	v_mul_f32_e32 v56, 0x3d372713, v52
	v_mul_f32_e32 v56, v52, v56
	v_fma_f32 v56, v52, v56, v52
	v_mul_f32_e32 v56, 0x3fcc422a, v56
	v_mul_f32_e32 v56, 0xbfb8aa3b, v56
	v_exp_f32_e32 v56, v56
	s_nop 0
	v_add_f32_e32 v56, 1.0, v56
	v_rcp_f32_e32 v56, v56
	s_nop 0
	v_mul_f32_e32 v56, v52, v56
	v_mul_f32_e32 v52, 0x3d372713, v57
	v_mul_f32_e32 v52, v57, v52
	v_fma_f32 v52, v57, v52, v57
	v_mul_f32_e32 v52, 0x3fcc422a, v52
	v_mul_f32_e32 v52, 0xbfb8aa3b, v52
	v_exp_f32_e32 v52, v52
	s_nop 0
	v_add_f32_e32 v52, 1.0, v52
	v_rcp_f32_e32 v52, v52
	s_nop 0
	v_mul_f32_e32 v52, v57, v52
	v_mul_f32_e32 v57, 0x3d372713, v53
	v_mul_f32_e32 v57, v53, v57
	v_fma_f32 v57, v53, v57, v53
	v_mul_f32_e32 v57, 0x3fcc422a, v57
	v_mul_f32_e32 v57, 0xbfb8aa3b, v57
	v_exp_f32_e32 v57, v57
	v_cvt_pk_bf16_f32 v51, v51, v52
	v_cvt_pk_bf16_f32 v52, v58, v55
	s_nop 0
	v_add_f32_e32 v57, 1.0, v57
	v_rcp_f32_e32 v57, v57
	s_nop 0
	v_mul_f32_e32 v53, v53, v57
	v_cvt_pk_bf16_f32 v53, v56, v53
	global_store_dwordx4 v[66:67], v[50:53], off offset:256
	s_nop 1
	v_cvt_f32_u32_e32 v50, v140
	v_fmamk_f32 v52, v50, 0x30000000, v209
	v_lshlrev_b64 v[50:51], s85, v[146:147]
	v_min_u32_e32 v50, 1, v50
	v_or_b32_e32 v50, v51, v50
	v_cvt_f32_u32_e32 v50, v50
	s_waitcnt vmcnt(11)
	v_mov_b32_e32 v146, v139
	v_ldexp_f32 v50, v50, s23
	v_fmac_f32_e32 v52, 2.0, v50
	v_rsq_f32_e32 v52, v52
	v_lshl_add_u64 v[50:51], v[134:135], 0, s[8:9]
	s_mov_b64 s[8:9], 0x50000
	v_pk_mul_f32 v[46:47], v[46:47], v[52:53] op_sel_hi:[1,0]
	v_pk_mul_f32 v[48:49], v[48:49], v[52:53] op_sel_hi:[1,0]
	v_pk_mul_f32 v[44:45], v[44:45], v[52:53] op_sel_hi:[1,0]
	v_pk_mul_f32 v[42:43], v[42:43], v[52:53] op_sel_hi:[1,0]
	v_mul_f32_e32 v53, 0x3d372713, v46
	v_mul_f32_e32 v53, v46, v53
	v_fma_f32 v53, v46, v53, v46
	v_mul_f32_e32 v53, 0x3fcc422a, v53
	v_mul_f32_e32 v53, 0xbfb8aa3b, v53
	v_exp_f32_e32 v53, v53
	s_nop 0
	v_add_f32_e32 v53, 1.0, v53
	v_rcp_f32_e32 v53, v53
	s_nop 0
	v_mul_f32_e32 v46, v46, v53
	v_mul_f32_e32 v53, 0x3d372713, v42
	v_mul_f32_e32 v53, v42, v53
	v_fma_f32 v53, v42, v53, v42
	v_mul_f32_e32 v53, 0x3fcc422a, v53
	v_mul_f32_e32 v53, 0xbfb8aa3b, v53
	v_exp_f32_e32 v53, v53
	s_nop 0
	v_add_f32_e32 v53, 1.0, v53
	v_rcp_f32_e32 v53, v53
	s_nop 0
	v_mul_f32_e32 v53, v42, v53
	v_mul_f32_e32 v42, 0x3d372713, v47
	v_mul_f32_e32 v42, v47, v42
	v_fma_f32 v42, v47, v42, v47
	v_mul_f32_e32 v42, 0x3fcc422a, v42
	v_mul_f32_e32 v42, 0xbfb8aa3b, v42
	v_exp_f32_e32 v42, v42
	v_pk_mul_f32 v[38:39], v[38:39], v[52:53] op_sel_hi:[1,0]
	v_pk_mul_f32 v[34:35], v[34:35], v[52:53] op_sel_hi:[1,0]
	v_pk_mul_f32 v[40:41], v[40:41], v[52:53] op_sel_hi:[1,0]
	v_add_f32_e32 v42, 1.0, v42
	v_rcp_f32_e32 v42, v42
	v_pk_mul_f32 v[36:37], v[36:37], v[52:53] op_sel_hi:[1,0]
	v_mul_f32_e32 v42, v47, v42
	v_mul_f32_e32 v47, 0x3d372713, v43
	v_mul_f32_e32 v47, v43, v47
	v_fma_f32 v47, v43, v47, v43
	v_mul_f32_e32 v47, 0x3fcc422a, v47
	v_mul_f32_e32 v47, 0xbfb8aa3b, v47
	v_exp_f32_e32 v47, v47
	v_cvt_pk_bf16_f32 v42, v46, v42
	v_add_co_u32_e32 v46, vcc, s2, v134
	v_add_f32_e32 v47, 1.0, v47
	v_rcp_f32_e32 v47, v47
	s_mov_b32 s2, 0x50000
	v_mul_f32_e32 v47, v43, v47
	v_mul_f32_e32 v43, 0x3d372713, v48
	v_mul_f32_e32 v43, v48, v43
	v_fma_f32 v43, v48, v43, v48
	v_mul_f32_e32 v43, 0x3fcc422a, v43
	v_mul_f32_e32 v43, 0xbfb8aa3b, v43
	v_exp_f32_e32 v43, v43
	s_nop 0
	v_add_f32_e32 v43, 1.0, v43
	v_rcp_f32_e32 v43, v43
	s_nop 0
	v_mul_f32_e32 v43, v48, v43
	v_mul_f32_e32 v48, 0x3d372713, v44
	v_mul_f32_e32 v48, v44, v48
	v_fma_f32 v48, v44, v48, v44
	v_mul_f32_e32 v48, 0x3fcc422a, v48
	v_mul_f32_e32 v48, 0xbfb8aa3b, v48
	v_exp_f32_e32 v48, v48
	s_nop 0
	v_add_f32_e32 v48, 1.0, v48
	v_rcp_f32_e32 v48, v48
	s_nop 0
	v_mul_f32_e32 v48, v44, v48
	v_mul_f32_e32 v44, 0x3d372713, v49
	v_mul_f32_e32 v44, v49, v44
	v_fma_f32 v44, v49, v44, v49
	v_mul_f32_e32 v44, 0x3fcc422a, v44
	v_mul_f32_e32 v44, 0xbfb8aa3b, v44
	v_exp_f32_e32 v44, v44
	s_nop 0
	v_add_f32_e32 v44, 1.0, v44
	v_rcp_f32_e32 v44, v44
	s_nop 0
	v_mul_f32_e32 v44, v49, v44
	v_mul_f32_e32 v49, 0x3d372713, v45
	v_mul_f32_e32 v49, v45, v49
	v_fma_f32 v49, v45, v49, v45
	v_mul_f32_e32 v49, 0x3fcc422a, v49
	v_mul_f32_e32 v49, 0xbfb8aa3b, v49
	v_exp_f32_e32 v49, v49
	v_cvt_pk_bf16_f32 v43, v43, v44
	v_cvt_pk_bf16_f32 v44, v53, v47
	v_addc_co_u32_e32 v47, vcc, 0, v135, vcc
	v_add_f32_e32 v49, 1.0, v49
	v_rcp_f32_e32 v49, v49
	s_nop 0
	v_mul_f32_e32 v45, v45, v49
	v_cvt_pk_bf16_f32 v45, v48, v45
	global_store_dwordx4 v[46:47], v[42:45], off
	s_nop 1
	v_mul_f32_e32 v42, 0x3d372713, v38
	v_mul_f32_e32 v42, v38, v42
	v_fma_f32 v42, v38, v42, v38
	v_mul_f32_e32 v42, 0x3fcc422a, v42
	v_mul_f32_e32 v42, 0xbfb8aa3b, v42
	v_exp_f32_e32 v42, v42
	s_nop 0
	v_add_f32_e32 v42, 1.0, v42
	v_rcp_f32_e32 v42, v42
	s_nop 0
	v_mul_f32_e32 v38, v38, v42
	v_mul_f32_e32 v42, 0x3d372713, v34
	v_mul_f32_e32 v42, v34, v42
	v_fma_f32 v42, v34, v42, v34
	v_mul_f32_e32 v42, 0x3fcc422a, v42
	v_mul_f32_e32 v42, 0xbfb8aa3b, v42
	v_exp_f32_e32 v42, v42
	s_nop 0
	v_add_f32_e32 v42, 1.0, v42
	v_rcp_f32_e32 v42, v42
	s_nop 0
	v_mul_f32_e32 v42, v34, v42
	v_mul_f32_e32 v34, 0x3d372713, v39
	v_mul_f32_e32 v34, v39, v34
	v_fma_f32 v34, v39, v34, v39
	v_mul_f32_e32 v34, 0x3fcc422a, v34
	v_mul_f32_e32 v34, 0xbfb8aa3b, v34
	v_exp_f32_e32 v34, v34
	s_nop 0
	v_add_f32_e32 v34, 1.0, v34
	v_rcp_f32_e32 v34, v34
	s_nop 0
	v_mul_f32_e32 v34, v39, v34
	v_mul_f32_e32 v39, 0x3d372713, v35
	v_mul_f32_e32 v39, v35, v39
	v_fma_f32 v39, v35, v39, v35
	v_mul_f32_e32 v39, 0x3fcc422a, v39
	v_mul_f32_e32 v39, 0xbfb8aa3b, v39
	v_exp_f32_e32 v39, v39
	v_cvt_pk_bf16_f32 v34, v38, v34
	s_nop 0
	v_add_f32_e32 v39, 1.0, v39
	v_rcp_f32_e32 v39, v39
	s_nop 0
	v_mul_f32_e32 v39, v35, v39
	v_mul_f32_e32 v35, 0x3d372713, v40
	v_mul_f32_e32 v35, v40, v35
	v_fma_f32 v35, v40, v35, v40
	v_mul_f32_e32 v35, 0x3fcc422a, v35
	v_mul_f32_e32 v35, 0xbfb8aa3b, v35
	v_exp_f32_e32 v35, v35
	s_nop 0
	v_add_f32_e32 v35, 1.0, v35
	v_rcp_f32_e32 v35, v35
	s_nop 0
	v_mul_f32_e32 v35, v40, v35
	v_mul_f32_e32 v40, 0x3d372713, v36
	v_mul_f32_e32 v40, v36, v40
	v_fma_f32 v40, v36, v40, v36
	v_mul_f32_e32 v40, 0x3fcc422a, v40
	v_mul_f32_e32 v40, 0xbfb8aa3b, v40
	v_exp_f32_e32 v40, v40
	s_nop 0
	v_add_f32_e32 v40, 1.0, v40
	v_rcp_f32_e32 v40, v40
	s_nop 0
	v_mul_f32_e32 v40, v36, v40
	v_mul_f32_e32 v36, 0x3d372713, v41
	v_mul_f32_e32 v36, v41, v36
	v_fma_f32 v36, v41, v36, v41
	v_mul_f32_e32 v36, 0x3fcc422a, v36
	v_mul_f32_e32 v36, 0xbfb8aa3b, v36
	v_exp_f32_e32 v36, v36
	s_nop 0
	v_add_f32_e32 v36, 1.0, v36
	v_rcp_f32_e32 v36, v36
	s_nop 0
	v_mul_f32_e32 v36, v41, v36
	v_mul_f32_e32 v41, 0x3d372713, v37
	v_mul_f32_e32 v41, v37, v41
	v_fma_f32 v41, v37, v41, v37
	v_mul_f32_e32 v41, 0x3fcc422a, v41
	v_mul_f32_e32 v41, 0xbfb8aa3b, v41
	v_exp_f32_e32 v41, v41
	v_cvt_pk_bf16_f32 v35, v35, v36
	v_cvt_pk_bf16_f32 v36, v42, v39
	s_nop 0
	v_add_f32_e32 v41, 1.0, v41
	v_rcp_f32_e32 v41, v41
	s_nop 0
	v_mul_f32_e32 v37, v37, v41
	v_cvt_pk_bf16_f32 v37, v40, v37
	global_store_dwordx4 v[50:51], v[34:37], off offset:256
	s_nop 1
	v_cvt_f32_u32_e32 v34, v138
	v_fmamk_f32 v36, v34, 0x30000000, v209
	v_lshlrev_b64 v[34:35], s85, v[146:147]
	v_min_u32_e32 v34, 1, v34
	v_or_b32_e32 v34, v35, v34
	v_cvt_f32_u32_e32 v34, v34
	s_waitcnt vmcnt(12)
	v_mov_b32_e32 v146, v137
	v_ldexp_f32 v34, v34, s23
	v_fmac_f32_e32 v36, 2.0, v34
	v_rsq_f32_e32 v36, v36
	v_lshl_add_u64 v[34:35], v[134:135], 0, s[8:9]
	s_mov_b64 s[8:9], 0x58000
	v_pk_mul_f32 v[30:31], v[30:31], v[36:37] op_sel_hi:[1,0]
	v_pk_mul_f32 v[32:33], v[32:33], v[36:37] op_sel_hi:[1,0]
	v_pk_mul_f32 v[28:29], v[28:29], v[36:37] op_sel_hi:[1,0]
	v_pk_mul_f32 v[26:27], v[26:27], v[36:37] op_sel_hi:[1,0]
	v_mul_f32_e32 v37, 0x3d372713, v30
	v_mul_f32_e32 v37, v30, v37
	v_fma_f32 v37, v30, v37, v30
	v_mul_f32_e32 v37, 0x3fcc422a, v37
	v_mul_f32_e32 v37, 0xbfb8aa3b, v37
	v_exp_f32_e32 v37, v37
	s_nop 0
	v_add_f32_e32 v37, 1.0, v37
	v_rcp_f32_e32 v37, v37
	s_nop 0
	v_mul_f32_e32 v30, v30, v37
	v_mul_f32_e32 v37, 0x3d372713, v26
	v_mul_f32_e32 v37, v26, v37
	v_fma_f32 v37, v26, v37, v26
	v_mul_f32_e32 v37, 0x3fcc422a, v37
	v_mul_f32_e32 v37, 0xbfb8aa3b, v37
	v_exp_f32_e32 v37, v37
	s_nop 0
	v_add_f32_e32 v37, 1.0, v37
	v_rcp_f32_e32 v37, v37
	s_nop 0
	v_mul_f32_e32 v37, v26, v37
	v_mul_f32_e32 v26, 0x3d372713, v31
	v_mul_f32_e32 v26, v31, v26
	v_fma_f32 v26, v31, v26, v31
	v_mul_f32_e32 v26, 0x3fcc422a, v26
	v_mul_f32_e32 v26, 0xbfb8aa3b, v26
	v_exp_f32_e32 v26, v26
	v_pk_mul_f32 v[22:23], v[22:23], v[36:37] op_sel_hi:[1,0]
	v_pk_mul_f32 v[18:19], v[18:19], v[36:37] op_sel_hi:[1,0]
	v_pk_mul_f32 v[24:25], v[24:25], v[36:37] op_sel_hi:[1,0]
	v_add_f32_e32 v26, 1.0, v26
	v_rcp_f32_e32 v26, v26
	v_pk_mul_f32 v[20:21], v[20:21], v[36:37] op_sel_hi:[1,0]
	v_mul_f32_e32 v26, v31, v26
	v_mul_f32_e32 v31, 0x3d372713, v27
	v_mul_f32_e32 v31, v27, v31
	v_fma_f32 v31, v27, v31, v27
	v_mul_f32_e32 v31, 0x3fcc422a, v31
	v_mul_f32_e32 v31, 0xbfb8aa3b, v31
	v_exp_f32_e32 v31, v31
	v_cvt_pk_bf16_f32 v26, v30, v26
	v_add_co_u32_e32 v30, vcc, s2, v134
	v_add_f32_e32 v31, 1.0, v31
	v_rcp_f32_e32 v31, v31
	s_mov_b32 s2, 0x58000
	v_mul_f32_e32 v31, v27, v31
	v_mul_f32_e32 v27, 0x3d372713, v32
	v_mul_f32_e32 v27, v32, v27
	v_fma_f32 v27, v32, v27, v32
	v_mul_f32_e32 v27, 0x3fcc422a, v27
	v_mul_f32_e32 v27, 0xbfb8aa3b, v27
	v_exp_f32_e32 v27, v27
	s_nop 0
	v_add_f32_e32 v27, 1.0, v27
	v_rcp_f32_e32 v27, v27
	s_nop 0
	v_mul_f32_e32 v27, v32, v27
	v_mul_f32_e32 v32, 0x3d372713, v28
	v_mul_f32_e32 v32, v28, v32
	v_fma_f32 v32, v28, v32, v28
	v_mul_f32_e32 v32, 0x3fcc422a, v32
	v_mul_f32_e32 v32, 0xbfb8aa3b, v32
	v_exp_f32_e32 v32, v32
	s_nop 0
	v_add_f32_e32 v32, 1.0, v32
	v_rcp_f32_e32 v32, v32
	s_nop 0
	v_mul_f32_e32 v32, v28, v32
	v_mul_f32_e32 v28, 0x3d372713, v33
	v_mul_f32_e32 v28, v33, v28
	v_fma_f32 v28, v33, v28, v33
	v_mul_f32_e32 v28, 0x3fcc422a, v28
	v_mul_f32_e32 v28, 0xbfb8aa3b, v28
	v_exp_f32_e32 v28, v28
	s_nop 0
	v_add_f32_e32 v28, 1.0, v28
	v_rcp_f32_e32 v28, v28
	s_nop 0
	v_mul_f32_e32 v28, v33, v28
	v_mul_f32_e32 v33, 0x3d372713, v29
	v_mul_f32_e32 v33, v29, v33
	v_fma_f32 v33, v29, v33, v29
	v_mul_f32_e32 v33, 0x3fcc422a, v33
	v_mul_f32_e32 v33, 0xbfb8aa3b, v33
	v_exp_f32_e32 v33, v33
	v_cvt_pk_bf16_f32 v27, v27, v28
	v_cvt_pk_bf16_f32 v28, v37, v31
	v_addc_co_u32_e32 v31, vcc, 0, v135, vcc
	v_add_f32_e32 v33, 1.0, v33
	v_rcp_f32_e32 v33, v33
	s_nop 0
	v_mul_f32_e32 v29, v29, v33
	v_cvt_pk_bf16_f32 v29, v32, v29
	global_store_dwordx4 v[30:31], v[26:29], off
	s_nop 1
	v_mul_f32_e32 v26, 0x3d372713, v22
	v_mul_f32_e32 v26, v22, v26
	v_fma_f32 v26, v22, v26, v22
	v_mul_f32_e32 v26, 0x3fcc422a, v26
	v_mul_f32_e32 v26, 0xbfb8aa3b, v26
	v_exp_f32_e32 v26, v26
	s_nop 0
	v_add_f32_e32 v26, 1.0, v26
	v_rcp_f32_e32 v26, v26
	s_nop 0
	v_mul_f32_e32 v22, v22, v26
	v_mul_f32_e32 v26, 0x3d372713, v18
	v_mul_f32_e32 v26, v18, v26
	v_fma_f32 v26, v18, v26, v18
	v_mul_f32_e32 v26, 0x3fcc422a, v26
	v_mul_f32_e32 v26, 0xbfb8aa3b, v26
	v_exp_f32_e32 v26, v26
	s_nop 0
	v_add_f32_e32 v26, 1.0, v26
	v_rcp_f32_e32 v26, v26
	s_nop 0
	v_mul_f32_e32 v26, v18, v26
	v_mul_f32_e32 v18, 0x3d372713, v23
	v_mul_f32_e32 v18, v23, v18
	v_fma_f32 v18, v23, v18, v23
	v_mul_f32_e32 v18, 0x3fcc422a, v18
	v_mul_f32_e32 v18, 0xbfb8aa3b, v18
	v_exp_f32_e32 v18, v18
	s_nop 0
	v_add_f32_e32 v18, 1.0, v18
	v_rcp_f32_e32 v18, v18
	s_nop 0
	v_mul_f32_e32 v18, v23, v18
	v_mul_f32_e32 v23, 0x3d372713, v19
	v_mul_f32_e32 v23, v19, v23
	v_fma_f32 v23, v19, v23, v19
	v_mul_f32_e32 v23, 0x3fcc422a, v23
	v_mul_f32_e32 v23, 0xbfb8aa3b, v23
	v_exp_f32_e32 v23, v23
	v_cvt_pk_bf16_f32 v18, v22, v18
	s_nop 0
	v_add_f32_e32 v23, 1.0, v23
	v_rcp_f32_e32 v23, v23
	s_nop 0
	v_mul_f32_e32 v23, v19, v23
	v_mul_f32_e32 v19, 0x3d372713, v24
	v_mul_f32_e32 v19, v24, v19
	v_fma_f32 v19, v24, v19, v24
	v_mul_f32_e32 v19, 0x3fcc422a, v19
	v_mul_f32_e32 v19, 0xbfb8aa3b, v19
	v_exp_f32_e32 v19, v19
	s_nop 0
	v_add_f32_e32 v19, 1.0, v19
	v_rcp_f32_e32 v19, v19
	s_nop 0
	v_mul_f32_e32 v19, v24, v19
	v_mul_f32_e32 v24, 0x3d372713, v20
	v_mul_f32_e32 v24, v20, v24
	v_fma_f32 v24, v20, v24, v20
	v_mul_f32_e32 v24, 0x3fcc422a, v24
	v_mul_f32_e32 v24, 0xbfb8aa3b, v24
	v_exp_f32_e32 v24, v24
	s_nop 0
	v_add_f32_e32 v24, 1.0, v24
	v_rcp_f32_e32 v24, v24
	s_nop 0
	v_mul_f32_e32 v24, v20, v24
	v_mul_f32_e32 v20, 0x3d372713, v25
	v_mul_f32_e32 v20, v25, v20
	v_fma_f32 v20, v25, v20, v25
	v_mul_f32_e32 v20, 0x3fcc422a, v20
	v_mul_f32_e32 v20, 0xbfb8aa3b, v20
	v_exp_f32_e32 v20, v20
	s_nop 0
	v_add_f32_e32 v20, 1.0, v20
	v_rcp_f32_e32 v20, v20
	s_nop 0
	v_mul_f32_e32 v20, v25, v20
	v_mul_f32_e32 v25, 0x3d372713, v21
	v_mul_f32_e32 v25, v21, v25
	v_fma_f32 v25, v21, v25, v21
	v_mul_f32_e32 v25, 0x3fcc422a, v25
	v_mul_f32_e32 v25, 0xbfb8aa3b, v25
	v_exp_f32_e32 v25, v25
	v_cvt_pk_bf16_f32 v19, v19, v20
	v_cvt_pk_bf16_f32 v20, v26, v23
	s_nop 0
	v_add_f32_e32 v25, 1.0, v25
	v_rcp_f32_e32 v25, v25
	s_nop 0
	v_mul_f32_e32 v21, v21, v25
	v_cvt_pk_bf16_f32 v21, v24, v21
	global_store_dwordx4 v[34:35], v[18:21], off offset:256
	s_nop 1
	v_cvt_f32_u32_e32 v18, v136
	v_fmamk_f32 v20, v18, 0x30000000, v209
	v_lshlrev_b64 v[18:19], s85, v[146:147]
	v_min_u32_e32 v18, 1, v18
	v_or_b32_e32 v18, v19, v18
	v_cvt_f32_u32_e32 v18, v18
	v_ldexp_f32 v18, v18, s23
	v_fmac_f32_e32 v20, 2.0, v18
	v_rsq_f32_e32 v20, v20
	v_lshl_add_u64 v[18:19], v[134:135], 0, s[8:9]
	s_mov_b64 s[8:9], -1
	v_pk_mul_f32 v[14:15], v[14:15], v[20:21] op_sel_hi:[1,0]
	v_pk_mul_f32 v[16:17], v[16:17], v[20:21] op_sel_hi:[1,0]
	v_pk_mul_f32 v[12:13], v[12:13], v[20:21] op_sel_hi:[1,0]
	v_pk_mul_f32 v[10:11], v[10:11], v[20:21] op_sel_hi:[1,0]
	v_mul_f32_e32 v21, 0x3d372713, v14
	v_mul_f32_e32 v21, v14, v21
	v_fma_f32 v21, v14, v21, v14
	v_mul_f32_e32 v21, 0x3fcc422a, v21
	v_mul_f32_e32 v21, 0xbfb8aa3b, v21
	v_exp_f32_e32 v21, v21
	s_nop 0
	v_add_f32_e32 v21, 1.0, v21
	v_rcp_f32_e32 v21, v21
	s_nop 0
	v_mul_f32_e32 v14, v14, v21
	v_mul_f32_e32 v21, 0x3d372713, v10
	v_mul_f32_e32 v21, v10, v21
	v_fma_f32 v21, v10, v21, v10
	v_mul_f32_e32 v21, 0x3fcc422a, v21
	v_mul_f32_e32 v21, 0xbfb8aa3b, v21
	v_exp_f32_e32 v21, v21
	s_nop 0
	v_add_f32_e32 v21, 1.0, v21
	v_rcp_f32_e32 v21, v21
	s_nop 0
	v_mul_f32_e32 v21, v10, v21
	v_mul_f32_e32 v10, 0x3d372713, v15
	v_mul_f32_e32 v10, v15, v10
	v_fma_f32 v10, v15, v10, v15
	v_mul_f32_e32 v10, 0x3fcc422a, v10
	v_mul_f32_e32 v10, 0xbfb8aa3b, v10
	v_exp_f32_e32 v10, v10
	v_pk_mul_f32 v[6:7], v[6:7], v[20:21] op_sel_hi:[1,0]
	v_pk_mul_f32 v[2:3], v[2:3], v[20:21] op_sel_hi:[1,0]
	v_pk_mul_f32 v[8:9], v[8:9], v[20:21] op_sel_hi:[1,0]
	v_add_f32_e32 v10, 1.0, v10
	v_rcp_f32_e32 v10, v10
	v_pk_mul_f32 v[4:5], v[4:5], v[20:21] op_sel_hi:[1,0]
	v_mul_f32_e32 v10, v15, v10
	v_mul_f32_e32 v15, 0x3d372713, v11
	v_mul_f32_e32 v15, v11, v15
	v_fma_f32 v15, v11, v15, v11
	v_mul_f32_e32 v15, 0x3fcc422a, v15
	v_mul_f32_e32 v15, 0xbfb8aa3b, v15
	v_exp_f32_e32 v15, v15
	v_cvt_pk_bf16_f32 v10, v14, v10
	v_add_co_u32_e32 v14, vcc, s2, v134
	v_add_f32_e32 v15, 1.0, v15
	v_rcp_f32_e32 v15, v15
	s_nop 0
	v_mul_f32_e32 v15, v11, v15
	v_mul_f32_e32 v11, 0x3d372713, v16
	v_mul_f32_e32 v11, v16, v11
	v_fma_f32 v11, v16, v11, v16
	v_mul_f32_e32 v11, 0x3fcc422a, v11
	v_mul_f32_e32 v11, 0xbfb8aa3b, v11
	v_exp_f32_e32 v11, v11
	s_nop 0
	v_add_f32_e32 v11, 1.0, v11
	v_rcp_f32_e32 v11, v11
	s_nop 0
	v_mul_f32_e32 v11, v16, v11
	v_mul_f32_e32 v16, 0x3d372713, v12
	v_mul_f32_e32 v16, v12, v16
	v_fma_f32 v16, v12, v16, v12
	v_mul_f32_e32 v16, 0x3fcc422a, v16
	v_mul_f32_e32 v16, 0xbfb8aa3b, v16
	v_exp_f32_e32 v16, v16
	s_nop 0
	v_add_f32_e32 v16, 1.0, v16
	v_rcp_f32_e32 v16, v16
	s_nop 0
	v_mul_f32_e32 v16, v12, v16
	v_mul_f32_e32 v12, 0x3d372713, v17
	v_mul_f32_e32 v12, v17, v12
	v_fma_f32 v12, v17, v12, v17
	v_mul_f32_e32 v12, 0x3fcc422a, v12
	v_mul_f32_e32 v12, 0xbfb8aa3b, v12
	v_exp_f32_e32 v12, v12
	s_nop 0
	v_add_f32_e32 v12, 1.0, v12
	v_rcp_f32_e32 v12, v12
	s_nop 0
	v_mul_f32_e32 v12, v17, v12
	v_mul_f32_e32 v17, 0x3d372713, v13
	v_mul_f32_e32 v17, v13, v17
	v_fma_f32 v17, v13, v17, v13
	v_mul_f32_e32 v17, 0x3fcc422a, v17
	v_mul_f32_e32 v17, 0xbfb8aa3b, v17
	v_exp_f32_e32 v17, v17
	v_cvt_pk_bf16_f32 v11, v11, v12
	v_cvt_pk_bf16_f32 v12, v21, v15
	v_addc_co_u32_e32 v15, vcc, 0, v135, vcc
	v_add_f32_e32 v17, 1.0, v17
	v_rcp_f32_e32 v17, v17
	s_andn2_b64 vcc, exec, s[42:43]
	v_mul_f32_e32 v13, v13, v17
	v_cvt_pk_bf16_f32 v13, v16, v13
	global_store_dwordx4 v[14:15], v[10:13], off
	s_nop 1
	v_mul_f32_e32 v10, 0x3d372713, v6
	v_mul_f32_e32 v10, v6, v10
	v_fma_f32 v10, v6, v10, v6
	v_mul_f32_e32 v10, 0x3fcc422a, v10
	v_mul_f32_e32 v10, 0xbfb8aa3b, v10
	v_exp_f32_e32 v10, v10
	s_nop 0
	v_add_f32_e32 v10, 1.0, v10
	v_rcp_f32_e32 v10, v10
	s_nop 0
	v_mul_f32_e32 v6, v6, v10
	v_mul_f32_e32 v10, 0x3d372713, v2
	v_mul_f32_e32 v10, v2, v10
	v_fma_f32 v10, v2, v10, v2
	v_mul_f32_e32 v10, 0x3fcc422a, v10
	v_mul_f32_e32 v10, 0xbfb8aa3b, v10
	v_exp_f32_e32 v10, v10
	s_nop 0
	v_add_f32_e32 v10, 1.0, v10
	v_rcp_f32_e32 v10, v10
	s_nop 0
	v_mul_f32_e32 v10, v2, v10
	v_mul_f32_e32 v2, 0x3d372713, v7
	v_mul_f32_e32 v2, v7, v2
	v_fma_f32 v2, v7, v2, v7
	v_mul_f32_e32 v2, 0x3fcc422a, v2
	v_mul_f32_e32 v2, 0xbfb8aa3b, v2
	v_exp_f32_e32 v2, v2
	s_nop 0
	v_add_f32_e32 v2, 1.0, v2
	v_rcp_f32_e32 v2, v2
	s_nop 0
	v_mul_f32_e32 v2, v7, v2
	v_mul_f32_e32 v7, 0x3d372713, v3
	v_mul_f32_e32 v7, v3, v7
	v_fma_f32 v7, v3, v7, v3
	v_mul_f32_e32 v7, 0x3fcc422a, v7
	v_mul_f32_e32 v7, 0xbfb8aa3b, v7
	v_exp_f32_e32 v7, v7
	v_cvt_pk_bf16_f32 v2, v6, v2
	s_nop 0
	v_add_f32_e32 v7, 1.0, v7
	v_rcp_f32_e32 v7, v7
	s_nop 0
	v_mul_f32_e32 v7, v3, v7
	v_mul_f32_e32 v3, 0x3d372713, v8
	v_mul_f32_e32 v3, v8, v3
	v_fma_f32 v3, v8, v3, v8
	v_mul_f32_e32 v3, 0x3fcc422a, v3
	v_mul_f32_e32 v3, 0xbfb8aa3b, v3
	v_exp_f32_e32 v3, v3
	s_nop 0
	v_add_f32_e32 v3, 1.0, v3
	v_rcp_f32_e32 v3, v3
	s_nop 0
	v_mul_f32_e32 v3, v8, v3
	v_mul_f32_e32 v8, 0x3d372713, v4
	v_mul_f32_e32 v8, v4, v8
	v_fma_f32 v8, v4, v8, v4
	v_mul_f32_e32 v8, 0x3fcc422a, v8
	v_mul_f32_e32 v8, 0xbfb8aa3b, v8
	v_exp_f32_e32 v8, v8
	s_nop 0
	v_add_f32_e32 v8, 1.0, v8
	v_rcp_f32_e32 v8, v8
	s_nop 0
	v_mul_f32_e32 v8, v4, v8
	v_mul_f32_e32 v4, 0x3d372713, v9
	v_mul_f32_e32 v4, v9, v4
	v_fma_f32 v4, v9, v4, v9
	v_mul_f32_e32 v4, 0x3fcc422a, v4
	v_mul_f32_e32 v4, 0xbfb8aa3b, v4
	v_exp_f32_e32 v4, v4
	s_nop 0
	v_add_f32_e32 v4, 1.0, v4
	v_rcp_f32_e32 v4, v4
	s_nop 0
	v_mul_f32_e32 v4, v9, v4
	v_mul_f32_e32 v9, 0x3d372713, v5
	v_mul_f32_e32 v9, v5, v9
	v_fma_f32 v9, v5, v9, v5
	v_mul_f32_e32 v9, 0x3fcc422a, v9
	v_mul_f32_e32 v9, 0xbfb8aa3b, v9
	v_exp_f32_e32 v9, v9
	v_cvt_pk_bf16_f32 v3, v3, v4
	v_cvt_pk_bf16_f32 v4, v10, v7
	s_nop 0
	v_add_f32_e32 v9, 1.0, v9
	v_rcp_f32_e32 v9, v9
	s_nop 0
	v_mul_f32_e32 v5, v5, v9
	v_cvt_pk_bf16_f32 v5, v8, v5
	global_store_dwordx4 v[18:19], v[2:5], off offset:256
	s_cbranch_vccnz .LBB0_901
	s_andn2_b64 vcc, exec, s[38:39]
	s_cbranch_vccnz .LBB0_900
	s_mov_b32 m0, -1
	s_branch .LBB0_900

.LBB0_1192:
	s_lshl_b32 s12, s70, 22
	s_and_b64 s[8:9], s[26:27], exec
	s_cselect_b32 s8, s12, s30
	s_lshl_b32 s22, s71, 22
	s_and_b64 s[66:67], s[26:27], exec
	s_cselect_b32 s9, s22, s31
	s_add_i32 s30, s30, 0x200080
	s_addk_i32 s31, 0x100
	s_mov_b32 s72, -2
	s_cmp_eq_u32 m0, -1
	s_cbranch_scc0 .Lgk_rs_5
	s_barrier
.Lgk_rs_5:
	v_add_u32_e32 v141, 0x10000, v139
	ds_read_b128 v[142:145], v141
	ds_read_b128 v[154:157], v141 offset:1024
	ds_read_b128 v[170:173], v141 offset:2048
	ds_read_b128 v[174:177], v141 offset:3072
	v_add_u32_e32 v141, 0x14000, v139
	ds_read_b128 v[178:181], v141
	ds_read_b128 v[182:185], v141 offset:1024
	ds_read_b128 v[186:189], v141 offset:2048
	ds_read_b128 v[190:193], v141 offset:3072
	s_add_i32 s52, s30, 0xffe00080
	s_cmpk_eq_i32 s72, 0x7c
	s_cselect_b32 s52, s8, s52
	s_cselect_b32 s82, s9, s31
	s_or_b32 s73, s52, 0x80
	s_mov_b32 m0, s69
	ds_read_b128 v[194:197], v140
	ds_read_b128 v[198:201], v140 offset:1024
	ds_read_b128 v[202:205], v140 offset:2048
	ds_read_b128 v[228:231], v140 offset:3072
	ds_read_b128 v[232:235], v140 offset:4096
	ds_read_b128 v[236:239], v140 offset:5120
	ds_read_b128 v[240:243], v140 offset:6144
	ds_read_b128 v[244:247], v140 offset:7168
	buffer_load_dwordx4 v131, s[60:63], s30 offen lds
	s_mov_b32 m0, s46
	s_nop 0
	buffer_load_dwordx4 v135, s[60:63], s30 offen lds
	s_waitcnt vmcnt(8)
	s_waitcnt lgkmcnt(0)
	s_setprio 1
	s_barrier
	v_mfma_f32_16x16x32_bf16 v[126:129], v[142:145], v[194:197], 0
	v_mfma_f32_16x16x32_bf16 v[126:129], v[154:157], v[198:201], v[126:129]
	v_mfma_f32_16x16x32_bf16 v[122:125], v[170:173], v[194:197], 0
	v_mfma_f32_16x16x32_bf16 v[122:125], v[174:177], v[198:201], v[122:125]
	v_mfma_f32_16x16x32_bf16 v[58:61], v[186:189], v[194:197], 0
	v_mfma_f32_16x16x32_bf16 v[58:61], v[190:193], v[198:201], v[58:61]
	v_mfma_f32_16x16x32_bf16 v[62:65], v[178:181], v[194:197], 0
	v_mfma_f32_16x16x32_bf16 v[62:65], v[182:185], v[198:201], v[62:65]
	v_mfma_f32_16x16x32_bf16 v[54:57], v[178:181], v[202:205], 0
	v_mfma_f32_16x16x32_bf16 v[54:57], v[182:185], v[228:231], v[54:57]
	v_mfma_f32_16x16x32_bf16 v[50:53], v[186:189], v[202:205], 0
	v_mfma_f32_16x16x32_bf16 v[50:53], v[190:193], v[228:231], v[50:53]
	v_mfma_f32_16x16x32_bf16 v[114:117], v[170:173], v[202:205], 0
	v_mfma_f32_16x16x32_bf16 v[114:117], v[174:177], v[228:231], v[114:117]
	v_mfma_f32_16x16x32_bf16 v[118:121], v[142:145], v[202:205], 0
	v_mfma_f32_16x16x32_bf16 v[118:121], v[154:157], v[228:231], v[118:121]
	v_mfma_f32_16x16x32_bf16 v[110:113], v[142:145], v[232:235], 0
	v_mfma_f32_16x16x32_bf16 v[110:113], v[154:157], v[236:239], v[110:113]
	v_mfma_f32_16x16x32_bf16 v[106:109], v[170:173], v[232:235], 0
	v_mfma_f32_16x16x32_bf16 v[106:109], v[174:177], v[236:239], v[106:109]
	v_mfma_f32_16x16x32_bf16 v[42:45], v[186:189], v[232:235], 0
	v_mfma_f32_16x16x32_bf16 v[42:45], v[190:193], v[236:239], v[42:45]
	v_mfma_f32_16x16x32_bf16 v[46:49], v[178:181], v[232:235], 0
	v_mfma_f32_16x16x32_bf16 v[46:49], v[182:185], v[236:239], v[46:49]
	v_mfma_f32_16x16x32_bf16 v[38:41], v[178:181], v[240:243], 0
	v_mfma_f32_16x16x32_bf16 v[38:41], v[182:185], v[244:247], v[38:41]
	v_mfma_f32_16x16x32_bf16 v[34:37], v[186:189], v[240:243], 0
	v_mfma_f32_16x16x32_bf16 v[34:37], v[190:193], v[244:247], v[34:37]
	v_mfma_f32_16x16x32_bf16 v[98:101], v[170:173], v[240:243], 0
	v_mfma_f32_16x16x32_bf16 v[98:101], v[174:177], v[244:247], v[98:101]
	v_mfma_f32_16x16x32_bf16 v[102:105], v[142:145], v[240:243], 0
	v_mfma_f32_16x16x32_bf16 v[102:105], v[154:157], v[244:247], v[102:105]
	s_barrier
	s_setprio 0
	s_mov_b32 s66, s62
	s_mov_b32 s67, s63
	s_mov_b32 m0, s15
	ds_read_b128 v[194:197], v140 offset:16384
	buffer_load_dwordx4 v134, s[64:67], s82 offen lds
	s_add_i32 s53, s82, 0x200000
	s_mov_b32 m0, s16
	ds_read_b128 v[198:201], v140 offset:17408
	buffer_load_dwordx4 v136, s[64:67], s82 offen lds
	s_mov_b32 m0, s21
	ds_read_b128 v[202:205], v140 offset:18432
	buffer_load_dwordx4 v134, s[64:67], s53 offen lds
	s_mov_b32 m0, s23
	ds_read_b128 v[228:231], v140 offset:19456
	buffer_load_dwordx4 v136, s[64:67], s53 offen lds
	s_mov_b32 m0, s2
	ds_read_b128 v[232:235], v140 offset:20480
	buffer_load_dwordx4 v131, s[60:63], s52 offen lds
	s_mov_b32 m0, s24
	ds_read_b128 v[236:239], v140 offset:21504
	buffer_load_dwordx4 v135, s[60:63], s52 offen lds
	ds_read_b128 v[240:243], v140 offset:22528
	ds_read_b128 v[244:247], v140 offset:23552
	s_waitcnt vmcnt(8)
	s_waitcnt lgkmcnt(0)
	s_setprio 1
	s_barrier
	v_mfma_f32_16x16x32_bf16 v[94:97], v[142:145], v[194:197], 0
	v_mfma_f32_16x16x32_bf16 v[94:97], v[154:157], v[198:201], v[94:97]
	v_mfma_f32_16x16x32_bf16 v[90:93], v[170:173], v[194:197], 0
	v_mfma_f32_16x16x32_bf16 v[90:93], v[174:177], v[198:201], v[90:93]
	v_mfma_f32_16x16x32_bf16 v[26:29], v[186:189], v[194:197], 0
	v_mfma_f32_16x16x32_bf16 v[26:29], v[190:193], v[198:201], v[26:29]
	v_mfma_f32_16x16x32_bf16 v[30:33], v[178:181], v[194:197], 0
	v_mfma_f32_16x16x32_bf16 v[30:33], v[182:185], v[198:201], v[30:33]
	v_mfma_f32_16x16x32_bf16 v[22:25], v[178:181], v[202:205], 0
	v_mfma_f32_16x16x32_bf16 v[22:25], v[182:185], v[228:231], v[22:25]
	v_mfma_f32_16x16x32_bf16 v[18:21], v[186:189], v[202:205], 0
	v_mfma_f32_16x16x32_bf16 v[18:21], v[190:193], v[228:231], v[18:21]
	v_mfma_f32_16x16x32_bf16 v[82:85], v[170:173], v[202:205], 0
	v_mfma_f32_16x16x32_bf16 v[82:85], v[174:177], v[228:231], v[82:85]
	v_mfma_f32_16x16x32_bf16 v[86:89], v[142:145], v[202:205], 0
	v_mfma_f32_16x16x32_bf16 v[86:89], v[154:157], v[228:231], v[86:89]
	v_mfma_f32_16x16x32_bf16 v[78:81], v[142:145], v[232:235], 0
	v_mfma_f32_16x16x32_bf16 v[78:81], v[154:157], v[236:239], v[78:81]
	v_mfma_f32_16x16x32_bf16 v[74:77], v[170:173], v[232:235], 0
	v_mfma_f32_16x16x32_bf16 v[74:77], v[174:177], v[236:239], v[74:77]
	v_mfma_f32_16x16x32_bf16 v[10:13], v[186:189], v[232:235], 0
	v_mfma_f32_16x16x32_bf16 v[10:13], v[190:193], v[236:239], v[10:13]
	v_mfma_f32_16x16x32_bf16 v[14:17], v[178:181], v[232:235], 0
	v_mfma_f32_16x16x32_bf16 v[14:17], v[182:185], v[236:239], v[14:17]
	v_mfma_f32_16x16x32_bf16 v[6:9], v[178:181], v[240:243], 0
	v_mfma_f32_16x16x32_bf16 v[6:9], v[182:185], v[244:247], v[6:9]
	v_mfma_f32_16x16x32_bf16 v[2:5], v[186:189], v[240:243], 0
	v_mfma_f32_16x16x32_bf16 v[2:5], v[190:193], v[244:247], v[2:5]
	v_mfma_f32_16x16x32_bf16 v[66:69], v[170:173], v[240:243], 0
	v_mfma_f32_16x16x32_bf16 v[66:69], v[174:177], v[244:247], v[66:69]
	v_mfma_f32_16x16x32_bf16 v[70:73], v[142:145], v[240:243], 0
	v_mfma_f32_16x16x32_bf16 v[70:73], v[154:157], v[244:247], v[70:73]
	s_barrier
	s_setprio 0
	v_add_u32_e32 v141, 0x18000, v139
	ds_read_b128 v[142:145], v141
	ds_read_b128 v[154:157], v141 offset:1024
	ds_read_b128 v[170:173], v141 offset:2048
	ds_read_b128 v[174:177], v141 offset:3072
	v_add_u32_e32 v141, 0x1c000, v139
	ds_read_b128 v[178:181], v141
	ds_read_b128 v[182:185], v141 offset:1024
	ds_read_b128 v[186:189], v141 offset:2048
	ds_read_b128 v[190:193], v141 offset:3072
	s_add_i32 s52, s52, 0x200000
	s_mov_b32 m0, s25
	ds_read_b128 v[194:197], v140 offset:32768
	ds_read_b128 v[198:201], v140 offset:33792
	ds_read_b128 v[202:205], v140 offset:34816
	ds_read_b128 v[228:231], v140 offset:35840
	ds_read_b128 v[232:235], v140 offset:36864
	ds_read_b128 v[236:239], v140 offset:37888
	ds_read_b128 v[240:243], v140 offset:38912
	ds_read_b128 v[244:247], v140 offset:39936
	buffer_load_dwordx4 v131, s[60:63], s52 offen lds
	s_mov_b32 m0, s33
	s_nop 0
	buffer_load_dwordx4 v135, s[60:63], s52 offen lds
	s_waitcnt vmcnt(8)
	s_waitcnt lgkmcnt(0)
	s_setprio 1
	s_barrier
	v_mfma_f32_16x16x32_bf16 v[126:129], v[142:145], v[194:197], v[126:129]
	v_mfma_f32_16x16x32_bf16 v[126:129], v[154:157], v[198:201], v[126:129]
	v_mfma_f32_16x16x32_bf16 v[122:125], v[170:173], v[194:197], v[122:125]
	v_mfma_f32_16x16x32_bf16 v[122:125], v[174:177], v[198:201], v[122:125]
	v_mfma_f32_16x16x32_bf16 v[58:61], v[186:189], v[194:197], v[58:61]
	v_mfma_f32_16x16x32_bf16 v[58:61], v[190:193], v[198:201], v[58:61]
	v_mfma_f32_16x16x32_bf16 v[62:65], v[178:181], v[194:197], v[62:65]
	v_mfma_f32_16x16x32_bf16 v[62:65], v[182:185], v[198:201], v[62:65]
	v_mfma_f32_16x16x32_bf16 v[54:57], v[178:181], v[202:205], v[54:57]
	v_mfma_f32_16x16x32_bf16 v[54:57], v[182:185], v[228:231], v[54:57]
	v_mfma_f32_16x16x32_bf16 v[50:53], v[186:189], v[202:205], v[50:53]
	v_mfma_f32_16x16x32_bf16 v[50:53], v[190:193], v[228:231], v[50:53]
	v_mfma_f32_16x16x32_bf16 v[114:117], v[170:173], v[202:205], v[114:117]
	v_mfma_f32_16x16x32_bf16 v[114:117], v[174:177], v[228:231], v[114:117]
	v_mfma_f32_16x16x32_bf16 v[118:121], v[142:145], v[202:205], v[118:121]
	v_mfma_f32_16x16x32_bf16 v[118:121], v[154:157], v[228:231], v[118:121]
	v_mfma_f32_16x16x32_bf16 v[110:113], v[142:145], v[232:235], v[110:113]
	v_mfma_f32_16x16x32_bf16 v[110:113], v[154:157], v[236:239], v[110:113]
	v_mfma_f32_16x16x32_bf16 v[106:109], v[170:173], v[232:235], v[106:109]
	v_mfma_f32_16x16x32_bf16 v[106:109], v[174:177], v[236:239], v[106:109]
	v_mfma_f32_16x16x32_bf16 v[42:45], v[186:189], v[232:235], v[42:45]
	v_mfma_f32_16x16x32_bf16 v[42:45], v[190:193], v[236:239], v[42:45]
	v_mfma_f32_16x16x32_bf16 v[46:49], v[178:181], v[232:235], v[46:49]
	v_mfma_f32_16x16x32_bf16 v[46:49], v[182:185], v[236:239], v[46:49]
	v_mfma_f32_16x16x32_bf16 v[38:41], v[178:181], v[240:243], v[38:41]
	v_mfma_f32_16x16x32_bf16 v[38:41], v[182:185], v[244:247], v[38:41]
	v_mfma_f32_16x16x32_bf16 v[34:37], v[186:189], v[240:243], v[34:37]
	v_mfma_f32_16x16x32_bf16 v[34:37], v[190:193], v[244:247], v[34:37]
	v_mfma_f32_16x16x32_bf16 v[98:101], v[170:173], v[240:243], v[98:101]
	v_mfma_f32_16x16x32_bf16 v[98:101], v[174:177], v[244:247], v[98:101]
	v_mfma_f32_16x16x32_bf16 v[102:105], v[142:145], v[240:243], v[102:105]
	v_mfma_f32_16x16x32_bf16 v[102:105], v[154:157], v[244:247], v[102:105]
	s_barrier
	s_setprio 0
	s_or_b32 s52, s82, 0x80
	s_mov_b32 m0, s34
	ds_read_b128 v[194:197], v140 offset:49152
	buffer_load_dwordx4 v134, s[64:67], s52 offen lds
	s_add_i32 s82, s82, 0x200080
	s_mov_b32 m0, s35
	ds_read_b128 v[198:201], v140 offset:50176
	buffer_load_dwordx4 v136, s[64:67], s52 offen lds
	s_mov_b32 m0, s37
	ds_read_b128 v[202:205], v140 offset:51200
	buffer_load_dwordx4 v134, s[64:67], s82 offen lds
	s_mov_b32 m0, s44
	ds_read_b128 v[228:231], v140 offset:52224
	buffer_load_dwordx4 v136, s[64:67], s82 offen lds
	s_mov_b32 m0, s14
	ds_read_b128 v[232:235], v140 offset:53248
	buffer_load_dwordx4 v131, s[60:63], s73 offen lds
	s_mov_b32 m0, s36
	ds_read_b128 v[236:239], v140 offset:54272
	buffer_load_dwordx4 v135, s[60:63], s73 offen lds
	ds_read_b128 v[240:243], v140 offset:55296
	ds_read_b128 v[244:247], v140 offset:56320
	s_waitcnt vmcnt(8)
	s_waitcnt lgkmcnt(0)
	s_setprio 1
	s_barrier
	v_mfma_f32_16x16x32_bf16 v[94:97], v[142:145], v[194:197], v[94:97]
	v_mfma_f32_16x16x32_bf16 v[94:97], v[154:157], v[198:201], v[94:97]
	v_mfma_f32_16x16x32_bf16 v[90:93], v[170:173], v[194:197], v[90:93]
	v_mfma_f32_16x16x32_bf16 v[90:93], v[174:177], v[198:201], v[90:93]
	v_mfma_f32_16x16x32_bf16 v[26:29], v[186:189], v[194:197], v[26:29]
	v_mfma_f32_16x16x32_bf16 v[26:29], v[190:193], v[198:201], v[26:29]
	v_mfma_f32_16x16x32_bf16 v[30:33], v[178:181], v[194:197], v[30:33]
	v_mfma_f32_16x16x32_bf16 v[30:33], v[182:185], v[198:201], v[30:33]
	v_mfma_f32_16x16x32_bf16 v[22:25], v[178:181], v[202:205], v[22:25]
	v_mfma_f32_16x16x32_bf16 v[22:25], v[182:185], v[228:231], v[22:25]
	v_mfma_f32_16x16x32_bf16 v[18:21], v[186:189], v[202:205], v[18:21]
	v_mfma_f32_16x16x32_bf16 v[18:21], v[190:193], v[228:231], v[18:21]
	v_mfma_f32_16x16x32_bf16 v[82:85], v[170:173], v[202:205], v[82:85]
	v_mfma_f32_16x16x32_bf16 v[82:85], v[174:177], v[228:231], v[82:85]
	v_mfma_f32_16x16x32_bf16 v[86:89], v[142:145], v[202:205], v[86:89]
	v_mfma_f32_16x16x32_bf16 v[86:89], v[154:157], v[228:231], v[86:89]
	v_mfma_f32_16x16x32_bf16 v[78:81], v[142:145], v[232:235], v[78:81]
	v_mfma_f32_16x16x32_bf16 v[78:81], v[154:157], v[236:239], v[78:81]
	v_mfma_f32_16x16x32_bf16 v[74:77], v[170:173], v[232:235], v[74:77]
	v_mfma_f32_16x16x32_bf16 v[74:77], v[174:177], v[236:239], v[74:77]
	v_mfma_f32_16x16x32_bf16 v[10:13], v[186:189], v[232:235], v[10:13]
	v_mfma_f32_16x16x32_bf16 v[10:13], v[190:193], v[236:239], v[10:13]
	v_mfma_f32_16x16x32_bf16 v[14:17], v[178:181], v[232:235], v[14:17]
	v_mfma_f32_16x16x32_bf16 v[14:17], v[182:185], v[236:239], v[14:17]
	v_mfma_f32_16x16x32_bf16 v[6:9], v[178:181], v[240:243], v[6:9]
	v_mfma_f32_16x16x32_bf16 v[6:9], v[182:185], v[244:247], v[6:9]
	v_mfma_f32_16x16x32_bf16 v[2:5], v[186:189], v[240:243], v[2:5]
	v_mfma_f32_16x16x32_bf16 v[2:5], v[190:193], v[244:247], v[2:5]
	v_mfma_f32_16x16x32_bf16 v[66:69], v[170:173], v[240:243], v[66:69]
	v_mfma_f32_16x16x32_bf16 v[66:69], v[174:177], v[244:247], v[66:69]
	v_mfma_f32_16x16x32_bf16 v[70:73], v[142:145], v[240:243], v[70:73]
	v_mfma_f32_16x16x32_bf16 v[70:73], v[154:157], v[244:247], v[70:73]
	s_barrier
	s_setprio 0
	s_add_i32 s72, s72, 2
	s_addk_i32 s30, 0x100
	s_addk_i32 s31, 0x100
	s_cmpk_gt_u32 s72, 0x7d

.LBB0_1208:
	s_or_b64 exec, exec, s[8:9]
	s_andn2_b64 vcc, exec, s[26:27]
	s_mov_b64 s[8:9], -1
	s_cbranch_vccnz .LBB0_1189
	s_andn2_b64 vcc, exec, s[40:41]
	s_cbranch_vccnz .LBB0_1188
	s_mov_b32 m0, -1
	s_branch .LBB0_1188

.LBB0_1222:
	s_lshl_b32 s14, s82, 22
	s_and_b64 s[8:9], s[44:45], exec
	s_cselect_b32 s8, s14, s19
	s_lshl_b32 s46, s84, 22
	s_and_b64 s[26:27], s[44:45], exec
	s_cselect_b32 s9, s46, s22
	s_add_i32 s19, s19, 0x200080
	s_addk_i32 s22, 0x100
	s_mov_b32 s26, -2
	s_cmp_eq_u32 m0, -1
	s_cbranch_scc0 .Lgk_rs_6
	s_barrier
.Lgk_rs_6:
	v_add_u32_e32 v141, 0x10000, v139
	ds_read_b128 v[142:145], v141
	ds_read_b128 v[154:157], v141 offset:1024
	ds_read_b128 v[170:173], v141 offset:2048
	ds_read_b128 v[174:177], v141 offset:3072
	v_add_u32_e32 v141, 0x14000, v139
	ds_read_b128 v[178:181], v141
	ds_read_b128 v[182:185], v141 offset:1024
	ds_read_b128 v[186:189], v141 offset:2048
	ds_read_b128 v[190:193], v141 offset:3072
	s_add_i32 s27, s19, 0xffe00080
	s_cmpk_eq_i32 s26, 0x7c
	s_cselect_b32 s52, s8, s27
	s_cselect_b32 s47, s9, s22
	s_or_b32 s27, s52, 0x80
	s_mov_b32 m0, s71
	ds_read_b128 v[194:197], v140
	ds_read_b128 v[198:201], v140 offset:1024
	ds_read_b128 v[202:205], v140 offset:2048
	ds_read_b128 v[228:231], v140 offset:3072
	ds_read_b128 v[232:235], v140 offset:4096
	ds_read_b128 v[236:239], v140 offset:5120
	ds_read_b128 v[240:243], v140 offset:6144
	ds_read_b128 v[244:247], v140 offset:7168
	buffer_load_dwordx4 v131, s[60:63], s19 offen lds
	s_mov_b32 m0, s72
	s_nop 0
	buffer_load_dwordx4 v135, s[60:63], s19 offen lds
	s_waitcnt vmcnt(8)
	s_waitcnt lgkmcnt(0)
	s_setprio 1
	s_barrier
	v_mfma_f32_16x16x32_bf16 v[126:129], v[142:145], v[194:197], 0
	v_mfma_f32_16x16x32_bf16 v[126:129], v[154:157], v[198:201], v[126:129]
	v_mfma_f32_16x16x32_bf16 v[122:125], v[170:173], v[194:197], 0
	v_mfma_f32_16x16x32_bf16 v[122:125], v[174:177], v[198:201], v[122:125]
	v_mfma_f32_16x16x32_bf16 v[58:61], v[186:189], v[194:197], 0
	v_mfma_f32_16x16x32_bf16 v[58:61], v[190:193], v[198:201], v[58:61]
	v_mfma_f32_16x16x32_bf16 v[62:65], v[178:181], v[194:197], 0
	v_mfma_f32_16x16x32_bf16 v[62:65], v[182:185], v[198:201], v[62:65]
	v_mfma_f32_16x16x32_bf16 v[54:57], v[178:181], v[202:205], 0
	v_mfma_f32_16x16x32_bf16 v[54:57], v[182:185], v[228:231], v[54:57]
	v_mfma_f32_16x16x32_bf16 v[50:53], v[186:189], v[202:205], 0
	v_mfma_f32_16x16x32_bf16 v[50:53], v[190:193], v[228:231], v[50:53]
	v_mfma_f32_16x16x32_bf16 v[114:117], v[170:173], v[202:205], 0
	v_mfma_f32_16x16x32_bf16 v[114:117], v[174:177], v[228:231], v[114:117]
	v_mfma_f32_16x16x32_bf16 v[118:121], v[142:145], v[202:205], 0
	v_mfma_f32_16x16x32_bf16 v[118:121], v[154:157], v[228:231], v[118:121]
	v_mfma_f32_16x16x32_bf16 v[110:113], v[142:145], v[232:235], 0
	v_mfma_f32_16x16x32_bf16 v[110:113], v[154:157], v[236:239], v[110:113]
	v_mfma_f32_16x16x32_bf16 v[106:109], v[170:173], v[232:235], 0
	v_mfma_f32_16x16x32_bf16 v[106:109], v[174:177], v[236:239], v[106:109]
	v_mfma_f32_16x16x32_bf16 v[42:45], v[186:189], v[232:235], 0
	v_mfma_f32_16x16x32_bf16 v[42:45], v[190:193], v[236:239], v[42:45]
	v_mfma_f32_16x16x32_bf16 v[46:49], v[178:181], v[232:235], 0
	v_mfma_f32_16x16x32_bf16 v[46:49], v[182:185], v[236:239], v[46:49]
	v_mfma_f32_16x16x32_bf16 v[38:41], v[178:181], v[240:243], 0
	v_mfma_f32_16x16x32_bf16 v[38:41], v[182:185], v[244:247], v[38:41]
	v_mfma_f32_16x16x32_bf16 v[34:37], v[186:189], v[240:243], 0
	v_mfma_f32_16x16x32_bf16 v[34:37], v[190:193], v[244:247], v[34:37]
	v_mfma_f32_16x16x32_bf16 v[98:101], v[170:173], v[240:243], 0
	v_mfma_f32_16x16x32_bf16 v[98:101], v[174:177], v[244:247], v[98:101]
	v_mfma_f32_16x16x32_bf16 v[102:105], v[142:145], v[240:243], 0
	v_mfma_f32_16x16x32_bf16 v[102:105], v[154:157], v[244:247], v[102:105]
	s_barrier
	s_setprio 0
	s_mov_b32 s66, s62
	s_mov_b32 s67, s63
	s_mov_b32 m0, s2
	ds_read_b128 v[194:197], v140 offset:16384
	buffer_load_dwordx4 v134, s[64:67], s47 offen lds
	s_add_i32 s53, s47, 0x200000
	s_mov_b32 m0, s21
	ds_read_b128 v[198:201], v140 offset:17408
	buffer_load_dwordx4 v136, s[64:67], s47 offen lds
	s_mov_b32 m0, s23
	ds_read_b128 v[202:205], v140 offset:18432
	buffer_load_dwordx4 v134, s[64:67], s53 offen lds
	s_mov_b32 m0, s24
	ds_read_b128 v[228:231], v140 offset:19456
	buffer_load_dwordx4 v136, s[64:67], s53 offen lds
	s_mov_b32 m0, s16
	ds_read_b128 v[232:235], v140 offset:20480
	buffer_load_dwordx4 v131, s[60:63], s52 offen lds
	s_mov_b32 m0, s25
	ds_read_b128 v[236:239], v140 offset:21504
	buffer_load_dwordx4 v135, s[60:63], s52 offen lds
	ds_read_b128 v[240:243], v140 offset:22528
	ds_read_b128 v[244:247], v140 offset:23552
	s_waitcnt vmcnt(8)
	s_waitcnt lgkmcnt(0)
	s_setprio 1
	s_barrier
	v_mfma_f32_16x16x32_bf16 v[94:97], v[142:145], v[194:197], 0
	v_mfma_f32_16x16x32_bf16 v[94:97], v[154:157], v[198:201], v[94:97]
	v_mfma_f32_16x16x32_bf16 v[90:93], v[170:173], v[194:197], 0
	v_mfma_f32_16x16x32_bf16 v[90:93], v[174:177], v[198:201], v[90:93]
	v_mfma_f32_16x16x32_bf16 v[26:29], v[186:189], v[194:197], 0
	v_mfma_f32_16x16x32_bf16 v[26:29], v[190:193], v[198:201], v[26:29]
	v_mfma_f32_16x16x32_bf16 v[30:33], v[178:181], v[194:197], 0
	v_mfma_f32_16x16x32_bf16 v[30:33], v[182:185], v[198:201], v[30:33]
	v_mfma_f32_16x16x32_bf16 v[22:25], v[178:181], v[202:205], 0
	v_mfma_f32_16x16x32_bf16 v[22:25], v[182:185], v[228:231], v[22:25]
	v_mfma_f32_16x16x32_bf16 v[18:21], v[186:189], v[202:205], 0
	v_mfma_f32_16x16x32_bf16 v[18:21], v[190:193], v[228:231], v[18:21]
	v_mfma_f32_16x16x32_bf16 v[82:85], v[170:173], v[202:205], 0
	v_mfma_f32_16x16x32_bf16 v[82:85], v[174:177], v[228:231], v[82:85]
	v_mfma_f32_16x16x32_bf16 v[86:89], v[142:145], v[202:205], 0
	v_mfma_f32_16x16x32_bf16 v[86:89], v[154:157], v[228:231], v[86:89]
	v_mfma_f32_16x16x32_bf16 v[78:81], v[142:145], v[232:235], 0
	v_mfma_f32_16x16x32_bf16 v[78:81], v[154:157], v[236:239], v[78:81]
	v_mfma_f32_16x16x32_bf16 v[74:77], v[170:173], v[232:235], 0
	v_mfma_f32_16x16x32_bf16 v[74:77], v[174:177], v[236:239], v[74:77]
	v_mfma_f32_16x16x32_bf16 v[10:13], v[186:189], v[232:235], 0
	v_mfma_f32_16x16x32_bf16 v[10:13], v[190:193], v[236:239], v[10:13]
	v_mfma_f32_16x16x32_bf16 v[14:17], v[178:181], v[232:235], 0
	v_mfma_f32_16x16x32_bf16 v[14:17], v[182:185], v[236:239], v[14:17]
	v_mfma_f32_16x16x32_bf16 v[6:9], v[178:181], v[240:243], 0
	v_mfma_f32_16x16x32_bf16 v[6:9], v[182:185], v[244:247], v[6:9]
	v_mfma_f32_16x16x32_bf16 v[2:5], v[186:189], v[240:243], 0
	v_mfma_f32_16x16x32_bf16 v[2:5], v[190:193], v[244:247], v[2:5]
	v_mfma_f32_16x16x32_bf16 v[66:69], v[170:173], v[240:243], 0
	v_mfma_f32_16x16x32_bf16 v[66:69], v[174:177], v[244:247], v[66:69]
	v_mfma_f32_16x16x32_bf16 v[70:73], v[142:145], v[240:243], 0
	v_mfma_f32_16x16x32_bf16 v[70:73], v[154:157], v[244:247], v[70:73]
	s_barrier
	s_setprio 0
	v_add_u32_e32 v141, 0x18000, v139
	ds_read_b128 v[142:145], v141
	ds_read_b128 v[154:157], v141 offset:1024
	ds_read_b128 v[170:173], v141 offset:2048
	ds_read_b128 v[174:177], v141 offset:3072
	v_add_u32_e32 v141, 0x1c000, v139
	ds_read_b128 v[178:181], v141
	ds_read_b128 v[182:185], v141 offset:1024
	ds_read_b128 v[186:189], v141 offset:2048
	ds_read_b128 v[190:193], v141 offset:3072
	s_add_i32 s52, s52, 0x200000
	s_mov_b32 m0, s30
	ds_read_b128 v[194:197], v140 offset:32768
	ds_read_b128 v[198:201], v140 offset:33792
	ds_read_b128 v[202:205], v140 offset:34816
	ds_read_b128 v[228:231], v140 offset:35840
	ds_read_b128 v[232:235], v140 offset:36864
	ds_read_b128 v[236:239], v140 offset:37888
	ds_read_b128 v[240:243], v140 offset:38912
	ds_read_b128 v[244:247], v140 offset:39936
	buffer_load_dwordx4 v131, s[60:63], s52 offen lds
	s_mov_b32 m0, s31
	s_nop 0
	buffer_load_dwordx4 v135, s[60:63], s52 offen lds
	s_waitcnt vmcnt(8)
	s_waitcnt lgkmcnt(0)
	s_setprio 1
	s_barrier
	v_mfma_f32_16x16x32_bf16 v[126:129], v[142:145], v[194:197], v[126:129]
	v_mfma_f32_16x16x32_bf16 v[126:129], v[154:157], v[198:201], v[126:129]
	v_mfma_f32_16x16x32_bf16 v[122:125], v[170:173], v[194:197], v[122:125]
	v_mfma_f32_16x16x32_bf16 v[122:125], v[174:177], v[198:201], v[122:125]
	v_mfma_f32_16x16x32_bf16 v[58:61], v[186:189], v[194:197], v[58:61]
	v_mfma_f32_16x16x32_bf16 v[58:61], v[190:193], v[198:201], v[58:61]
	v_mfma_f32_16x16x32_bf16 v[62:65], v[178:181], v[194:197], v[62:65]
	v_mfma_f32_16x16x32_bf16 v[62:65], v[182:185], v[198:201], v[62:65]
	v_mfma_f32_16x16x32_bf16 v[54:57], v[178:181], v[202:205], v[54:57]
	v_mfma_f32_16x16x32_bf16 v[54:57], v[182:185], v[228:231], v[54:57]
	v_mfma_f32_16x16x32_bf16 v[50:53], v[186:189], v[202:205], v[50:53]
	v_mfma_f32_16x16x32_bf16 v[50:53], v[190:193], v[228:231], v[50:53]
	v_mfma_f32_16x16x32_bf16 v[114:117], v[170:173], v[202:205], v[114:117]
	v_mfma_f32_16x16x32_bf16 v[114:117], v[174:177], v[228:231], v[114:117]
	v_mfma_f32_16x16x32_bf16 v[118:121], v[142:145], v[202:205], v[118:121]
	v_mfma_f32_16x16x32_bf16 v[118:121], v[154:157], v[228:231], v[118:121]
	v_mfma_f32_16x16x32_bf16 v[110:113], v[142:145], v[232:235], v[110:113]
	v_mfma_f32_16x16x32_bf16 v[110:113], v[154:157], v[236:239], v[110:113]
	v_mfma_f32_16x16x32_bf16 v[106:109], v[170:173], v[232:235], v[106:109]
	v_mfma_f32_16x16x32_bf16 v[106:109], v[174:177], v[236:239], v[106:109]
	v_mfma_f32_16x16x32_bf16 v[42:45], v[186:189], v[232:235], v[42:45]
	v_mfma_f32_16x16x32_bf16 v[42:45], v[190:193], v[236:239], v[42:45]
	v_mfma_f32_16x16x32_bf16 v[46:49], v[178:181], v[232:235], v[46:49]
	v_mfma_f32_16x16x32_bf16 v[46:49], v[182:185], v[236:239], v[46:49]
	v_mfma_f32_16x16x32_bf16 v[38:41], v[178:181], v[240:243], v[38:41]
	v_mfma_f32_16x16x32_bf16 v[38:41], v[182:185], v[244:247], v[38:41]
	v_mfma_f32_16x16x32_bf16 v[34:37], v[186:189], v[240:243], v[34:37]
	v_mfma_f32_16x16x32_bf16 v[34:37], v[190:193], v[244:247], v[34:37]
	v_mfma_f32_16x16x32_bf16 v[98:101], v[170:173], v[240:243], v[98:101]
	v_mfma_f32_16x16x32_bf16 v[98:101], v[174:177], v[244:247], v[98:101]
	v_mfma_f32_16x16x32_bf16 v[102:105], v[142:145], v[240:243], v[102:105]
	v_mfma_f32_16x16x32_bf16 v[102:105], v[154:157], v[244:247], v[102:105]
	s_barrier
	s_setprio 0
	s_or_b32 s52, s47, 0x80
	s_mov_b32 m0, s33
	ds_read_b128 v[194:197], v140 offset:49152
	buffer_load_dwordx4 v134, s[64:67], s52 offen lds
	s_add_i32 s47, s47, 0x200080
	s_mov_b32 m0, s34
	ds_read_b128 v[198:201], v140 offset:50176
	buffer_load_dwordx4 v136, s[64:67], s52 offen lds
	s_mov_b32 m0, s37
	ds_read_b128 v[202:205], v140 offset:51200
	buffer_load_dwordx4 v134, s[64:67], s47 offen lds
	s_mov_b32 m0, s68
	ds_read_b128 v[228:231], v140 offset:52224
	buffer_load_dwordx4 v136, s[64:67], s47 offen lds
	s_mov_b32 m0, s35
	ds_read_b128 v[232:235], v140 offset:53248
	buffer_load_dwordx4 v131, s[60:63], s27 offen lds
	s_mov_b32 m0, s36
	ds_read_b128 v[236:239], v140 offset:54272
	buffer_load_dwordx4 v135, s[60:63], s27 offen lds
	ds_read_b128 v[240:243], v140 offset:55296
	ds_read_b128 v[244:247], v140 offset:56320
	s_waitcnt vmcnt(8)
	s_waitcnt lgkmcnt(0)
	s_setprio 1
	s_barrier
	v_mfma_f32_16x16x32_bf16 v[94:97], v[142:145], v[194:197], v[94:97]
	v_mfma_f32_16x16x32_bf16 v[94:97], v[154:157], v[198:201], v[94:97]
	v_mfma_f32_16x16x32_bf16 v[90:93], v[170:173], v[194:197], v[90:93]
	v_mfma_f32_16x16x32_bf16 v[90:93], v[174:177], v[198:201], v[90:93]
	v_mfma_f32_16x16x32_bf16 v[26:29], v[186:189], v[194:197], v[26:29]
	v_mfma_f32_16x16x32_bf16 v[26:29], v[190:193], v[198:201], v[26:29]
	v_mfma_f32_16x16x32_bf16 v[30:33], v[178:181], v[194:197], v[30:33]
	v_mfma_f32_16x16x32_bf16 v[30:33], v[182:185], v[198:201], v[30:33]
	v_mfma_f32_16x16x32_bf16 v[22:25], v[178:181], v[202:205], v[22:25]
	v_mfma_f32_16x16x32_bf16 v[22:25], v[182:185], v[228:231], v[22:25]
	v_mfma_f32_16x16x32_bf16 v[18:21], v[186:189], v[202:205], v[18:21]
	v_mfma_f32_16x16x32_bf16 v[18:21], v[190:193], v[228:231], v[18:21]
	v_mfma_f32_16x16x32_bf16 v[82:85], v[170:173], v[202:205], v[82:85]
	v_mfma_f32_16x16x32_bf16 v[82:85], v[174:177], v[228:231], v[82:85]
	v_mfma_f32_16x16x32_bf16 v[86:89], v[142:145], v[202:205], v[86:89]
	v_mfma_f32_16x16x32_bf16 v[86:89], v[154:157], v[228:231], v[86:89]
	v_mfma_f32_16x16x32_bf16 v[78:81], v[142:145], v[232:235], v[78:81]
	v_mfma_f32_16x16x32_bf16 v[78:81], v[154:157], v[236:239], v[78:81]
	v_mfma_f32_16x16x32_bf16 v[74:77], v[170:173], v[232:235], v[74:77]
	v_mfma_f32_16x16x32_bf16 v[74:77], v[174:177], v[236:239], v[74:77]
	v_mfma_f32_16x16x32_bf16 v[10:13], v[186:189], v[232:235], v[10:13]
	v_mfma_f32_16x16x32_bf16 v[10:13], v[190:193], v[236:239], v[10:13]
	v_mfma_f32_16x16x32_bf16 v[14:17], v[178:181], v[232:235], v[14:17]
	v_mfma_f32_16x16x32_bf16 v[14:17], v[182:185], v[236:239], v[14:17]
	v_mfma_f32_16x16x32_bf16 v[6:9], v[178:181], v[240:243], v[6:9]
	v_mfma_f32_16x16x32_bf16 v[6:9], v[182:185], v[244:247], v[6:9]
	v_mfma_f32_16x16x32_bf16 v[2:5], v[186:189], v[240:243], v[2:5]
	v_mfma_f32_16x16x32_bf16 v[2:5], v[190:193], v[244:247], v[2:5]
	v_mfma_f32_16x16x32_bf16 v[66:69], v[170:173], v[240:243], v[66:69]
	v_mfma_f32_16x16x32_bf16 v[66:69], v[174:177], v[244:247], v[66:69]
	v_mfma_f32_16x16x32_bf16 v[70:73], v[142:145], v[240:243], v[70:73]
	v_mfma_f32_16x16x32_bf16 v[70:73], v[154:157], v[244:247], v[70:73]
	s_barrier
	s_setprio 0
	s_add_i32 s26, s26, 2
	s_addk_i32 s19, 0x100
	s_addk_i32 s22, 0x100
	s_cmpk_gt_u32 s26, 0x7d

.LBB0_1238:
	s_or_b64 exec, exec, s[8:9]
	s_andn2_b64 vcc, exec, s[44:45]
	s_mov_b64 s[8:9], -1
	s_cbranch_vccnz .LBB0_1219
	s_andn2_b64 vcc, exec, s[40:41]
	s_cbranch_vccnz .LBB0_1218
	s_mov_b32 m0, -1
	s_branch .LBB0_1218

.LBB0_1252:
	s_lshl_b32 s12, s73, 20
	s_and_b64 s[8:9], s[40:41], exec
	s_cselect_b32 s8, s12, s26
	s_lshl_b32 s22, s82, 20
	s_and_b64 s[70:71], s[40:41], exec
	s_cselect_b32 s9, s22, s27
	s_add_i32 s26, s26, 0x80080
	s_addk_i32 s27, 0x100
	s_mov_b32 s83, -2
	s_cmp_eq_u32 m0, -1
	s_cbranch_scc0 .Lgk_rs_7
	s_barrier
.Lgk_rs_7:
	v_add_u32_e32 v141, 0x10000, v139
	ds_read_b128 v[142:145], v141
	ds_read_b128 v[154:157], v141 offset:1024
	ds_read_b128 v[170:173], v141 offset:2048
	ds_read_b128 v[174:177], v141 offset:3072
	v_add_u32_e32 v141, 0x14000, v139
	ds_read_b128 v[178:181], v141
	ds_read_b128 v[182:185], v141 offset:1024
	ds_read_b128 v[186:189], v141 offset:2048
	ds_read_b128 v[190:193], v141 offset:3072
	s_add_i32 s52, s26, 0xfff80080
	s_cmp_eq_u32 s83, 28
	s_cselect_b32 s52, s8, s52
	s_cselect_b32 s85, s9, s27
	s_or_b32 s84, s52, 0x80
	s_mov_b32 m0, s72
	ds_read_b128 v[194:197], v140
	ds_read_b128 v[198:201], v140 offset:1024
	ds_read_b128 v[202:205], v140 offset:2048
	ds_read_b128 v[228:231], v140 offset:3072
	ds_read_b128 v[232:235], v140 offset:4096
	ds_read_b128 v[236:239], v140 offset:5120
	ds_read_b128 v[240:243], v140 offset:6144
	ds_read_b128 v[244:247], v140 offset:7168
	buffer_load_dwordx4 v131, s[60:63], s26 offen lds
	s_mov_b32 m0, s46
	s_nop 0
	buffer_load_dwordx4 v135, s[60:63], s26 offen lds
	s_waitcnt vmcnt(8)
	s_waitcnt lgkmcnt(0)
	s_setprio 1
	s_barrier
	v_mfma_f32_16x16x32_bf16 v[126:129], v[142:145], v[194:197], 0
	v_mfma_f32_16x16x32_bf16 v[126:129], v[154:157], v[198:201], v[126:129]
	v_mfma_f32_16x16x32_bf16 v[122:125], v[170:173], v[194:197], 0
	v_mfma_f32_16x16x32_bf16 v[122:125], v[174:177], v[198:201], v[122:125]
	v_mfma_f32_16x16x32_bf16 v[58:61], v[186:189], v[194:197], 0
	v_mfma_f32_16x16x32_bf16 v[58:61], v[190:193], v[198:201], v[58:61]
	v_mfma_f32_16x16x32_bf16 v[62:65], v[178:181], v[194:197], 0
	v_mfma_f32_16x16x32_bf16 v[62:65], v[182:185], v[198:201], v[62:65]
	v_mfma_f32_16x16x32_bf16 v[54:57], v[178:181], v[202:205], 0
	v_mfma_f32_16x16x32_bf16 v[54:57], v[182:185], v[228:231], v[54:57]
	v_mfma_f32_16x16x32_bf16 v[50:53], v[186:189], v[202:205], 0
	v_mfma_f32_16x16x32_bf16 v[50:53], v[190:193], v[228:231], v[50:53]
	v_mfma_f32_16x16x32_bf16 v[114:117], v[170:173], v[202:205], 0
	v_mfma_f32_16x16x32_bf16 v[114:117], v[174:177], v[228:231], v[114:117]
	v_mfma_f32_16x16x32_bf16 v[118:121], v[142:145], v[202:205], 0
	v_mfma_f32_16x16x32_bf16 v[118:121], v[154:157], v[228:231], v[118:121]
	v_mfma_f32_16x16x32_bf16 v[110:113], v[142:145], v[232:235], 0
	v_mfma_f32_16x16x32_bf16 v[110:113], v[154:157], v[236:239], v[110:113]
	v_mfma_f32_16x16x32_bf16 v[106:109], v[170:173], v[232:235], 0
	v_mfma_f32_16x16x32_bf16 v[106:109], v[174:177], v[236:239], v[106:109]
	v_mfma_f32_16x16x32_bf16 v[42:45], v[186:189], v[232:235], 0
	v_mfma_f32_16x16x32_bf16 v[42:45], v[190:193], v[236:239], v[42:45]
	v_mfma_f32_16x16x32_bf16 v[46:49], v[178:181], v[232:235], 0
	v_mfma_f32_16x16x32_bf16 v[46:49], v[182:185], v[236:239], v[46:49]
	v_mfma_f32_16x16x32_bf16 v[38:41], v[178:181], v[240:243], 0
	v_mfma_f32_16x16x32_bf16 v[38:41], v[182:185], v[244:247], v[38:41]
	v_mfma_f32_16x16x32_bf16 v[34:37], v[186:189], v[240:243], 0
	v_mfma_f32_16x16x32_bf16 v[34:37], v[190:193], v[244:247], v[34:37]
	v_mfma_f32_16x16x32_bf16 v[98:101], v[170:173], v[240:243], 0
	v_mfma_f32_16x16x32_bf16 v[98:101], v[174:177], v[244:247], v[98:101]
	v_mfma_f32_16x16x32_bf16 v[102:105], v[142:145], v[240:243], 0
	v_mfma_f32_16x16x32_bf16 v[102:105], v[154:157], v[244:247], v[102:105]
	s_barrier
	s_setprio 0
	s_mov_b32 s70, s62
	s_mov_b32 s71, s63
	s_mov_b32 m0, s21
	ds_read_b128 v[194:197], v140 offset:16384
	buffer_load_dwordx4 v134, s[68:71], s85 offen lds
	s_add_i32 s53, s85, 0x80000
	s_mov_b32 m0, s23
	ds_read_b128 v[198:201], v140 offset:17408
	buffer_load_dwordx4 v136, s[68:71], s85 offen lds
	s_mov_b32 m0, s24
	ds_read_b128 v[202:205], v140 offset:18432
	buffer_load_dwordx4 v134, s[68:71], s53 offen lds
	s_mov_b32 m0, s25
	ds_read_b128 v[228:231], v140 offset:19456
	buffer_load_dwordx4 v136, s[68:71], s53 offen lds
	s_mov_b32 m0, s16
	ds_read_b128 v[232:235], v140 offset:20480
	buffer_load_dwordx4 v131, s[60:63], s52 offen lds
	s_mov_b32 m0, s30
	ds_read_b128 v[236:239], v140 offset:21504
	buffer_load_dwordx4 v135, s[60:63], s52 offen lds
	ds_read_b128 v[240:243], v140 offset:22528
	ds_read_b128 v[244:247], v140 offset:23552
	s_waitcnt vmcnt(8)
	s_waitcnt lgkmcnt(0)
	s_setprio 1
	s_barrier
	v_mfma_f32_16x16x32_bf16 v[94:97], v[142:145], v[194:197], 0
	v_mfma_f32_16x16x32_bf16 v[94:97], v[154:157], v[198:201], v[94:97]
	v_mfma_f32_16x16x32_bf16 v[90:93], v[170:173], v[194:197], 0
	v_mfma_f32_16x16x32_bf16 v[90:93], v[174:177], v[198:201], v[90:93]
	v_mfma_f32_16x16x32_bf16 v[26:29], v[186:189], v[194:197], 0
	v_mfma_f32_16x16x32_bf16 v[26:29], v[190:193], v[198:201], v[26:29]
	v_mfma_f32_16x16x32_bf16 v[30:33], v[178:181], v[194:197], 0
	v_mfma_f32_16x16x32_bf16 v[30:33], v[182:185], v[198:201], v[30:33]
	v_mfma_f32_16x16x32_bf16 v[22:25], v[178:181], v[202:205], 0
	v_mfma_f32_16x16x32_bf16 v[22:25], v[182:185], v[228:231], v[22:25]
	v_mfma_f32_16x16x32_bf16 v[18:21], v[186:189], v[202:205], 0
	v_mfma_f32_16x16x32_bf16 v[18:21], v[190:193], v[228:231], v[18:21]
	v_mfma_f32_16x16x32_bf16 v[82:85], v[170:173], v[202:205], 0
	v_mfma_f32_16x16x32_bf16 v[82:85], v[174:177], v[228:231], v[82:85]
	v_mfma_f32_16x16x32_bf16 v[86:89], v[142:145], v[202:205], 0
	v_mfma_f32_16x16x32_bf16 v[86:89], v[154:157], v[228:231], v[86:89]
	v_mfma_f32_16x16x32_bf16 v[78:81], v[142:145], v[232:235], 0
	v_mfma_f32_16x16x32_bf16 v[78:81], v[154:157], v[236:239], v[78:81]
	v_mfma_f32_16x16x32_bf16 v[74:77], v[170:173], v[232:235], 0
	v_mfma_f32_16x16x32_bf16 v[74:77], v[174:177], v[236:239], v[74:77]
	v_mfma_f32_16x16x32_bf16 v[10:13], v[186:189], v[232:235], 0
	v_mfma_f32_16x16x32_bf16 v[10:13], v[190:193], v[236:239], v[10:13]
	v_mfma_f32_16x16x32_bf16 v[14:17], v[178:181], v[232:235], 0
	v_mfma_f32_16x16x32_bf16 v[14:17], v[182:185], v[236:239], v[14:17]
	v_mfma_f32_16x16x32_bf16 v[6:9], v[178:181], v[240:243], 0
	v_mfma_f32_16x16x32_bf16 v[6:9], v[182:185], v[244:247], v[6:9]
	v_mfma_f32_16x16x32_bf16 v[2:5], v[186:189], v[240:243], 0
	v_mfma_f32_16x16x32_bf16 v[2:5], v[190:193], v[244:247], v[2:5]
	v_mfma_f32_16x16x32_bf16 v[66:69], v[170:173], v[240:243], 0
	v_mfma_f32_16x16x32_bf16 v[66:69], v[174:177], v[244:247], v[66:69]
	v_mfma_f32_16x16x32_bf16 v[70:73], v[142:145], v[240:243], 0
	v_mfma_f32_16x16x32_bf16 v[70:73], v[154:157], v[244:247], v[70:73]
	s_barrier
	s_setprio 0
	v_add_u32_e32 v141, 0x18000, v139
	ds_read_b128 v[142:145], v141
	ds_read_b128 v[154:157], v141 offset:1024
	ds_read_b128 v[170:173], v141 offset:2048
	ds_read_b128 v[174:177], v141 offset:3072
	v_add_u32_e32 v141, 0x1c000, v139
	ds_read_b128 v[178:181], v141
	ds_read_b128 v[182:185], v141 offset:1024
	ds_read_b128 v[186:189], v141 offset:2048
	ds_read_b128 v[190:193], v141 offset:3072
	s_add_i32 s52, s52, 0x80000
	s_mov_b32 m0, s31
	ds_read_b128 v[194:197], v140 offset:32768
	ds_read_b128 v[198:201], v140 offset:33792
	ds_read_b128 v[202:205], v140 offset:34816
	ds_read_b128 v[228:231], v140 offset:35840
	ds_read_b128 v[232:235], v140 offset:36864
	ds_read_b128 v[236:239], v140 offset:37888
	ds_read_b128 v[240:243], v140 offset:38912
	ds_read_b128 v[244:247], v140 offset:39936
	buffer_load_dwordx4 v131, s[60:63], s52 offen lds
	s_mov_b32 m0, s33
	s_nop 0
	buffer_load_dwordx4 v135, s[60:63], s52 offen lds
	s_waitcnt vmcnt(8)
	s_waitcnt lgkmcnt(0)
	s_setprio 1
	s_barrier
	v_mfma_f32_16x16x32_bf16 v[126:129], v[142:145], v[194:197], v[126:129]
	v_mfma_f32_16x16x32_bf16 v[126:129], v[154:157], v[198:201], v[126:129]
	v_mfma_f32_16x16x32_bf16 v[122:125], v[170:173], v[194:197], v[122:125]
	v_mfma_f32_16x16x32_bf16 v[122:125], v[174:177], v[198:201], v[122:125]
	v_mfma_f32_16x16x32_bf16 v[58:61], v[186:189], v[194:197], v[58:61]
	v_mfma_f32_16x16x32_bf16 v[58:61], v[190:193], v[198:201], v[58:61]
	v_mfma_f32_16x16x32_bf16 v[62:65], v[178:181], v[194:197], v[62:65]
	v_mfma_f32_16x16x32_bf16 v[62:65], v[182:185], v[198:201], v[62:65]
	v_mfma_f32_16x16x32_bf16 v[54:57], v[178:181], v[202:205], v[54:57]
	v_mfma_f32_16x16x32_bf16 v[54:57], v[182:185], v[228:231], v[54:57]
	v_mfma_f32_16x16x32_bf16 v[50:53], v[186:189], v[202:205], v[50:53]
	v_mfma_f32_16x16x32_bf16 v[50:53], v[190:193], v[228:231], v[50:53]
	v_mfma_f32_16x16x32_bf16 v[114:117], v[170:173], v[202:205], v[114:117]
	v_mfma_f32_16x16x32_bf16 v[114:117], v[174:177], v[228:231], v[114:117]
	v_mfma_f32_16x16x32_bf16 v[118:121], v[142:145], v[202:205], v[118:121]
	v_mfma_f32_16x16x32_bf16 v[118:121], v[154:157], v[228:231], v[118:121]
	v_mfma_f32_16x16x32_bf16 v[110:113], v[142:145], v[232:235], v[110:113]
	v_mfma_f32_16x16x32_bf16 v[110:113], v[154:157], v[236:239], v[110:113]
	v_mfma_f32_16x16x32_bf16 v[106:109], v[170:173], v[232:235], v[106:109]
	v_mfma_f32_16x16x32_bf16 v[106:109], v[174:177], v[236:239], v[106:109]
	v_mfma_f32_16x16x32_bf16 v[42:45], v[186:189], v[232:235], v[42:45]
	v_mfma_f32_16x16x32_bf16 v[42:45], v[190:193], v[236:239], v[42:45]
	v_mfma_f32_16x16x32_bf16 v[46:49], v[178:181], v[232:235], v[46:49]
	v_mfma_f32_16x16x32_bf16 v[46:49], v[182:185], v[236:239], v[46:49]
	v_mfma_f32_16x16x32_bf16 v[38:41], v[178:181], v[240:243], v[38:41]
	v_mfma_f32_16x16x32_bf16 v[38:41], v[182:185], v[244:247], v[38:41]
	v_mfma_f32_16x16x32_bf16 v[34:37], v[186:189], v[240:243], v[34:37]
	v_mfma_f32_16x16x32_bf16 v[34:37], v[190:193], v[244:247], v[34:37]
	v_mfma_f32_16x16x32_bf16 v[98:101], v[170:173], v[240:243], v[98:101]
	v_mfma_f32_16x16x32_bf16 v[98:101], v[174:177], v[244:247], v[98:101]
	v_mfma_f32_16x16x32_bf16 v[102:105], v[142:145], v[240:243], v[102:105]
	v_mfma_f32_16x16x32_bf16 v[102:105], v[154:157], v[244:247], v[102:105]
	s_barrier
	s_setprio 0
	s_or_b32 s52, s85, 0x80
	s_mov_b32 m0, s34
	ds_read_b128 v[194:197], v140 offset:49152
	buffer_load_dwordx4 v134, s[68:71], s52 offen lds
	s_add_i32 s85, s85, 0x80080
	s_mov_b32 m0, s35
	ds_read_b128 v[198:201], v140 offset:50176
	buffer_load_dwordx4 v136, s[68:71], s52 offen lds
	s_mov_b32 m0, s37
	ds_read_b128 v[202:205], v140 offset:51200
	buffer_load_dwordx4 v134, s[68:71], s85 offen lds
	s_mov_b32 m0, s65
	ds_read_b128 v[228:231], v140 offset:52224
	buffer_load_dwordx4 v136, s[68:71], s85 offen lds
	s_mov_b32 m0, s14
	ds_read_b128 v[232:235], v140 offset:53248
	buffer_load_dwordx4 v131, s[60:63], s84 offen lds
	s_mov_b32 m0, s36
	ds_read_b128 v[236:239], v140 offset:54272
	buffer_load_dwordx4 v135, s[60:63], s84 offen lds
	ds_read_b128 v[240:243], v140 offset:55296
	ds_read_b128 v[244:247], v140 offset:56320
	s_waitcnt vmcnt(8)
	s_waitcnt lgkmcnt(0)
	s_setprio 1
	s_barrier
	v_mfma_f32_16x16x32_bf16 v[94:97], v[142:145], v[194:197], v[94:97]
	v_mfma_f32_16x16x32_bf16 v[94:97], v[154:157], v[198:201], v[94:97]
	v_mfma_f32_16x16x32_bf16 v[90:93], v[170:173], v[194:197], v[90:93]
	v_mfma_f32_16x16x32_bf16 v[90:93], v[174:177], v[198:201], v[90:93]
	v_mfma_f32_16x16x32_bf16 v[26:29], v[186:189], v[194:197], v[26:29]
	v_mfma_f32_16x16x32_bf16 v[26:29], v[190:193], v[198:201], v[26:29]
	v_mfma_f32_16x16x32_bf16 v[30:33], v[178:181], v[194:197], v[30:33]
	v_mfma_f32_16x16x32_bf16 v[30:33], v[182:185], v[198:201], v[30:33]
	v_mfma_f32_16x16x32_bf16 v[22:25], v[178:181], v[202:205], v[22:25]
	v_mfma_f32_16x16x32_bf16 v[22:25], v[182:185], v[228:231], v[22:25]
	v_mfma_f32_16x16x32_bf16 v[18:21], v[186:189], v[202:205], v[18:21]
	v_mfma_f32_16x16x32_bf16 v[18:21], v[190:193], v[228:231], v[18:21]
	v_mfma_f32_16x16x32_bf16 v[82:85], v[170:173], v[202:205], v[82:85]
	v_mfma_f32_16x16x32_bf16 v[82:85], v[174:177], v[228:231], v[82:85]
	v_mfma_f32_16x16x32_bf16 v[86:89], v[142:145], v[202:205], v[86:89]
	v_mfma_f32_16x16x32_bf16 v[86:89], v[154:157], v[228:231], v[86:89]
	v_mfma_f32_16x16x32_bf16 v[78:81], v[142:145], v[232:235], v[78:81]
	v_mfma_f32_16x16x32_bf16 v[78:81], v[154:157], v[236:239], v[78:81]
	v_mfma_f32_16x16x32_bf16 v[74:77], v[170:173], v[232:235], v[74:77]
	v_mfma_f32_16x16x32_bf16 v[74:77], v[174:177], v[236:239], v[74:77]
	v_mfma_f32_16x16x32_bf16 v[10:13], v[186:189], v[232:235], v[10:13]
	v_mfma_f32_16x16x32_bf16 v[10:13], v[190:193], v[236:239], v[10:13]
	v_mfma_f32_16x16x32_bf16 v[14:17], v[178:181], v[232:235], v[14:17]
	v_mfma_f32_16x16x32_bf16 v[14:17], v[182:185], v[236:239], v[14:17]
	v_mfma_f32_16x16x32_bf16 v[6:9], v[178:181], v[240:243], v[6:9]
	v_mfma_f32_16x16x32_bf16 v[6:9], v[182:185], v[244:247], v[6:9]
	v_mfma_f32_16x16x32_bf16 v[2:5], v[186:189], v[240:243], v[2:5]
	v_mfma_f32_16x16x32_bf16 v[2:5], v[190:193], v[244:247], v[2:5]
	v_mfma_f32_16x16x32_bf16 v[66:69], v[170:173], v[240:243], v[66:69]
	v_mfma_f32_16x16x32_bf16 v[66:69], v[174:177], v[244:247], v[66:69]
	v_mfma_f32_16x16x32_bf16 v[70:73], v[142:145], v[240:243], v[70:73]
	v_mfma_f32_16x16x32_bf16 v[70:73], v[154:157], v[244:247], v[70:73]
	s_barrier
	s_setprio 0
	s_add_i32 s83, s83, 2
	s_addk_i32 s26, 0x100
	s_addk_i32 s27, 0x100
	s_cmp_gt_u32 s83, 29

.LBB0_1268:
	s_or_b64 exec, exec, s[8:9]
	s_andn2_b64 vcc, exec, s[40:41]
	s_mov_b64 s[8:9], -1
	v_readlane_b32 s83, v252, 30
	s_cbranch_vccnz .LBB0_1249
	s_andn2_b64 vcc, exec, s[42:43]
	s_cbranch_vccnz .LBB0_1248
	s_mov_b32 m0, -1
	s_branch .LBB0_1248

.LBB0_1282:
	s_lshl_b32 s46, s85, 20
	s_and_b64 s[8:9], s[40:41], exec
	s_cselect_b32 s8, s46, s19
	s_lshl_b32 s47, s14, 20
	s_and_b64 s[26:27], s[40:41], exec
	s_cselect_b32 s9, s47, s22
	s_add_i32 s19, s19, 0x80080
	s_addk_i32 s22, 0x100
	s_mov_b32 s26, -2
	s_cmp_eq_u32 m0, -1
	s_cbranch_scc0 .Lgk_rs_8
	s_barrier
.Lgk_rs_8:
	v_add_u32_e32 v141, 0x10000, v139
	ds_read_b128 v[142:145], v141
	ds_read_b128 v[154:157], v141 offset:1024
	ds_read_b128 v[170:173], v141 offset:2048
	ds_read_b128 v[174:177], v141 offset:3072
	v_add_u32_e32 v141, 0x14000, v139
	ds_read_b128 v[178:181], v141
	ds_read_b128 v[182:185], v141 offset:1024
	ds_read_b128 v[186:189], v141 offset:2048
	ds_read_b128 v[190:193], v141 offset:3072
	s_add_i32 s27, s19, 0xfff80080
	s_cmp_eq_u32 s26, 28
	s_cselect_b32 s52, s8, s27
	s_cselect_b32 s83, s9, s22
	s_or_b32 s27, s52, 0x80
	s_mov_b32 m0, s73
	ds_read_b128 v[194:197], v140
	ds_read_b128 v[198:201], v140 offset:1024
	ds_read_b128 v[202:205], v140 offset:2048
	ds_read_b128 v[228:231], v140 offset:3072
	ds_read_b128 v[232:235], v140 offset:4096
	ds_read_b128 v[236:239], v140 offset:5120
	ds_read_b128 v[240:243], v140 offset:6144
	ds_read_b128 v[244:247], v140 offset:7168
	buffer_load_dwordx4 v131, s[60:63], s19 offen lds
	s_mov_b32 m0, s82
	s_nop 0
	buffer_load_dwordx4 v135, s[60:63], s19 offen lds
	s_waitcnt vmcnt(8)
	s_waitcnt lgkmcnt(0)
	s_setprio 1
	s_barrier
	v_mfma_f32_16x16x32_bf16 v[126:129], v[142:145], v[194:197], 0
	v_mfma_f32_16x16x32_bf16 v[126:129], v[154:157], v[198:201], v[126:129]
	v_mfma_f32_16x16x32_bf16 v[122:125], v[170:173], v[194:197], 0
	v_mfma_f32_16x16x32_bf16 v[122:125], v[174:177], v[198:201], v[122:125]
	v_mfma_f32_16x16x32_bf16 v[58:61], v[186:189], v[194:197], 0
	v_mfma_f32_16x16x32_bf16 v[58:61], v[190:193], v[198:201], v[58:61]
	v_mfma_f32_16x16x32_bf16 v[62:65], v[178:181], v[194:197], 0
	v_mfma_f32_16x16x32_bf16 v[62:65], v[182:185], v[198:201], v[62:65]
	v_mfma_f32_16x16x32_bf16 v[54:57], v[178:181], v[202:205], 0
	v_mfma_f32_16x16x32_bf16 v[54:57], v[182:185], v[228:231], v[54:57]
	v_mfma_f32_16x16x32_bf16 v[50:53], v[186:189], v[202:205], 0
	v_mfma_f32_16x16x32_bf16 v[50:53], v[190:193], v[228:231], v[50:53]
	v_mfma_f32_16x16x32_bf16 v[114:117], v[170:173], v[202:205], 0
	v_mfma_f32_16x16x32_bf16 v[114:117], v[174:177], v[228:231], v[114:117]
	v_mfma_f32_16x16x32_bf16 v[118:121], v[142:145], v[202:205], 0
	v_mfma_f32_16x16x32_bf16 v[118:121], v[154:157], v[228:231], v[118:121]
	v_mfma_f32_16x16x32_bf16 v[110:113], v[142:145], v[232:235], 0
	v_mfma_f32_16x16x32_bf16 v[110:113], v[154:157], v[236:239], v[110:113]
	v_mfma_f32_16x16x32_bf16 v[106:109], v[170:173], v[232:235], 0
	v_mfma_f32_16x16x32_bf16 v[106:109], v[174:177], v[236:239], v[106:109]
	v_mfma_f32_16x16x32_bf16 v[42:45], v[186:189], v[232:235], 0
	v_mfma_f32_16x16x32_bf16 v[42:45], v[190:193], v[236:239], v[42:45]
	v_mfma_f32_16x16x32_bf16 v[46:49], v[178:181], v[232:235], 0
	v_mfma_f32_16x16x32_bf16 v[46:49], v[182:185], v[236:239], v[46:49]
	v_mfma_f32_16x16x32_bf16 v[38:41], v[178:181], v[240:243], 0
	v_mfma_f32_16x16x32_bf16 v[38:41], v[182:185], v[244:247], v[38:41]
	v_mfma_f32_16x16x32_bf16 v[34:37], v[186:189], v[240:243], 0
	v_mfma_f32_16x16x32_bf16 v[34:37], v[190:193], v[244:247], v[34:37]
	v_mfma_f32_16x16x32_bf16 v[98:101], v[170:173], v[240:243], 0
	v_mfma_f32_16x16x32_bf16 v[98:101], v[174:177], v[244:247], v[98:101]
	v_mfma_f32_16x16x32_bf16 v[102:105], v[142:145], v[240:243], 0
	v_mfma_f32_16x16x32_bf16 v[102:105], v[154:157], v[244:247], v[102:105]
	s_barrier
	s_setprio 0
	s_mov_b32 s70, s62
	s_mov_b32 s71, s63
	s_mov_b32 m0, s21
	ds_read_b128 v[194:197], v140 offset:16384
	buffer_load_dwordx4 v134, s[68:71], s83 offen lds
	s_add_i32 s53, s83, 0x80000
	s_mov_b32 m0, s23
	ds_read_b128 v[198:201], v140 offset:17408
	buffer_load_dwordx4 v136, s[68:71], s83 offen lds
	s_mov_b32 m0, s24
	ds_read_b128 v[202:205], v140 offset:18432
	buffer_load_dwordx4 v134, s[68:71], s53 offen lds
	s_mov_b32 m0, s25
	ds_read_b128 v[228:231], v140 offset:19456
	buffer_load_dwordx4 v136, s[68:71], s53 offen lds
	s_mov_b32 m0, s2
	ds_read_b128 v[232:235], v140 offset:20480
	buffer_load_dwordx4 v131, s[60:63], s52 offen lds
	s_mov_b32 m0, s30
	ds_read_b128 v[236:239], v140 offset:21504
	buffer_load_dwordx4 v135, s[60:63], s52 offen lds
	ds_read_b128 v[240:243], v140 offset:22528
	ds_read_b128 v[244:247], v140 offset:23552
	s_waitcnt vmcnt(8)
	s_waitcnt lgkmcnt(0)
	s_setprio 1
	s_barrier
	v_mfma_f32_16x16x32_bf16 v[94:97], v[142:145], v[194:197], 0
	v_mfma_f32_16x16x32_bf16 v[94:97], v[154:157], v[198:201], v[94:97]
	v_mfma_f32_16x16x32_bf16 v[90:93], v[170:173], v[194:197], 0
	v_mfma_f32_16x16x32_bf16 v[90:93], v[174:177], v[198:201], v[90:93]
	v_mfma_f32_16x16x32_bf16 v[26:29], v[186:189], v[194:197], 0
	v_mfma_f32_16x16x32_bf16 v[26:29], v[190:193], v[198:201], v[26:29]
	v_mfma_f32_16x16x32_bf16 v[30:33], v[178:181], v[194:197], 0
	v_mfma_f32_16x16x32_bf16 v[30:33], v[182:185], v[198:201], v[30:33]
	v_mfma_f32_16x16x32_bf16 v[22:25], v[178:181], v[202:205], 0
	v_mfma_f32_16x16x32_bf16 v[22:25], v[182:185], v[228:231], v[22:25]
	v_mfma_f32_16x16x32_bf16 v[18:21], v[186:189], v[202:205], 0
	v_mfma_f32_16x16x32_bf16 v[18:21], v[190:193], v[228:231], v[18:21]
	v_mfma_f32_16x16x32_bf16 v[82:85], v[170:173], v[202:205], 0
	v_mfma_f32_16x16x32_bf16 v[82:85], v[174:177], v[228:231], v[82:85]
	v_mfma_f32_16x16x32_bf16 v[86:89], v[142:145], v[202:205], 0
	v_mfma_f32_16x16x32_bf16 v[86:89], v[154:157], v[228:231], v[86:89]
	v_mfma_f32_16x16x32_bf16 v[78:81], v[142:145], v[232:235], 0
	v_mfma_f32_16x16x32_bf16 v[78:81], v[154:157], v[236:239], v[78:81]
	v_mfma_f32_16x16x32_bf16 v[74:77], v[170:173], v[232:235], 0
	v_mfma_f32_16x16x32_bf16 v[74:77], v[174:177], v[236:239], v[74:77]
	v_mfma_f32_16x16x32_bf16 v[10:13], v[186:189], v[232:235], 0
	v_mfma_f32_16x16x32_bf16 v[10:13], v[190:193], v[236:239], v[10:13]
	v_mfma_f32_16x16x32_bf16 v[14:17], v[178:181], v[232:235], 0
	v_mfma_f32_16x16x32_bf16 v[14:17], v[182:185], v[236:239], v[14:17]
	v_mfma_f32_16x16x32_bf16 v[6:9], v[178:181], v[240:243], 0
	v_mfma_f32_16x16x32_bf16 v[6:9], v[182:185], v[244:247], v[6:9]
	v_mfma_f32_16x16x32_bf16 v[2:5], v[186:189], v[240:243], 0
	v_mfma_f32_16x16x32_bf16 v[2:5], v[190:193], v[244:247], v[2:5]
	v_mfma_f32_16x16x32_bf16 v[66:69], v[170:173], v[240:243], 0
	v_mfma_f32_16x16x32_bf16 v[66:69], v[174:177], v[244:247], v[66:69]
	v_mfma_f32_16x16x32_bf16 v[70:73], v[142:145], v[240:243], 0
	v_mfma_f32_16x16x32_bf16 v[70:73], v[154:157], v[244:247], v[70:73]
	s_barrier
	s_setprio 0
	v_add_u32_e32 v141, 0x18000, v139
	ds_read_b128 v[142:145], v141
	ds_read_b128 v[154:157], v141 offset:1024
	ds_read_b128 v[170:173], v141 offset:2048
	ds_read_b128 v[174:177], v141 offset:3072
	v_add_u32_e32 v141, 0x1c000, v139
	ds_read_b128 v[178:181], v141
	ds_read_b128 v[182:185], v141 offset:1024
	ds_read_b128 v[186:189], v141 offset:2048
	ds_read_b128 v[190:193], v141 offset:3072
	s_add_i32 s52, s52, 0x80000
	s_mov_b32 m0, s31
	ds_read_b128 v[194:197], v140 offset:32768
	ds_read_b128 v[198:201], v140 offset:33792
	ds_read_b128 v[202:205], v140 offset:34816
	ds_read_b128 v[228:231], v140 offset:35840
	ds_read_b128 v[232:235], v140 offset:36864
	ds_read_b128 v[236:239], v140 offset:37888
	ds_read_b128 v[240:243], v140 offset:38912
	ds_read_b128 v[244:247], v140 offset:39936
	buffer_load_dwordx4 v131, s[60:63], s52 offen lds
	s_mov_b32 m0, s33
	s_nop 0
	buffer_load_dwordx4 v135, s[60:63], s52 offen lds
	s_waitcnt vmcnt(8)
	s_waitcnt lgkmcnt(0)
	s_setprio 1
	s_barrier
	v_mfma_f32_16x16x32_bf16 v[126:129], v[142:145], v[194:197], v[126:129]
	v_mfma_f32_16x16x32_bf16 v[126:129], v[154:157], v[198:201], v[126:129]
	v_mfma_f32_16x16x32_bf16 v[122:125], v[170:173], v[194:197], v[122:125]
	v_mfma_f32_16x16x32_bf16 v[122:125], v[174:177], v[198:201], v[122:125]
	v_mfma_f32_16x16x32_bf16 v[58:61], v[186:189], v[194:197], v[58:61]
	v_mfma_f32_16x16x32_bf16 v[58:61], v[190:193], v[198:201], v[58:61]
	v_mfma_f32_16x16x32_bf16 v[62:65], v[178:181], v[194:197], v[62:65]
	v_mfma_f32_16x16x32_bf16 v[62:65], v[182:185], v[198:201], v[62:65]
	v_mfma_f32_16x16x32_bf16 v[54:57], v[178:181], v[202:205], v[54:57]
	v_mfma_f32_16x16x32_bf16 v[54:57], v[182:185], v[228:231], v[54:57]
	v_mfma_f32_16x16x32_bf16 v[50:53], v[186:189], v[202:205], v[50:53]
	v_mfma_f32_16x16x32_bf16 v[50:53], v[190:193], v[228:231], v[50:53]
	v_mfma_f32_16x16x32_bf16 v[114:117], v[170:173], v[202:205], v[114:117]
	v_mfma_f32_16x16x32_bf16 v[114:117], v[174:177], v[228:231], v[114:117]
	v_mfma_f32_16x16x32_bf16 v[118:121], v[142:145], v[202:205], v[118:121]
	v_mfma_f32_16x16x32_bf16 v[118:121], v[154:157], v[228:231], v[118:121]
	v_mfma_f32_16x16x32_bf16 v[110:113], v[142:145], v[232:235], v[110:113]
	v_mfma_f32_16x16x32_bf16 v[110:113], v[154:157], v[236:239], v[110:113]
	v_mfma_f32_16x16x32_bf16 v[106:109], v[170:173], v[232:235], v[106:109]
	v_mfma_f32_16x16x32_bf16 v[106:109], v[174:177], v[236:239], v[106:109]
	v_mfma_f32_16x16x32_bf16 v[42:45], v[186:189], v[232:235], v[42:45]
	v_mfma_f32_16x16x32_bf16 v[42:45], v[190:193], v[236:239], v[42:45]
	v_mfma_f32_16x16x32_bf16 v[46:49], v[178:181], v[232:235], v[46:49]
	v_mfma_f32_16x16x32_bf16 v[46:49], v[182:185], v[236:239], v[46:49]
	v_mfma_f32_16x16x32_bf16 v[38:41], v[178:181], v[240:243], v[38:41]
	v_mfma_f32_16x16x32_bf16 v[38:41], v[182:185], v[244:247], v[38:41]
	v_mfma_f32_16x16x32_bf16 v[34:37], v[186:189], v[240:243], v[34:37]
	v_mfma_f32_16x16x32_bf16 v[34:37], v[190:193], v[244:247], v[34:37]
	v_mfma_f32_16x16x32_bf16 v[98:101], v[170:173], v[240:243], v[98:101]
	v_mfma_f32_16x16x32_bf16 v[98:101], v[174:177], v[244:247], v[98:101]
	v_mfma_f32_16x16x32_bf16 v[102:105], v[142:145], v[240:243], v[102:105]
	v_mfma_f32_16x16x32_bf16 v[102:105], v[154:157], v[244:247], v[102:105]
	s_barrier
	s_setprio 0
	s_or_b32 s52, s83, 0x80
	s_mov_b32 m0, s34
	ds_read_b128 v[194:197], v140 offset:49152
	buffer_load_dwordx4 v134, s[68:71], s52 offen lds
	s_add_i32 s83, s83, 0x80080
	s_mov_b32 m0, s35
	ds_read_b128 v[198:201], v140 offset:50176
	buffer_load_dwordx4 v136, s[68:71], s52 offen lds
	s_mov_b32 m0, s65
	ds_read_b128 v[202:205], v140 offset:51200
	buffer_load_dwordx4 v134, s[68:71], s83 offen lds
	s_mov_b32 m0, s66
	ds_read_b128 v[228:231], v140 offset:52224
	buffer_load_dwordx4 v136, s[68:71], s83 offen lds
	s_mov_b32 m0, s36
	ds_read_b128 v[232:235], v140 offset:53248
	buffer_load_dwordx4 v131, s[60:63], s27 offen lds
	s_mov_b32 m0, s37
	ds_read_b128 v[236:239], v140 offset:54272
	buffer_load_dwordx4 v135, s[60:63], s27 offen lds
	ds_read_b128 v[240:243], v140 offset:55296
	ds_read_b128 v[244:247], v140 offset:56320
	s_waitcnt vmcnt(8)
	s_waitcnt lgkmcnt(0)
	s_setprio 1
	s_barrier
	v_mfma_f32_16x16x32_bf16 v[94:97], v[142:145], v[194:197], v[94:97]
	v_mfma_f32_16x16x32_bf16 v[94:97], v[154:157], v[198:201], v[94:97]
	v_mfma_f32_16x16x32_bf16 v[90:93], v[170:173], v[194:197], v[90:93]
	v_mfma_f32_16x16x32_bf16 v[90:93], v[174:177], v[198:201], v[90:93]
	v_mfma_f32_16x16x32_bf16 v[26:29], v[186:189], v[194:197], v[26:29]
	v_mfma_f32_16x16x32_bf16 v[26:29], v[190:193], v[198:201], v[26:29]
	v_mfma_f32_16x16x32_bf16 v[30:33], v[178:181], v[194:197], v[30:33]
	v_mfma_f32_16x16x32_bf16 v[30:33], v[182:185], v[198:201], v[30:33]
	v_mfma_f32_16x16x32_bf16 v[22:25], v[178:181], v[202:205], v[22:25]
	v_mfma_f32_16x16x32_bf16 v[22:25], v[182:185], v[228:231], v[22:25]
	v_mfma_f32_16x16x32_bf16 v[18:21], v[186:189], v[202:205], v[18:21]
	v_mfma_f32_16x16x32_bf16 v[18:21], v[190:193], v[228:231], v[18:21]
	v_mfma_f32_16x16x32_bf16 v[82:85], v[170:173], v[202:205], v[82:85]
	v_mfma_f32_16x16x32_bf16 v[82:85], v[174:177], v[228:231], v[82:85]
	v_mfma_f32_16x16x32_bf16 v[86:89], v[142:145], v[202:205], v[86:89]
	v_mfma_f32_16x16x32_bf16 v[86:89], v[154:157], v[228:231], v[86:89]
	v_mfma_f32_16x16x32_bf16 v[78:81], v[142:145], v[232:235], v[78:81]
	v_mfma_f32_16x16x32_bf16 v[78:81], v[154:157], v[236:239], v[78:81]
	v_mfma_f32_16x16x32_bf16 v[74:77], v[170:173], v[232:235], v[74:77]
	v_mfma_f32_16x16x32_bf16 v[74:77], v[174:177], v[236:239], v[74:77]
	v_mfma_f32_16x16x32_bf16 v[10:13], v[186:189], v[232:235], v[10:13]
	v_mfma_f32_16x16x32_bf16 v[10:13], v[190:193], v[236:239], v[10:13]
	v_mfma_f32_16x16x32_bf16 v[14:17], v[178:181], v[232:235], v[14:17]
	v_mfma_f32_16x16x32_bf16 v[14:17], v[182:185], v[236:239], v[14:17]
	v_mfma_f32_16x16x32_bf16 v[6:9], v[178:181], v[240:243], v[6:9]
	v_mfma_f32_16x16x32_bf16 v[6:9], v[182:185], v[244:247], v[6:9]
	v_mfma_f32_16x16x32_bf16 v[2:5], v[186:189], v[240:243], v[2:5]
	v_mfma_f32_16x16x32_bf16 v[2:5], v[190:193], v[244:247], v[2:5]
	v_mfma_f32_16x16x32_bf16 v[66:69], v[170:173], v[240:243], v[66:69]
	v_mfma_f32_16x16x32_bf16 v[66:69], v[174:177], v[244:247], v[66:69]
	v_mfma_f32_16x16x32_bf16 v[70:73], v[142:145], v[240:243], v[70:73]
	v_mfma_f32_16x16x32_bf16 v[70:73], v[154:157], v[244:247], v[70:73]
	s_barrier
	s_setprio 0
	s_add_i32 s26, s26, 2
	s_addk_i32 s19, 0x100
	s_addk_i32 s22, 0x100
	s_cmp_gt_u32 s26, 29

.LBB0_1298:
	s_or_b64 exec, exec, s[8:9]
	s_andn2_b64 vcc, exec, s[40:41]
	s_mov_b64 s[8:9], -1
	s_cbranch_vccnz .LBB0_1279
	s_andn2_b64 vcc, exec, s[42:43]
	s_cbranch_vccnz .LBB0_1278
	s_mov_b32 m0, -1
	s_branch .LBB0_1278

.LBB0_1588:
	s_lshl_b32 s85, s84, 20
	s_and_b64 s[8:9], s[42:43], exec
	s_cselect_b32 s8, s85, s13
	s_lshl_b32 s48, s73, 20
	s_and_b64 s[22:23], s[42:43], exec
	s_cselect_b32 s9, s48, s21
	s_add_i32 s13, s13, 0x80080
	s_addk_i32 s21, 0x100
	s_mov_b32 s22, -2
	s_waitcnt lgkmcnt(0)
	s_cmp_eq_u32 m0, -1
	s_cbranch_scc0 .Lgk_rs_9
	s_barrier
.Lgk_rs_9:
	v_add_u32_e32 v170, 0x10000, v140
	v_add_u32_e32 v186, 0x14000, v140
	ds_read_b128 v[132:135], v170
	ds_read_b128 v[142:145], v170 offset:1024
	ds_read_b128 v[154:157], v170 offset:2048
	ds_read_b128 v[170:173], v170 offset:3072
	ds_read_b128 v[174:177], v186
	ds_read_b128 v[178:181], v186 offset:1024
	ds_read_b128 v[182:185], v186 offset:2048
	ds_read_b128 v[186:189], v186 offset:3072
	s_add_i32 s23, s13, 0xfff80080
	s_cmp_eq_u32 s22, 28
	s_cselect_b32 s27, s8, s23
	s_cselect_b32 s26, s9, s21
	s_or_b32 s23, s27, 0x80
	s_mov_b32 m0, s70
	ds_read_b128 v[190:193], v141
	ds_read_b128 v[194:197], v141 offset:1024
	ds_read_b128 v[198:201], v141 offset:2048
	ds_read_b128 v[202:205], v141 offset:3072
	ds_read_b128 v[228:231], v141 offset:4096
	ds_read_b128 v[232:235], v141 offset:5120
	ds_read_b128 v[236:239], v141 offset:6144
	ds_read_b128 v[240:243], v141 offset:7168
	buffer_load_dwordx4 v136, s[60:63], s13 offen lds
	s_mov_b32 m0, s72
	s_nop 0
	buffer_load_dwordx4 v138, s[60:63], s13 offen lds
	s_waitcnt vmcnt(8)
	s_waitcnt lgkmcnt(0)
	s_setprio 1
	s_barrier
	v_mfma_f32_16x16x32_bf16 v[126:129], v[132:135], v[190:193], 0
	v_mfma_f32_16x16x32_bf16 v[126:129], v[142:145], v[194:197], v[126:129]
	v_mfma_f32_16x16x32_bf16 v[106:109], v[154:157], v[190:193], 0
	v_mfma_f32_16x16x32_bf16 v[106:109], v[170:173], v[194:197], v[106:109]
	v_mfma_f32_16x16x32_bf16 v[110:113], v[182:185], v[190:193], 0
	v_mfma_f32_16x16x32_bf16 v[110:113], v[186:189], v[194:197], v[110:113]
	v_mfma_f32_16x16x32_bf16 v[122:125], v[174:177], v[190:193], 0
	v_mfma_f32_16x16x32_bf16 v[122:125], v[178:181], v[194:197], v[122:125]
	v_mfma_f32_16x16x32_bf16 v[102:105], v[174:177], v[198:201], 0
	v_mfma_f32_16x16x32_bf16 v[102:105], v[178:181], v[202:205], v[102:105]
	v_mfma_f32_16x16x32_bf16 v[98:101], v[182:185], v[198:201], 0
	v_mfma_f32_16x16x32_bf16 v[98:101], v[186:189], v[202:205], v[98:101]
	v_mfma_f32_16x16x32_bf16 v[114:117], v[154:157], v[198:201], 0
	v_mfma_f32_16x16x32_bf16 v[114:117], v[170:173], v[202:205], v[114:117]
	v_mfma_f32_16x16x32_bf16 v[118:121], v[132:135], v[198:201], 0
	v_mfma_f32_16x16x32_bf16 v[118:121], v[142:145], v[202:205], v[118:121]
	v_mfma_f32_16x16x32_bf16 v[94:97], v[132:135], v[228:231], 0
	v_mfma_f32_16x16x32_bf16 v[94:97], v[142:145], v[232:235], v[94:97]
	v_mfma_f32_16x16x32_bf16 v[90:93], v[154:157], v[228:231], 0
	v_mfma_f32_16x16x32_bf16 v[90:93], v[170:173], v[232:235], v[90:93]
	v_mfma_f32_16x16x32_bf16 v[82:85], v[182:185], v[228:231], 0
	v_mfma_f32_16x16x32_bf16 v[82:85], v[186:189], v[232:235], v[82:85]
	v_mfma_f32_16x16x32_bf16 v[86:89], v[174:177], v[228:231], 0
	v_mfma_f32_16x16x32_bf16 v[86:89], v[178:181], v[232:235], v[86:89]
	v_mfma_f32_16x16x32_bf16 v[70:73], v[174:177], v[236:239], 0
	v_mfma_f32_16x16x32_bf16 v[70:73], v[178:181], v[240:243], v[70:73]
	v_mfma_f32_16x16x32_bf16 v[66:69], v[182:185], v[236:239], 0
	v_mfma_f32_16x16x32_bf16 v[66:69], v[186:189], v[240:243], v[66:69]
	v_mfma_f32_16x16x32_bf16 v[74:77], v[154:157], v[236:239], 0
	v_mfma_f32_16x16x32_bf16 v[74:77], v[170:173], v[240:243], v[74:77]
	v_mfma_f32_16x16x32_bf16 v[78:81], v[132:135], v[236:239], 0
	v_mfma_f32_16x16x32_bf16 v[78:81], v[142:145], v[240:243], v[78:81]
	s_barrier
	s_setprio 0
	s_mov_b32 s46, s62
	s_mov_b32 s47, s63
	s_mov_b32 m0, s15
	ds_read_b128 v[190:193], v141 offset:16384
	buffer_load_dwordx4 v137, s[44:47], s26 offen lds
	s_add_i32 s49, s26, 0x80000
	s_mov_b32 m0, s16
	ds_read_b128 v[194:197], v141 offset:17408
	buffer_load_dwordx4 v139, s[44:47], s26 offen lds
	s_mov_b32 m0, s18
	ds_read_b128 v[198:201], v141 offset:18432
	buffer_load_dwordx4 v137, s[44:47], s49 offen lds
	s_mov_b32 m0, s19
	ds_read_b128 v[202:205], v141 offset:19456
	buffer_load_dwordx4 v139, s[44:47], s49 offen lds
	s_mov_b32 m0, s14
	ds_read_b128 v[228:231], v141 offset:20480
	buffer_load_dwordx4 v136, s[60:63], s27 offen lds
	s_mov_b32 m0, s24
	ds_read_b128 v[232:235], v141 offset:21504
	buffer_load_dwordx4 v138, s[60:63], s27 offen lds
	ds_read_b128 v[236:239], v141 offset:22528
	ds_read_b128 v[240:243], v141 offset:23552
	s_waitcnt vmcnt(8)
	s_waitcnt lgkmcnt(0)
	s_setprio 1
	s_barrier
	v_mfma_f32_16x16x32_bf16 v[62:65], v[132:135], v[190:193], 0
	v_mfma_f32_16x16x32_bf16 v[62:65], v[142:145], v[194:197], v[62:65]
	v_mfma_f32_16x16x32_bf16 v[58:61], v[154:157], v[190:193], 0
	v_mfma_f32_16x16x32_bf16 v[58:61], v[170:173], v[194:197], v[58:61]
	v_mfma_f32_16x16x32_bf16 v[50:53], v[182:185], v[190:193], 0
	v_mfma_f32_16x16x32_bf16 v[50:53], v[186:189], v[194:197], v[50:53]
	v_mfma_f32_16x16x32_bf16 v[54:57], v[174:177], v[190:193], 0
	v_mfma_f32_16x16x32_bf16 v[54:57], v[178:181], v[194:197], v[54:57]
	v_mfma_f32_16x16x32_bf16 v[38:41], v[174:177], v[198:201], 0
	v_mfma_f32_16x16x32_bf16 v[38:41], v[178:181], v[202:205], v[38:41]
	v_mfma_f32_16x16x32_bf16 v[34:37], v[182:185], v[198:201], 0
	v_mfma_f32_16x16x32_bf16 v[34:37], v[186:189], v[202:205], v[34:37]
	v_mfma_f32_16x16x32_bf16 v[42:45], v[154:157], v[198:201], 0
	v_mfma_f32_16x16x32_bf16 v[42:45], v[170:173], v[202:205], v[42:45]
	v_mfma_f32_16x16x32_bf16 v[46:49], v[132:135], v[198:201], 0
	v_mfma_f32_16x16x32_bf16 v[46:49], v[142:145], v[202:205], v[46:49]
	v_mfma_f32_16x16x32_bf16 v[30:33], v[132:135], v[228:231], 0
	v_mfma_f32_16x16x32_bf16 v[30:33], v[142:145], v[232:235], v[30:33]
	v_mfma_f32_16x16x32_bf16 v[26:29], v[154:157], v[228:231], 0
	v_mfma_f32_16x16x32_bf16 v[26:29], v[170:173], v[232:235], v[26:29]
	v_mfma_f32_16x16x32_bf16 v[18:21], v[182:185], v[228:231], 0
	v_mfma_f32_16x16x32_bf16 v[18:21], v[186:189], v[232:235], v[18:21]
	v_mfma_f32_16x16x32_bf16 v[22:25], v[174:177], v[228:231], 0
	v_mfma_f32_16x16x32_bf16 v[22:25], v[178:181], v[232:235], v[22:25]
	v_mfma_f32_16x16x32_bf16 v[6:9], v[174:177], v[236:239], 0
	v_mfma_f32_16x16x32_bf16 v[6:9], v[178:181], v[240:243], v[6:9]
	v_mfma_f32_16x16x32_bf16 v[2:5], v[182:185], v[236:239], 0
	v_mfma_f32_16x16x32_bf16 v[2:5], v[186:189], v[240:243], v[2:5]
	v_mfma_f32_16x16x32_bf16 v[10:13], v[154:157], v[236:239], 0
	v_mfma_f32_16x16x32_bf16 v[10:13], v[170:173], v[240:243], v[10:13]
	v_mfma_f32_16x16x32_bf16 v[14:17], v[132:135], v[236:239], 0
	v_mfma_f32_16x16x32_bf16 v[14:17], v[142:145], v[240:243], v[14:17]
	s_barrier
	s_setprio 0
	v_add_u32_e32 v170, 0x18000, v140
	v_add_u32_e32 v186, 0x1c000, v140
	ds_read_b128 v[132:135], v170
	ds_read_b128 v[142:145], v170 offset:1024
	ds_read_b128 v[154:157], v170 offset:2048
	ds_read_b128 v[170:173], v170 offset:3072
	ds_read_b128 v[174:177], v186
	ds_read_b128 v[178:181], v186 offset:1024
	ds_read_b128 v[182:185], v186 offset:2048
	ds_read_b128 v[186:189], v186 offset:3072
	s_add_i32 s27, s27, 0x80000
	s_mov_b32 m0, s25
	ds_read_b128 v[190:193], v141 offset:32768
	ds_read_b128 v[194:197], v141 offset:33792
	ds_read_b128 v[198:201], v141 offset:34816
	ds_read_b128 v[202:205], v141 offset:35840
	ds_read_b128 v[228:231], v141 offset:36864
	ds_read_b128 v[232:235], v141 offset:37888
	ds_read_b128 v[236:239], v141 offset:38912
	ds_read_b128 v[240:243], v141 offset:39936
	buffer_load_dwordx4 v136, s[60:63], s27 offen lds
	s_mov_b32 m0, s30
	s_nop 0
	buffer_load_dwordx4 v138, s[60:63], s27 offen lds
	s_waitcnt vmcnt(8)
	s_waitcnt lgkmcnt(0)
	s_setprio 1
	s_barrier
	v_mfma_f32_16x16x32_bf16 v[126:129], v[132:135], v[190:193], v[126:129]
	v_mfma_f32_16x16x32_bf16 v[126:129], v[142:145], v[194:197], v[126:129]
	v_mfma_f32_16x16x32_bf16 v[106:109], v[154:157], v[190:193], v[106:109]
	v_mfma_f32_16x16x32_bf16 v[106:109], v[170:173], v[194:197], v[106:109]
	v_mfma_f32_16x16x32_bf16 v[110:113], v[182:185], v[190:193], v[110:113]
	v_mfma_f32_16x16x32_bf16 v[110:113], v[186:189], v[194:197], v[110:113]
	v_mfma_f32_16x16x32_bf16 v[122:125], v[174:177], v[190:193], v[122:125]
	v_mfma_f32_16x16x32_bf16 v[122:125], v[178:181], v[194:197], v[122:125]
	v_mfma_f32_16x16x32_bf16 v[102:105], v[174:177], v[198:201], v[102:105]
	v_mfma_f32_16x16x32_bf16 v[102:105], v[178:181], v[202:205], v[102:105]
	v_mfma_f32_16x16x32_bf16 v[98:101], v[182:185], v[198:201], v[98:101]
	v_mfma_f32_16x16x32_bf16 v[98:101], v[186:189], v[202:205], v[98:101]
	v_mfma_f32_16x16x32_bf16 v[114:117], v[154:157], v[198:201], v[114:117]
	v_mfma_f32_16x16x32_bf16 v[114:117], v[170:173], v[202:205], v[114:117]
	v_mfma_f32_16x16x32_bf16 v[118:121], v[132:135], v[198:201], v[118:121]
	v_mfma_f32_16x16x32_bf16 v[118:121], v[142:145], v[202:205], v[118:121]
	v_mfma_f32_16x16x32_bf16 v[94:97], v[132:135], v[228:231], v[94:97]
	v_mfma_f32_16x16x32_bf16 v[94:97], v[142:145], v[232:235], v[94:97]
	v_mfma_f32_16x16x32_bf16 v[90:93], v[154:157], v[228:231], v[90:93]
	v_mfma_f32_16x16x32_bf16 v[90:93], v[170:173], v[232:235], v[90:93]
	v_mfma_f32_16x16x32_bf16 v[82:85], v[182:185], v[228:231], v[82:85]
	v_mfma_f32_16x16x32_bf16 v[82:85], v[186:189], v[232:235], v[82:85]
	v_mfma_f32_16x16x32_bf16 v[86:89], v[174:177], v[228:231], v[86:89]
	v_mfma_f32_16x16x32_bf16 v[86:89], v[178:181], v[232:235], v[86:89]
	v_mfma_f32_16x16x32_bf16 v[70:73], v[174:177], v[236:239], v[70:73]
	v_mfma_f32_16x16x32_bf16 v[70:73], v[178:181], v[240:243], v[70:73]
	v_mfma_f32_16x16x32_bf16 v[66:69], v[182:185], v[236:239], v[66:69]
	v_mfma_f32_16x16x32_bf16 v[66:69], v[186:189], v[240:243], v[66:69]
	v_mfma_f32_16x16x32_bf16 v[74:77], v[154:157], v[236:239], v[74:77]
	v_mfma_f32_16x16x32_bf16 v[74:77], v[170:173], v[240:243], v[74:77]
	v_mfma_f32_16x16x32_bf16 v[78:81], v[132:135], v[236:239], v[78:81]
	v_mfma_f32_16x16x32_bf16 v[78:81], v[142:145], v[240:243], v[78:81]
	s_barrier
	s_setprio 0
	s_or_b32 s27, s26, 0x80
	s_mov_b32 m0, s36
	ds_read_b128 v[190:193], v141 offset:49152
	buffer_load_dwordx4 v137, s[44:47], s27 offen lds
	s_add_i32 s26, s26, 0x80080
	s_mov_b32 m0, s37
	ds_read_b128 v[194:197], v141 offset:50176
	buffer_load_dwordx4 v139, s[44:47], s27 offen lds
	s_mov_b32 m0, s68
	ds_read_b128 v[198:201], v141 offset:51200
	buffer_load_dwordx4 v137, s[44:47], s26 offen lds
	s_mov_b32 m0, s69
	ds_read_b128 v[202:205], v141 offset:52224
	buffer_load_dwordx4 v139, s[44:47], s26 offen lds
	s_mov_b32 m0, s66
	ds_read_b128 v[228:231], v141 offset:53248
	buffer_load_dwordx4 v136, s[60:63], s23 offen lds
	s_mov_b32 m0, s67
	ds_read_b128 v[232:235], v141 offset:54272
	buffer_load_dwordx4 v138, s[60:63], s23 offen lds
	ds_read_b128 v[236:239], v141 offset:55296
	ds_read_b128 v[240:243], v141 offset:56320
	s_waitcnt vmcnt(8)
	s_waitcnt lgkmcnt(0)
	s_setprio 1
	s_barrier
	v_mfma_f32_16x16x32_bf16 v[62:65], v[132:135], v[190:193], v[62:65]
	v_mfma_f32_16x16x32_bf16 v[62:65], v[142:145], v[194:197], v[62:65]
	v_mfma_f32_16x16x32_bf16 v[58:61], v[154:157], v[190:193], v[58:61]
	v_mfma_f32_16x16x32_bf16 v[58:61], v[170:173], v[194:197], v[58:61]
	v_mfma_f32_16x16x32_bf16 v[50:53], v[182:185], v[190:193], v[50:53]
	v_mfma_f32_16x16x32_bf16 v[50:53], v[186:189], v[194:197], v[50:53]
	v_mfma_f32_16x16x32_bf16 v[54:57], v[174:177], v[190:193], v[54:57]
	v_mfma_f32_16x16x32_bf16 v[54:57], v[178:181], v[194:197], v[54:57]
	v_mfma_f32_16x16x32_bf16 v[38:41], v[174:177], v[198:201], v[38:41]
	v_mfma_f32_16x16x32_bf16 v[38:41], v[178:181], v[202:205], v[38:41]
	v_mfma_f32_16x16x32_bf16 v[34:37], v[182:185], v[198:201], v[34:37]
	v_mfma_f32_16x16x32_bf16 v[34:37], v[186:189], v[202:205], v[34:37]
	v_mfma_f32_16x16x32_bf16 v[42:45], v[154:157], v[198:201], v[42:45]
	v_mfma_f32_16x16x32_bf16 v[42:45], v[170:173], v[202:205], v[42:45]
	v_mfma_f32_16x16x32_bf16 v[46:49], v[132:135], v[198:201], v[46:49]
	v_mfma_f32_16x16x32_bf16 v[46:49], v[142:145], v[202:205], v[46:49]
	v_mfma_f32_16x16x32_bf16 v[30:33], v[132:135], v[228:231], v[30:33]
	v_mfma_f32_16x16x32_bf16 v[30:33], v[142:145], v[232:235], v[30:33]
	v_mfma_f32_16x16x32_bf16 v[26:29], v[154:157], v[228:231], v[26:29]
	v_mfma_f32_16x16x32_bf16 v[26:29], v[170:173], v[232:235], v[26:29]
	v_mfma_f32_16x16x32_bf16 v[18:21], v[182:185], v[228:231], v[18:21]
	v_mfma_f32_16x16x32_bf16 v[18:21], v[186:189], v[232:235], v[18:21]
	v_mfma_f32_16x16x32_bf16 v[22:25], v[174:177], v[228:231], v[22:25]
	v_mfma_f32_16x16x32_bf16 v[22:25], v[178:181], v[232:235], v[22:25]
	v_mfma_f32_16x16x32_bf16 v[6:9], v[174:177], v[236:239], v[6:9]
	v_mfma_f32_16x16x32_bf16 v[6:9], v[178:181], v[240:243], v[6:9]
	v_mfma_f32_16x16x32_bf16 v[2:5], v[182:185], v[236:239], v[2:5]
	v_mfma_f32_16x16x32_bf16 v[2:5], v[186:189], v[240:243], v[2:5]
	v_mfma_f32_16x16x32_bf16 v[10:13], v[154:157], v[236:239], v[10:13]
	v_mfma_f32_16x16x32_bf16 v[10:13], v[170:173], v[240:243], v[10:13]
	v_mfma_f32_16x16x32_bf16 v[14:17], v[132:135], v[236:239], v[14:17]
	v_mfma_f32_16x16x32_bf16 v[14:17], v[142:145], v[240:243], v[14:17]
	s_barrier
	s_setprio 0
	s_add_i32 s22, s22, 2
	s_addk_i32 s13, 0x100
	s_addk_i32 s21, 0x100
	s_cmp_gt_u32 s22, 29

.LBB0_1879:
	s_lshl_b32 s18, s91, 20
	s_and_b64 s[8:9], s[48:49], exec
	s_cselect_b32 s8, s18, s95
	s_lshl_b32 s19, s92, 20
	s_and_b64 s[42:43], s[48:49], exec
	s_cselect_b32 s9, s19, s94
	s_add_i32 vcc_lo, s95, 0x80080
	s_add_i32 vcc_hi, s94, 0x100
	s_mov_b32 s94, -2
	s_cmp_eq_u32 m0, -1
	s_cbranch_scc0 .Lgk_rs_10
	s_barrier
.Lgk_rs_10:
	v_add_u32_e32 v139, 0x10000, v136
	ds_read_b128 v[140:143], v139
	ds_read_b128 v[154:157], v139 offset:1024
	ds_read_b128 v[170:173], v139 offset:2048
	ds_read_b128 v[174:177], v139 offset:3072
	v_add_u32_e32 v139, 0x14000, v136
	ds_read_b128 v[178:181], v139
	ds_read_b128 v[182:185], v139 offset:1024
	ds_read_b128 v[186:189], v139 offset:2048
	ds_read_b128 v[190:193], v139 offset:3072
	s_add_i32 s42, vcc_lo, 0xfff80080
	s_cmp_eq_u32 s94, 28
	s_cselect_b32 s52, s8, s42
	s_cselect_b32 s96, s9, vcc_hi
	s_or_b32 s95, s52, 0x80
	s_mov_b32 m0, s72
	ds_read_b128 v[194:197], v137
	ds_read_b128 v[198:201], v137 offset:1024
	ds_read_b128 v[202:205], v137 offset:2048
	ds_read_b128 v[228:231], v137 offset:3072
	ds_read_b128 v[232:235], v137 offset:4096
	ds_read_b128 v[236:239], v137 offset:5120
	ds_read_b128 v[240:243], v137 offset:6144
	ds_read_b128 v[244:247], v137 offset:7168
	buffer_load_dwordx4 v132, s[60:63], vcc_lo offen lds
	s_mov_b32 m0, s47
	s_nop 0
	buffer_load_dwordx4 v134, s[60:63], vcc_lo offen lds
	s_waitcnt vmcnt(8)
	s_waitcnt lgkmcnt(0)
	s_setprio 1
	s_barrier
	v_mfma_f32_16x16x32_bf16 v[114:117], v[140:143], v[194:197], 0
	v_mfma_f32_16x16x32_bf16 v[114:117], v[154:157], v[198:201], v[114:117]
	v_mfma_f32_16x16x32_bf16 v[110:113], v[170:173], v[194:197], 0
	v_mfma_f32_16x16x32_bf16 v[110:113], v[174:177], v[198:201], v[110:113]
	v_mfma_f32_16x16x32_bf16 v[122:125], v[186:189], v[194:197], 0
	v_mfma_f32_16x16x32_bf16 v[122:125], v[190:193], v[198:201], v[122:125]
	v_mfma_f32_16x16x32_bf16 v[126:129], v[178:181], v[194:197], 0
	v_mfma_f32_16x16x32_bf16 v[126:129], v[182:185], v[198:201], v[126:129]
	v_mfma_f32_16x16x32_bf16 v[118:121], v[178:181], v[202:205], 0
	v_mfma_f32_16x16x32_bf16 v[118:121], v[182:185], v[228:231], v[118:121]
	v_mfma_f32_16x16x32_bf16 v[98:101], v[186:189], v[202:205], 0
	v_mfma_f32_16x16x32_bf16 v[98:101], v[190:193], v[228:231], v[98:101]
	v_mfma_f32_16x16x32_bf16 v[102:105], v[170:173], v[202:205], 0
	v_mfma_f32_16x16x32_bf16 v[102:105], v[174:177], v[228:231], v[102:105]
	v_mfma_f32_16x16x32_bf16 v[106:109], v[140:143], v[202:205], 0
	v_mfma_f32_16x16x32_bf16 v[106:109], v[154:157], v[228:231], v[106:109]
	v_mfma_f32_16x16x32_bf16 v[94:97], v[140:143], v[232:235], 0
	v_mfma_f32_16x16x32_bf16 v[94:97], v[154:157], v[236:239], v[94:97]
	v_mfma_f32_16x16x32_bf16 v[86:89], v[170:173], v[232:235], 0
	v_mfma_f32_16x16x32_bf16 v[86:89], v[174:177], v[236:239], v[86:89]
	v_mfma_f32_16x16x32_bf16 v[82:85], v[186:189], v[232:235], 0
	v_mfma_f32_16x16x32_bf16 v[82:85], v[190:193], v[236:239], v[82:85]
	v_mfma_f32_16x16x32_bf16 v[90:93], v[178:181], v[232:235], 0
	v_mfma_f32_16x16x32_bf16 v[90:93], v[182:185], v[236:239], v[90:93]
	v_mfma_f32_16x16x32_bf16 v[74:77], v[178:181], v[240:243], 0
	v_mfma_f32_16x16x32_bf16 v[74:77], v[182:185], v[244:247], v[74:77]
	v_mfma_f32_16x16x32_bf16 v[66:69], v[186:189], v[240:243], 0
	v_mfma_f32_16x16x32_bf16 v[66:69], v[190:193], v[244:247], v[66:69]
	v_mfma_f32_16x16x32_bf16 v[70:73], v[170:173], v[240:243], 0
	v_mfma_f32_16x16x32_bf16 v[70:73], v[174:177], v[244:247], v[70:73]
	v_mfma_f32_16x16x32_bf16 v[78:81], v[140:143], v[240:243], 0
	v_mfma_f32_16x16x32_bf16 v[78:81], v[154:157], v[244:247], v[78:81]
	s_barrier
	s_setprio 0
	s_mov_b32 s42, s62
	s_mov_b32 s43, s63
	s_mov_b32 m0, s13
	ds_read_b128 v[194:197], v137 offset:16384
	buffer_load_dwordx4 v133, s[40:43], s96 offen lds
	s_add_i32 s53, s96, 0x80000
	s_mov_b32 m0, s14
	ds_read_b128 v[198:201], v137 offset:17408
	buffer_load_dwordx4 v135, s[40:43], s96 offen lds
	s_mov_b32 m0, s15
	ds_read_b128 v[202:205], v137 offset:18432
	buffer_load_dwordx4 v133, s[40:43], s53 offen lds
	s_mov_b32 m0, s16
	ds_read_b128 v[228:231], v137 offset:19456
	buffer_load_dwordx4 v135, s[40:43], s53 offen lds
	s_mov_b32 m0, s2
	ds_read_b128 v[232:235], v137 offset:20480
	buffer_load_dwordx4 v132, s[60:63], s52 offen lds
	s_mov_b32 m0, s21
	ds_read_b128 v[236:239], v137 offset:21504
	buffer_load_dwordx4 v134, s[60:63], s52 offen lds
	ds_read_b128 v[240:243], v137 offset:22528
	ds_read_b128 v[244:247], v137 offset:23552
	s_waitcnt vmcnt(8)
	s_waitcnt lgkmcnt(0)
	s_setprio 1
	s_barrier
	v_mfma_f32_16x16x32_bf16 v[62:65], v[140:143], v[194:197], 0
	v_mfma_f32_16x16x32_bf16 v[62:65], v[154:157], v[198:201], v[62:65]
	v_mfma_f32_16x16x32_bf16 v[54:57], v[170:173], v[194:197], 0
	v_mfma_f32_16x16x32_bf16 v[54:57], v[174:177], v[198:201], v[54:57]
	v_mfma_f32_16x16x32_bf16 v[50:53], v[186:189], v[194:197], 0
	v_mfma_f32_16x16x32_bf16 v[50:53], v[190:193], v[198:201], v[50:53]
	v_mfma_f32_16x16x32_bf16 v[58:61], v[178:181], v[194:197], 0
	v_mfma_f32_16x16x32_bf16 v[58:61], v[182:185], v[198:201], v[58:61]
	v_mfma_f32_16x16x32_bf16 v[42:45], v[178:181], v[202:205], 0
	v_mfma_f32_16x16x32_bf16 v[42:45], v[182:185], v[228:231], v[42:45]
	v_mfma_f32_16x16x32_bf16 v[34:37], v[186:189], v[202:205], 0
	v_mfma_f32_16x16x32_bf16 v[34:37], v[190:193], v[228:231], v[34:37]
	v_mfma_f32_16x16x32_bf16 v[38:41], v[170:173], v[202:205], 0
	v_mfma_f32_16x16x32_bf16 v[38:41], v[174:177], v[228:231], v[38:41]
	v_mfma_f32_16x16x32_bf16 v[46:49], v[140:143], v[202:205], 0
	v_mfma_f32_16x16x32_bf16 v[46:49], v[154:157], v[228:231], v[46:49]
	v_mfma_f32_16x16x32_bf16 v[30:33], v[140:143], v[232:235], 0
	v_mfma_f32_16x16x32_bf16 v[30:33], v[154:157], v[236:239], v[30:33]
	v_mfma_f32_16x16x32_bf16 v[22:25], v[170:173], v[232:235], 0
	v_mfma_f32_16x16x32_bf16 v[22:25], v[174:177], v[236:239], v[22:25]
	v_mfma_f32_16x16x32_bf16 v[18:21], v[186:189], v[232:235], 0
	v_mfma_f32_16x16x32_bf16 v[18:21], v[190:193], v[236:239], v[18:21]
	v_mfma_f32_16x16x32_bf16 v[26:29], v[178:181], v[232:235], 0
	v_mfma_f32_16x16x32_bf16 v[26:29], v[182:185], v[236:239], v[26:29]
	v_mfma_f32_16x16x32_bf16 v[10:13], v[178:181], v[240:243], 0
	v_mfma_f32_16x16x32_bf16 v[10:13], v[182:185], v[244:247], v[10:13]
	v_mfma_f32_16x16x32_bf16 v[2:5], v[186:189], v[240:243], 0
	v_mfma_f32_16x16x32_bf16 v[2:5], v[190:193], v[244:247], v[2:5]
	v_mfma_f32_16x16x32_bf16 v[6:9], v[170:173], v[240:243], 0
	v_mfma_f32_16x16x32_bf16 v[6:9], v[174:177], v[244:247], v[6:9]
	v_mfma_f32_16x16x32_bf16 v[14:17], v[140:143], v[240:243], 0
	v_mfma_f32_16x16x32_bf16 v[14:17], v[154:157], v[244:247], v[14:17]
	s_barrier
	s_setprio 0
	v_add_u32_e32 v139, 0x18000, v136
	ds_read_b128 v[140:143], v139
	ds_read_b128 v[154:157], v139 offset:1024
	ds_read_b128 v[170:173], v139 offset:2048
	ds_read_b128 v[174:177], v139 offset:3072
	v_add_u32_e32 v139, 0x1c000, v136
	ds_read_b128 v[178:181], v139
	ds_read_b128 v[182:185], v139 offset:1024
	ds_read_b128 v[186:189], v139 offset:2048
	ds_read_b128 v[190:193], v139 offset:3072
	s_add_i32 s52, s52, 0x80000
	s_mov_b32 m0, s23
	ds_read_b128 v[194:197], v137 offset:32768
	ds_read_b128 v[198:201], v137 offset:33792
	ds_read_b128 v[202:205], v137 offset:34816
	ds_read_b128 v[228:231], v137 offset:35840
	ds_read_b128 v[232:235], v137 offset:36864
	ds_read_b128 v[236:239], v137 offset:37888
	ds_read_b128 v[240:243], v137 offset:38912
	ds_read_b128 v[244:247], v137 offset:39936
	buffer_load_dwordx4 v132, s[60:63], s52 offen lds
	s_mov_b32 m0, s24
	s_nop 0
	buffer_load_dwordx4 v134, s[60:63], s52 offen lds
	s_waitcnt vmcnt(8)
	s_waitcnt lgkmcnt(0)
	s_setprio 1
	s_barrier
	v_mfma_f32_16x16x32_bf16 v[114:117], v[140:143], v[194:197], v[114:117]
	v_mfma_f32_16x16x32_bf16 v[114:117], v[154:157], v[198:201], v[114:117]
	v_mfma_f32_16x16x32_bf16 v[110:113], v[170:173], v[194:197], v[110:113]
	v_mfma_f32_16x16x32_bf16 v[110:113], v[174:177], v[198:201], v[110:113]
	v_mfma_f32_16x16x32_bf16 v[122:125], v[186:189], v[194:197], v[122:125]
	v_mfma_f32_16x16x32_bf16 v[122:125], v[190:193], v[198:201], v[122:125]
	v_mfma_f32_16x16x32_bf16 v[126:129], v[178:181], v[194:197], v[126:129]
	v_mfma_f32_16x16x32_bf16 v[126:129], v[182:185], v[198:201], v[126:129]
	v_mfma_f32_16x16x32_bf16 v[118:121], v[178:181], v[202:205], v[118:121]
	v_mfma_f32_16x16x32_bf16 v[118:121], v[182:185], v[228:231], v[118:121]
	v_mfma_f32_16x16x32_bf16 v[98:101], v[186:189], v[202:205], v[98:101]
	v_mfma_f32_16x16x32_bf16 v[98:101], v[190:193], v[228:231], v[98:101]
	v_mfma_f32_16x16x32_bf16 v[102:105], v[170:173], v[202:205], v[102:105]
	v_mfma_f32_16x16x32_bf16 v[102:105], v[174:177], v[228:231], v[102:105]
	v_mfma_f32_16x16x32_bf16 v[106:109], v[140:143], v[202:205], v[106:109]
	v_mfma_f32_16x16x32_bf16 v[106:109], v[154:157], v[228:231], v[106:109]
	v_mfma_f32_16x16x32_bf16 v[94:97], v[140:143], v[232:235], v[94:97]
	v_mfma_f32_16x16x32_bf16 v[94:97], v[154:157], v[236:239], v[94:97]
	v_mfma_f32_16x16x32_bf16 v[86:89], v[170:173], v[232:235], v[86:89]
	v_mfma_f32_16x16x32_bf16 v[86:89], v[174:177], v[236:239], v[86:89]
	v_mfma_f32_16x16x32_bf16 v[82:85], v[186:189], v[232:235], v[82:85]
	v_mfma_f32_16x16x32_bf16 v[82:85], v[190:193], v[236:239], v[82:85]
	v_mfma_f32_16x16x32_bf16 v[90:93], v[178:181], v[232:235], v[90:93]
	v_mfma_f32_16x16x32_bf16 v[90:93], v[182:185], v[236:239], v[90:93]
	v_mfma_f32_16x16x32_bf16 v[74:77], v[178:181], v[240:243], v[74:77]
	v_mfma_f32_16x16x32_bf16 v[74:77], v[182:185], v[244:247], v[74:77]
	v_mfma_f32_16x16x32_bf16 v[66:69], v[186:189], v[240:243], v[66:69]
	v_mfma_f32_16x16x32_bf16 v[66:69], v[190:193], v[244:247], v[66:69]
	v_mfma_f32_16x16x32_bf16 v[70:73], v[170:173], v[240:243], v[70:73]
	v_mfma_f32_16x16x32_bf16 v[70:73], v[174:177], v[244:247], v[70:73]
	v_mfma_f32_16x16x32_bf16 v[78:81], v[140:143], v[240:243], v[78:81]
	v_mfma_f32_16x16x32_bf16 v[78:81], v[154:157], v[244:247], v[78:81]
	s_barrier
	s_setprio 0
	s_or_b32 s52, s96, 0x80
	s_mov_b32 m0, s31
	ds_read_b128 v[194:197], v137 offset:49152
	buffer_load_dwordx4 v133, s[40:43], s52 offen lds
	s_add_i32 s96, s96, 0x80080
	s_mov_b32 m0, s33
	ds_read_b128 v[198:201], v137 offset:50176
	buffer_load_dwordx4 v135, s[40:43], s52 offen lds
	s_mov_b32 m0, s36
	ds_read_b128 v[202:205], v137 offset:51200
	buffer_load_dwordx4 v133, s[40:43], s96 offen lds
	s_mov_b32 m0, s37
	ds_read_b128 v[228:231], v137 offset:52224
	buffer_load_dwordx4 v135, s[40:43], s96 offen lds
	s_mov_b32 m0, s34
	ds_read_b128 v[232:235], v137 offset:53248
	buffer_load_dwordx4 v132, s[60:63], s95 offen lds
	s_mov_b32 m0, s35
	ds_read_b128 v[236:239], v137 offset:54272
	buffer_load_dwordx4 v134, s[60:63], s95 offen lds
	ds_read_b128 v[240:243], v137 offset:55296
	ds_read_b128 v[244:247], v137 offset:56320
	s_waitcnt vmcnt(8)
	s_waitcnt lgkmcnt(0)
	s_setprio 1
	s_barrier
	v_mfma_f32_16x16x32_bf16 v[62:65], v[140:143], v[194:197], v[62:65]
	v_mfma_f32_16x16x32_bf16 v[62:65], v[154:157], v[198:201], v[62:65]
	v_mfma_f32_16x16x32_bf16 v[54:57], v[170:173], v[194:197], v[54:57]
	v_mfma_f32_16x16x32_bf16 v[54:57], v[174:177], v[198:201], v[54:57]
	v_mfma_f32_16x16x32_bf16 v[50:53], v[186:189], v[194:197], v[50:53]
	v_mfma_f32_16x16x32_bf16 v[50:53], v[190:193], v[198:201], v[50:53]
	v_mfma_f32_16x16x32_bf16 v[58:61], v[178:181], v[194:197], v[58:61]
	v_mfma_f32_16x16x32_bf16 v[58:61], v[182:185], v[198:201], v[58:61]
	v_mfma_f32_16x16x32_bf16 v[42:45], v[178:181], v[202:205], v[42:45]
	v_mfma_f32_16x16x32_bf16 v[42:45], v[182:185], v[228:231], v[42:45]
	v_mfma_f32_16x16x32_bf16 v[34:37], v[186:189], v[202:205], v[34:37]
	v_mfma_f32_16x16x32_bf16 v[34:37], v[190:193], v[228:231], v[34:37]
	v_mfma_f32_16x16x32_bf16 v[38:41], v[170:173], v[202:205], v[38:41]
	v_mfma_f32_16x16x32_bf16 v[38:41], v[174:177], v[228:231], v[38:41]
	v_mfma_f32_16x16x32_bf16 v[46:49], v[140:143], v[202:205], v[46:49]
	v_mfma_f32_16x16x32_bf16 v[46:49], v[154:157], v[228:231], v[46:49]
	v_mfma_f32_16x16x32_bf16 v[30:33], v[140:143], v[232:235], v[30:33]
	v_mfma_f32_16x16x32_bf16 v[30:33], v[154:157], v[236:239], v[30:33]
	v_mfma_f32_16x16x32_bf16 v[22:25], v[170:173], v[232:235], v[22:25]
	v_mfma_f32_16x16x32_bf16 v[22:25], v[174:177], v[236:239], v[22:25]
	v_mfma_f32_16x16x32_bf16 v[18:21], v[186:189], v[232:235], v[18:21]
	v_mfma_f32_16x16x32_bf16 v[18:21], v[190:193], v[236:239], v[18:21]
	v_mfma_f32_16x16x32_bf16 v[26:29], v[178:181], v[232:235], v[26:29]
	v_mfma_f32_16x16x32_bf16 v[26:29], v[182:185], v[236:239], v[26:29]
	v_mfma_f32_16x16x32_bf16 v[10:13], v[178:181], v[240:243], v[10:13]
	v_mfma_f32_16x16x32_bf16 v[10:13], v[182:185], v[244:247], v[10:13]
	v_mfma_f32_16x16x32_bf16 v[2:5], v[186:189], v[240:243], v[2:5]
	v_mfma_f32_16x16x32_bf16 v[2:5], v[190:193], v[244:247], v[2:5]
	v_mfma_f32_16x16x32_bf16 v[6:9], v[170:173], v[240:243], v[6:9]
	v_mfma_f32_16x16x32_bf16 v[6:9], v[174:177], v[244:247], v[6:9]
	v_mfma_f32_16x16x32_bf16 v[14:17], v[140:143], v[240:243], v[14:17]
	v_mfma_f32_16x16x32_bf16 v[14:17], v[154:157], v[244:247], v[14:17]
	s_barrier
	s_setprio 0
	s_add_i32 s94, s94, 2
	s_addk_i32 vcc_lo, 0x100
	s_addk_i32 vcc_hi, 0x100
	s_cmp_gt_u32 s94, 29

.LBB0_1883:
	s_lshl_b32 s8, s93, 8
	s_add_i32 s8, s8, s46
	s_ashr_i32 s9, s8, 31
	v_lshl_add_u64 v[140:141], s[8:9], 3, v[130:131]
	global_load_dwordx2 v[142:143], v[140:141], off
	global_load_dwordx2 v[144:145], v[140:141], off offset:128
	v_pk_mul_f32 v[154:155], v[114:115], v[126:127]
	v_pk_mul_f32 v[156:157], v[112:113], v[124:125]
	v_pk_mul_f32 v[170:171], v[110:111], v[122:123]
	v_pk_mul_f32 v[172:173], v[108:109], v[120:121]
	v_pk_mul_f32 v[174:175], v[106:107], v[118:119]
	global_load_dwordx2 v[176:177], v[140:141], off offset:256
	global_load_dwordx2 v[126:127], v[140:141], off offset:384
	global_load_dwordx2 v[124:125], v[140:141], off offset:1024
	global_load_dwordx2 v[122:123], v[140:141], off offset:1152
	global_load_dwordx2 v[120:121], v[140:141], off offset:1280
	global_load_dwordx2 v[118:119], v[140:141], off offset:1408
	s_flbit_i32_b32 s8, 0
	s_min_u32 s42, s8, 32
	s_mul_i32 s8, s93, 0x58
	s_sub_i32 s93, 32, s42
	v_pk_mul_f32 v[128:129], v[116:117], v[128:129]
	s_lshl_b32 s9, s90, 1
	s_or_b32 s9, s9, s73
	s_add_i32 s8, s9, s8
	s_ashr_i32 s9, s8, 31
	s_lshl_b64 s[8:9], s[8:9], 15
	s_add_u32 s43, s25, s8
	s_addc_u32 s90, s30, s9
	s_add_u32 s8, s43, s66
	s_addc_u32 s9, s90, s67
	s_add_u32 s8, s8, s88
	s_addc_u32 s9, s9, 0
	v_pk_mul_f32 v[98:99], v[102:103], v[98:99]
	v_pk_mul_f32 v[100:101], v[104:105], v[100:101]
	v_pk_mul_f32 v[90:91], v[94:95], v[90:91]
	v_pk_mul_f32 v[92:93], v[96:97], v[92:93]
	v_pk_mul_f32 v[82:83], v[86:87], v[82:83]
	v_pk_mul_f32 v[84:85], v[88:89], v[84:85]
	v_pk_mul_f32 v[74:75], v[78:79], v[74:75]
	v_pk_mul_f32 v[76:77], v[80:81], v[76:77]
	v_pk_mul_f32 v[66:67], v[70:71], v[66:67]
	v_pk_mul_f32 v[68:69], v[72:73], v[68:69]
	v_pk_mul_f32 v[58:59], v[62:63], v[58:59]
	v_pk_mul_f32 v[60:61], v[64:65], v[60:61]
	v_pk_mul_f32 v[50:51], v[54:55], v[50:51]
	v_pk_mul_f32 v[52:53], v[56:57], v[52:53]
	v_pk_mul_f32 v[42:43], v[46:47], v[42:43]
	v_pk_mul_f32 v[44:45], v[48:49], v[44:45]
	v_pk_mul_f32 v[34:35], v[38:39], v[34:35]
	v_pk_mul_f32 v[36:37], v[40:41], v[36:37]
	v_pk_mul_f32 v[26:27], v[30:31], v[26:27]
	v_pk_mul_f32 v[28:29], v[32:33], v[28:29]
	v_pk_mul_f32 v[18:19], v[22:23], v[18:19]
	v_pk_mul_f32 v[20:21], v[24:25], v[20:21]
	v_pk_mul_f32 v[12:13], v[16:17], v[12:13]
	v_pk_mul_f32 v[10:11], v[14:15], v[10:11]
	v_pk_mul_f32 v[4:5], v[8:9], v[4:5]
	v_pk_mul_f32 v[2:3], v[6:7], v[2:3]
	v_readlane_b32 s96, v252, 46
	s_waitcnt vmcnt(0)
	v_cvt_f32_u32_e32 v139, v142
	v_mov_b32_e32 v146, v143
	v_lshlrev_b64 v[140:141], s42, v[146:147]
	v_min_u32_e32 v140, 1, v140
	v_mov_b32_e32 v146, v145
	v_or_b32_e32 v141, v141, v140
	v_lshlrev_b64 v[142:143], s42, v[146:147]
	v_fmamk_f32 v140, v139, 0x30000000, v209
	v_cvt_f32_u32_e32 v139, v141
	v_min_u32_e32 v145, 1, v142
	v_or_b32_e32 v141, v143, v145
	v_cvt_f32_u32_e32 v144, v144
	v_cvt_f32_u32_e32 v141, v141
	v_ldexp_f32 v139, v139, s93
	v_fmac_f32_e32 v140, 2.0, v139
	v_rsq_f32_e32 v139, v140
	v_fmamk_f32 v142, v144, 0x30000000, v209
	v_ldexp_f32 v141, v141, s93
	v_fmac_f32_e32 v142, 2.0, v141
	v_rsq_f32_e32 v141, v142
	v_mul_f32_e32 v144, 0xbfb8aa3b, v139
	v_pk_mul_f32 v[114:115], v[114:115], v[144:145] op_sel_hi:[1,0]
	v_pk_mul_f32 v[116:117], v[116:117], v[144:145] op_sel_hi:[1,0]
	v_exp_f32_e32 v114, v114
	v_exp_f32_e32 v115, v115
	v_pk_mul_f32 v[110:111], v[110:111], v[144:145] op_sel_hi:[1,0]
	v_pk_mul_f32 v[112:113], v[112:113], v[144:145] op_sel_hi:[1,0]
	v_mul_f32_e32 v144, 0xbfb8aa3b, v141
	v_exp_f32_e32 v116, v116
	v_exp_f32_e32 v117, v117
	v_exp_f32_e32 v110, v110
	v_exp_f32_e32 v111, v111
	v_exp_f32_e32 v112, v112
	v_exp_f32_e32 v113, v113
	v_pk_mul_f32 v[178:179], v[102:103], v[144:145] op_sel_hi:[1,0]
	v_pk_mul_f32 v[106:107], v[106:107], v[144:145] op_sel_hi:[1,0]
	v_exp_f32_e32 v178, v178
	v_exp_f32_e32 v179, v179
	v_pk_mul_f32 v[108:109], v[108:109], v[144:145] op_sel_hi:[1,0]
	v_pk_mul_f32 v[144:145], v[104:105], v[144:145] op_sel_hi:[1,0]
	v_exp_f32_e32 v106, v106
	v_exp_f32_e32 v107, v107
	v_pk_fma_f32 v[114:115], v[140:141], v[114:115], v[140:141] op_sel_hi:[0,1,0]
	v_exp_f32_e32 v108, v108
	v_exp_f32_e32 v109, v109
	v_exp_f32_e32 v144, v144
	v_exp_f32_e32 v145, v145
	v_pk_fma_f32 v[116:117], v[140:141], v[116:117], v[140:141] op_sel_hi:[0,1,0]
	v_rcp_f32_e32 v114, v114
	v_rcp_f32_e32 v115, v115
	v_pk_fma_f32 v[110:111], v[140:141], v[110:111], v[140:141] op_sel_hi:[0,1,0]
	v_pk_fma_f32 v[112:113], v[140:141], v[112:113], v[140:141] op_sel_hi:[0,1,0]
	v_rcp_f32_e32 v116, v116
	v_rcp_f32_e32 v117, v117
	v_rcp_f32_e32 v110, v110
	v_rcp_f32_e32 v111, v111
	v_rcp_f32_e32 v112, v112
	v_rcp_f32_e32 v113, v113
	v_pk_fma_f32 v[140:141], v[142:143], v[178:179], v[142:143] op_sel_hi:[0,1,0]
	v_pk_fma_f32 v[106:107], v[142:143], v[106:107], v[142:143] op_sel_hi:[0,1,0]
	v_rcp_f32_e32 v140, v140
	v_rcp_f32_e32 v141, v141
	v_pk_fma_f32 v[108:109], v[142:143], v[108:109], v[142:143] op_sel_hi:[0,1,0]
	v_pk_fma_f32 v[142:143], v[142:143], v[144:145], v[142:143] op_sel_hi:[0,1,0]
	v_rcp_f32_e32 v144, v106
	v_rcp_f32_e32 v145, v107
	v_pk_mul_f32 v[106:107], v[154:155], v[114:115]
	v_rcp_f32_e32 v178, v108
	v_rcp_f32_e32 v179, v109
	v_pk_mul_f32 v[108:109], v[128:129], v[116:117]
	v_cvt_pk_bf16_f32 v106, v106, v107
	v_pk_mul_f32 v[110:111], v[170:171], v[110:111]
	v_cvt_pk_bf16_f32 v107, v108, v109
	v_pk_mul_f32 v[112:113], v[156:157], v[112:113]
	v_cvt_pk_bf16_f32 v108, v110, v111
	v_mov_b32_e32 v146, v177
	v_cvt_pk_bf16_f32 v109, v112, v113
	global_store_dwordx4 v138, v[106:109], s[8:9]
	v_pk_mul_f32 v[102:103], v[98:99], v[140:141]
	v_lshlrev_b64 v[98:99], s42, v[146:147]
	v_rcp_f32_e32 v106, v142
	v_rcp_f32_e32 v107, v143
	v_min_u32_e32 v98, 1, v98
	v_or_b32_e32 v98, v99, v98
	s_add_u32 s8, s43, s68
	v_pk_mul_f32 v[104:105], v[100:101], v[106:107]
	v_cvt_f32_u32_e32 v100, v176
	v_cvt_f32_u32_e32 v101, v98
	s_addc_u32 s9, s90, s69
	s_add_u32 s8, s8, s88
	v_fmamk_f32 v106, v100, 0x30000000, v209
	v_ldexp_f32 v100, v101, s93
	v_fmac_f32_e32 v106, 2.0, v100
	v_rsq_f32_e32 v107, v106
	v_pk_mul_f32 v[110:111], v[174:175], v[144:145]
	s_addc_u32 s9, s9, 0
	v_cvt_pk_bf16_f32 v98, v110, v111
	v_pk_mul_f32 v[112:113], v[172:173], v[178:179]
	v_mov_b32_e32 v146, v127
	v_cvt_pk_bf16_f32 v99, v112, v113
	v_cvt_pk_bf16_f32 v100, v102, v103
	v_cvt_pk_bf16_f32 v101, v104, v105
	global_store_dwordx4 v138, v[98:101], s[8:9]
	s_add_u32 s8, s43, s70
	s_addc_u32 s9, s90, s71
	v_mul_f32_e32 v98, 0xbfb8aa3b, v107
	v_pk_mul_f32 v[100:101], v[94:95], v[98:99] op_sel_hi:[1,0]
	v_pk_mul_f32 v[94:95], v[86:87], v[98:99] op_sel_hi:[1,0]
	v_pk_mul_f32 v[102:103], v[96:97], v[98:99] op_sel_hi:[1,0]
	v_exp_f32_e32 v94, v94
	v_exp_f32_e32 v95, v95
	v_pk_mul_f32 v[96:97], v[88:89], v[98:99] op_sel_hi:[1,0]
	v_exp_f32_e32 v100, v100
	v_exp_f32_e32 v96, v96
	v_exp_f32_e32 v97, v97
	v_pk_fma_f32 v[94:95], v[106:107], v[94:95], v[106:107] op_sel_hi:[0,1,0]
	v_rcp_f32_e32 v94, v94
	v_rcp_f32_e32 v95, v95
	v_exp_f32_e32 v101, v101
	v_pk_fma_f32 v[96:97], v[106:107], v[96:97], v[106:107] op_sel_hi:[0,1,0]
	v_rcp_f32_e32 v96, v96
	v_rcp_f32_e32 v97, v97
	v_pk_mul_f32 v[86:87], v[82:83], v[94:95]
	v_lshlrev_b64 v[82:83], s42, v[146:147]
	v_pk_fma_f32 v[100:101], v[106:107], v[100:101], v[106:107] op_sel_hi:[0,1,0]
	v_min_u32_e32 v82, 1, v82
	v_rcp_f32_e32 v100, v100
	v_rcp_f32_e32 v101, v101
	v_or_b32_e32 v82, v83, v82
	v_pk_mul_f32 v[88:89], v[84:85], v[96:97]
	v_cvt_f32_u32_e32 v84, v126
	v_cvt_f32_u32_e32 v85, v82
	v_exp_f32_e32 v102, v102
	v_exp_f32_e32 v103, v103
	v_pk_mul_f32 v[90:91], v[90:91], v[100:101]
	s_add_u32 s8, s8, s88
	v_cvt_pk_bf16_f32 v82, v90, v91
	v_fmamk_f32 v90, v84, 0x30000000, v209
	v_ldexp_f32 v84, v85, s93
	v_pk_fma_f32 v[102:103], v[106:107], v[102:103], v[106:107] op_sel_hi:[0,1,0]
	v_fmac_f32_e32 v90, 2.0, v84
	v_rcp_f32_e32 v102, v102
	v_rcp_f32_e32 v103, v103
	v_rsq_f32_e32 v91, v90
	s_addc_u32 s9, s9, 0
	v_mov_b32_e32 v146, v125
	v_pk_mul_f32 v[92:93], v[92:93], v[102:103]
	s_nop 0
	v_cvt_pk_bf16_f32 v83, v92, v93
	v_cvt_pk_bf16_f32 v84, v86, v87
	v_cvt_pk_bf16_f32 v85, v88, v89
	global_store_dwordx4 v138, v[82:85], s[8:9]
	s_add_u32 s8, s43, s26
	s_addc_u32 s9, s90, s27
	v_mul_f32_e32 v82, 0xbfb8aa3b, v91
	v_pk_mul_f32 v[84:85], v[78:79], v[82:83] op_sel_hi:[1,0]
	v_pk_mul_f32 v[78:79], v[70:71], v[82:83] op_sel_hi:[1,0]
	v_pk_mul_f32 v[86:87], v[80:81], v[82:83] op_sel_hi:[1,0]
	v_exp_f32_e32 v78, v78
	v_exp_f32_e32 v79, v79
	v_pk_mul_f32 v[80:81], v[72:73], v[82:83] op_sel_hi:[1,0]
	v_exp_f32_e32 v84, v84
	v_exp_f32_e32 v80, v80
	v_exp_f32_e32 v81, v81
	v_pk_fma_f32 v[78:79], v[90:91], v[78:79], v[90:91] op_sel_hi:[0,1,0]
	v_rcp_f32_e32 v78, v78
	v_rcp_f32_e32 v79, v79
	v_exp_f32_e32 v85, v85
	v_pk_fma_f32 v[80:81], v[90:91], v[80:81], v[90:91] op_sel_hi:[0,1,0]
	v_rcp_f32_e32 v80, v80
	v_rcp_f32_e32 v81, v81
	v_pk_mul_f32 v[70:71], v[66:67], v[78:79]
	v_lshlrev_b64 v[66:67], s42, v[146:147]
	v_pk_fma_f32 v[84:85], v[90:91], v[84:85], v[90:91] op_sel_hi:[0,1,0]
	v_min_u32_e32 v66, 1, v66
	v_rcp_f32_e32 v84, v84
	v_rcp_f32_e32 v85, v85
	v_or_b32_e32 v66, v67, v66
	v_pk_mul_f32 v[72:73], v[68:69], v[80:81]
	v_cvt_f32_u32_e32 v68, v124
	v_cvt_f32_u32_e32 v69, v66
	v_exp_f32_e32 v86, v86
	v_exp_f32_e32 v87, v87
	v_pk_mul_f32 v[74:75], v[74:75], v[84:85]
	s_add_u32 s8, s8, s88
	v_cvt_pk_bf16_f32 v66, v74, v75
	v_fmamk_f32 v74, v68, 0x30000000, v209
	v_ldexp_f32 v68, v69, s93
	v_pk_fma_f32 v[86:87], v[90:91], v[86:87], v[90:91] op_sel_hi:[0,1,0]
	v_fmac_f32_e32 v74, 2.0, v68
	v_rcp_f32_e32 v86, v86
	v_rcp_f32_e32 v87, v87
	v_rsq_f32_e32 v75, v74
	s_addc_u32 s9, s9, 0
	v_mov_b32_e32 v146, v123
	v_pk_mul_f32 v[76:77], v[76:77], v[86:87]
	s_nop 0
	v_cvt_pk_bf16_f32 v67, v76, v77
	v_cvt_pk_bf16_f32 v68, v70, v71
	v_cvt_pk_bf16_f32 v69, v72, v73
	global_store_dwordx4 v138, v[66:69], s[8:9]
	s_add_u32 s8, s43, s82
	s_addc_u32 s9, s90, s84
	v_mul_f32_e32 v66, 0xbfb8aa3b, v75
	v_pk_mul_f32 v[68:69], v[62:63], v[66:67] op_sel_hi:[1,0]
	v_pk_mul_f32 v[62:63], v[54:55], v[66:67] op_sel_hi:[1,0]
	v_pk_mul_f32 v[70:71], v[64:65], v[66:67] op_sel_hi:[1,0]
	v_exp_f32_e32 v62, v62
	v_exp_f32_e32 v63, v63
	v_pk_mul_f32 v[64:65], v[56:57], v[66:67] op_sel_hi:[1,0]
	v_exp_f32_e32 v68, v68
	v_exp_f32_e32 v64, v64
	v_exp_f32_e32 v65, v65
	v_pk_fma_f32 v[62:63], v[74:75], v[62:63], v[74:75] op_sel_hi:[0,1,0]
	v_rcp_f32_e32 v62, v62
	v_rcp_f32_e32 v63, v63
	v_exp_f32_e32 v69, v69
	v_pk_fma_f32 v[64:65], v[74:75], v[64:65], v[74:75] op_sel_hi:[0,1,0]
	v_rcp_f32_e32 v64, v64
	v_rcp_f32_e32 v65, v65
	v_pk_mul_f32 v[54:55], v[50:51], v[62:63]
	v_lshlrev_b64 v[50:51], s42, v[146:147]
	v_pk_fma_f32 v[68:69], v[74:75], v[68:69], v[74:75] op_sel_hi:[0,1,0]
	v_min_u32_e32 v50, 1, v50
	v_rcp_f32_e32 v68, v68
	v_rcp_f32_e32 v69, v69
	v_or_b32_e32 v50, v51, v50
	v_pk_mul_f32 v[56:57], v[52:53], v[64:65]
	v_cvt_f32_u32_e32 v52, v122
	v_cvt_f32_u32_e32 v53, v50
	v_exp_f32_e32 v70, v70
	v_exp_f32_e32 v71, v71
	v_pk_mul_f32 v[58:59], v[58:59], v[68:69]
	s_add_u32 s8, s8, s88
	v_cvt_pk_bf16_f32 v50, v58, v59
	v_fmamk_f32 v58, v52, 0x30000000, v209
	v_ldexp_f32 v52, v53, s93
	v_pk_fma_f32 v[70:71], v[74:75], v[70:71], v[74:75] op_sel_hi:[0,1,0]
	v_fmac_f32_e32 v58, 2.0, v52
	v_rcp_f32_e32 v70, v70
	v_rcp_f32_e32 v71, v71
	v_rsq_f32_e32 v59, v58
	s_addc_u32 s9, s9, 0
	v_mov_b32_e32 v146, v121
	v_pk_mul_f32 v[60:61], v[60:61], v[70:71]
	s_nop 0
	v_cvt_pk_bf16_f32 v51, v60, v61
	v_cvt_pk_bf16_f32 v52, v54, v55
	v_cvt_pk_bf16_f32 v53, v56, v57
	global_store_dwordx4 v138, v[50:53], s[8:9]
	s_add_u32 s8, s43, s85
	s_addc_u32 s9, s90, s22
	v_mul_f32_e32 v50, 0xbfb8aa3b, v59
	v_pk_mul_f32 v[52:53], v[46:47], v[50:51] op_sel_hi:[1,0]
	v_pk_mul_f32 v[46:47], v[38:39], v[50:51] op_sel_hi:[1,0]
	v_pk_mul_f32 v[54:55], v[48:49], v[50:51] op_sel_hi:[1,0]
	v_exp_f32_e32 v46, v46
	v_exp_f32_e32 v47, v47
	v_pk_mul_f32 v[48:49], v[40:41], v[50:51] op_sel_hi:[1,0]
	v_exp_f32_e32 v52, v52
	v_exp_f32_e32 v48, v48
	v_exp_f32_e32 v49, v49
	v_pk_fma_f32 v[46:47], v[58:59], v[46:47], v[58:59] op_sel_hi:[0,1,0]
	v_rcp_f32_e32 v46, v46
	v_rcp_f32_e32 v47, v47
	v_exp_f32_e32 v53, v53
	v_pk_fma_f32 v[48:49], v[58:59], v[48:49], v[58:59] op_sel_hi:[0,1,0]
	v_rcp_f32_e32 v48, v48
	v_rcp_f32_e32 v49, v49
	v_pk_mul_f32 v[38:39], v[34:35], v[46:47]
	v_lshlrev_b64 v[34:35], s42, v[146:147]
	v_pk_fma_f32 v[52:53], v[58:59], v[52:53], v[58:59] op_sel_hi:[0,1,0]
	v_min_u32_e32 v34, 1, v34
	v_rcp_f32_e32 v52, v52
	v_rcp_f32_e32 v53, v53
	v_or_b32_e32 v34, v35, v34
	v_pk_mul_f32 v[40:41], v[36:37], v[48:49]
	v_cvt_f32_u32_e32 v36, v120
	v_cvt_f32_u32_e32 v37, v34
	v_exp_f32_e32 v54, v54
	v_exp_f32_e32 v55, v55
	v_pk_mul_f32 v[42:43], v[42:43], v[52:53]
	s_add_u32 s8, s8, s88
	v_cvt_pk_bf16_f32 v34, v42, v43
	v_fmamk_f32 v42, v36, 0x30000000, v209
	v_ldexp_f32 v36, v37, s93
	v_pk_fma_f32 v[54:55], v[58:59], v[54:55], v[58:59] op_sel_hi:[0,1,0]
	v_fmac_f32_e32 v42, 2.0, v36
	v_rcp_f32_e32 v54, v54
	v_rcp_f32_e32 v55, v55
	v_rsq_f32_e32 v43, v42
	s_addc_u32 s9, s9, 0
	v_mov_b32_e32 v146, v119
	v_pk_mul_f32 v[44:45], v[44:45], v[54:55]
	s_nop 0
	v_cvt_pk_bf16_f32 v35, v44, v45
	v_cvt_pk_bf16_f32 v36, v38, v39
	v_cvt_pk_bf16_f32 v37, v40, v41
	global_store_dwordx4 v138, v[34:37], s[8:9]
	s_add_u32 s8, s43, s83
	s_addc_u32 s9, s90, s12
	v_mul_f32_e32 v34, 0xbfb8aa3b, v43
	v_pk_mul_f32 v[36:37], v[30:31], v[34:35] op_sel_hi:[1,0]
	v_pk_mul_f32 v[30:31], v[22:23], v[34:35] op_sel_hi:[1,0]
	v_pk_mul_f32 v[38:39], v[32:33], v[34:35] op_sel_hi:[1,0]
	v_exp_f32_e32 v30, v30
	v_exp_f32_e32 v31, v31
	v_pk_mul_f32 v[32:33], v[24:25], v[34:35] op_sel_hi:[1,0]
	v_exp_f32_e32 v36, v36
	v_exp_f32_e32 v32, v32
	v_exp_f32_e32 v33, v33
	v_pk_fma_f32 v[30:31], v[42:43], v[30:31], v[42:43] op_sel_hi:[0,1,0]
	v_rcp_f32_e32 v30, v30
	v_rcp_f32_e32 v31, v31
	v_exp_f32_e32 v37, v37
	v_pk_fma_f32 v[32:33], v[42:43], v[32:33], v[42:43] op_sel_hi:[0,1,0]
	v_rcp_f32_e32 v32, v32
	v_rcp_f32_e32 v33, v33
	v_pk_mul_f32 v[22:23], v[18:19], v[30:31]
	v_lshlrev_b64 v[18:19], s42, v[146:147]
	v_pk_fma_f32 v[36:37], v[42:43], v[36:37], v[42:43] op_sel_hi:[0,1,0]
	v_min_u32_e32 v18, 1, v18
	v_rcp_f32_e32 v36, v36
	v_rcp_f32_e32 v37, v37
	v_or_b32_e32 v18, v19, v18
	v_pk_mul_f32 v[24:25], v[20:21], v[32:33]
	v_cvt_f32_u32_e32 v20, v118
	v_cvt_f32_u32_e32 v21, v18
	v_exp_f32_e32 v38, v38
	v_exp_f32_e32 v39, v39
	v_pk_mul_f32 v[26:27], v[26:27], v[36:37]
	s_add_u32 s8, s8, s88
	v_cvt_pk_bf16_f32 v18, v26, v27
	v_fmamk_f32 v26, v20, 0x30000000, v209
	v_ldexp_f32 v20, v21, s93
	v_pk_fma_f32 v[38:39], v[42:43], v[38:39], v[42:43] op_sel_hi:[0,1,0]
	v_fmac_f32_e32 v26, 2.0, v20
	v_rcp_f32_e32 v38, v38
	v_rcp_f32_e32 v39, v39
	v_rsq_f32_e32 v27, v26
	s_addc_u32 s9, s9, 0
	v_pk_mul_f32 v[28:29], v[28:29], v[38:39]
	s_nop 0
	v_cvt_pk_bf16_f32 v19, v28, v29
	v_cvt_pk_bf16_f32 v20, v22, v23
	v_cvt_pk_bf16_f32 v21, v24, v25
	global_store_dwordx4 v138, v[18:21], s[8:9]
	s_add_u32 s8, s43, s86
	s_addc_u32 s9, s90, s87
	v_mul_f32_e32 v18, 0xbfb8aa3b, v27
	v_pk_mul_f32 v[20:21], v[14:15], v[18:19] op_sel_hi:[1,0]
	v_pk_mul_f32 v[22:23], v[16:17], v[18:19] op_sel_hi:[1,0]
	v_pk_mul_f32 v[14:15], v[6:7], v[18:19] op_sel_hi:[1,0]
	v_pk_mul_f32 v[16:17], v[8:9], v[18:19] op_sel_hi:[1,0]
	v_exp_f32_e32 v20, v20
	v_exp_f32_e32 v21, v21
	v_exp_f32_e32 v22, v22
	v_exp_f32_e32 v23, v23
	v_exp_f32_e32 v14, v14
	v_exp_f32_e32 v15, v15
	v_exp_f32_e32 v16, v16
	v_exp_f32_e32 v17, v17
	v_pk_fma_f32 v[20:21], v[26:27], v[20:21], v[26:27] op_sel_hi:[0,1,0]
	v_pk_fma_f32 v[22:23], v[26:27], v[22:23], v[26:27] op_sel_hi:[0,1,0]
	v_pk_fma_f32 v[14:15], v[26:27], v[14:15], v[26:27] op_sel_hi:[0,1,0]
	v_pk_fma_f32 v[16:17], v[26:27], v[16:17], v[26:27] op_sel_hi:[0,1,0]
	v_rcp_f32_e32 v20, v20
	v_rcp_f32_e32 v21, v21
	v_rcp_f32_e32 v22, v22
	v_rcp_f32_e32 v23, v23
	v_rcp_f32_e32 v14, v14
	v_rcp_f32_e32 v15, v15
	v_rcp_f32_e32 v16, v16
	v_rcp_f32_e32 v17, v17
	s_add_u32 s8, s8, s88
	s_addc_u32 s9, s9, 0
	v_pk_mul_f32 v[10:11], v[10:11], v[20:21]
	v_pk_mul_f32 v[12:13], v[12:13], v[22:23]
	v_pk_mul_f32 v[6:7], v[2:3], v[14:15]
	v_pk_mul_f32 v[8:9], v[4:5], v[16:17]
	v_cvt_pk_bf16_f32 v2, v10, v11
	v_cvt_pk_bf16_f32 v3, v12, v13
	v_cvt_pk_bf16_f32 v4, v6, v7
	s_andn2_b64 vcc, exec, s[48:49]
	v_cvt_pk_bf16_f32 v5, v8, v9
	global_store_dwordx4 v138, v[2:5], s[8:9]
	s_mov_b64 s[8:9], -1
	s_cbranch_vccnz .LBB0_1869
	s_andn2_b64 vcc, exec, s[44:45]
	s_cbranch_vccnz .LBB0_1868
	s_mov_b32 m0, -1
	s_branch .LBB0_1868

.LBB0_2155:
	s_mul_i32 s49, s48, 0x2c0000
	s_and_b64 s[8:9], s[42:43], exec
	s_mul_i32 s23, s15, 0x2c0000
	s_cselect_b32 s8, s49, s21
	s_cselect_b32 s9, s23, s13
	s_addk_i32 s13, 0x100
	s_add_i32 s21, s21, 0xc000
	s_mov_b32 s22, -2
	s_waitcnt lgkmcnt(0)
	s_cmp_eq_u32 m0, -1
	s_cbranch_scc0 .Lgk_rs_11
	s_barrier
.Lgk_rs_11:
	v_add_u32_e32 v170, 0x10000, v140
	v_add_u32_e32 v186, 0x14000, v140
	ds_read_b128 v[132:135], v170
	ds_read_b128 v[142:145], v170 offset:1024
	ds_read_b128 v[154:157], v170 offset:2048
	ds_read_b128 v[170:173], v170 offset:3072
	ds_read_b128 v[174:177], v186
	ds_read_b128 v[178:181], v186 offset:1024
	ds_read_b128 v[182:185], v186 offset:2048
	ds_read_b128 v[186:189], v186 offset:3072
	s_add_i32 s26, s21, 0x4000
	s_cmpk_eq_i32 s22, 0x54
	s_cselect_b32 s52, s8, s26
	s_cselect_b32 s27, s9, s13
	s_or_b32 s26, s52, 0x8000
	s_mov_b32 m0, s84
	ds_read_b128 v[190:193], v141
	ds_read_b128 v[194:197], v141 offset:1024
	ds_read_b128 v[198:201], v141 offset:2048
	ds_read_b128 v[202:205], v141 offset:3072
	ds_read_b128 v[228:231], v141 offset:4096
	ds_read_b128 v[232:235], v141 offset:5120
	ds_read_b128 v[236:239], v141 offset:6144
	ds_read_b128 v[240:243], v141 offset:7168
	buffer_load_dwordx4 v136, s[60:63], s21 offen lds
	s_mov_b32 m0, s16
	s_nop 0
	buffer_load_dwordx4 v138, s[60:63], s21 offen lds
	s_waitcnt vmcnt(8)
	s_waitcnt lgkmcnt(0)
	s_setprio 1
	s_barrier
	v_mfma_f32_16x16x32_bf16 v[126:129], v[132:135], v[190:193], 0
	v_mfma_f32_16x16x32_bf16 v[126:129], v[142:145], v[194:197], v[126:129]
	v_mfma_f32_16x16x32_bf16 v[106:109], v[154:157], v[190:193], 0
	v_mfma_f32_16x16x32_bf16 v[106:109], v[170:173], v[194:197], v[106:109]
	v_mfma_f32_16x16x32_bf16 v[110:113], v[182:185], v[190:193], 0
	v_mfma_f32_16x16x32_bf16 v[110:113], v[186:189], v[194:197], v[110:113]
	v_mfma_f32_16x16x32_bf16 v[122:125], v[174:177], v[190:193], 0
	v_mfma_f32_16x16x32_bf16 v[122:125], v[178:181], v[194:197], v[122:125]
	v_mfma_f32_16x16x32_bf16 v[102:105], v[174:177], v[198:201], 0
	v_mfma_f32_16x16x32_bf16 v[102:105], v[178:181], v[202:205], v[102:105]
	v_mfma_f32_16x16x32_bf16 v[98:101], v[182:185], v[198:201], 0
	v_mfma_f32_16x16x32_bf16 v[98:101], v[186:189], v[202:205], v[98:101]
	v_mfma_f32_16x16x32_bf16 v[114:117], v[154:157], v[198:201], 0
	v_mfma_f32_16x16x32_bf16 v[114:117], v[170:173], v[202:205], v[114:117]
	v_mfma_f32_16x16x32_bf16 v[118:121], v[132:135], v[198:201], 0
	v_mfma_f32_16x16x32_bf16 v[118:121], v[142:145], v[202:205], v[118:121]
	v_mfma_f32_16x16x32_bf16 v[94:97], v[132:135], v[228:231], 0
	v_mfma_f32_16x16x32_bf16 v[94:97], v[142:145], v[232:235], v[94:97]
	v_mfma_f32_16x16x32_bf16 v[90:93], v[154:157], v[228:231], 0
	v_mfma_f32_16x16x32_bf16 v[90:93], v[170:173], v[232:235], v[90:93]
	v_mfma_f32_16x16x32_bf16 v[82:85], v[182:185], v[228:231], 0
	v_mfma_f32_16x16x32_bf16 v[82:85], v[186:189], v[232:235], v[82:85]
	v_mfma_f32_16x16x32_bf16 v[86:89], v[174:177], v[228:231], 0
	v_mfma_f32_16x16x32_bf16 v[86:89], v[178:181], v[232:235], v[86:89]
	v_mfma_f32_16x16x32_bf16 v[70:73], v[174:177], v[236:239], 0
	v_mfma_f32_16x16x32_bf16 v[70:73], v[178:181], v[240:243], v[70:73]
	v_mfma_f32_16x16x32_bf16 v[66:69], v[182:185], v[236:239], 0
	v_mfma_f32_16x16x32_bf16 v[66:69], v[186:189], v[240:243], v[66:69]
	v_mfma_f32_16x16x32_bf16 v[74:77], v[154:157], v[236:239], 0
	v_mfma_f32_16x16x32_bf16 v[74:77], v[170:173], v[240:243], v[74:77]
	v_mfma_f32_16x16x32_bf16 v[78:81], v[132:135], v[236:239], 0
	v_mfma_f32_16x16x32_bf16 v[78:81], v[142:145], v[240:243], v[78:81]
	s_barrier
	s_setprio 0
	s_mov_b32 s46, s62
	s_mov_b32 s47, s63
	s_mov_b32 m0, s18
	ds_read_b128 v[190:193], v141 offset:16384
	buffer_load_dwordx4 v137, s[44:47], s27 offen lds
	s_add_i32 s53, s27, 0x160000
	s_mov_b32 m0, s19
	ds_read_b128 v[194:197], v141 offset:17408
	buffer_load_dwordx4 v139, s[44:47], s27 offen lds
	s_mov_b32 m0, s24
	ds_read_b128 v[198:201], v141 offset:18432
	buffer_load_dwordx4 v137, s[44:47], s53 offen lds
	s_mov_b32 m0, s25
	ds_read_b128 v[202:205], v141 offset:19456
	buffer_load_dwordx4 v139, s[44:47], s53 offen lds
	s_mov_b32 m0, s14
	ds_read_b128 v[228:231], v141 offset:20480
	buffer_load_dwordx4 v136, s[60:63], s52 offen lds
	s_mov_b32 m0, s30
	ds_read_b128 v[232:235], v141 offset:21504
	buffer_load_dwordx4 v138, s[60:63], s52 offen lds
	ds_read_b128 v[236:239], v141 offset:22528
	ds_read_b128 v[240:243], v141 offset:23552
	s_waitcnt vmcnt(8)
	s_waitcnt lgkmcnt(0)
	s_setprio 1
	s_barrier
	v_mfma_f32_16x16x32_bf16 v[62:65], v[132:135], v[190:193], 0
	v_mfma_f32_16x16x32_bf16 v[62:65], v[142:145], v[194:197], v[62:65]
	v_mfma_f32_16x16x32_bf16 v[58:61], v[154:157], v[190:193], 0
	v_mfma_f32_16x16x32_bf16 v[58:61], v[170:173], v[194:197], v[58:61]
	v_mfma_f32_16x16x32_bf16 v[50:53], v[182:185], v[190:193], 0
	v_mfma_f32_16x16x32_bf16 v[50:53], v[186:189], v[194:197], v[50:53]
	v_mfma_f32_16x16x32_bf16 v[54:57], v[174:177], v[190:193], 0
	v_mfma_f32_16x16x32_bf16 v[54:57], v[178:181], v[194:197], v[54:57]
	v_mfma_f32_16x16x32_bf16 v[38:41], v[174:177], v[198:201], 0
	v_mfma_f32_16x16x32_bf16 v[38:41], v[178:181], v[202:205], v[38:41]
	v_mfma_f32_16x16x32_bf16 v[34:37], v[182:185], v[198:201], 0
	v_mfma_f32_16x16x32_bf16 v[34:37], v[186:189], v[202:205], v[34:37]
	v_mfma_f32_16x16x32_bf16 v[42:45], v[154:157], v[198:201], 0
	v_mfma_f32_16x16x32_bf16 v[42:45], v[170:173], v[202:205], v[42:45]
	v_mfma_f32_16x16x32_bf16 v[46:49], v[132:135], v[198:201], 0
	v_mfma_f32_16x16x32_bf16 v[46:49], v[142:145], v[202:205], v[46:49]
	v_mfma_f32_16x16x32_bf16 v[30:33], v[132:135], v[228:231], 0
	v_mfma_f32_16x16x32_bf16 v[30:33], v[142:145], v[232:235], v[30:33]
	v_mfma_f32_16x16x32_bf16 v[26:29], v[154:157], v[228:231], 0
	v_mfma_f32_16x16x32_bf16 v[26:29], v[170:173], v[232:235], v[26:29]
	v_mfma_f32_16x16x32_bf16 v[18:21], v[182:185], v[228:231], 0
	v_mfma_f32_16x16x32_bf16 v[18:21], v[186:189], v[232:235], v[18:21]
	v_mfma_f32_16x16x32_bf16 v[22:25], v[174:177], v[228:231], 0
	v_mfma_f32_16x16x32_bf16 v[22:25], v[178:181], v[232:235], v[22:25]
	v_mfma_f32_16x16x32_bf16 v[6:9], v[174:177], v[236:239], 0
	v_mfma_f32_16x16x32_bf16 v[6:9], v[178:181], v[240:243], v[6:9]
	v_mfma_f32_16x16x32_bf16 v[2:5], v[182:185], v[236:239], 0
	v_mfma_f32_16x16x32_bf16 v[2:5], v[186:189], v[240:243], v[2:5]
	v_mfma_f32_16x16x32_bf16 v[10:13], v[154:157], v[236:239], 0
	v_mfma_f32_16x16x32_bf16 v[10:13], v[170:173], v[240:243], v[10:13]
	v_mfma_f32_16x16x32_bf16 v[14:17], v[132:135], v[236:239], 0
	v_mfma_f32_16x16x32_bf16 v[14:17], v[142:145], v[240:243], v[14:17]
	s_barrier
	s_setprio 0
	v_add_u32_e32 v170, 0x18000, v140
	v_add_u32_e32 v186, 0x1c000, v140
	ds_read_b128 v[132:135], v170
	ds_read_b128 v[142:145], v170 offset:1024
	ds_read_b128 v[154:157], v170 offset:2048
	ds_read_b128 v[170:173], v170 offset:3072
	ds_read_b128 v[174:177], v186
	ds_read_b128 v[178:181], v186 offset:1024
	ds_read_b128 v[182:185], v186 offset:2048
	ds_read_b128 v[186:189], v186 offset:3072
	s_bitset1_b32 s52, 14
	s_mov_b32 m0, s31
	ds_read_b128 v[190:193], v141 offset:32768
	ds_read_b128 v[194:197], v141 offset:33792
	ds_read_b128 v[198:201], v141 offset:34816
	ds_read_b128 v[202:205], v141 offset:35840
	ds_read_b128 v[228:231], v141 offset:36864
	ds_read_b128 v[232:235], v141 offset:37888
	ds_read_b128 v[236:239], v141 offset:38912
	ds_read_b128 v[240:243], v141 offset:39936
	buffer_load_dwordx4 v136, s[60:63], s52 offen lds
	s_mov_b32 m0, s33
	s_nop 0
	buffer_load_dwordx4 v138, s[60:63], s52 offen lds
	s_waitcnt vmcnt(8)
	s_waitcnt lgkmcnt(0)
	s_setprio 1
	s_barrier
	v_mfma_f32_16x16x32_bf16 v[126:129], v[132:135], v[190:193], v[126:129]
	v_mfma_f32_16x16x32_bf16 v[126:129], v[142:145], v[194:197], v[126:129]
	v_mfma_f32_16x16x32_bf16 v[106:109], v[154:157], v[190:193], v[106:109]
	v_mfma_f32_16x16x32_bf16 v[106:109], v[170:173], v[194:197], v[106:109]
	v_mfma_f32_16x16x32_bf16 v[110:113], v[182:185], v[190:193], v[110:113]
	v_mfma_f32_16x16x32_bf16 v[110:113], v[186:189], v[194:197], v[110:113]
	v_mfma_f32_16x16x32_bf16 v[122:125], v[174:177], v[190:193], v[122:125]
	v_mfma_f32_16x16x32_bf16 v[122:125], v[178:181], v[194:197], v[122:125]
	v_mfma_f32_16x16x32_bf16 v[102:105], v[174:177], v[198:201], v[102:105]
	v_mfma_f32_16x16x32_bf16 v[102:105], v[178:181], v[202:205], v[102:105]
	v_mfma_f32_16x16x32_bf16 v[98:101], v[182:185], v[198:201], v[98:101]
	v_mfma_f32_16x16x32_bf16 v[98:101], v[186:189], v[202:205], v[98:101]
	v_mfma_f32_16x16x32_bf16 v[114:117], v[154:157], v[198:201], v[114:117]
	v_mfma_f32_16x16x32_bf16 v[114:117], v[170:173], v[202:205], v[114:117]
	v_mfma_f32_16x16x32_bf16 v[118:121], v[132:135], v[198:201], v[118:121]
	v_mfma_f32_16x16x32_bf16 v[118:121], v[142:145], v[202:205], v[118:121]
	v_mfma_f32_16x16x32_bf16 v[94:97], v[132:135], v[228:231], v[94:97]
	v_mfma_f32_16x16x32_bf16 v[94:97], v[142:145], v[232:235], v[94:97]
	v_mfma_f32_16x16x32_bf16 v[90:93], v[154:157], v[228:231], v[90:93]
	v_mfma_f32_16x16x32_bf16 v[90:93], v[170:173], v[232:235], v[90:93]
	v_mfma_f32_16x16x32_bf16 v[82:85], v[182:185], v[228:231], v[82:85]
	v_mfma_f32_16x16x32_bf16 v[82:85], v[186:189], v[232:235], v[82:85]
	v_mfma_f32_16x16x32_bf16 v[86:89], v[174:177], v[228:231], v[86:89]
	v_mfma_f32_16x16x32_bf16 v[86:89], v[178:181], v[232:235], v[86:89]
	v_mfma_f32_16x16x32_bf16 v[70:73], v[174:177], v[236:239], v[70:73]
	v_mfma_f32_16x16x32_bf16 v[70:73], v[178:181], v[240:243], v[70:73]
	v_mfma_f32_16x16x32_bf16 v[66:69], v[182:185], v[236:239], v[66:69]
	v_mfma_f32_16x16x32_bf16 v[66:69], v[186:189], v[240:243], v[66:69]
	v_mfma_f32_16x16x32_bf16 v[74:77], v[154:157], v[236:239], v[74:77]
	v_mfma_f32_16x16x32_bf16 v[74:77], v[170:173], v[240:243], v[74:77]
	v_mfma_f32_16x16x32_bf16 v[78:81], v[132:135], v[236:239], v[78:81]
	v_mfma_f32_16x16x32_bf16 v[78:81], v[142:145], v[240:243], v[78:81]
	s_barrier
	s_setprio 0
	s_or_b32 s52, s27, 0x80
	s_mov_b32 m0, s68
	ds_read_b128 v[190:193], v141 offset:49152
	buffer_load_dwordx4 v137, s[44:47], s52 offen lds
	s_add_i32 s27, s27, 0x160080
	s_mov_b32 m0, s69
	ds_read_b128 v[194:197], v141 offset:50176
	buffer_load_dwordx4 v139, s[44:47], s52 offen lds
	s_mov_b32 m0, s72
	ds_read_b128 v[198:201], v141 offset:51200
	buffer_load_dwordx4 v137, s[44:47], s27 offen lds
	s_mov_b32 m0, s73
	ds_read_b128 v[202:205], v141 offset:52224
	buffer_load_dwordx4 v139, s[44:47], s27 offen lds
	s_mov_b32 m0, s70
	ds_read_b128 v[228:231], v141 offset:53248
	buffer_load_dwordx4 v136, s[60:63], s26 offen lds
	s_mov_b32 m0, s71
	ds_read_b128 v[232:235], v141 offset:54272
	buffer_load_dwordx4 v138, s[60:63], s26 offen lds
	ds_read_b128 v[236:239], v141 offset:55296
	ds_read_b128 v[240:243], v141 offset:56320
	s_waitcnt vmcnt(8)
	s_waitcnt lgkmcnt(0)
	s_setprio 1
	s_barrier
	v_mfma_f32_16x16x32_bf16 v[62:65], v[132:135], v[190:193], v[62:65]
	v_mfma_f32_16x16x32_bf16 v[62:65], v[142:145], v[194:197], v[62:65]
	v_mfma_f32_16x16x32_bf16 v[58:61], v[154:157], v[190:193], v[58:61]
	v_mfma_f32_16x16x32_bf16 v[58:61], v[170:173], v[194:197], v[58:61]
	v_mfma_f32_16x16x32_bf16 v[50:53], v[182:185], v[190:193], v[50:53]
	v_mfma_f32_16x16x32_bf16 v[50:53], v[186:189], v[194:197], v[50:53]
	v_mfma_f32_16x16x32_bf16 v[54:57], v[174:177], v[190:193], v[54:57]
	v_mfma_f32_16x16x32_bf16 v[54:57], v[178:181], v[194:197], v[54:57]
	v_mfma_f32_16x16x32_bf16 v[38:41], v[174:177], v[198:201], v[38:41]
	v_mfma_f32_16x16x32_bf16 v[38:41], v[178:181], v[202:205], v[38:41]
	v_mfma_f32_16x16x32_bf16 v[34:37], v[182:185], v[198:201], v[34:37]
	v_mfma_f32_16x16x32_bf16 v[34:37], v[186:189], v[202:205], v[34:37]
	v_mfma_f32_16x16x32_bf16 v[42:45], v[154:157], v[198:201], v[42:45]
	v_mfma_f32_16x16x32_bf16 v[42:45], v[170:173], v[202:205], v[42:45]
	v_mfma_f32_16x16x32_bf16 v[46:49], v[132:135], v[198:201], v[46:49]
	v_mfma_f32_16x16x32_bf16 v[46:49], v[142:145], v[202:205], v[46:49]
	v_mfma_f32_16x16x32_bf16 v[30:33], v[132:135], v[228:231], v[30:33]
	v_mfma_f32_16x16x32_bf16 v[30:33], v[142:145], v[232:235], v[30:33]
	v_mfma_f32_16x16x32_bf16 v[26:29], v[154:157], v[228:231], v[26:29]
	v_mfma_f32_16x16x32_bf16 v[26:29], v[170:173], v[232:235], v[26:29]
	v_mfma_f32_16x16x32_bf16 v[18:21], v[182:185], v[228:231], v[18:21]
	v_mfma_f32_16x16x32_bf16 v[18:21], v[186:189], v[232:235], v[18:21]
	v_mfma_f32_16x16x32_bf16 v[22:25], v[174:177], v[228:231], v[22:25]
	v_mfma_f32_16x16x32_bf16 v[22:25], v[178:181], v[232:235], v[22:25]
	v_mfma_f32_16x16x32_bf16 v[6:9], v[174:177], v[236:239], v[6:9]
	v_mfma_f32_16x16x32_bf16 v[6:9], v[178:181], v[240:243], v[6:9]
	v_mfma_f32_16x16x32_bf16 v[2:5], v[182:185], v[236:239], v[2:5]
	v_mfma_f32_16x16x32_bf16 v[2:5], v[186:189], v[240:243], v[2:5]
	v_mfma_f32_16x16x32_bf16 v[10:13], v[154:157], v[236:239], v[10:13]
	v_mfma_f32_16x16x32_bf16 v[10:13], v[170:173], v[240:243], v[10:13]
	v_mfma_f32_16x16x32_bf16 v[14:17], v[132:135], v[236:239], v[14:17]
	v_mfma_f32_16x16x32_bf16 v[14:17], v[142:145], v[240:243], v[14:17]
	s_barrier
	s_setprio 0
	s_addk_i32 s13, 0x100
	s_add_i32 s22, s22, 2
	s_add_i32 s21, s21, 0x10000
	s_cmpk_gt_u32 s22, 0x55

.LBB0_2161:
	s_or_b64 exec, exec, s[8:9]
	s_andn2_b64 vcc, exec, s[42:43]
	s_mov_b64 s[8:9], -1
	s_cbranch_vccnz .LBB0_2152
	s_andn2_b64 vcc, exec, s[64:65]
	s_cbranch_vccnz .LBB0_2151
	s_mov_b32 m0, -1
	s_branch .LBB0_2151

.LBB0_2173:
	v_mov_b32_e32 v125, 0
	s_mul_i32 s69, s68, s12
	s_mul_i32 s70, s67, s12
	s_andn2_b64 vcc, exec, s[34:35]
	v_mov_b32_e32 v124, v125
	v_mov_b32_e32 v123, v125
	v_mov_b32_e32 v122, v125
	v_mov_b32_e32 v129, v125
	v_mov_b32_e32 v128, v125
	v_mov_b32_e32 v127, v125
	v_mov_b32_e32 v126, v125
	v_mov_b32_e32 v113, v125
	v_mov_b32_e32 v112, v125
	v_mov_b32_e32 v111, v125
	v_mov_b32_e32 v110, v125
	v_mov_b32_e32 v109, v125
	v_mov_b32_e32 v108, v125
	v_mov_b32_e32 v107, v125
	v_mov_b32_e32 v106, v125
	v_mov_b32_e32 v97, v125
	v_mov_b32_e32 v96, v125
	v_mov_b32_e32 v95, v125
	v_mov_b32_e32 v94, v125
	v_mov_b32_e32 v93, v125
	v_mov_b32_e32 v92, v125
	v_mov_b32_e32 v91, v125
	v_mov_b32_e32 v90, v125
	v_mov_b32_e32 v81, v125
	v_mov_b32_e32 v80, v125
	v_mov_b32_e32 v79, v125
	v_mov_b32_e32 v78, v125
	v_mov_b32_e32 v77, v125
	v_mov_b32_e32 v76, v125
	v_mov_b32_e32 v75, v125
	v_mov_b32_e32 v74, v125
	v_mov_b32_e32 v121, v125
	v_mov_b32_e32 v120, v125
	v_mov_b32_e32 v119, v125
	v_mov_b32_e32 v118, v125
	v_mov_b32_e32 v117, v125
	v_mov_b32_e32 v116, v125
	v_mov_b32_e32 v115, v125
	v_mov_b32_e32 v114, v125
	v_mov_b32_e32 v105, v125
	v_mov_b32_e32 v104, v125
	v_mov_b32_e32 v103, v125
	v_mov_b32_e32 v102, v125
	v_mov_b32_e32 v101, v125
	v_mov_b32_e32 v100, v125
	v_mov_b32_e32 v99, v125
	v_mov_b32_e32 v98, v125
	v_mov_b32_e32 v89, v125
	v_mov_b32_e32 v88, v125
	v_mov_b32_e32 v87, v125
	v_mov_b32_e32 v86, v125
	v_mov_b32_e32 v85, v125
	v_mov_b32_e32 v84, v125
	v_mov_b32_e32 v83, v125
	v_mov_b32_e32 v82, v125
	v_mov_b32_e32 v73, v125
	v_mov_b32_e32 v72, v125
	v_mov_b32_e32 v71, v125
	v_mov_b32_e32 v70, v125
	v_mov_b32_e32 v69, v125
	v_mov_b32_e32 v68, v125
	v_mov_b32_e32 v67, v125
	v_mov_b32_e32 v66, v125
	v_mov_b32_e32 v65, v125
	v_mov_b32_e32 v64, v125
	v_mov_b32_e32 v63, v125
	v_mov_b32_e32 v62, v125
	v_mov_b32_e32 v61, v125
	v_mov_b32_e32 v60, v125
	v_mov_b32_e32 v59, v125
	v_mov_b32_e32 v58, v125
	v_mov_b32_e32 v49, v125
	v_mov_b32_e32 v48, v125
	v_mov_b32_e32 v47, v125
	v_mov_b32_e32 v46, v125
	v_mov_b32_e32 v45, v125
	v_mov_b32_e32 v44, v125
	v_mov_b32_e32 v43, v125
	v_mov_b32_e32 v42, v125
	v_mov_b32_e32 v33, v125
	v_mov_b32_e32 v32, v125
	v_mov_b32_e32 v31, v125
	v_mov_b32_e32 v30, v125
	v_mov_b32_e32 v29, v125
	v_mov_b32_e32 v28, v125
	v_mov_b32_e32 v27, v125
	v_mov_b32_e32 v26, v125
	v_mov_b32_e32 v17, v125
	v_mov_b32_e32 v16, v125
	v_mov_b32_e32 v15, v125
	v_mov_b32_e32 v14, v125
	v_mov_b32_e32 v13, v125
	v_mov_b32_e32 v12, v125
	v_mov_b32_e32 v11, v125
	v_mov_b32_e32 v10, v125
	v_mov_b32_e32 v57, v125
	v_mov_b32_e32 v56, v125
	v_mov_b32_e32 v55, v125
	v_mov_b32_e32 v54, v125
	v_mov_b32_e32 v53, v125
	v_mov_b32_e32 v52, v125
	v_mov_b32_e32 v51, v125
	v_mov_b32_e32 v50, v125
	v_mov_b32_e32 v41, v125
	v_mov_b32_e32 v40, v125
	v_mov_b32_e32 v39, v125
	v_mov_b32_e32 v38, v125
	v_mov_b32_e32 v37, v125
	v_mov_b32_e32 v36, v125
	v_mov_b32_e32 v35, v125
	v_mov_b32_e32 v34, v125
	v_mov_b32_e32 v25, v125
	v_mov_b32_e32 v24, v125
	v_mov_b32_e32 v23, v125
	v_mov_b32_e32 v22, v125
	v_mov_b32_e32 v21, v125
	v_mov_b32_e32 v20, v125
	v_mov_b32_e32 v19, v125
	v_mov_b32_e32 v18, v125
	v_mov_b32_e32 v9, v125
	v_mov_b32_e32 v8, v125
	v_mov_b32_e32 v7, v125
	v_mov_b32_e32 v6, v125
	v_mov_b32_e32 v5, v125
	v_mov_b32_e32 v4, v125
	v_mov_b32_e32 v3, v125
	v_mov_b32_e32 v2, v125
	s_cbranch_vccnz .LBB0_2177
	s_and_b64 s[8:9], s[40:41], exec
	s_cselect_b32 s8, s69, s73
	s_cselect_b32 s9, s70, s82
	s_addk_i32 s73, 0x80
	s_addk_i32 s82, 0x100
	s_mov_b32 s83, 0
	s_cmp_eq_u32 m0, -1
	s_cbranch_scc0 .Lgk_rs_12
	s_barrier
.Lgk_rs_12:
	v_add_u32_e32 v144, 0x10000, v134
	ds_read_b128 v[136:139], v144
	ds_read_b128 v[140:143], v144 offset:1024
	ds_read_b128 v[154:157], v144 offset:2048
	ds_read_b128 v[170:173], v144 offset:3072
	v_add_u32_e32 v144, 0x14000, v134
	ds_read_b128 v[174:177], v144
	ds_read_b128 v[178:181], v144 offset:1024
	ds_read_b128 v[182:185], v144 offset:2048
	ds_read_b128 v[186:189], v144 offset:3072
	s_add_i32 s46, s73, 0x80
	s_cmp_eq_u32 s49, s83
	s_cselect_b32 s52, s8, s46
	s_cselect_b32 s85, s9, s82
	s_add_i32 s84, s52, 0x80
	s_add_i32 s46, s2, s73
	s_mov_b32 m0, s64
	ds_read_b128 v[190:193], v135
	ds_read_b128 v[194:197], v135 offset:1024
	ds_read_b128 v[198:201], v135 offset:2048
	ds_read_b128 v[202:205], v135 offset:3072
	ds_read_b128 v[228:231], v135 offset:4096
	ds_read_b128 v[232:235], v135 offset:5120
	ds_read_b128 v[236:239], v135 offset:6144
	ds_read_b128 v[240:243], v135 offset:7168
	buffer_load_dwordx4 v130, s[60:63], s46 offen lds
	s_mov_b32 m0, s65
	s_nop 0
	buffer_load_dwordx4 v132, s[60:63], s46 offen lds
	s_waitcnt vmcnt(8)
	s_waitcnt lgkmcnt(0)
	s_setprio 1
	s_barrier
	v_mfma_f32_16x16x32_bf16 v[122:125], v[136:139], v[190:193], 0
	v_mfma_f32_16x16x32_bf16 v[122:125], v[140:143], v[194:197], v[122:125]
	v_mfma_f32_16x16x32_bf16 v[126:129], v[154:157], v[190:193], 0
	v_mfma_f32_16x16x32_bf16 v[126:129], v[170:173], v[194:197], v[126:129]
	v_mfma_f32_16x16x32_bf16 v[114:117], v[182:185], v[190:193], 0
	v_mfma_f32_16x16x32_bf16 v[114:117], v[186:189], v[194:197], v[114:117]
	v_mfma_f32_16x16x32_bf16 v[118:121], v[174:177], v[190:193], 0
	v_mfma_f32_16x16x32_bf16 v[118:121], v[178:181], v[194:197], v[118:121]
	v_mfma_f32_16x16x32_bf16 v[102:105], v[174:177], v[198:201], 0
	v_mfma_f32_16x16x32_bf16 v[102:105], v[178:181], v[202:205], v[102:105]
	v_mfma_f32_16x16x32_bf16 v[98:101], v[182:185], v[198:201], 0
	v_mfma_f32_16x16x32_bf16 v[98:101], v[186:189], v[202:205], v[98:101]
	v_mfma_f32_16x16x32_bf16 v[106:109], v[154:157], v[198:201], 0
	v_mfma_f32_16x16x32_bf16 v[106:109], v[170:173], v[202:205], v[106:109]
	v_mfma_f32_16x16x32_bf16 v[110:113], v[136:139], v[198:201], 0
	v_mfma_f32_16x16x32_bf16 v[110:113], v[140:143], v[202:205], v[110:113]
	v_mfma_f32_16x16x32_bf16 v[94:97], v[136:139], v[228:231], 0
	v_mfma_f32_16x16x32_bf16 v[94:97], v[140:143], v[232:235], v[94:97]
	v_mfma_f32_16x16x32_bf16 v[90:93], v[154:157], v[228:231], 0
	v_mfma_f32_16x16x32_bf16 v[90:93], v[170:173], v[232:235], v[90:93]
	v_mfma_f32_16x16x32_bf16 v[82:85], v[182:185], v[228:231], 0
	v_mfma_f32_16x16x32_bf16 v[82:85], v[186:189], v[232:235], v[82:85]
	v_mfma_f32_16x16x32_bf16 v[86:89], v[174:177], v[228:231], 0
	v_mfma_f32_16x16x32_bf16 v[86:89], v[178:181], v[232:235], v[86:89]
	v_mfma_f32_16x16x32_bf16 v[70:73], v[174:177], v[236:239], 0
	v_mfma_f32_16x16x32_bf16 v[70:73], v[178:181], v[240:243], v[70:73]
	v_mfma_f32_16x16x32_bf16 v[66:69], v[182:185], v[236:239], 0
	v_mfma_f32_16x16x32_bf16 v[66:69], v[186:189], v[240:243], v[66:69]
	v_mfma_f32_16x16x32_bf16 v[74:77], v[154:157], v[236:239], 0
	v_mfma_f32_16x16x32_bf16 v[74:77], v[170:173], v[240:243], v[74:77]
	v_mfma_f32_16x16x32_bf16 v[78:81], v[136:139], v[236:239], 0
	v_mfma_f32_16x16x32_bf16 v[78:81], v[140:143], v[240:243], v[78:81]
	s_barrier
	s_setprio 0
	s_mov_b32 s46, s62
	s_mov_b32 s47, s63
	s_mov_b32 m0, s14
	ds_read_b128 v[190:193], v135 offset:16384
	buffer_load_dwordx4 v131, s[44:47], s85 offen lds
	s_add_i32 s53, s85, s2
	s_mov_b32 m0, s15
	ds_read_b128 v[194:197], v135 offset:17408
	buffer_load_dwordx4 v133, s[44:47], s85 offen lds
	s_mov_b32 m0, s16
	ds_read_b128 v[198:201], v135 offset:18432
	buffer_load_dwordx4 v131, s[44:47], s53 offen lds
	s_mov_b32 m0, s18
	ds_read_b128 v[202:205], v135 offset:19456
	buffer_load_dwordx4 v133, s[44:47], s53 offen lds
	s_mov_b32 m0, s13
	ds_read_b128 v[228:231], v135 offset:20480
	buffer_load_dwordx4 v130, s[60:63], s52 offen lds
	s_mov_b32 m0, s19
	ds_read_b128 v[232:235], v135 offset:21504
	buffer_load_dwordx4 v132, s[60:63], s52 offen lds
	ds_read_b128 v[236:239], v135 offset:22528
	ds_read_b128 v[240:243], v135 offset:23552
	s_waitcnt vmcnt(8)
	s_waitcnt lgkmcnt(0)
	s_setprio 1
	s_barrier
	v_mfma_f32_16x16x32_bf16 v[62:65], v[136:139], v[190:193], 0
	v_mfma_f32_16x16x32_bf16 v[62:65], v[140:143], v[194:197], v[62:65]
	v_mfma_f32_16x16x32_bf16 v[58:61], v[154:157], v[190:193], 0
	v_mfma_f32_16x16x32_bf16 v[58:61], v[170:173], v[194:197], v[58:61]
	v_mfma_f32_16x16x32_bf16 v[50:53], v[182:185], v[190:193], 0
	v_mfma_f32_16x16x32_bf16 v[50:53], v[186:189], v[194:197], v[50:53]
	v_mfma_f32_16x16x32_bf16 v[54:57], v[174:177], v[190:193], 0
	v_mfma_f32_16x16x32_bf16 v[54:57], v[178:181], v[194:197], v[54:57]
	v_mfma_f32_16x16x32_bf16 v[38:41], v[174:177], v[198:201], 0
	v_mfma_f32_16x16x32_bf16 v[38:41], v[178:181], v[202:205], v[38:41]
	v_mfma_f32_16x16x32_bf16 v[34:37], v[182:185], v[198:201], 0
	v_mfma_f32_16x16x32_bf16 v[34:37], v[186:189], v[202:205], v[34:37]
	v_mfma_f32_16x16x32_bf16 v[42:45], v[154:157], v[198:201], 0
	v_mfma_f32_16x16x32_bf16 v[42:45], v[170:173], v[202:205], v[42:45]
	v_mfma_f32_16x16x32_bf16 v[46:49], v[136:139], v[198:201], 0
	v_mfma_f32_16x16x32_bf16 v[46:49], v[140:143], v[202:205], v[46:49]
	v_mfma_f32_16x16x32_bf16 v[30:33], v[136:139], v[228:231], 0
	v_mfma_f32_16x16x32_bf16 v[30:33], v[140:143], v[232:235], v[30:33]
	v_mfma_f32_16x16x32_bf16 v[26:29], v[154:157], v[228:231], 0
	v_mfma_f32_16x16x32_bf16 v[26:29], v[170:173], v[232:235], v[26:29]
	v_mfma_f32_16x16x32_bf16 v[18:21], v[182:185], v[228:231], 0
	v_mfma_f32_16x16x32_bf16 v[18:21], v[186:189], v[232:235], v[18:21]
	v_mfma_f32_16x16x32_bf16 v[22:25], v[174:177], v[228:231], 0
	v_mfma_f32_16x16x32_bf16 v[22:25], v[178:181], v[232:235], v[22:25]
	v_mfma_f32_16x16x32_bf16 v[6:9], v[174:177], v[236:239], 0
	v_mfma_f32_16x16x32_bf16 v[6:9], v[178:181], v[240:243], v[6:9]
	v_mfma_f32_16x16x32_bf16 v[2:5], v[182:185], v[236:239], 0
	v_mfma_f32_16x16x32_bf16 v[2:5], v[186:189], v[240:243], v[2:5]
	v_mfma_f32_16x16x32_bf16 v[10:13], v[154:157], v[236:239], 0
	v_mfma_f32_16x16x32_bf16 v[10:13], v[170:173], v[240:243], v[10:13]
	v_mfma_f32_16x16x32_bf16 v[14:17], v[136:139], v[236:239], 0
	v_mfma_f32_16x16x32_bf16 v[14:17], v[140:143], v[240:243], v[14:17]
	s_barrier
	s_setprio 0
	v_add_u32_e32 v144, 0x18000, v134
	ds_read_b128 v[136:139], v144
	ds_read_b128 v[140:143], v144 offset:1024
	ds_read_b128 v[154:157], v144 offset:2048
	ds_read_b128 v[170:173], v144 offset:3072
	v_add_u32_e32 v144, 0x1c000, v134
	ds_read_b128 v[174:177], v144
	ds_read_b128 v[178:181], v144 offset:1024
	ds_read_b128 v[182:185], v144 offset:2048
	ds_read_b128 v[186:189], v144 offset:3072
	s_add_i32 s52, s52, s2
	s_mov_b32 m0, s21
	ds_read_b128 v[190:193], v135 offset:32768
	ds_read_b128 v[194:197], v135 offset:33792
	ds_read_b128 v[198:201], v135 offset:34816
	ds_read_b128 v[202:205], v135 offset:35840
	ds_read_b128 v[228:231], v135 offset:36864
	ds_read_b128 v[232:235], v135 offset:37888
	ds_read_b128 v[236:239], v135 offset:38912
	ds_read_b128 v[240:243], v135 offset:39936
	buffer_load_dwordx4 v130, s[60:63], s52 offen lds
	s_mov_b32 m0, s22
	s_nop 0
	buffer_load_dwordx4 v132, s[60:63], s52 offen lds
	s_waitcnt vmcnt(8)
	s_waitcnt lgkmcnt(0)
	s_setprio 1
	s_barrier
	v_mfma_f32_16x16x32_bf16 v[122:125], v[136:139], v[190:193], v[122:125]
	v_mfma_f32_16x16x32_bf16 v[122:125], v[140:143], v[194:197], v[122:125]
	v_mfma_f32_16x16x32_bf16 v[126:129], v[154:157], v[190:193], v[126:129]
	v_mfma_f32_16x16x32_bf16 v[126:129], v[170:173], v[194:197], v[126:129]
	v_mfma_f32_16x16x32_bf16 v[114:117], v[182:185], v[190:193], v[114:117]
	v_mfma_f32_16x16x32_bf16 v[114:117], v[186:189], v[194:197], v[114:117]
	v_mfma_f32_16x16x32_bf16 v[118:121], v[174:177], v[190:193], v[118:121]
	v_mfma_f32_16x16x32_bf16 v[118:121], v[178:181], v[194:197], v[118:121]
	v_mfma_f32_16x16x32_bf16 v[102:105], v[174:177], v[198:201], v[102:105]
	v_mfma_f32_16x16x32_bf16 v[102:105], v[178:181], v[202:205], v[102:105]
	v_mfma_f32_16x16x32_bf16 v[98:101], v[182:185], v[198:201], v[98:101]
	v_mfma_f32_16x16x32_bf16 v[98:101], v[186:189], v[202:205], v[98:101]
	v_mfma_f32_16x16x32_bf16 v[106:109], v[154:157], v[198:201], v[106:109]
	v_mfma_f32_16x16x32_bf16 v[106:109], v[170:173], v[202:205], v[106:109]
	v_mfma_f32_16x16x32_bf16 v[110:113], v[136:139], v[198:201], v[110:113]
	v_mfma_f32_16x16x32_bf16 v[110:113], v[140:143], v[202:205], v[110:113]
	v_mfma_f32_16x16x32_bf16 v[94:97], v[136:139], v[228:231], v[94:97]
	v_mfma_f32_16x16x32_bf16 v[94:97], v[140:143], v[232:235], v[94:97]
	v_mfma_f32_16x16x32_bf16 v[90:93], v[154:157], v[228:231], v[90:93]
	v_mfma_f32_16x16x32_bf16 v[90:93], v[170:173], v[232:235], v[90:93]
	v_mfma_f32_16x16x32_bf16 v[82:85], v[182:185], v[228:231], v[82:85]
	v_mfma_f32_16x16x32_bf16 v[82:85], v[186:189], v[232:235], v[82:85]
	v_mfma_f32_16x16x32_bf16 v[86:89], v[174:177], v[228:231], v[86:89]
	v_mfma_f32_16x16x32_bf16 v[86:89], v[178:181], v[232:235], v[86:89]
	v_mfma_f32_16x16x32_bf16 v[70:73], v[174:177], v[236:239], v[70:73]
	v_mfma_f32_16x16x32_bf16 v[70:73], v[178:181], v[240:243], v[70:73]
	v_mfma_f32_16x16x32_bf16 v[66:69], v[182:185], v[236:239], v[66:69]
	v_mfma_f32_16x16x32_bf16 v[66:69], v[186:189], v[240:243], v[66:69]
	v_mfma_f32_16x16x32_bf16 v[74:77], v[154:157], v[236:239], v[74:77]
	v_mfma_f32_16x16x32_bf16 v[74:77], v[170:173], v[240:243], v[74:77]
	v_mfma_f32_16x16x32_bf16 v[78:81], v[136:139], v[236:239], v[78:81]
	v_mfma_f32_16x16x32_bf16 v[78:81], v[140:143], v[240:243], v[78:81]
	s_barrier
	s_setprio 0
	s_add_i32 s52, s85, 0x80
	s_mov_b32 m0, s33
	ds_read_b128 v[190:193], v135 offset:49152
	buffer_load_dwordx4 v131, s[44:47], s52 offen lds
	s_mov_b32 m0, s36
	ds_read_b128 v[194:197], v135 offset:50176
	buffer_load_dwordx4 v133, s[44:47], s52 offen lds
	s_add_i32 s52, s52, s2
	s_mov_b32 m0, s43
	ds_read_b128 v[198:201], v135 offset:51200
	buffer_load_dwordx4 v131, s[44:47], s52 offen lds
	s_mov_b32 m0, s48
	ds_read_b128 v[202:205], v135 offset:52224
	buffer_load_dwordx4 v133, s[44:47], s52 offen lds
	s_mov_b32 m0, s37
	ds_read_b128 v[228:231], v135 offset:53248
	buffer_load_dwordx4 v130, s[60:63], s84 offen lds
	s_mov_b32 m0, s42
	ds_read_b128 v[232:235], v135 offset:54272
	buffer_load_dwordx4 v132, s[60:63], s84 offen lds
	ds_read_b128 v[236:239], v135 offset:55296
	ds_read_b128 v[240:243], v135 offset:56320
	s_waitcnt vmcnt(8)
	s_waitcnt lgkmcnt(0)
	s_setprio 1
	s_barrier
	v_mfma_f32_16x16x32_bf16 v[62:65], v[136:139], v[190:193], v[62:65]
	v_mfma_f32_16x16x32_bf16 v[62:65], v[140:143], v[194:197], v[62:65]
	v_mfma_f32_16x16x32_bf16 v[58:61], v[154:157], v[190:193], v[58:61]
	v_mfma_f32_16x16x32_bf16 v[58:61], v[170:173], v[194:197], v[58:61]
	v_mfma_f32_16x16x32_bf16 v[50:53], v[182:185], v[190:193], v[50:53]
	v_mfma_f32_16x16x32_bf16 v[50:53], v[186:189], v[194:197], v[50:53]
	v_mfma_f32_16x16x32_bf16 v[54:57], v[174:177], v[190:193], v[54:57]
	v_mfma_f32_16x16x32_bf16 v[54:57], v[178:181], v[194:197], v[54:57]
	v_mfma_f32_16x16x32_bf16 v[38:41], v[174:177], v[198:201], v[38:41]
	v_mfma_f32_16x16x32_bf16 v[38:41], v[178:181], v[202:205], v[38:41]
	v_mfma_f32_16x16x32_bf16 v[34:37], v[182:185], v[198:201], v[34:37]
	v_mfma_f32_16x16x32_bf16 v[34:37], v[186:189], v[202:205], v[34:37]
	v_mfma_f32_16x16x32_bf16 v[42:45], v[154:157], v[198:201], v[42:45]
	v_mfma_f32_16x16x32_bf16 v[42:45], v[170:173], v[202:205], v[42:45]
	v_mfma_f32_16x16x32_bf16 v[46:49], v[136:139], v[198:201], v[46:49]
	v_mfma_f32_16x16x32_bf16 v[46:49], v[140:143], v[202:205], v[46:49]
	v_mfma_f32_16x16x32_bf16 v[30:33], v[136:139], v[228:231], v[30:33]
	v_mfma_f32_16x16x32_bf16 v[30:33], v[140:143], v[232:235], v[30:33]
	v_mfma_f32_16x16x32_bf16 v[26:29], v[154:157], v[228:231], v[26:29]
	v_mfma_f32_16x16x32_bf16 v[26:29], v[170:173], v[232:235], v[26:29]
	v_mfma_f32_16x16x32_bf16 v[18:21], v[182:185], v[228:231], v[18:21]
	v_mfma_f32_16x16x32_bf16 v[18:21], v[186:189], v[232:235], v[18:21]
	v_mfma_f32_16x16x32_bf16 v[22:25], v[174:177], v[228:231], v[22:25]
	v_mfma_f32_16x16x32_bf16 v[22:25], v[178:181], v[232:235], v[22:25]
	v_mfma_f32_16x16x32_bf16 v[6:9], v[174:177], v[236:239], v[6:9]
	v_mfma_f32_16x16x32_bf16 v[6:9], v[178:181], v[240:243], v[6:9]
	v_mfma_f32_16x16x32_bf16 v[2:5], v[182:185], v[236:239], v[2:5]
	v_mfma_f32_16x16x32_bf16 v[2:5], v[186:189], v[240:243], v[2:5]
	v_mfma_f32_16x16x32_bf16 v[10:13], v[154:157], v[236:239], v[10:13]
	v_mfma_f32_16x16x32_bf16 v[10:13], v[170:173], v[240:243], v[10:13]
	v_mfma_f32_16x16x32_bf16 v[14:17], v[136:139], v[236:239], v[14:17]
	v_mfma_f32_16x16x32_bf16 v[14:17], v[140:143], v[240:243], v[14:17]
	s_barrier
	s_setprio 0
	s_add_i32 s83, s83, 2
	s_addk_i32 s73, 0x100
	s_addk_i32 s82, 0x100
	s_cmp_ge_i32 s83, s23

.LBB0_2179:
	s_lshl_b32 s8, s72, 8
	s_add_i32 s8, s8, s24
	s_lshl_b32 s9, s71, 8
	s_or_b32 s46, s9, s25
	s_ashr_i32 s9, s8, 31
	s_ashr_i32 s47, s46, 31
	s_lshl_b64 s[72:73], s[8:9], 12
	s_add_u32 s9, s30, s72
	s_addc_u32 s52, s31, s73
	s_lshl_b64 s[46:47], s[46:47], 1
	s_add_u32 s72, s9, s46
	s_addc_u32 s73, s52, s47
	v_lshl_add_u64 v[136:137], s[72:73], 0, v[146:147]
	v_cvt_pk_bf16_f32 v122, v122, v123
	v_cvt_pk_bf16_f32 v123, v124, v125
	v_cvt_pk_bf16_f32 v124, v126, v127
	v_cvt_pk_bf16_f32 v125, v128, v129
	global_store_dwordx4 v146, v[122:125], s[72:73]
	v_cvt_pk_bf16_f32 v118, v118, v119
	v_cvt_pk_bf16_f32 v119, v120, v121
	v_cvt_pk_bf16_f32 v120, v114, v115
	v_cvt_pk_bf16_f32 v121, v116, v117
	global_store_dwordx4 v146, v[118:121], s[72:73] offset:256
	s_or_b32 s72, s8, 16
	s_ashr_i32 s73, s72, 31
	s_lshl_b64 s[72:73], s[72:73], 12
	s_add_u32 s9, s30, s72
	s_addc_u32 s52, s31, s73
	s_add_u32 s72, s9, s46
	s_addc_u32 s73, s52, s47
	v_cvt_pk_bf16_f32 v110, v110, v111
	v_cvt_pk_bf16_f32 v111, v112, v113
	v_cvt_pk_bf16_f32 v112, v106, v107
	v_cvt_pk_bf16_f32 v113, v108, v109
	global_store_dwordx4 v146, v[110:113], s[72:73]
	v_cvt_pk_bf16_f32 v102, v102, v103
	v_cvt_pk_bf16_f32 v103, v104, v105
	v_cvt_pk_bf16_f32 v104, v98, v99
	v_cvt_pk_bf16_f32 v105, v100, v101
	global_store_dwordx4 v146, v[102:105], s[72:73] offset:256
	s_or_b32 s72, s8, 32
	s_ashr_i32 s73, s72, 31
	s_lshl_b64 s[72:73], s[72:73], 12
	s_add_u32 s9, s30, s72
	s_addc_u32 s52, s31, s73
	s_add_u32 s72, s9, s46
	s_addc_u32 s73, s52, s47
	s_or_b32 s8, s8, 48
	s_ashr_i32 s9, s8, 31
	s_lshl_b64 s[8:9], s[8:9], 12
	s_add_u32 s8, s30, s8
	s_addc_u32 s9, s31, s9
	s_add_u32 s8, s8, s46
	s_addc_u32 s9, s9, s47
	v_cvt_pk_bf16_f32 v94, v94, v95
	v_cvt_pk_bf16_f32 v95, v96, v97
	v_cvt_pk_bf16_f32 v96, v90, v91
	v_cvt_pk_bf16_f32 v97, v92, v93
	global_store_dwordx4 v146, v[94:97], s[72:73]
	v_cvt_pk_bf16_f32 v86, v86, v87
	v_cvt_pk_bf16_f32 v87, v88, v89
	v_cvt_pk_bf16_f32 v88, v82, v83
	v_cvt_pk_bf16_f32 v89, v84, v85
	global_store_dwordx4 v146, v[86:89], s[72:73] offset:256
	v_cvt_pk_bf16_f32 v78, v78, v79
	v_cvt_pk_bf16_f32 v79, v80, v81
	v_cvt_pk_bf16_f32 v80, v74, v75
	v_cvt_pk_bf16_f32 v81, v76, v77
	global_store_dwordx4 v146, v[78:81], s[8:9]
	v_cvt_pk_bf16_f32 v70, v70, v71
	v_cvt_pk_bf16_f32 v71, v72, v73
	v_cvt_pk_bf16_f32 v72, v66, v67
	v_cvt_pk_bf16_f32 v73, v68, v69
	global_store_dwordx4 v146, v[70:73], s[8:9] offset:256
	s_mov_b64 s[8:9], 0x80000
	v_lshl_add_u64 v[66:67], v[136:137], 0, s[8:9]
	s_mov_b32 s8, 0x80000
	v_cvt_pk_bf16_f32 v62, v62, v63
	v_cvt_pk_bf16_f32 v63, v64, v65
	v_cvt_pk_bf16_f32 v64, v58, v59
	v_add_co_u32_e32 v58, vcc, s8, v136
	s_mov_b64 s[8:9], 0x90000
	s_nop 0
	v_addc_co_u32_e32 v59, vcc, 0, v137, vcc
	v_cvt_pk_bf16_f32 v65, v60, v61
	global_store_dwordx4 v[58:59], v[62:65], off
	v_cvt_pk_bf16_f32 v54, v54, v55
	v_cvt_pk_bf16_f32 v55, v56, v57
	v_cvt_pk_bf16_f32 v56, v50, v51
	v_lshl_add_u64 v[50:51], v[136:137], 0, s[8:9]
	s_mov_b32 s8, 0x90000
	v_cvt_pk_bf16_f32 v57, v52, v53
	global_store_dwordx4 v[66:67], v[54:57], off offset:256
	v_cvt_pk_bf16_f32 v46, v46, v47
	v_cvt_pk_bf16_f32 v47, v48, v49
	v_cvt_pk_bf16_f32 v48, v42, v43
	v_add_co_u32_e32 v42, vcc, s8, v136
	s_mov_b64 s[8:9], 0xa0000
	s_nop 0
	v_addc_co_u32_e32 v43, vcc, 0, v137, vcc
	v_cvt_pk_bf16_f32 v49, v44, v45
	global_store_dwordx4 v[42:43], v[46:49], off
	v_cvt_pk_bf16_f32 v38, v38, v39
	v_cvt_pk_bf16_f32 v39, v40, v41
	v_cvt_pk_bf16_f32 v40, v34, v35
	v_lshl_add_u64 v[34:35], v[136:137], 0, s[8:9]
	s_mov_b32 s8, 0xa0000
	v_cvt_pk_bf16_f32 v41, v36, v37
	global_store_dwordx4 v[50:51], v[38:41], off offset:256
	v_cvt_pk_bf16_f32 v30, v30, v31
	v_cvt_pk_bf16_f32 v31, v32, v33
	v_cvt_pk_bf16_f32 v32, v26, v27
	v_add_co_u32_e32 v26, vcc, s8, v136
	v_cvt_pk_bf16_f32 v33, v28, v29
	s_mov_b64 s[8:9], 0xb0000
	s_nop 0
	v_addc_co_u32_e32 v27, vcc, 0, v137, vcc
	global_store_dwordx4 v[26:27], v[30:33], off
	v_cvt_pk_bf16_f32 v22, v22, v23
	v_cvt_pk_bf16_f32 v23, v24, v25
	v_cvt_pk_bf16_f32 v24, v18, v19
	v_cvt_pk_bf16_f32 v25, v20, v21
	global_store_dwordx4 v[34:35], v[22:25], off offset:256
	v_cvt_pk_bf16_f32 v14, v14, v15
	v_cvt_pk_bf16_f32 v15, v16, v17
	v_cvt_pk_bf16_f32 v16, v10, v11
	v_add_co_u32_e32 v10, vcc, 0xb0000, v136
	v_lshl_add_u64 v[18:19], v[136:137], 0, s[8:9]
	s_nop 0
	v_addc_co_u32_e32 v11, vcc, 0, v137, vcc
	s_andn2_b64 vcc, exec, s[40:41]
	s_mov_b64 s[8:9], -1
	v_cvt_pk_bf16_f32 v17, v12, v13
	global_store_dwordx4 v[10:11], v[14:17], off
	v_cvt_pk_bf16_f32 v6, v6, v7
	v_cvt_pk_bf16_f32 v7, v8, v9
	v_cvt_pk_bf16_f32 v8, v2, v3
	v_cvt_pk_bf16_f32 v9, v4, v5
	global_store_dwordx4 v[18:19], v[6:9], off offset:256
	s_cbranch_vccnz .LBB0_2170
	s_andn2_b64 vcc, exec, s[26:27]
	s_cbranch_vccnz .LBB0_2169
	s_mov_b32 m0, -1
	s_branch .LBB0_2169

.LBB0_2449:
	s_lshl_b32 s73, s72, 20
	s_and_b64 s[8:9], s[40:41], exec
	s_cselect_b32 s8, s73, s13
	s_lshl_b32 s84, s71, 20
	s_and_b64 s[24:25], s[40:41], exec
	s_cselect_b32 s9, s84, s21
	s_add_i32 s13, s13, 0x80080
	s_addk_i32 s21, 0x100
	s_mov_b32 s22, -2
	s_waitcnt lgkmcnt(0)
	s_cmp_eq_u32 m0, -1
	s_cbranch_scc0 .Lgk_rs_13
	s_barrier
.Lgk_rs_13:
	v_add_u32_e32 v142, 0x10000, v188
	v_add_u32_e32 v182, 0x14000, v188
	ds_read_b128 v[130:133], v142
	ds_read_b128 v[134:137], v142 offset:1024
	ds_read_b128 v[138:141], v142 offset:2048
	ds_read_b128 v[142:145], v142 offset:3072
	ds_read_b128 v[154:157], v182
	ds_read_b128 v[174:177], v182 offset:1024
	ds_read_b128 v[178:181], v182 offset:2048
	ds_read_b128 v[190:193], v182 offset:3072
	s_add_i32 s24, s13, 0xfff80080
	s_cmp_eq_u32 s22, 28
	s_cselect_b32 s52, s8, s24
	s_cselect_b32 s25, s9, s21
	s_or_b32 s24, s52, 0x80
	s_mov_b32 m0, s68
	ds_read_b128 v[194:197], v189
	ds_read_b128 v[198:201], v189 offset:1024
	ds_read_b128 v[202:205], v189 offset:2048
	ds_read_b128 v[228:231], v189 offset:3072
	ds_read_b128 v[232:235], v189 offset:4096
	ds_read_b128 v[236:239], v189 offset:5120
	ds_read_b128 v[240:243], v189 offset:6144
	ds_read_b128 v[244:247], v189 offset:7168
	buffer_load_dwordx4 v184, s[60:63], s13 offen lds
	s_mov_b32 m0, s70
	s_nop 0
	buffer_load_dwordx4 v186, s[60:63], s13 offen lds
	s_waitcnt vmcnt(8)
	s_waitcnt lgkmcnt(0)
	s_setprio 1
	s_barrier
	v_mfma_f32_16x16x32_bf16 v[126:129], v[130:133], v[194:197], 0
	v_mfma_f32_16x16x32_bf16 v[126:129], v[134:137], v[198:201], v[126:129]
	v_mfma_f32_16x16x32_bf16 v[122:125], v[138:141], v[194:197], 0
	v_mfma_f32_16x16x32_bf16 v[122:125], v[142:145], v[198:201], v[122:125]
	v_mfma_f32_16x16x32_bf16 v[114:117], v[178:181], v[194:197], 0
	v_mfma_f32_16x16x32_bf16 v[114:117], v[190:193], v[198:201], v[114:117]
	v_mfma_f32_16x16x32_bf16 v[118:121], v[154:157], v[194:197], 0
	v_mfma_f32_16x16x32_bf16 v[118:121], v[174:177], v[198:201], v[118:121]
	v_mfma_f32_16x16x32_bf16 v[102:105], v[154:157], v[202:205], 0
	v_mfma_f32_16x16x32_bf16 v[102:105], v[174:177], v[228:231], v[102:105]
	v_mfma_f32_16x16x32_bf16 v[98:101], v[178:181], v[202:205], 0
	v_mfma_f32_16x16x32_bf16 v[98:101], v[190:193], v[228:231], v[98:101]
	v_mfma_f32_16x16x32_bf16 v[106:109], v[138:141], v[202:205], 0
	v_mfma_f32_16x16x32_bf16 v[106:109], v[142:145], v[228:231], v[106:109]
	v_mfma_f32_16x16x32_bf16 v[110:113], v[130:133], v[202:205], 0
	v_mfma_f32_16x16x32_bf16 v[110:113], v[134:137], v[228:231], v[110:113]
	v_mfma_f32_16x16x32_bf16 v[94:97], v[130:133], v[232:235], 0
	v_mfma_f32_16x16x32_bf16 v[94:97], v[134:137], v[236:239], v[94:97]
	v_mfma_f32_16x16x32_bf16 v[90:93], v[138:141], v[232:235], 0
	v_mfma_f32_16x16x32_bf16 v[90:93], v[142:145], v[236:239], v[90:93]
	v_mfma_f32_16x16x32_bf16 v[82:85], v[178:181], v[232:235], 0
	v_mfma_f32_16x16x32_bf16 v[82:85], v[190:193], v[236:239], v[82:85]
	v_mfma_f32_16x16x32_bf16 v[86:89], v[154:157], v[232:235], 0
	v_mfma_f32_16x16x32_bf16 v[86:89], v[174:177], v[236:239], v[86:89]
	v_mfma_f32_16x16x32_bf16 v[70:73], v[154:157], v[240:243], 0
	v_mfma_f32_16x16x32_bf16 v[70:73], v[174:177], v[244:247], v[70:73]
	v_mfma_f32_16x16x32_bf16 v[66:69], v[178:181], v[240:243], 0
	v_mfma_f32_16x16x32_bf16 v[66:69], v[190:193], v[244:247], v[66:69]
	v_mfma_f32_16x16x32_bf16 v[74:77], v[138:141], v[240:243], 0
	v_mfma_f32_16x16x32_bf16 v[74:77], v[142:145], v[244:247], v[74:77]
	v_mfma_f32_16x16x32_bf16 v[78:81], v[130:133], v[240:243], 0
	v_mfma_f32_16x16x32_bf16 v[78:81], v[134:137], v[244:247], v[78:81]
	s_barrier
	s_setprio 0
	s_mov_b32 s46, s62
	s_mov_b32 s47, s63
	s_mov_b32 m0, s16
	ds_read_b128 v[194:197], v189 offset:16384
	buffer_load_dwordx4 v185, s[44:47], s25 offen lds
	s_add_i32 s53, s25, 0x80000
	s_mov_b32 m0, s18
	ds_read_b128 v[198:201], v189 offset:17408
	buffer_load_dwordx4 v187, s[44:47], s25 offen lds
	s_mov_b32 m0, s19
	ds_read_b128 v[202:205], v189 offset:18432
	buffer_load_dwordx4 v185, s[44:47], s53 offen lds
	s_mov_b32 m0, s23
	ds_read_b128 v[228:231], v189 offset:19456
	buffer_load_dwordx4 v187, s[44:47], s53 offen lds
	s_mov_b32 m0, s15
	ds_read_b128 v[232:235], v189 offset:20480
	buffer_load_dwordx4 v184, s[60:63], s52 offen lds
	s_mov_b32 m0, s26
	ds_read_b128 v[236:239], v189 offset:21504
	buffer_load_dwordx4 v186, s[60:63], s52 offen lds
	ds_read_b128 v[240:243], v189 offset:22528
	ds_read_b128 v[244:247], v189 offset:23552
	s_waitcnt vmcnt(8)
	s_waitcnt lgkmcnt(0)
	s_setprio 1
	s_barrier
	v_mfma_f32_16x16x32_bf16 v[62:65], v[130:133], v[194:197], 0
	v_mfma_f32_16x16x32_bf16 v[62:65], v[134:137], v[198:201], v[62:65]
	v_mfma_f32_16x16x32_bf16 v[58:61], v[138:141], v[194:197], 0
	v_mfma_f32_16x16x32_bf16 v[58:61], v[142:145], v[198:201], v[58:61]
	v_mfma_f32_16x16x32_bf16 v[50:53], v[178:181], v[194:197], 0
	v_mfma_f32_16x16x32_bf16 v[50:53], v[190:193], v[198:201], v[50:53]
	v_mfma_f32_16x16x32_bf16 v[54:57], v[154:157], v[194:197], 0
	v_mfma_f32_16x16x32_bf16 v[54:57], v[174:177], v[198:201], v[54:57]
	v_mfma_f32_16x16x32_bf16 v[38:41], v[154:157], v[202:205], 0
	v_mfma_f32_16x16x32_bf16 v[38:41], v[174:177], v[228:231], v[38:41]
	v_mfma_f32_16x16x32_bf16 v[34:37], v[178:181], v[202:205], 0
	v_mfma_f32_16x16x32_bf16 v[34:37], v[190:193], v[228:231], v[34:37]
	v_mfma_f32_16x16x32_bf16 v[42:45], v[138:141], v[202:205], 0
	v_mfma_f32_16x16x32_bf16 v[42:45], v[142:145], v[228:231], v[42:45]
	v_mfma_f32_16x16x32_bf16 v[46:49], v[130:133], v[202:205], 0
	v_mfma_f32_16x16x32_bf16 v[46:49], v[134:137], v[228:231], v[46:49]
	v_mfma_f32_16x16x32_bf16 v[30:33], v[130:133], v[232:235], 0
	v_mfma_f32_16x16x32_bf16 v[30:33], v[134:137], v[236:239], v[30:33]
	v_mfma_f32_16x16x32_bf16 v[26:29], v[138:141], v[232:235], 0
	v_mfma_f32_16x16x32_bf16 v[26:29], v[142:145], v[236:239], v[26:29]
	v_mfma_f32_16x16x32_bf16 v[18:21], v[178:181], v[232:235], 0
	v_mfma_f32_16x16x32_bf16 v[18:21], v[190:193], v[236:239], v[18:21]
	v_mfma_f32_16x16x32_bf16 v[22:25], v[154:157], v[232:235], 0
	v_mfma_f32_16x16x32_bf16 v[22:25], v[174:177], v[236:239], v[22:25]
	v_mfma_f32_16x16x32_bf16 v[6:9], v[154:157], v[240:243], 0
	v_mfma_f32_16x16x32_bf16 v[6:9], v[174:177], v[244:247], v[6:9]
	v_mfma_f32_16x16x32_bf16 v[2:5], v[178:181], v[240:243], 0
	v_mfma_f32_16x16x32_bf16 v[2:5], v[190:193], v[244:247], v[2:5]
	v_mfma_f32_16x16x32_bf16 v[10:13], v[138:141], v[240:243], 0
	v_mfma_f32_16x16x32_bf16 v[10:13], v[142:145], v[244:247], v[10:13]
	v_mfma_f32_16x16x32_bf16 v[14:17], v[130:133], v[240:243], 0
	v_mfma_f32_16x16x32_bf16 v[14:17], v[134:137], v[244:247], v[14:17]
	s_barrier
	s_setprio 0
	v_add_u32_e32 v142, 0x18000, v188
	v_add_u32_e32 v182, 0x1c000, v188
	ds_read_b128 v[130:133], v142
	ds_read_b128 v[134:137], v142 offset:1024
	ds_read_b128 v[138:141], v142 offset:2048
	ds_read_b128 v[142:145], v142 offset:3072
	ds_read_b128 v[154:157], v182
	ds_read_b128 v[174:177], v182 offset:1024
	ds_read_b128 v[178:181], v182 offset:2048
	ds_read_b128 v[190:193], v182 offset:3072
	s_add_i32 s52, s52, 0x80000
	s_mov_b32 m0, s27
	ds_read_b128 v[194:197], v189 offset:32768
	ds_read_b128 v[198:201], v189 offset:33792
	ds_read_b128 v[202:205], v189 offset:34816
	ds_read_b128 v[228:231], v189 offset:35840
	ds_read_b128 v[232:235], v189 offset:36864
	ds_read_b128 v[236:239], v189 offset:37888
	ds_read_b128 v[240:243], v189 offset:38912
	ds_read_b128 v[244:247], v189 offset:39936
	buffer_load_dwordx4 v184, s[60:63], s52 offen lds
	s_mov_b32 m0, s30
	s_nop 0
	buffer_load_dwordx4 v186, s[60:63], s52 offen lds
	s_waitcnt vmcnt(8)
	s_waitcnt lgkmcnt(0)
	s_setprio 1
	s_barrier
	v_mfma_f32_16x16x32_bf16 v[126:129], v[130:133], v[194:197], v[126:129]
	v_mfma_f32_16x16x32_bf16 v[126:129], v[134:137], v[198:201], v[126:129]
	v_mfma_f32_16x16x32_bf16 v[122:125], v[138:141], v[194:197], v[122:125]
	v_mfma_f32_16x16x32_bf16 v[122:125], v[142:145], v[198:201], v[122:125]
	v_mfma_f32_16x16x32_bf16 v[114:117], v[178:181], v[194:197], v[114:117]
	v_mfma_f32_16x16x32_bf16 v[114:117], v[190:193], v[198:201], v[114:117]
	v_mfma_f32_16x16x32_bf16 v[118:121], v[154:157], v[194:197], v[118:121]
	v_mfma_f32_16x16x32_bf16 v[118:121], v[174:177], v[198:201], v[118:121]
	v_mfma_f32_16x16x32_bf16 v[102:105], v[154:157], v[202:205], v[102:105]
	v_mfma_f32_16x16x32_bf16 v[102:105], v[174:177], v[228:231], v[102:105]
	v_mfma_f32_16x16x32_bf16 v[98:101], v[178:181], v[202:205], v[98:101]
	v_mfma_f32_16x16x32_bf16 v[98:101], v[190:193], v[228:231], v[98:101]
	v_mfma_f32_16x16x32_bf16 v[106:109], v[138:141], v[202:205], v[106:109]
	v_mfma_f32_16x16x32_bf16 v[106:109], v[142:145], v[228:231], v[106:109]
	v_mfma_f32_16x16x32_bf16 v[110:113], v[130:133], v[202:205], v[110:113]
	v_mfma_f32_16x16x32_bf16 v[110:113], v[134:137], v[228:231], v[110:113]
	v_mfma_f32_16x16x32_bf16 v[94:97], v[130:133], v[232:235], v[94:97]
	v_mfma_f32_16x16x32_bf16 v[94:97], v[134:137], v[236:239], v[94:97]
	v_mfma_f32_16x16x32_bf16 v[90:93], v[138:141], v[232:235], v[90:93]
	v_mfma_f32_16x16x32_bf16 v[90:93], v[142:145], v[236:239], v[90:93]
	v_mfma_f32_16x16x32_bf16 v[82:85], v[178:181], v[232:235], v[82:85]
	v_mfma_f32_16x16x32_bf16 v[82:85], v[190:193], v[236:239], v[82:85]
	v_mfma_f32_16x16x32_bf16 v[86:89], v[154:157], v[232:235], v[86:89]
	v_mfma_f32_16x16x32_bf16 v[86:89], v[174:177], v[236:239], v[86:89]
	v_mfma_f32_16x16x32_bf16 v[70:73], v[154:157], v[240:243], v[70:73]
	v_mfma_f32_16x16x32_bf16 v[70:73], v[174:177], v[244:247], v[70:73]
	v_mfma_f32_16x16x32_bf16 v[66:69], v[178:181], v[240:243], v[66:69]
	v_mfma_f32_16x16x32_bf16 v[66:69], v[190:193], v[244:247], v[66:69]
	v_mfma_f32_16x16x32_bf16 v[74:77], v[138:141], v[240:243], v[74:77]
	v_mfma_f32_16x16x32_bf16 v[74:77], v[142:145], v[244:247], v[74:77]
	v_mfma_f32_16x16x32_bf16 v[78:81], v[130:133], v[240:243], v[78:81]
	v_mfma_f32_16x16x32_bf16 v[78:81], v[134:137], v[244:247], v[78:81]
	s_barrier
	s_setprio 0
	s_or_b32 s52, s25, 0x80
	s_mov_b32 m0, s36
	ds_read_b128 v[194:197], v189 offset:49152
	buffer_load_dwordx4 v185, s[44:47], s52 offen lds
	s_add_i32 s25, s25, 0x80080
	s_mov_b32 m0, s37
	ds_read_b128 v[198:201], v189 offset:50176
	buffer_load_dwordx4 v187, s[44:47], s52 offen lds
	s_mov_b32 m0, s66
	ds_read_b128 v[202:205], v189 offset:51200
	buffer_load_dwordx4 v185, s[44:47], s25 offen lds
	s_mov_b32 m0, s67
	ds_read_b128 v[228:231], v189 offset:52224
	buffer_load_dwordx4 v187, s[44:47], s25 offen lds
	s_mov_b32 m0, s48
	ds_read_b128 v[232:235], v189 offset:53248
	buffer_load_dwordx4 v184, s[60:63], s24 offen lds
	s_mov_b32 m0, s49
	ds_read_b128 v[236:239], v189 offset:54272
	buffer_load_dwordx4 v186, s[60:63], s24 offen lds
	ds_read_b128 v[240:243], v189 offset:55296
	ds_read_b128 v[244:247], v189 offset:56320
	s_waitcnt vmcnt(8)
	s_waitcnt lgkmcnt(0)
	s_setprio 1
	s_barrier
	v_mfma_f32_16x16x32_bf16 v[62:65], v[130:133], v[194:197], v[62:65]
	v_mfma_f32_16x16x32_bf16 v[62:65], v[134:137], v[198:201], v[62:65]
	v_mfma_f32_16x16x32_bf16 v[58:61], v[138:141], v[194:197], v[58:61]
	v_mfma_f32_16x16x32_bf16 v[58:61], v[142:145], v[198:201], v[58:61]
	v_mfma_f32_16x16x32_bf16 v[50:53], v[178:181], v[194:197], v[50:53]
	v_mfma_f32_16x16x32_bf16 v[50:53], v[190:193], v[198:201], v[50:53]
	v_mfma_f32_16x16x32_bf16 v[54:57], v[154:157], v[194:197], v[54:57]
	v_mfma_f32_16x16x32_bf16 v[54:57], v[174:177], v[198:201], v[54:57]
	v_mfma_f32_16x16x32_bf16 v[38:41], v[154:157], v[202:205], v[38:41]
	v_mfma_f32_16x16x32_bf16 v[38:41], v[174:177], v[228:231], v[38:41]
	v_mfma_f32_16x16x32_bf16 v[34:37], v[178:181], v[202:205], v[34:37]
	v_mfma_f32_16x16x32_bf16 v[34:37], v[190:193], v[228:231], v[34:37]
	v_mfma_f32_16x16x32_bf16 v[42:45], v[138:141], v[202:205], v[42:45]
	v_mfma_f32_16x16x32_bf16 v[42:45], v[142:145], v[228:231], v[42:45]
	v_mfma_f32_16x16x32_bf16 v[46:49], v[130:133], v[202:205], v[46:49]
	v_mfma_f32_16x16x32_bf16 v[46:49], v[134:137], v[228:231], v[46:49]
	v_mfma_f32_16x16x32_bf16 v[30:33], v[130:133], v[232:235], v[30:33]
	v_mfma_f32_16x16x32_bf16 v[30:33], v[134:137], v[236:239], v[30:33]
	v_mfma_f32_16x16x32_bf16 v[26:29], v[138:141], v[232:235], v[26:29]
	v_mfma_f32_16x16x32_bf16 v[26:29], v[142:145], v[236:239], v[26:29]
	v_mfma_f32_16x16x32_bf16 v[18:21], v[178:181], v[232:235], v[18:21]
	v_mfma_f32_16x16x32_bf16 v[18:21], v[190:193], v[236:239], v[18:21]
	v_mfma_f32_16x16x32_bf16 v[22:25], v[154:157], v[232:235], v[22:25]
	v_mfma_f32_16x16x32_bf16 v[22:25], v[174:177], v[236:239], v[22:25]
	v_mfma_f32_16x16x32_bf16 v[6:9], v[154:157], v[240:243], v[6:9]
	v_mfma_f32_16x16x32_bf16 v[6:9], v[174:177], v[244:247], v[6:9]
	v_mfma_f32_16x16x32_bf16 v[2:5], v[178:181], v[240:243], v[2:5]
	v_mfma_f32_16x16x32_bf16 v[2:5], v[190:193], v[244:247], v[2:5]
	v_mfma_f32_16x16x32_bf16 v[10:13], v[138:141], v[240:243], v[10:13]
	v_mfma_f32_16x16x32_bf16 v[10:13], v[142:145], v[244:247], v[10:13]
	v_mfma_f32_16x16x32_bf16 v[14:17], v[130:133], v[240:243], v[14:17]
	v_mfma_f32_16x16x32_bf16 v[14:17], v[134:137], v[244:247], v[14:17]
	s_barrier
	s_setprio 0
	s_add_i32 s22, s22, 2
	s_addk_i32 s13, 0x100
	s_addk_i32 s21, 0x100
	s_cmp_gt_u32 s22, 29
